# GEMM K-loops: every s_setprio flip deleted (schedule unchanged) - A/B of the per-phase priority flips
# speedup vs baseline: 1.0048x; 1.0048x over previous
; #define PG8_STAGE(bufoff, gbase, voff) do { _Pragma("unroll") for (int _i = 0; _i < 2; ++_i) \
;         __builtin_amdgcn_global_load_lds((const unsigned*)((const char*)(gbase) + (voff)[_i]), (LAS unsigned*)(lds + (bufoff) + ldsw + _i * 8192), 16, 0, 0); } while (0)
; #define PG8_LDA(dst, b, h) do { _Pragma("unroll") for (int m = 0; m < 4; ++m) _Pragma("unroll") for (int k = 0; k < 2; ++k) dst[m][k] = *(const LAS bf16x8*)(lds + PG8_SA(b, h) + aoff + m * 2048 + k * 1024); } while (0)
; #define PG8_LDB(dst, b, h) do { _Pragma("unroll") for (int n = 0; n < 2; ++n) _Pragma("unroll") for (int k = 0; k < 2; ++k) dst[n][k] = *(const LAS bf16x8*)(lds + PG8_SB(b, h) + boff + n * 2048 + k * 1024); } while (0)
; #define PG8_MMA(ai, bj, At, Bt) do { __builtin_amdgcn_s_setprio(1); _Pragma("unroll") for (int m = 0; m < 4; ++m) _Pragma("unroll") for (int n = 0; n < 2; ++n) _Pragma("unroll") for (int k = 0; k < 2; ++k) \
;         acc[ai][bj][m][n] = __builtin_amdgcn_mfma_f32_16x16x32_bf16(Bt[n][k], At[m][k], acc[ai][bj][m][n], 0, 0, 0); __builtin_amdgcn_s_setprio(0); } while (0)
; #define PG8_BAR __builtin_amdgcn_s_barrier()
; template <class Epi>
; __device__ __forceinline__ void gemm_phase(LAS unsigned char* lds, const Gemm g, const StaticOrder& S, const Epi& E) {
;     ...
;         const bool has_next = S.next(ui + 1, nxt);
;         const char* nA = has_next ? (const char*)g.A + (size_t)nxt.pm * tstepA : cA; const char* nB = has_next ? (const char*)g.Bt + (size_t)nxt.pn * tstepB : cB;
; #pragma nounroll
;         for (int t = 0; t < nt; t += 2) {
;             const bool last = (t == nt - 2);
;             const char* a1 = cA + (size_t)(t + 1) * kstep;
;             const char* a2 = last ? nA : cA + (size_t)(t + 2) * kstep; const char* b2 = last ? nB : cB + (size_t)(t + 2) * kstep;
;             const char* a3 = a2 + kstep; const char* b3 = b2 + kstep;
;             PG8_LDB(B0, 0, 0); PG8_LDB(B1, 0, 1); PG8_SCHED; PG8_LDA(At, 0, 0); PG8_STAGE(PG8_SA(1, 1), a1 + hstepA, voffA);
;             PG8_WAIT_V(8); PG8_WAIT_L(0); PG8_BAR; PG8_MMA(0, 0, At, B0); PG8_MMA(0, 1, At, B1); PG8_BAR; PG8_SCHED;
;             PG8_LDA(At, 0, 1); PG8_STAGE(PG8_SB(0, 0), b2, voffB); PG8_STAGE(PG8_SB(0, 1), b2 + hstepB, voffB); PG8_STAGE(PG8_SA(0, 0), a2, voffA);
;             PG8_WAIT_V(8); PG8_WAIT_L(0); PG8_BAR; PG8_MMA(1, 0, At, B0); PG8_MMA(1, 1, At, B1); PG8_BAR; PG8_SCHED;
.LBB0_191:
	s_ashr_i32 s65, s64, 31
	s_lshl_b64 s[68:69], s[64:65], 19
	s_add_u32 s68, s24, s68
	s_addc_u32 s69, s25, s69
	s_and_b64 s[70:71], s[4:5], exec
	s_cselect_b32 s7, s69, s75
	s_cselect_b32 s65, s68, s74
	s_ashr_i32 s63, s62, 31
	s_lshl_b64 s[70:71], s[62:63], 19
	s_add_u32 s70, s10, s70
	s_addc_u32 s71, s11, s71
	s_and_b64 s[78:79], s[4:5], exec
	s_cselect_b32 s63, s71, s77
	s_cselect_b32 s73, s70, s76
	s_add_u32 s74, s74, 0x40080
	s_addc_u32 s75, s75, 0
	s_add_u32 s87, s76, 0x100
	s_addc_u32 s88, s77, 0
	s_mov_b32 s89, -2
	v_lshl_add_u32 v248, s72, 8, v150
	v_add_u32_e32 v248, s41, v248
	v_ashrrev_i32_e32 v249, 31, v248
	v_lshl_add_u64 v[248:249], v[248:249], 2, s[50:51]
	global_load_dword v240, v[248:249], off
	global_load_dword v241, v[248:249], off offset:64
	global_load_dword v242, v[248:249], off offset:128
	global_load_dword v243, v[248:249], off offset:192
	global_load_dword v244, v[248:249], off offset:512
	global_load_dword v245, v[248:249], off offset:576
	global_load_dword v246, v[248:249], off offset:640
	global_load_dword v247, v[248:249], off offset:704
	ds_read_b128 v[144:147], v153
	ds_read_b128 v[158:161], v153 offset:1024
	ds_read_b128 v[162:165], v153 offset:2048
	ds_read_b128 v[166:169], v153 offset:3072
	ds_read_b128 v[170:173], v154
	ds_read_b128 v[178:181], v154 offset:1024
	ds_read_b128 v[182:185], v154 offset:2048
	ds_read_b128 v[186:189], v154 offset:3072
	s_add_u32 s76, s74, 0xfffc0080
	s_addc_u32 s77, s75, -1
	s_cmp_eq_u32 s89, 12
	s_cselect_b32 s79, s7, s77
	s_cselect_b32 s78, s65, s76
	s_cselect_b32 s77, s63, s88
	s_cselect_b32 s76, s73, s87
	v_lshl_add_u64 v[148:149], s[74:75], 0, v[136:137]
	s_add_i32 m0, s19, 0xc000
	ds_read_b128 v[190:193], v155
	ds_read_b128 v[194:197], v155 offset:1024
	ds_read_b128 v[198:201], v155 offset:2048
	ds_read_b128 v[202:205], v155 offset:3072
	ds_read_b128 v[206:209], v155 offset:4096
	ds_read_b128 v[210:213], v155 offset:5120
	ds_read_b128 v[214:217], v155 offset:6144
	ds_read_b128 v[218:221], v155 offset:7168
	global_load_lds_dwordx4 v[148:149], off
	v_lshl_add_u64 v[148:149], s[74:75], 0, v[138:139]
	s_add_i32 m0, s19, 0xe000
	s_nop 0
	global_load_lds_dwordx4 v[148:149], off
	s_waitcnt vmcnt(8)
	s_waitcnt lgkmcnt(0)
	s_barrier
	s_waitcnt lgkmcnt(0)
	v_mfma_f32_16x16x32_bf16 v[124:127], v[144:147], v[190:193], 0
	v_mfma_f32_16x16x32_bf16 v[120:123], v[162:165], v[190:193], 0
	v_mfma_f32_16x16x32_bf16 v[108:111], v[144:147], v[198:201], 0
	v_mfma_f32_16x16x32_bf16 v[104:107], v[162:165], v[198:201], 0
	v_mfma_f32_16x16x32_bf16 v[92:95], v[144:147], v[206:209], 0
	v_mfma_f32_16x16x32_bf16 v[88:91], v[162:165], v[206:209], 0
	v_mfma_f32_16x16x32_bf16 v[76:79], v[144:147], v[214:217], 0
	v_mfma_f32_16x16x32_bf16 v[72:75], v[162:165], v[214:217], 0
	v_mfma_f32_16x16x32_bf16 v[124:127], v[158:161], v[194:197], v[124:127]
	v_mfma_f32_16x16x32_bf16 v[120:123], v[166:169], v[194:197], v[120:123]
	v_mfma_f32_16x16x32_bf16 v[108:111], v[158:161], v[202:205], v[108:111]
	v_mfma_f32_16x16x32_bf16 v[104:107], v[166:169], v[202:205], v[104:107]
	v_mfma_f32_16x16x32_bf16 v[92:95], v[158:161], v[210:213], v[92:95]
	v_mfma_f32_16x16x32_bf16 v[88:91], v[166:169], v[210:213], v[88:91]
	v_mfma_f32_16x16x32_bf16 v[76:79], v[158:161], v[218:221], v[76:79]
	v_mfma_f32_16x16x32_bf16 v[72:75], v[166:169], v[218:221], v[72:75]
	v_mfma_f32_16x16x32_bf16 v[116:119], v[170:173], v[190:193], 0
	v_mfma_f32_16x16x32_bf16 v[112:115], v[182:185], v[190:193], 0
	v_mfma_f32_16x16x32_bf16 v[100:103], v[170:173], v[198:201], 0
	v_mfma_f32_16x16x32_bf16 v[96:99], v[182:185], v[198:201], 0
	v_mfma_f32_16x16x32_bf16 v[84:87], v[170:173], v[206:209], 0
	v_mfma_f32_16x16x32_bf16 v[80:83], v[182:185], v[206:209], 0
	v_mfma_f32_16x16x32_bf16 v[68:71], v[170:173], v[214:217], 0
	v_mfma_f32_16x16x32_bf16 v[64:67], v[182:185], v[214:217], 0
	v_mfma_f32_16x16x32_bf16 v[116:119], v[178:181], v[194:197], v[116:119]
	v_mfma_f32_16x16x32_bf16 v[112:115], v[186:189], v[194:197], v[112:115]
	v_mfma_f32_16x16x32_bf16 v[100:103], v[178:181], v[202:205], v[100:103]
	v_mfma_f32_16x16x32_bf16 v[96:99], v[186:189], v[202:205], v[96:99]
	v_mfma_f32_16x16x32_bf16 v[84:87], v[178:181], v[210:213], v[84:87]
	v_mfma_f32_16x16x32_bf16 v[80:83], v[186:189], v[210:213], v[80:83]
	v_mfma_f32_16x16x32_bf16 v[68:71], v[178:181], v[218:221], v[68:71]
	v_mfma_f32_16x16x32_bf16 v[64:67], v[186:189], v[218:221], v[64:67]
	s_barrier
	s_add_i32 s90, s84, s3
	v_lshl_add_u64 v[148:149], s[76:77], 0, v[130:131]
	s_mov_b32 m0, s90
	ds_read_b128 v[190:193], v155 offset:16384
	ds_read_b128 v[194:197], v155 offset:17408
	ds_read_b128 v[198:201], v155 offset:18432
	ds_read_b128 v[202:205], v155 offset:19456
	ds_read_b128 v[206:209], v155 offset:20480
	ds_read_b128 v[210:213], v155 offset:21504
	ds_read_b128 v[214:217], v155 offset:22528
	ds_read_b128 v[218:221], v155 offset:23552
	global_load_lds_dwordx4 v[148:149], off
	s_add_i32 m0, s90, 0x2000
	s_add_u32 s90, s76, 0x40000
	v_lshl_add_u64 v[174:175], s[76:77], 0, v[134:135]
	s_addc_u32 s91, s77, 0
	s_add_i32 s92, s85, s3
	global_load_lds_dwordx4 v[174:175], off
	v_lshl_add_u64 v[222:223], s[90:91], 0, v[130:131]
	s_mov_b32 m0, s92
	v_lshl_add_u64 v[226:227], s[78:79], 0, v[132:133]
	global_load_lds_dwordx4 v[222:223], off
	v_lshl_add_u64 v[222:223], s[90:91], 0, v[134:135]
	s_add_i32 m0, s92, 0x2000
	s_nop 0
	global_load_lds_dwordx4 v[222:223], off
	v_lshl_add_u64 v[222:223], s[78:79], 0, v[128:129]
	s_mov_b32 m0, s19
	s_nop 0
	global_load_lds_dwordx4 v[222:223], off
	s_mov_b32 m0, s23
	s_nop 0
	global_load_lds_dwordx4 v[226:227], off
	s_waitcnt vmcnt(8)
	s_waitcnt lgkmcnt(0)
	s_barrier
; #define PG8_STAGE(bufoff, gbase, voff) do { _Pragma("unroll") for (int _i = 0; _i < 2; ++_i) \
;         __builtin_amdgcn_global_load_lds((const unsigned*)((const char*)(gbase) + (voff)[_i]), (LAS unsigned*)(lds + (bufoff) + ldsw + _i * 8192), 16, 0, 0); } while (0)
; #define PG8_LDA(dst, b, h) do { _Pragma("unroll") for (int m = 0; m < 4; ++m) _Pragma("unroll") for (int k = 0; k < 2; ++k) dst[m][k] = *(const LAS bf16x8*)(lds + PG8_SA(b, h) + aoff + m * 2048 + k * 1024); } while (0)
; #define PG8_LDB(dst, b, h) do { _Pragma("unroll") for (int n = 0; n < 2; ++n) _Pragma("unroll") for (int k = 0; k < 2; ++k) dst[n][k] = *(const LAS bf16x8*)(lds + PG8_SB(b, h) + boff + n * 2048 + k * 1024); } while (0)
; #define PG8_MMA(ai, bj, At, Bt) do { __builtin_amdgcn_s_setprio(1); _Pragma("unroll") for (int m = 0; m < 4; ++m) _Pragma("unroll") for (int n = 0; n < 2; ++n) _Pragma("unroll") for (int k = 0; k < 2; ++k) \
;         acc[ai][bj][m][n] = __builtin_amdgcn_mfma_f32_16x16x32_bf16(Bt[n][k], At[m][k], acc[ai][bj][m][n], 0, 0, 0); __builtin_amdgcn_s_setprio(0); } while (0)
; #define PG8_WAIT_V(n) asm volatile("s_waitcnt vmcnt(" #n ")" ::: "memory")
; #define PG8_WAIT_L(n) asm volatile("s_waitcnt lgkmcnt(" #n ")" ::: "memory")
; #define PG8_BAR __builtin_amdgcn_s_barrier()
; #define PG8_SCHED __builtin_amdgcn_sched_barrier(0)
; template <class Epi>
; __device__ __forceinline__ void gemm_phase(LAS unsigned char* lds, const Gemm g, const StaticOrder& S, const Epi& E) {
;     ...
;             PG8_WAIT_V(8); PG8_WAIT_L(0); PG8_BAR; PG8_MMA(1, 0, At, B0); PG8_MMA(1, 1, At, B1); PG8_BAR; PG8_SCHED;
;             PG8_LDB(B0, 1, 0); PG8_LDB(B1, 1, 1); PG8_SCHED; PG8_LDA(At, 1, 0); PG8_STAGE(PG8_SA(0, 1), a2 + hstepA, voffA);
;             PG8_WAIT_V(8); PG8_WAIT_L(0); PG8_BAR; PG8_MMA(0, 0, At, B0); PG8_MMA(0, 1, At, B1); PG8_BAR; PG8_SCHED;
	s_waitcnt lgkmcnt(0)
	v_mfma_f32_16x16x32_bf16 v[60:63], v[144:147], v[190:193], 0
	v_mfma_f32_16x16x32_bf16 v[56:59], v[162:165], v[190:193], 0
	v_mfma_f32_16x16x32_bf16 v[44:47], v[144:147], v[198:201], 0
	v_mfma_f32_16x16x32_bf16 v[40:43], v[162:165], v[198:201], 0
	v_mfma_f32_16x16x32_bf16 v[28:31], v[144:147], v[206:209], 0
	v_mfma_f32_16x16x32_bf16 v[24:27], v[162:165], v[206:209], 0
	v_mfma_f32_16x16x32_bf16 v[12:15], v[144:147], v[214:217], 0
	v_mfma_f32_16x16x32_bf16 v[8:11], v[162:165], v[214:217], 0
	v_mfma_f32_16x16x32_bf16 v[60:63], v[158:161], v[194:197], v[60:63]
	v_mfma_f32_16x16x32_bf16 v[56:59], v[166:169], v[194:197], v[56:59]
	v_mfma_f32_16x16x32_bf16 v[44:47], v[158:161], v[202:205], v[44:47]
	v_mfma_f32_16x16x32_bf16 v[40:43], v[166:169], v[202:205], v[40:43]
	v_mfma_f32_16x16x32_bf16 v[28:31], v[158:161], v[210:213], v[28:31]
	v_mfma_f32_16x16x32_bf16 v[24:27], v[166:169], v[210:213], v[24:27]
	v_mfma_f32_16x16x32_bf16 v[12:15], v[158:161], v[218:221], v[12:15]
	v_mfma_f32_16x16x32_bf16 v[8:11], v[166:169], v[218:221], v[8:11]
	v_mfma_f32_16x16x32_bf16 v[52:55], v[170:173], v[190:193], 0
	v_mfma_f32_16x16x32_bf16 v[48:51], v[182:185], v[190:193], 0
	v_mfma_f32_16x16x32_bf16 v[36:39], v[170:173], v[198:201], 0
	v_mfma_f32_16x16x32_bf16 v[32:35], v[182:185], v[198:201], 0
	v_mfma_f32_16x16x32_bf16 v[20:23], v[170:173], v[206:209], 0
	v_mfma_f32_16x16x32_bf16 v[16:19], v[182:185], v[206:209], 0
	v_mfma_f32_16x16x32_bf16 v[4:7], v[170:173], v[214:217], 0
	v_mfma_f32_16x16x32_bf16 v[0:3], v[182:185], v[214:217], 0
	v_mfma_f32_16x16x32_bf16 v[52:55], v[178:181], v[194:197], v[52:55]
	v_mfma_f32_16x16x32_bf16 v[48:51], v[186:189], v[194:197], v[48:51]
	v_mfma_f32_16x16x32_bf16 v[36:39], v[178:181], v[202:205], v[36:39]
	v_mfma_f32_16x16x32_bf16 v[32:35], v[186:189], v[202:205], v[32:35]
	v_mfma_f32_16x16x32_bf16 v[20:23], v[178:181], v[210:213], v[20:23]
	v_mfma_f32_16x16x32_bf16 v[16:19], v[186:189], v[210:213], v[16:19]
	v_mfma_f32_16x16x32_bf16 v[4:7], v[178:181], v[218:221], v[4:7]
	v_mfma_f32_16x16x32_bf16 v[0:3], v[186:189], v[218:221], v[0:3]
	s_barrier
	s_add_i32 s90, 0, 0x18000
	v_add_u32_e32 v157, s90, v152
	s_add_i32 s91, 0, 0x1c000
	ds_read_b128 v[144:147], v157
	ds_read_b128 v[158:161], v157 offset:1024
	ds_read_b128 v[162:165], v157 offset:2048
	ds_read_b128 v[166:169], v157 offset:3072
	v_add_u32_e32 v157, s91, v152
	ds_read_b128 v[170:173], v157
	ds_read_b128 v[178:181], v157 offset:1024
	ds_read_b128 v[182:185], v157 offset:2048
	ds_read_b128 v[186:189], v157 offset:3072
	s_add_u32 s78, s78, 0x40000
	s_addc_u32 s79, s79, 0
	s_mov_b32 m0, s33
	v_lshl_add_u64 v[228:229], s[78:79], 0, v[128:129]
	ds_read_b128 v[190:193], v155 offset:32768
	ds_read_b128 v[194:197], v155 offset:33792
	ds_read_b128 v[198:201], v155 offset:34816
	ds_read_b128 v[202:205], v155 offset:35840
	ds_read_b128 v[206:209], v155 offset:36864
	ds_read_b128 v[210:213], v155 offset:37888
	ds_read_b128 v[214:217], v155 offset:38912
	ds_read_b128 v[218:221], v155 offset:39936
	global_load_lds_dwordx4 v[228:229], off
	v_lshl_add_u64 v[228:229], s[78:79], 0, v[132:133]
	s_mov_b32 m0, s35
	s_nop 0
	global_load_lds_dwordx4 v[228:229], off
	s_waitcnt vmcnt(8)
	s_waitcnt lgkmcnt(0)
	s_barrier
	s_waitcnt lgkmcnt(0)
	v_mfma_f32_16x16x32_bf16 v[124:127], v[144:147], v[190:193], v[124:127]
	v_mfma_f32_16x16x32_bf16 v[120:123], v[162:165], v[190:193], v[120:123]
	v_mfma_f32_16x16x32_bf16 v[108:111], v[144:147], v[198:201], v[108:111]
	v_mfma_f32_16x16x32_bf16 v[104:107], v[162:165], v[198:201], v[104:107]
	v_mfma_f32_16x16x32_bf16 v[92:95], v[144:147], v[206:209], v[92:95]
	v_mfma_f32_16x16x32_bf16 v[88:91], v[162:165], v[206:209], v[88:91]
	v_mfma_f32_16x16x32_bf16 v[76:79], v[144:147], v[214:217], v[76:79]
	v_mfma_f32_16x16x32_bf16 v[72:75], v[162:165], v[214:217], v[72:75]
	v_mfma_f32_16x16x32_bf16 v[124:127], v[158:161], v[194:197], v[124:127]
	v_mfma_f32_16x16x32_bf16 v[120:123], v[166:169], v[194:197], v[120:123]
	v_mfma_f32_16x16x32_bf16 v[108:111], v[158:161], v[202:205], v[108:111]
	v_mfma_f32_16x16x32_bf16 v[104:107], v[166:169], v[202:205], v[104:107]
	v_mfma_f32_16x16x32_bf16 v[92:95], v[158:161], v[210:213], v[92:95]
	v_mfma_f32_16x16x32_bf16 v[88:91], v[166:169], v[210:213], v[88:91]
	v_mfma_f32_16x16x32_bf16 v[76:79], v[158:161], v[218:221], v[76:79]
	v_mfma_f32_16x16x32_bf16 v[72:75], v[166:169], v[218:221], v[72:75]
	v_mfma_f32_16x16x32_bf16 v[116:119], v[170:173], v[190:193], v[116:119]
	v_mfma_f32_16x16x32_bf16 v[112:115], v[182:185], v[190:193], v[112:115]
	v_mfma_f32_16x16x32_bf16 v[100:103], v[170:173], v[198:201], v[100:103]
	v_mfma_f32_16x16x32_bf16 v[96:99], v[182:185], v[198:201], v[96:99]
	v_mfma_f32_16x16x32_bf16 v[84:87], v[170:173], v[206:209], v[84:87]
	v_mfma_f32_16x16x32_bf16 v[80:83], v[182:185], v[206:209], v[80:83]
	v_mfma_f32_16x16x32_bf16 v[68:71], v[170:173], v[214:217], v[68:71]
	v_mfma_f32_16x16x32_bf16 v[64:67], v[182:185], v[214:217], v[64:67]
	v_mfma_f32_16x16x32_bf16 v[116:119], v[178:181], v[194:197], v[116:119]
	v_mfma_f32_16x16x32_bf16 v[112:115], v[186:189], v[194:197], v[112:115]
	v_mfma_f32_16x16x32_bf16 v[100:103], v[178:181], v[202:205], v[100:103]
	v_mfma_f32_16x16x32_bf16 v[96:99], v[186:189], v[202:205], v[96:99]
	v_mfma_f32_16x16x32_bf16 v[84:87], v[178:181], v[210:213], v[84:87]
	v_mfma_f32_16x16x32_bf16 v[80:83], v[186:189], v[210:213], v[80:83]
	v_mfma_f32_16x16x32_bf16 v[68:71], v[178:181], v[218:221], v[68:71]
	v_mfma_f32_16x16x32_bf16 v[64:67], v[186:189], v[218:221], v[64:67]
	s_barrier
; #define PG8_STAGE(bufoff, gbase, voff) do { _Pragma("unroll") for (int _i = 0; _i < 2; ++_i) \
;         __builtin_amdgcn_global_load_lds((const unsigned*)((const char*)(gbase) + (voff)[_i]), (LAS unsigned*)(lds + (bufoff) + ldsw + _i * 8192), 16, 0, 0); } while (0)
; #define PG8_LDA(dst, b, h) do { _Pragma("unroll") for (int m = 0; m < 4; ++m) _Pragma("unroll") for (int k = 0; k < 2; ++k) dst[m][k] = *(const LAS bf16x8*)(lds + PG8_SA(b, h) + aoff + m * 2048 + k * 1024); } while (0)
; #define PG8_LDB(dst, b, h) do { _Pragma("unroll") for (int n = 0; n < 2; ++n) _Pragma("unroll") for (int k = 0; k < 2; ++k) dst[n][k] = *(const LAS bf16x8*)(lds + PG8_SB(b, h) + boff + n * 2048 + k * 1024); } while (0)
; #define PG8_WAIT_V(n) asm volatile("s_waitcnt vmcnt(" #n ")" ::: "memory")
; #define PG8_WAIT_L(n) asm volatile("s_waitcnt lgkmcnt(" #n ")" ::: "memory")
; template <class Epi>
; __device__ __forceinline__ void gemm_phase(LAS unsigned char* lds, const Gemm g, const StaticOrder& S, const Epi& E) {
;     ...
;         for (int t = 0; t < nt; t += 2) {
;             const bool last = (t == nt - 2);
;             const char* a1 = cA + (size_t)(t + 1) * kstep;
;             const char* a2 = last ? nA : cA + (size_t)(t + 2) * kstep; const char* b2 = last ? nB : cB + (size_t)(t + 2) * kstep;
;             const char* a3 = a2 + kstep; const char* b3 = b2 + kstep;
;             PG8_LDB(B0, 0, 0); PG8_LDB(B1, 0, 1); PG8_SCHED; PG8_LDA(At, 0, 0); PG8_STAGE(PG8_SA(1, 1), a1 + hstepA, voffA);
;             PG8_WAIT_V(8); PG8_WAIT_L(0); PG8_BAR; PG8_MMA(0, 0, At, B0); PG8_MMA(0, 1, At, B1); PG8_BAR; PG8_SCHED;
;             PG8_LDA(At, 0, 1); PG8_STAGE(PG8_SB(0, 0), b2, voffB); PG8_STAGE(PG8_SB(0, 1), b2 + hstepB, voffB); PG8_STAGE(PG8_SA(0, 0), a2, voffA);
;             PG8_WAIT_V(8); PG8_WAIT_L(0); PG8_BAR; PG8_MMA(1, 0, At, B0); PG8_MMA(1, 1, At, B1); PG8_BAR; PG8_SCHED;
;             PG8_LDB(B0, 1, 0); PG8_LDB(B1, 1, 1); PG8_SCHED; PG8_LDA(At, 1, 0); PG8_STAGE(PG8_SA(0, 1), a2 + hstepA, voffA);
;             PG8_WAIT_V(8); PG8_WAIT_L(0); PG8_BAR; PG8_MMA(0, 0, At, B0); PG8_MMA(0, 1, At, B1); PG8_BAR; PG8_SCHED;
;             PG8_LDA(At, 1, 1); PG8_STAGE(PG8_SB(1, 0), b3, voffB); PG8_STAGE(PG8_SB(1, 1), b3 + hstepB, voffB); PG8_STAGE(PG8_SA(1, 0), a3, voffA);
;             PG8_WAIT_V(8); PG8_WAIT_L(0); PG8_BAR; PG8_MMA(1, 0, At, B0); PG8_MMA(1, 1, At, B1); PG8_BAR; PG8_SCHED;
	s_add_i32 s78, s90, s3
	v_lshl_add_u64 v[148:149], v[148:149], 0, s[12:13]
	s_mov_b32 m0, s78
	ds_read_b128 v[190:193], v155 offset:49152
	ds_read_b128 v[194:197], v155 offset:50176
	ds_read_b128 v[198:201], v155 offset:51200
	ds_read_b128 v[202:205], v155 offset:52224
	ds_read_b128 v[206:209], v155 offset:53248
	ds_read_b128 v[210:213], v155 offset:54272
	ds_read_b128 v[214:217], v155 offset:55296
	ds_read_b128 v[218:221], v155 offset:56320
	global_load_lds_dwordx4 v[148:149], off
	s_add_i32 m0, s78, 0x2000
	s_add_u32 s76, s76, 0x40080
	v_lshl_add_u64 v[148:149], v[174:175], 0, s[12:13]
	s_addc_u32 s77, s77, 0
	s_add_i32 s78, s91, s3
	global_load_lds_dwordx4 v[148:149], off
	v_lshl_add_u64 v[148:149], s[76:77], 0, v[130:131]
	s_mov_b32 m0, s78
	s_nop 0
	global_load_lds_dwordx4 v[148:149], off
	v_lshl_add_u64 v[148:149], s[76:77], 0, v[134:135]
	s_add_i32 m0, s78, 0x2000
	s_nop 0
	global_load_lds_dwordx4 v[148:149], off
	v_lshl_add_u64 v[148:149], v[222:223], 0, s[12:13]
	s_mov_b32 m0, s57
	s_nop 0
	global_load_lds_dwordx4 v[148:149], off
	v_lshl_add_u64 v[148:149], v[226:227], 0, s[12:13]
	s_mov_b32 m0, s80
	s_nop 0
	global_load_lds_dwordx4 v[148:149], off
	s_waitcnt vmcnt(8)
	s_waitcnt lgkmcnt(0)
	s_barrier
	s_waitcnt lgkmcnt(0)
	v_mfma_f32_16x16x32_bf16 v[60:63], v[144:147], v[190:193], v[60:63]
	v_mfma_f32_16x16x32_bf16 v[56:59], v[162:165], v[190:193], v[56:59]
	v_mfma_f32_16x16x32_bf16 v[44:47], v[144:147], v[198:201], v[44:47]
	v_mfma_f32_16x16x32_bf16 v[40:43], v[162:165], v[198:201], v[40:43]
	v_mfma_f32_16x16x32_bf16 v[28:31], v[144:147], v[206:209], v[28:31]
	v_mfma_f32_16x16x32_bf16 v[24:27], v[162:165], v[206:209], v[24:27]
	v_mfma_f32_16x16x32_bf16 v[12:15], v[144:147], v[214:217], v[12:15]
	v_mfma_f32_16x16x32_bf16 v[8:11], v[162:165], v[214:217], v[8:11]
	v_mfma_f32_16x16x32_bf16 v[60:63], v[158:161], v[194:197], v[60:63]
	v_mfma_f32_16x16x32_bf16 v[56:59], v[166:169], v[194:197], v[56:59]
	v_mfma_f32_16x16x32_bf16 v[44:47], v[158:161], v[202:205], v[44:47]
	v_mfma_f32_16x16x32_bf16 v[40:43], v[166:169], v[202:205], v[40:43]
	v_mfma_f32_16x16x32_bf16 v[28:31], v[158:161], v[210:213], v[28:31]
	v_mfma_f32_16x16x32_bf16 v[24:27], v[166:169], v[210:213], v[24:27]
	v_mfma_f32_16x16x32_bf16 v[12:15], v[158:161], v[218:221], v[12:15]
	v_mfma_f32_16x16x32_bf16 v[8:11], v[166:169], v[218:221], v[8:11]
	v_mfma_f32_16x16x32_bf16 v[52:55], v[170:173], v[190:193], v[52:55]
	v_mfma_f32_16x16x32_bf16 v[48:51], v[182:185], v[190:193], v[48:51]
	v_mfma_f32_16x16x32_bf16 v[36:39], v[170:173], v[198:201], v[36:39]
	v_mfma_f32_16x16x32_bf16 v[32:35], v[182:185], v[198:201], v[32:35]
	v_mfma_f32_16x16x32_bf16 v[20:23], v[170:173], v[206:209], v[20:23]
	v_mfma_f32_16x16x32_bf16 v[16:19], v[182:185], v[206:209], v[16:19]
	v_mfma_f32_16x16x32_bf16 v[4:7], v[170:173], v[214:217], v[4:7]
	v_mfma_f32_16x16x32_bf16 v[0:3], v[182:185], v[214:217], v[0:3]
	v_mfma_f32_16x16x32_bf16 v[52:55], v[178:181], v[194:197], v[52:55]
	v_mfma_f32_16x16x32_bf16 v[48:51], v[186:189], v[194:197], v[48:51]
	v_mfma_f32_16x16x32_bf16 v[36:39], v[178:181], v[202:205], v[36:39]
	v_mfma_f32_16x16x32_bf16 v[32:35], v[186:189], v[202:205], v[32:35]
	v_mfma_f32_16x16x32_bf16 v[20:23], v[178:181], v[210:213], v[20:23]
	v_mfma_f32_16x16x32_bf16 v[16:19], v[186:189], v[210:213], v[16:19]
	v_mfma_f32_16x16x32_bf16 v[4:7], v[178:181], v[218:221], v[4:7]
	v_mfma_f32_16x16x32_bf16 v[0:3], v[186:189], v[218:221], v[0:3]
	s_barrier
	s_add_i32 s89, s89, 2
	s_add_u32 s74, s74, 0x100
	s_addc_u32 s75, s75, 0
	s_add_u32 s87, s87, 0x100
	s_addc_u32 s88, s88, 0
	s_cmp_gt_u32 s89, 13
.LBB0_192:
	ds_read_b128 v[144:147], v153
	ds_read_b128 v[158:161], v153 offset:1024
	ds_read_b128 v[162:165], v153 offset:2048
	ds_read_b128 v[166:169], v153 offset:3072
	ds_read_b128 v[170:173], v154
	ds_read_b128 v[178:181], v154 offset:1024
	ds_read_b128 v[182:185], v154 offset:2048
	ds_read_b128 v[186:189], v154 offset:3072
	s_add_u32 s76, s74, 0xfffc0080
	s_addc_u32 s77, s75, -1
	s_cmp_eq_u32 s89, 12
	s_cselect_b32 s79, s7, s77
	s_cselect_b32 s78, s65, s76
	s_cselect_b32 s77, s63, s88
	s_cselect_b32 s76, s73, s87
	v_lshl_add_u64 v[148:149], s[74:75], 0, v[136:137]
	s_add_i32 m0, s19, 0xc000
	ds_read_b128 v[190:193], v155
	ds_read_b128 v[194:197], v155 offset:1024
	ds_read_b128 v[198:201], v155 offset:2048
	ds_read_b128 v[202:205], v155 offset:3072
	ds_read_b128 v[206:209], v155 offset:4096
	ds_read_b128 v[210:213], v155 offset:5120
	ds_read_b128 v[214:217], v155 offset:6144
	ds_read_b128 v[218:221], v155 offset:7168
	global_load_lds_dwordx4 v[148:149], off
	v_lshl_add_u64 v[148:149], s[74:75], 0, v[138:139]
	s_add_i32 m0, s19, 0xe000
	s_nop 0
	global_load_lds_dwordx4 v[148:149], off
	s_waitcnt vmcnt(8)
	s_waitcnt lgkmcnt(0)
	s_barrier
; #define PG8_STAGE(bufoff, gbase, voff) do { _Pragma("unroll") for (int _i = 0; _i < 2; ++_i) \
;         __builtin_amdgcn_global_load_lds((const unsigned*)((const char*)(gbase) + (voff)[_i]), (LAS unsigned*)(lds + (bufoff) + ldsw + _i * 8192), 16, 0, 0); } while (0)
; #define PG8_LDA(dst, b, h) do { _Pragma("unroll") for (int m = 0; m < 4; ++m) _Pragma("unroll") for (int k = 0; k < 2; ++k) dst[m][k] = *(const LAS bf16x8*)(lds + PG8_SA(b, h) + aoff + m * 2048 + k * 1024); } while (0)
; #define PG8_MMA(ai, bj, At, Bt) do { __builtin_amdgcn_s_setprio(1); _Pragma("unroll") for (int m = 0; m < 4; ++m) _Pragma("unroll") for (int n = 0; n < 2; ++n) _Pragma("unroll") for (int k = 0; k < 2; ++k) \
;         acc[ai][bj][m][n] = __builtin_amdgcn_mfma_f32_16x16x32_bf16(Bt[n][k], At[m][k], acc[ai][bj][m][n], 0, 0, 0); __builtin_amdgcn_s_setprio(0); } while (0)
; #define PG8_WAIT_V(n) asm volatile("s_waitcnt vmcnt(" #n ")" ::: "memory")
; #define PG8_WAIT_L(n) asm volatile("s_waitcnt lgkmcnt(" #n ")" ::: "memory")
; #define PG8_BAR __builtin_amdgcn_s_barrier()
; #define PG8_SCHED __builtin_amdgcn_sched_barrier(0)
; template <class Epi>
; __device__ __forceinline__ void gemm_phase(LAS unsigned char* lds, const Gemm g, const StaticOrder& S, const Epi& E) {
;     ...
;             PG8_WAIT_V(8); PG8_WAIT_L(0); PG8_BAR; PG8_MMA(0, 0, At, B0); PG8_MMA(0, 1, At, B1); PG8_BAR; PG8_SCHED;
;             PG8_LDA(At, 0, 1); PG8_STAGE(PG8_SB(0, 0), b2, voffB); PG8_STAGE(PG8_SB(0, 1), b2 + hstepB, voffB); PG8_STAGE(PG8_SA(0, 0), a2, voffA);
;             PG8_WAIT_V(8); PG8_WAIT_L(0); PG8_BAR; PG8_MMA(1, 0, At, B0); PG8_MMA(1, 1, At, B1); PG8_BAR; PG8_SCHED;
	s_waitcnt lgkmcnt(0)
	v_mfma_f32_16x16x32_bf16 v[124:127], v[144:147], v[190:193], v[124:127]
	v_mfma_f32_16x16x32_bf16 v[120:123], v[162:165], v[190:193], v[120:123]
	v_mfma_f32_16x16x32_bf16 v[108:111], v[144:147], v[198:201], v[108:111]
	v_mfma_f32_16x16x32_bf16 v[104:107], v[162:165], v[198:201], v[104:107]
	v_mfma_f32_16x16x32_bf16 v[92:95], v[144:147], v[206:209], v[92:95]
	v_mfma_f32_16x16x32_bf16 v[88:91], v[162:165], v[206:209], v[88:91]
	v_mfma_f32_16x16x32_bf16 v[76:79], v[144:147], v[214:217], v[76:79]
	v_mfma_f32_16x16x32_bf16 v[72:75], v[162:165], v[214:217], v[72:75]
	v_mfma_f32_16x16x32_bf16 v[124:127], v[158:161], v[194:197], v[124:127]
	v_mfma_f32_16x16x32_bf16 v[120:123], v[166:169], v[194:197], v[120:123]
	v_mfma_f32_16x16x32_bf16 v[108:111], v[158:161], v[202:205], v[108:111]
	v_mfma_f32_16x16x32_bf16 v[104:107], v[166:169], v[202:205], v[104:107]
	v_mfma_f32_16x16x32_bf16 v[92:95], v[158:161], v[210:213], v[92:95]
	v_mfma_f32_16x16x32_bf16 v[88:91], v[166:169], v[210:213], v[88:91]
	v_mfma_f32_16x16x32_bf16 v[76:79], v[158:161], v[218:221], v[76:79]
	v_mfma_f32_16x16x32_bf16 v[72:75], v[166:169], v[218:221], v[72:75]
	v_mfma_f32_16x16x32_bf16 v[116:119], v[170:173], v[190:193], v[116:119]
	v_mfma_f32_16x16x32_bf16 v[112:115], v[182:185], v[190:193], v[112:115]
	v_mfma_f32_16x16x32_bf16 v[100:103], v[170:173], v[198:201], v[100:103]
	v_mfma_f32_16x16x32_bf16 v[96:99], v[182:185], v[198:201], v[96:99]
	v_mfma_f32_16x16x32_bf16 v[84:87], v[170:173], v[206:209], v[84:87]
	v_mfma_f32_16x16x32_bf16 v[80:83], v[182:185], v[206:209], v[80:83]
	v_mfma_f32_16x16x32_bf16 v[68:71], v[170:173], v[214:217], v[68:71]
	v_mfma_f32_16x16x32_bf16 v[64:67], v[182:185], v[214:217], v[64:67]
	v_mfma_f32_16x16x32_bf16 v[116:119], v[178:181], v[194:197], v[116:119]
	v_mfma_f32_16x16x32_bf16 v[112:115], v[186:189], v[194:197], v[112:115]
	v_mfma_f32_16x16x32_bf16 v[100:103], v[178:181], v[202:205], v[100:103]
	v_mfma_f32_16x16x32_bf16 v[96:99], v[186:189], v[202:205], v[96:99]
	v_mfma_f32_16x16x32_bf16 v[84:87], v[178:181], v[210:213], v[84:87]
	v_mfma_f32_16x16x32_bf16 v[80:83], v[186:189], v[210:213], v[80:83]
	v_mfma_f32_16x16x32_bf16 v[68:71], v[178:181], v[218:221], v[68:71]
	v_mfma_f32_16x16x32_bf16 v[64:67], v[186:189], v[218:221], v[64:67]
	s_barrier
	s_add_i32 s90, s84, s3
	v_lshl_add_u64 v[148:149], s[76:77], 0, v[130:131]
	s_mov_b32 m0, s90
	ds_read_b128 v[190:193], v155 offset:16384
	ds_read_b128 v[194:197], v155 offset:17408
	ds_read_b128 v[198:201], v155 offset:18432
	ds_read_b128 v[202:205], v155 offset:19456
	ds_read_b128 v[206:209], v155 offset:20480
	ds_read_b128 v[210:213], v155 offset:21504
	ds_read_b128 v[214:217], v155 offset:22528
	ds_read_b128 v[218:221], v155 offset:23552
	global_load_lds_dwordx4 v[148:149], off
	s_add_i32 m0, s90, 0x2000
	s_add_u32 s90, s76, 0x40000
	v_lshl_add_u64 v[174:175], s[76:77], 0, v[134:135]
	s_addc_u32 s91, s77, 0
	s_add_i32 s92, s85, s3
	global_load_lds_dwordx4 v[174:175], off
	v_lshl_add_u64 v[222:223], s[90:91], 0, v[130:131]
	s_mov_b32 m0, s92
	v_lshl_add_u64 v[226:227], s[78:79], 0, v[132:133]
	global_load_lds_dwordx4 v[222:223], off
	v_lshl_add_u64 v[222:223], s[90:91], 0, v[134:135]
	s_add_i32 m0, s92, 0x2000
	s_nop 0
	global_load_lds_dwordx4 v[222:223], off
	v_lshl_add_u64 v[222:223], s[78:79], 0, v[128:129]
	s_mov_b32 m0, s19
	s_nop 0
	global_load_lds_dwordx4 v[222:223], off
	s_mov_b32 m0, s23
	s_nop 0
	global_load_lds_dwordx4 v[226:227], off
	s_waitcnt vmcnt(8)
	s_waitcnt lgkmcnt(0)
	s_barrier
	s_waitcnt lgkmcnt(0)
	v_mfma_f32_16x16x32_bf16 v[60:63], v[144:147], v[190:193], v[60:63]
	v_mfma_f32_16x16x32_bf16 v[56:59], v[162:165], v[190:193], v[56:59]
	v_mfma_f32_16x16x32_bf16 v[44:47], v[144:147], v[198:201], v[44:47]
	v_mfma_f32_16x16x32_bf16 v[40:43], v[162:165], v[198:201], v[40:43]
	v_mfma_f32_16x16x32_bf16 v[28:31], v[144:147], v[206:209], v[28:31]
	v_mfma_f32_16x16x32_bf16 v[24:27], v[162:165], v[206:209], v[24:27]
	v_mfma_f32_16x16x32_bf16 v[12:15], v[144:147], v[214:217], v[12:15]
	v_mfma_f32_16x16x32_bf16 v[8:11], v[162:165], v[214:217], v[8:11]
	v_mfma_f32_16x16x32_bf16 v[60:63], v[158:161], v[194:197], v[60:63]
	v_mfma_f32_16x16x32_bf16 v[56:59], v[166:169], v[194:197], v[56:59]
	v_mfma_f32_16x16x32_bf16 v[44:47], v[158:161], v[202:205], v[44:47]
	v_mfma_f32_16x16x32_bf16 v[40:43], v[166:169], v[202:205], v[40:43]
	v_mfma_f32_16x16x32_bf16 v[28:31], v[158:161], v[210:213], v[28:31]
	v_mfma_f32_16x16x32_bf16 v[24:27], v[166:169], v[210:213], v[24:27]
	v_mfma_f32_16x16x32_bf16 v[12:15], v[158:161], v[218:221], v[12:15]
	v_mfma_f32_16x16x32_bf16 v[8:11], v[166:169], v[218:221], v[8:11]
	v_mfma_f32_16x16x32_bf16 v[52:55], v[170:173], v[190:193], v[52:55]
	v_mfma_f32_16x16x32_bf16 v[48:51], v[182:185], v[190:193], v[48:51]
	v_mfma_f32_16x16x32_bf16 v[36:39], v[170:173], v[198:201], v[36:39]
	v_mfma_f32_16x16x32_bf16 v[32:35], v[182:185], v[198:201], v[32:35]
	v_mfma_f32_16x16x32_bf16 v[20:23], v[170:173], v[206:209], v[20:23]
	v_mfma_f32_16x16x32_bf16 v[16:19], v[182:185], v[206:209], v[16:19]
	v_mfma_f32_16x16x32_bf16 v[4:7], v[170:173], v[214:217], v[4:7]
	v_mfma_f32_16x16x32_bf16 v[0:3], v[182:185], v[214:217], v[0:3]
	v_mfma_f32_16x16x32_bf16 v[52:55], v[178:181], v[194:197], v[52:55]
	v_mfma_f32_16x16x32_bf16 v[48:51], v[186:189], v[194:197], v[48:51]
	v_mfma_f32_16x16x32_bf16 v[36:39], v[178:181], v[202:205], v[36:39]
	v_mfma_f32_16x16x32_bf16 v[32:35], v[186:189], v[202:205], v[32:35]
	v_mfma_f32_16x16x32_bf16 v[20:23], v[178:181], v[210:213], v[20:23]
	v_mfma_f32_16x16x32_bf16 v[16:19], v[186:189], v[210:213], v[16:19]
	v_mfma_f32_16x16x32_bf16 v[4:7], v[178:181], v[218:221], v[4:7]
	v_mfma_f32_16x16x32_bf16 v[0:3], v[186:189], v[218:221], v[0:3]
	s_barrier
; #define PG8_STAGE(bufoff, gbase, voff) do { _Pragma("unroll") for (int _i = 0; _i < 2; ++_i) \
;         __builtin_amdgcn_global_load_lds((const unsigned*)((const char*)(gbase) + (voff)[_i]), (LAS unsigned*)(lds + (bufoff) + ldsw + _i * 8192), 16, 0, 0); } while (0)
; #define PG8_LDA(dst, b, h) do { _Pragma("unroll") for (int m = 0; m < 4; ++m) _Pragma("unroll") for (int k = 0; k < 2; ++k) dst[m][k] = *(const LAS bf16x8*)(lds + PG8_SA(b, h) + aoff + m * 2048 + k * 1024); } while (0)
; #define PG8_LDB(dst, b, h) do { _Pragma("unroll") for (int n = 0; n < 2; ++n) _Pragma("unroll") for (int k = 0; k < 2; ++k) dst[n][k] = *(const LAS bf16x8*)(lds + PG8_SB(b, h) + boff + n * 2048 + k * 1024); } while (0)
; #define PG8_MMA(ai, bj, At, Bt) do { __builtin_amdgcn_s_setprio(1); _Pragma("unroll") for (int m = 0; m < 4; ++m) _Pragma("unroll") for (int n = 0; n < 2; ++n) _Pragma("unroll") for (int k = 0; k < 2; ++k) \
;         acc[ai][bj][m][n] = __builtin_amdgcn_mfma_f32_16x16x32_bf16(Bt[n][k], At[m][k], acc[ai][bj][m][n], 0, 0, 0); __builtin_amdgcn_s_setprio(0); } while (0)
; #define PG8_WAIT_V(n) asm volatile("s_waitcnt vmcnt(" #n ")" ::: "memory")
; #define PG8_WAIT_L(n) asm volatile("s_waitcnt lgkmcnt(" #n ")" ::: "memory")
; #define PG8_BAR __builtin_amdgcn_s_barrier()
; #define PG8_SCHED __builtin_amdgcn_sched_barrier(0)
; template <class Epi>
; __device__ __forceinline__ void gemm_phase(LAS unsigned char* lds, const Gemm g, const StaticOrder& S, const Epi& E) {
;     ...
;             PG8_LDB(B0, 1, 0); PG8_LDB(B1, 1, 1); PG8_SCHED; PG8_LDA(At, 1, 0); PG8_STAGE(PG8_SA(0, 1), a2 + hstepA, voffA);
;             PG8_WAIT_V(8); PG8_WAIT_L(0); PG8_BAR; PG8_MMA(0, 0, At, B0); PG8_MMA(0, 1, At, B1); PG8_BAR; PG8_SCHED;
	s_add_i32 s90, 0, 0x18000
	v_add_u32_e32 v157, s90, v152
	s_add_i32 s91, 0, 0x1c000
	ds_read_b128 v[144:147], v157
	ds_read_b128 v[158:161], v157 offset:1024
	ds_read_b128 v[162:165], v157 offset:2048
	ds_read_b128 v[166:169], v157 offset:3072
	v_add_u32_e32 v157, s91, v152
	ds_read_b128 v[170:173], v157
	ds_read_b128 v[178:181], v157 offset:1024
	ds_read_b128 v[182:185], v157 offset:2048
	ds_read_b128 v[186:189], v157 offset:3072
	s_add_u32 s78, s78, 0x40000
	s_addc_u32 s79, s79, 0
	s_mov_b32 m0, s33
	v_lshl_add_u64 v[228:229], s[78:79], 0, v[128:129]
	ds_read_b128 v[190:193], v155 offset:32768
	ds_read_b128 v[194:197], v155 offset:33792
	ds_read_b128 v[198:201], v155 offset:34816
	ds_read_b128 v[202:205], v155 offset:35840
	ds_read_b128 v[206:209], v155 offset:36864
	ds_read_b128 v[210:213], v155 offset:37888
	ds_read_b128 v[214:217], v155 offset:38912
	ds_read_b128 v[218:221], v155 offset:39936
	global_load_lds_dwordx4 v[228:229], off
	v_lshl_add_u64 v[228:229], s[78:79], 0, v[132:133]
	s_mov_b32 m0, s35
	s_nop 0
	global_load_lds_dwordx4 v[228:229], off
	s_waitcnt vmcnt(8)
	s_waitcnt lgkmcnt(0)
	s_barrier
	s_waitcnt lgkmcnt(0)
	v_mfma_f32_16x16x32_bf16 v[124:127], v[144:147], v[190:193], v[124:127]
	v_mfma_f32_16x16x32_bf16 v[120:123], v[162:165], v[190:193], v[120:123]
	v_mfma_f32_16x16x32_bf16 v[108:111], v[144:147], v[198:201], v[108:111]
	v_mfma_f32_16x16x32_bf16 v[104:107], v[162:165], v[198:201], v[104:107]
	v_mfma_f32_16x16x32_bf16 v[92:95], v[144:147], v[206:209], v[92:95]
	v_mfma_f32_16x16x32_bf16 v[88:91], v[162:165], v[206:209], v[88:91]
	v_mfma_f32_16x16x32_bf16 v[76:79], v[144:147], v[214:217], v[76:79]
	v_mfma_f32_16x16x32_bf16 v[72:75], v[162:165], v[214:217], v[72:75]
	v_mfma_f32_16x16x32_bf16 v[124:127], v[158:161], v[194:197], v[124:127]
	v_mfma_f32_16x16x32_bf16 v[120:123], v[166:169], v[194:197], v[120:123]
	v_mfma_f32_16x16x32_bf16 v[108:111], v[158:161], v[202:205], v[108:111]
	v_mfma_f32_16x16x32_bf16 v[104:107], v[166:169], v[202:205], v[104:107]
	v_mfma_f32_16x16x32_bf16 v[92:95], v[158:161], v[210:213], v[92:95]
	v_mfma_f32_16x16x32_bf16 v[88:91], v[166:169], v[210:213], v[88:91]
	v_mfma_f32_16x16x32_bf16 v[76:79], v[158:161], v[218:221], v[76:79]
	v_mfma_f32_16x16x32_bf16 v[72:75], v[166:169], v[218:221], v[72:75]
	v_mfma_f32_16x16x32_bf16 v[116:119], v[170:173], v[190:193], v[116:119]
	v_mfma_f32_16x16x32_bf16 v[112:115], v[182:185], v[190:193], v[112:115]
	v_mfma_f32_16x16x32_bf16 v[100:103], v[170:173], v[198:201], v[100:103]
	v_mfma_f32_16x16x32_bf16 v[96:99], v[182:185], v[198:201], v[96:99]
	v_mfma_f32_16x16x32_bf16 v[84:87], v[170:173], v[206:209], v[84:87]
	v_mfma_f32_16x16x32_bf16 v[80:83], v[182:185], v[206:209], v[80:83]
	v_mfma_f32_16x16x32_bf16 v[68:71], v[170:173], v[214:217], v[68:71]
	v_mfma_f32_16x16x32_bf16 v[64:67], v[182:185], v[214:217], v[64:67]
	v_mfma_f32_16x16x32_bf16 v[116:119], v[178:181], v[194:197], v[116:119]
	v_mfma_f32_16x16x32_bf16 v[112:115], v[186:189], v[194:197], v[112:115]
	v_mfma_f32_16x16x32_bf16 v[100:103], v[178:181], v[202:205], v[100:103]
	v_mfma_f32_16x16x32_bf16 v[96:99], v[186:189], v[202:205], v[96:99]
	v_mfma_f32_16x16x32_bf16 v[84:87], v[178:181], v[210:213], v[84:87]
	v_mfma_f32_16x16x32_bf16 v[80:83], v[186:189], v[210:213], v[80:83]
	v_mfma_f32_16x16x32_bf16 v[68:71], v[178:181], v[218:221], v[68:71]
	v_mfma_f32_16x16x32_bf16 v[64:67], v[186:189], v[218:221], v[64:67]
	s_barrier
; #define PG8_STAGE(bufoff, gbase, voff) do { _Pragma("unroll") for (int _i = 0; _i < 2; ++_i) \
;         __builtin_amdgcn_global_load_lds((const unsigned*)((const char*)(gbase) + (voff)[_i]), (LAS unsigned*)(lds + (bufoff) + ldsw + _i * 8192), 16, 0, 0); } while (0)
; #define PG8_LDA(dst, b, h) do { _Pragma("unroll") for (int m = 0; m < 4; ++m) _Pragma("unroll") for (int k = 0; k < 2; ++k) dst[m][k] = *(const LAS bf16x8*)(lds + PG8_SA(b, h) + aoff + m * 2048 + k * 1024); } while (0)
; #define PG8_MMA(ai, bj, At, Bt) do { __builtin_amdgcn_s_setprio(1); _Pragma("unroll") for (int m = 0; m < 4; ++m) _Pragma("unroll") for (int n = 0; n < 2; ++n) _Pragma("unroll") for (int k = 0; k < 2; ++k) \
;         acc[ai][bj][m][n] = __builtin_amdgcn_mfma_f32_16x16x32_bf16(Bt[n][k], At[m][k], acc[ai][bj][m][n], 0, 0, 0); __builtin_amdgcn_s_setprio(0); } while (0)
; #define PG8_WAIT_V(n) asm volatile("s_waitcnt vmcnt(" #n ")" ::: "memory")
; #define PG8_WAIT_L(n) asm volatile("s_waitcnt lgkmcnt(" #n ")" ::: "memory")
; #define PG8_BAR __builtin_amdgcn_s_barrier()
; #define PG8_SCHED __builtin_amdgcn_sched_barrier(0)
; template <class Epi>
; __device__ __forceinline__ void gemm_phase(LAS unsigned char* lds, const Gemm g, const StaticOrder& S, const Epi& E) {
;     ...
;             PG8_LDA(At, 1, 1); PG8_STAGE(PG8_SB(1, 0), b3, voffB); PG8_STAGE(PG8_SB(1, 1), b3 + hstepB, voffB); PG8_STAGE(PG8_SA(1, 0), a3, voffA);
;             PG8_WAIT_V(8); PG8_WAIT_L(0); PG8_BAR; PG8_MMA(1, 0, At, B0); PG8_MMA(1, 1, At, B1); PG8_BAR; PG8_SCHED;
;         }
;         if (wr == 0) PG8_BAR;
	s_add_i32 s78, s90, s3
	v_lshl_add_u64 v[148:149], v[148:149], 0, s[12:13]
	s_mov_b32 m0, s78
	ds_read_b128 v[190:193], v155 offset:49152
	ds_read_b128 v[194:197], v155 offset:50176
	ds_read_b128 v[198:201], v155 offset:51200
	ds_read_b128 v[202:205], v155 offset:52224
	ds_read_b128 v[206:209], v155 offset:53248
	ds_read_b128 v[210:213], v155 offset:54272
	ds_read_b128 v[214:217], v155 offset:55296
	ds_read_b128 v[218:221], v155 offset:56320
	global_load_lds_dwordx4 v[148:149], off
	s_add_i32 m0, s78, 0x2000
	s_add_u32 s76, s76, 0x40080
	v_lshl_add_u64 v[148:149], v[174:175], 0, s[12:13]
	s_addc_u32 s77, s77, 0
	s_add_i32 s78, s91, s3
	global_load_lds_dwordx4 v[148:149], off
	v_lshl_add_u64 v[148:149], s[76:77], 0, v[130:131]
	s_mov_b32 m0, s78
	s_nop 0
	global_load_lds_dwordx4 v[148:149], off
	v_lshl_add_u64 v[148:149], s[76:77], 0, v[134:135]
	s_add_i32 m0, s78, 0x2000
	s_nop 0
	global_load_lds_dwordx4 v[148:149], off
	v_lshl_add_u64 v[148:149], v[222:223], 0, s[12:13]
	s_mov_b32 m0, s57
	s_nop 0
	global_load_lds_dwordx4 v[148:149], off
	v_lshl_add_u64 v[148:149], v[226:227], 0, s[12:13]
	s_mov_b32 m0, s80
	s_nop 0
	global_load_lds_dwordx4 v[148:149], off
	s_waitcnt vmcnt(8)
	s_waitcnt lgkmcnt(0)
	s_barrier
	s_waitcnt lgkmcnt(0)
	v_mfma_f32_16x16x32_bf16 v[60:63], v[144:147], v[190:193], v[60:63]
	v_mfma_f32_16x16x32_bf16 v[56:59], v[162:165], v[190:193], v[56:59]
	v_mfma_f32_16x16x32_bf16 v[44:47], v[144:147], v[198:201], v[44:47]
	v_mfma_f32_16x16x32_bf16 v[40:43], v[162:165], v[198:201], v[40:43]
	v_mfma_f32_16x16x32_bf16 v[28:31], v[144:147], v[206:209], v[28:31]
	v_mfma_f32_16x16x32_bf16 v[24:27], v[162:165], v[206:209], v[24:27]
	v_mfma_f32_16x16x32_bf16 v[12:15], v[144:147], v[214:217], v[12:15]
	v_mfma_f32_16x16x32_bf16 v[8:11], v[162:165], v[214:217], v[8:11]
	v_mfma_f32_16x16x32_bf16 v[60:63], v[158:161], v[194:197], v[60:63]
	v_mfma_f32_16x16x32_bf16 v[56:59], v[166:169], v[194:197], v[56:59]
	v_mfma_f32_16x16x32_bf16 v[44:47], v[158:161], v[202:205], v[44:47]
	v_mfma_f32_16x16x32_bf16 v[40:43], v[166:169], v[202:205], v[40:43]
	v_mfma_f32_16x16x32_bf16 v[28:31], v[158:161], v[210:213], v[28:31]
	v_mfma_f32_16x16x32_bf16 v[24:27], v[166:169], v[210:213], v[24:27]
	v_mfma_f32_16x16x32_bf16 v[12:15], v[158:161], v[218:221], v[12:15]
	v_mfma_f32_16x16x32_bf16 v[8:11], v[166:169], v[218:221], v[8:11]
	v_mfma_f32_16x16x32_bf16 v[52:55], v[170:173], v[190:193], v[52:55]
	v_mfma_f32_16x16x32_bf16 v[48:51], v[182:185], v[190:193], v[48:51]
	v_mfma_f32_16x16x32_bf16 v[36:39], v[170:173], v[198:201], v[36:39]
	v_mfma_f32_16x16x32_bf16 v[32:35], v[182:185], v[198:201], v[32:35]
	v_mfma_f32_16x16x32_bf16 v[20:23], v[170:173], v[206:209], v[20:23]
	v_mfma_f32_16x16x32_bf16 v[16:19], v[182:185], v[206:209], v[16:19]
	v_mfma_f32_16x16x32_bf16 v[4:7], v[170:173], v[214:217], v[4:7]
	v_mfma_f32_16x16x32_bf16 v[0:3], v[182:185], v[214:217], v[0:3]
	v_mfma_f32_16x16x32_bf16 v[52:55], v[178:181], v[194:197], v[52:55]
	v_mfma_f32_16x16x32_bf16 v[48:51], v[186:189], v[194:197], v[48:51]
	v_mfma_f32_16x16x32_bf16 v[36:39], v[178:181], v[202:205], v[36:39]
	v_mfma_f32_16x16x32_bf16 v[32:35], v[186:189], v[202:205], v[32:35]
	v_mfma_f32_16x16x32_bf16 v[20:23], v[178:181], v[210:213], v[20:23]
	v_mfma_f32_16x16x32_bf16 v[16:19], v[186:189], v[210:213], v[16:19]
	v_mfma_f32_16x16x32_bf16 v[4:7], v[178:181], v[218:221], v[4:7]
	v_mfma_f32_16x16x32_bf16 v[0:3], v[186:189], v[218:221], v[0:3]
	s_barrier
	s_add_i32 s89, s89, 2
	s_add_u32 s74, s74, 0x100
	s_addc_u32 s75, s75, 0
	s_add_u32 s87, s87, 0x100
	s_addc_u32 s88, s88, 0
	s_cmp_gt_u32 s89, 13
	s_cbranch_scc0 .LBB0_192
	s_and_b64 vcc, exec, s[14:15]
	s_cbranch_vccz .LBB0_195
	s_barrier

; #define PG8_STAGE(bufoff, gbase, voff) do { _Pragma("unroll") for (int _i = 0; _i < 2; ++_i) \
;         __builtin_amdgcn_global_load_lds((const unsigned*)((const char*)(gbase) + (voff)[_i]), (LAS unsigned*)(lds + (bufoff) + ldsw + _i * 8192), 16, 0, 0); } while (0)
; #define PG8_LDA(dst, b, h) do { _Pragma("unroll") for (int m = 0; m < 4; ++m) _Pragma("unroll") for (int k = 0; k < 2; ++k) dst[m][k] = *(const LAS bf16x8*)(lds + PG8_SA(b, h) + aoff + m * 2048 + k * 1024); } while (0)
; #define PG8_LDB(dst, b, h) do { _Pragma("unroll") for (int n = 0; n < 2; ++n) _Pragma("unroll") for (int k = 0; k < 2; ++k) dst[n][k] = *(const LAS bf16x8*)(lds + PG8_SB(b, h) + boff + n * 2048 + k * 1024); } while (0)
; #define PG8_MMA(ai, bj, At, Bt) do { __builtin_amdgcn_s_setprio(1); _Pragma("unroll") for (int m = 0; m < 4; ++m) _Pragma("unroll") for (int n = 0; n < 2; ++n) _Pragma("unroll") for (int k = 0; k < 2; ++k) \
;         acc[ai][bj][m][n] = __builtin_amdgcn_mfma_f32_16x16x32_bf16(Bt[n][k], At[m][k], acc[ai][bj][m][n], 0, 0, 0); __builtin_amdgcn_s_setprio(0); } while (0)
; #define PG8_WAIT_V(n) asm volatile("s_waitcnt vmcnt(" #n ")" ::: "memory")
; #define PG8_WAIT_L(n) asm volatile("s_waitcnt lgkmcnt(" #n ")" ::: "memory")
; template <class Epi>
; __device__ __forceinline__ void gemm_phase(LAS unsigned char* lds, const Gemm g, const StaticOrder& S, const Epi& E) {
;     ...
;         const bool has_next = S.next(ui + 1, nxt);
;         const char* nA = has_next ? (const char*)g.A + (size_t)nxt.pm * tstepA : cA; const char* nB = has_next ? (const char*)g.Bt + (size_t)nxt.pn * tstepB : cB;
; #pragma nounroll
;         for (int t = 0; t < nt; t += 2) {
;             const bool last = (t == nt - 2);
;             const char* a1 = cA + (size_t)(t + 1) * kstep;
;             const char* a2 = last ? nA : cA + (size_t)(t + 2) * kstep; const char* b2 = last ? nB : cB + (size_t)(t + 2) * kstep;
;             const char* a3 = a2 + kstep; const char* b3 = b2 + kstep;
;             PG8_LDB(B0, 0, 0); PG8_LDB(B1, 0, 1); PG8_SCHED; PG8_LDA(At, 0, 0); PG8_STAGE(PG8_SA(1, 1), a1 + hstepA, voffA);
;             PG8_WAIT_V(8); PG8_WAIT_L(0); PG8_BAR; PG8_MMA(0, 0, At, B0); PG8_MMA(0, 1, At, B1); PG8_BAR; PG8_SCHED;
;             PG8_LDA(At, 0, 1); PG8_STAGE(PG8_SB(0, 0), b2, voffB); PG8_STAGE(PG8_SB(0, 1), b2 + hstepB, voffB); PG8_STAGE(PG8_SA(0, 0), a2, voffA);
.LBB0_456:
	s_ashr_i32 s23, s22, 31
	s_lshl_b64 s[28:29], s[22:23], 19
	s_add_u32 s28, s40, s28
	s_addc_u32 s29, s41, s29
	s_and_b64 s[30:31], s[4:5], exec
	s_cselect_b32 s1, s29, s39
	s_cselect_b32 s23, s28, s38
	s_ashr_i32 s19, s18, 31
	s_lshl_b64 s[30:31], s[18:19], 19
	s_add_u32 s30, s3, s30
	s_addc_u32 s31, s33, s31
	s_and_b64 s[52:53], s[4:5], exec
	s_cselect_b32 s19, s31, s43
	s_cselect_b32 s74, s30, s42
	s_add_u32 s38, s38, 0x40080
	s_addc_u32 s39, s39, 0
	s_add_u32 s75, s42, 0x100
	s_addc_u32 s76, s43, 0
	s_mov_b32 s77, -2
	s_waitcnt lgkmcnt(0)
	s_nop 0
	ds_read_b128 v[128:131], v173
	ds_read_b128 v[132:135], v173 offset:1024
	ds_read_b128 v[136:139], v173 offset:2048
	ds_read_b128 v[140:143], v173 offset:3072
	ds_read_b128 v[160:163], v174
	ds_read_b128 v[164:167], v174 offset:1024
	ds_read_b128 v[178:181], v174 offset:2048
	ds_read_b128 v[182:185], v174 offset:3072
	s_add_u32 s42, s38, 0xfffc0080
	s_addc_u32 s43, s39, -1
	s_cmp_eq_u32 s77, 12
	s_cselect_b32 s53, s1, s43
	s_cselect_b32 s52, s23, s42
	s_cselect_b32 s43, s19, s76
	s_cselect_b32 s42, s74, s75
	v_lshl_add_u64 v[168:169], s[38:39], 0, v[152:153]
	s_add_i32 m0, s35, 0xc000
	ds_read_b128 v[186:189], v175
	ds_read_b128 v[190:193], v175 offset:1024
	ds_read_b128 v[194:197], v175 offset:2048
	ds_read_b128 v[198:201], v175 offset:3072
	ds_read_b128 v[202:205], v175 offset:4096
	ds_read_b128 v[206:209], v175 offset:5120
	ds_read_b128 v[210:213], v175 offset:6144
	ds_read_b128 v[214:217], v175 offset:7168
	global_load_lds_dwordx4 v[168:169], off
	v_lshl_add_u64 v[168:169], s[38:39], 0, v[154:155]
	s_add_i32 m0, s35, 0xe000
	s_nop 0
	global_load_lds_dwordx4 v[168:169], off
	s_waitcnt vmcnt(8)
	s_waitcnt lgkmcnt(0)
	s_barrier
	s_waitcnt lgkmcnt(0)
	v_mfma_f32_16x16x32_bf16 v[124:127], v[128:131], v[186:189], 0
	v_mfma_f32_16x16x32_bf16 v[120:123], v[136:139], v[186:189], 0
	v_mfma_f32_16x16x32_bf16 v[108:111], v[128:131], v[194:197], 0
	v_mfma_f32_16x16x32_bf16 v[104:107], v[136:139], v[194:197], 0
	v_mfma_f32_16x16x32_bf16 v[92:95], v[128:131], v[202:205], 0
	v_mfma_f32_16x16x32_bf16 v[88:91], v[136:139], v[202:205], 0
	v_mfma_f32_16x16x32_bf16 v[76:79], v[128:131], v[210:213], 0
	v_mfma_f32_16x16x32_bf16 v[72:75], v[136:139], v[210:213], 0
	v_mfma_f32_16x16x32_bf16 v[124:127], v[132:135], v[190:193], v[124:127]
	v_mfma_f32_16x16x32_bf16 v[120:123], v[140:143], v[190:193], v[120:123]
	v_mfma_f32_16x16x32_bf16 v[108:111], v[132:135], v[198:201], v[108:111]
	v_mfma_f32_16x16x32_bf16 v[104:107], v[140:143], v[198:201], v[104:107]
	v_mfma_f32_16x16x32_bf16 v[92:95], v[132:135], v[206:209], v[92:95]
	v_mfma_f32_16x16x32_bf16 v[88:91], v[140:143], v[206:209], v[88:91]
	v_mfma_f32_16x16x32_bf16 v[76:79], v[132:135], v[214:217], v[76:79]
	v_mfma_f32_16x16x32_bf16 v[72:75], v[140:143], v[214:217], v[72:75]
	v_mfma_f32_16x16x32_bf16 v[116:119], v[160:163], v[186:189], 0
	v_mfma_f32_16x16x32_bf16 v[112:115], v[178:181], v[186:189], 0
	v_mfma_f32_16x16x32_bf16 v[100:103], v[160:163], v[194:197], 0
	v_mfma_f32_16x16x32_bf16 v[96:99], v[178:181], v[194:197], 0
	v_mfma_f32_16x16x32_bf16 v[84:87], v[160:163], v[202:205], 0
	v_mfma_f32_16x16x32_bf16 v[80:83], v[178:181], v[202:205], 0
	v_mfma_f32_16x16x32_bf16 v[68:71], v[160:163], v[210:213], 0
	v_mfma_f32_16x16x32_bf16 v[64:67], v[178:181], v[210:213], 0
	v_mfma_f32_16x16x32_bf16 v[116:119], v[164:167], v[190:193], v[116:119]
	v_mfma_f32_16x16x32_bf16 v[112:115], v[182:185], v[190:193], v[112:115]
	v_mfma_f32_16x16x32_bf16 v[100:103], v[164:167], v[198:201], v[100:103]
	v_mfma_f32_16x16x32_bf16 v[96:99], v[182:185], v[198:201], v[96:99]
	v_mfma_f32_16x16x32_bf16 v[84:87], v[164:167], v[206:209], v[84:87]
	v_mfma_f32_16x16x32_bf16 v[80:83], v[182:185], v[206:209], v[80:83]
	v_mfma_f32_16x16x32_bf16 v[68:71], v[164:167], v[214:217], v[68:71]
	v_mfma_f32_16x16x32_bf16 v[64:67], v[182:185], v[214:217], v[64:67]
	s_barrier
	s_add_i32 s78, s72, s54
	v_lshl_add_u64 v[168:169], s[42:43], 0, v[146:147]
	s_mov_b32 m0, s78
	ds_read_b128 v[186:189], v175 offset:16384
	ds_read_b128 v[190:193], v175 offset:17408
	ds_read_b128 v[194:197], v175 offset:18432
	ds_read_b128 v[198:201], v175 offset:19456
	ds_read_b128 v[202:205], v175 offset:20480
	ds_read_b128 v[206:209], v175 offset:21504
	ds_read_b128 v[210:213], v175 offset:22528
	ds_read_b128 v[214:217], v175 offset:23552
	global_load_lds_dwordx4 v[168:169], off
	s_add_i32 m0, s78, 0x2000
	s_add_u32 s78, s42, 0x40000
	v_lshl_add_u64 v[218:219], s[42:43], 0, v[150:151]
	s_addc_u32 s79, s43, 0
	s_add_i32 s80, s73, s54
	global_load_lds_dwordx4 v[218:219], off
	v_lshl_add_u64 v[220:221], s[78:79], 0, v[146:147]
	s_mov_b32 m0, s80
	v_lshl_add_u64 v[222:223], s[52:53], 0, v[148:149]
	global_load_lds_dwordx4 v[220:221], off
	v_lshl_add_u64 v[220:221], s[78:79], 0, v[150:151]
	s_add_i32 m0, s80, 0x2000
	s_nop 0
	global_load_lds_dwordx4 v[220:221], off
	v_lshl_add_u64 v[220:221], s[52:53], 0, v[144:145]
	s_mov_b32 m0, s35
	s_nop 0
	global_load_lds_dwordx4 v[220:221], off
	s_mov_b32 m0, s55
	s_nop 0
	global_load_lds_dwordx4 v[222:223], off
	s_waitcnt vmcnt(8)
	s_waitcnt lgkmcnt(0)
	s_barrier
; #define PG8_STAGE(bufoff, gbase, voff) do { _Pragma("unroll") for (int _i = 0; _i < 2; ++_i) \
;         __builtin_amdgcn_global_load_lds((const unsigned*)((const char*)(gbase) + (voff)[_i]), (LAS unsigned*)(lds + (bufoff) + ldsw + _i * 8192), 16, 0, 0); } while (0)
; #define PG8_LDA(dst, b, h) do { _Pragma("unroll") for (int m = 0; m < 4; ++m) _Pragma("unroll") for (int k = 0; k < 2; ++k) dst[m][k] = *(const LAS bf16x8*)(lds + PG8_SA(b, h) + aoff + m * 2048 + k * 1024); } while (0)
; #define PG8_LDB(dst, b, h) do { _Pragma("unroll") for (int n = 0; n < 2; ++n) _Pragma("unroll") for (int k = 0; k < 2; ++k) dst[n][k] = *(const LAS bf16x8*)(lds + PG8_SB(b, h) + boff + n * 2048 + k * 1024); } while (0)
; #define PG8_MMA(ai, bj, At, Bt) do { __builtin_amdgcn_s_setprio(1); _Pragma("unroll") for (int m = 0; m < 4; ++m) _Pragma("unroll") for (int n = 0; n < 2; ++n) _Pragma("unroll") for (int k = 0; k < 2; ++k) \
;         acc[ai][bj][m][n] = __builtin_amdgcn_mfma_f32_16x16x32_bf16(Bt[n][k], At[m][k], acc[ai][bj][m][n], 0, 0, 0); __builtin_amdgcn_s_setprio(0); } while (0)
; #define PG8_WAIT_V(n) asm volatile("s_waitcnt vmcnt(" #n ")" ::: "memory")
; #define PG8_WAIT_L(n) asm volatile("s_waitcnt lgkmcnt(" #n ")" ::: "memory")
; #define PG8_BAR __builtin_amdgcn_s_barrier()
; #define PG8_SCHED __builtin_amdgcn_sched_barrier(0)
; template <class Epi>
; __device__ __forceinline__ void gemm_phase(LAS unsigned char* lds, const Gemm g, const StaticOrder& S, const Epi& E) {
;     ...
;             PG8_WAIT_V(8); PG8_WAIT_L(0); PG8_BAR; PG8_MMA(1, 0, At, B0); PG8_MMA(1, 1, At, B1); PG8_BAR; PG8_SCHED;
;             PG8_LDB(B0, 1, 0); PG8_LDB(B1, 1, 1); PG8_SCHED; PG8_LDA(At, 1, 0); PG8_STAGE(PG8_SA(0, 1), a2 + hstepA, voffA);
;             PG8_WAIT_V(8); PG8_WAIT_L(0); PG8_BAR; PG8_MMA(0, 0, At, B0); PG8_MMA(0, 1, At, B1); PG8_BAR; PG8_SCHED;
	s_waitcnt lgkmcnt(0)
	v_mfma_f32_16x16x32_bf16 v[60:63], v[128:131], v[186:189], 0
	v_mfma_f32_16x16x32_bf16 v[56:59], v[136:139], v[186:189], 0
	v_mfma_f32_16x16x32_bf16 v[44:47], v[128:131], v[194:197], 0
	v_mfma_f32_16x16x32_bf16 v[40:43], v[136:139], v[194:197], 0
	v_mfma_f32_16x16x32_bf16 v[28:31], v[128:131], v[202:205], 0
	v_mfma_f32_16x16x32_bf16 v[24:27], v[136:139], v[202:205], 0
	v_mfma_f32_16x16x32_bf16 v[12:15], v[128:131], v[210:213], 0
	v_mfma_f32_16x16x32_bf16 v[8:11], v[136:139], v[210:213], 0
	v_mfma_f32_16x16x32_bf16 v[60:63], v[132:135], v[190:193], v[60:63]
	v_mfma_f32_16x16x32_bf16 v[56:59], v[140:143], v[190:193], v[56:59]
	v_mfma_f32_16x16x32_bf16 v[44:47], v[132:135], v[198:201], v[44:47]
	v_mfma_f32_16x16x32_bf16 v[40:43], v[140:143], v[198:201], v[40:43]
	v_mfma_f32_16x16x32_bf16 v[28:31], v[132:135], v[206:209], v[28:31]
	v_mfma_f32_16x16x32_bf16 v[24:27], v[140:143], v[206:209], v[24:27]
	v_mfma_f32_16x16x32_bf16 v[12:15], v[132:135], v[214:217], v[12:15]
	v_mfma_f32_16x16x32_bf16 v[8:11], v[140:143], v[214:217], v[8:11]
	v_mfma_f32_16x16x32_bf16 v[52:55], v[160:163], v[186:189], 0
	v_mfma_f32_16x16x32_bf16 v[48:51], v[178:181], v[186:189], 0
	v_mfma_f32_16x16x32_bf16 v[36:39], v[160:163], v[194:197], 0
	v_mfma_f32_16x16x32_bf16 v[32:35], v[178:181], v[194:197], 0
	v_mfma_f32_16x16x32_bf16 v[20:23], v[160:163], v[202:205], 0
	v_mfma_f32_16x16x32_bf16 v[16:19], v[178:181], v[202:205], 0
	v_mfma_f32_16x16x32_bf16 v[4:7], v[160:163], v[210:213], 0
	v_mfma_f32_16x16x32_bf16 v[0:3], v[178:181], v[210:213], 0
	v_mfma_f32_16x16x32_bf16 v[52:55], v[164:167], v[190:193], v[52:55]
	v_mfma_f32_16x16x32_bf16 v[48:51], v[182:185], v[190:193], v[48:51]
	v_mfma_f32_16x16x32_bf16 v[36:39], v[164:167], v[198:201], v[36:39]
	v_mfma_f32_16x16x32_bf16 v[32:35], v[182:185], v[198:201], v[32:35]
	v_mfma_f32_16x16x32_bf16 v[20:23], v[164:167], v[206:209], v[20:23]
	v_mfma_f32_16x16x32_bf16 v[16:19], v[182:185], v[206:209], v[16:19]
	v_mfma_f32_16x16x32_bf16 v[4:7], v[164:167], v[214:217], v[4:7]
	v_mfma_f32_16x16x32_bf16 v[0:3], v[182:185], v[214:217], v[0:3]
	s_barrier
	s_add_i32 s78, 0, 0x18000
	s_add_i32 s79, 0, 0x1c000
	v_add_u32_e32 v140, s78, v172
	v_add_u32_e32 v182, s79, v172
	ds_read_b128 v[128:131], v140
	ds_read_b128 v[132:135], v140 offset:1024
	ds_read_b128 v[136:139], v140 offset:2048
	ds_read_b128 v[140:143], v140 offset:3072
	ds_read_b128 v[160:163], v182
	ds_read_b128 v[164:167], v182 offset:1024
	ds_read_b128 v[178:181], v182 offset:2048
	ds_read_b128 v[182:185], v182 offset:3072
	s_add_u32 s52, s52, 0x40000
	s_addc_u32 s53, s53, 0
	s_mov_b32 m0, s56
	v_lshl_add_u64 v[226:227], s[52:53], 0, v[144:145]
	ds_read_b128 v[186:189], v175 offset:32768
	ds_read_b128 v[190:193], v175 offset:33792
	ds_read_b128 v[194:197], v175 offset:34816
	ds_read_b128 v[198:201], v175 offset:35840
	ds_read_b128 v[202:205], v175 offset:36864
	ds_read_b128 v[206:209], v175 offset:37888
	ds_read_b128 v[210:213], v175 offset:38912
	ds_read_b128 v[214:217], v175 offset:39936
	global_load_lds_dwordx4 v[226:227], off
	v_lshl_add_u64 v[226:227], s[52:53], 0, v[148:149]
	s_mov_b32 m0, s57
	s_nop 0
	global_load_lds_dwordx4 v[226:227], off
	s_waitcnt vmcnt(8)
	s_waitcnt lgkmcnt(0)
	s_barrier
	s_waitcnt lgkmcnt(0)
	v_mfma_f32_16x16x32_bf16 v[124:127], v[128:131], v[186:189], v[124:127]
	v_mfma_f32_16x16x32_bf16 v[120:123], v[136:139], v[186:189], v[120:123]
	v_mfma_f32_16x16x32_bf16 v[108:111], v[128:131], v[194:197], v[108:111]
	v_mfma_f32_16x16x32_bf16 v[104:107], v[136:139], v[194:197], v[104:107]
	v_mfma_f32_16x16x32_bf16 v[92:95], v[128:131], v[202:205], v[92:95]
	v_mfma_f32_16x16x32_bf16 v[88:91], v[136:139], v[202:205], v[88:91]
	v_mfma_f32_16x16x32_bf16 v[76:79], v[128:131], v[210:213], v[76:79]
	v_mfma_f32_16x16x32_bf16 v[72:75], v[136:139], v[210:213], v[72:75]
	v_mfma_f32_16x16x32_bf16 v[124:127], v[132:135], v[190:193], v[124:127]
	v_mfma_f32_16x16x32_bf16 v[120:123], v[140:143], v[190:193], v[120:123]
	v_mfma_f32_16x16x32_bf16 v[108:111], v[132:135], v[198:201], v[108:111]
	v_mfma_f32_16x16x32_bf16 v[104:107], v[140:143], v[198:201], v[104:107]
	v_mfma_f32_16x16x32_bf16 v[92:95], v[132:135], v[206:209], v[92:95]
	v_mfma_f32_16x16x32_bf16 v[88:91], v[140:143], v[206:209], v[88:91]
	v_mfma_f32_16x16x32_bf16 v[76:79], v[132:135], v[214:217], v[76:79]
	v_mfma_f32_16x16x32_bf16 v[72:75], v[140:143], v[214:217], v[72:75]
	v_mfma_f32_16x16x32_bf16 v[116:119], v[160:163], v[186:189], v[116:119]
	v_mfma_f32_16x16x32_bf16 v[112:115], v[178:181], v[186:189], v[112:115]
	v_mfma_f32_16x16x32_bf16 v[100:103], v[160:163], v[194:197], v[100:103]
	v_mfma_f32_16x16x32_bf16 v[96:99], v[178:181], v[194:197], v[96:99]
	v_mfma_f32_16x16x32_bf16 v[84:87], v[160:163], v[202:205], v[84:87]
	v_mfma_f32_16x16x32_bf16 v[80:83], v[178:181], v[202:205], v[80:83]
	v_mfma_f32_16x16x32_bf16 v[68:71], v[160:163], v[210:213], v[68:71]
	v_mfma_f32_16x16x32_bf16 v[64:67], v[178:181], v[210:213], v[64:67]
	v_mfma_f32_16x16x32_bf16 v[116:119], v[164:167], v[190:193], v[116:119]
	v_mfma_f32_16x16x32_bf16 v[112:115], v[182:185], v[190:193], v[112:115]
	v_mfma_f32_16x16x32_bf16 v[100:103], v[164:167], v[198:201], v[100:103]
	v_mfma_f32_16x16x32_bf16 v[96:99], v[182:185], v[198:201], v[96:99]
	v_mfma_f32_16x16x32_bf16 v[84:87], v[164:167], v[206:209], v[84:87]
	v_mfma_f32_16x16x32_bf16 v[80:83], v[182:185], v[206:209], v[80:83]
	v_mfma_f32_16x16x32_bf16 v[68:71], v[164:167], v[214:217], v[68:71]
	v_mfma_f32_16x16x32_bf16 v[64:67], v[182:185], v[214:217], v[64:67]
	s_barrier
; #define PG8_STAGE(bufoff, gbase, voff) do { _Pragma("unroll") for (int _i = 0; _i < 2; ++_i) \
;         __builtin_amdgcn_global_load_lds((const unsigned*)((const char*)(gbase) + (voff)[_i]), (LAS unsigned*)(lds + (bufoff) + ldsw + _i * 8192), 16, 0, 0); } while (0)
; #define PG8_LDA(dst, b, h) do { _Pragma("unroll") for (int m = 0; m < 4; ++m) _Pragma("unroll") for (int k = 0; k < 2; ++k) dst[m][k] = *(const LAS bf16x8*)(lds + PG8_SA(b, h) + aoff + m * 2048 + k * 1024); } while (0)
; #define PG8_LDB(dst, b, h) do { _Pragma("unroll") for (int n = 0; n < 2; ++n) _Pragma("unroll") for (int k = 0; k < 2; ++k) dst[n][k] = *(const LAS bf16x8*)(lds + PG8_SB(b, h) + boff + n * 2048 + k * 1024); } while (0)
; #define PG8_WAIT_V(n) asm volatile("s_waitcnt vmcnt(" #n ")" ::: "memory")
; #define PG8_WAIT_L(n) asm volatile("s_waitcnt lgkmcnt(" #n ")" ::: "memory")
; template <class Epi>
; __device__ __forceinline__ void gemm_phase(LAS unsigned char* lds, const Gemm g, const StaticOrder& S, const Epi& E) {
;     ...
;         for (int t = 0; t < nt; t += 2) {
;             const bool last = (t == nt - 2);
;             const char* a1 = cA + (size_t)(t + 1) * kstep;
;             const char* a2 = last ? nA : cA + (size_t)(t + 2) * kstep; const char* b2 = last ? nB : cB + (size_t)(t + 2) * kstep;
;             const char* a3 = a2 + kstep; const char* b3 = b2 + kstep;
;             PG8_LDB(B0, 0, 0); PG8_LDB(B1, 0, 1); PG8_SCHED; PG8_LDA(At, 0, 0); PG8_STAGE(PG8_SA(1, 1), a1 + hstepA, voffA);
;             PG8_WAIT_V(8); PG8_WAIT_L(0); PG8_BAR; PG8_MMA(0, 0, At, B0); PG8_MMA(0, 1, At, B1); PG8_BAR; PG8_SCHED;
;             PG8_LDA(At, 0, 1); PG8_STAGE(PG8_SB(0, 0), b2, voffB); PG8_STAGE(PG8_SB(0, 1), b2 + hstepB, voffB); PG8_STAGE(PG8_SA(0, 0), a2, voffA);
;             PG8_WAIT_V(8); PG8_WAIT_L(0); PG8_BAR; PG8_MMA(1, 0, At, B0); PG8_MMA(1, 1, At, B1); PG8_BAR; PG8_SCHED;
;             PG8_LDB(B0, 1, 0); PG8_LDB(B1, 1, 1); PG8_SCHED; PG8_LDA(At, 1, 0); PG8_STAGE(PG8_SA(0, 1), a2 + hstepA, voffA);
;             PG8_WAIT_V(8); PG8_WAIT_L(0); PG8_BAR; PG8_MMA(0, 0, At, B0); PG8_MMA(0, 1, At, B1); PG8_BAR; PG8_SCHED;
;             PG8_LDA(At, 1, 1); PG8_STAGE(PG8_SB(1, 0), b3, voffB); PG8_STAGE(PG8_SB(1, 1), b3 + hstepB, voffB); PG8_STAGE(PG8_SA(1, 0), a3, voffA);
;             PG8_WAIT_V(8); PG8_WAIT_L(0); PG8_BAR; PG8_MMA(1, 0, At, B0); PG8_MMA(1, 1, At, B1); PG8_BAR; PG8_SCHED;
	s_add_i32 s52, s78, s54
	v_lshl_add_u64 v[168:169], v[168:169], 0, s[12:13]
	s_mov_b32 m0, s52
	ds_read_b128 v[186:189], v175 offset:49152
	ds_read_b128 v[190:193], v175 offset:50176
	ds_read_b128 v[194:197], v175 offset:51200
	ds_read_b128 v[198:201], v175 offset:52224
	ds_read_b128 v[202:205], v175 offset:53248
	ds_read_b128 v[206:209], v175 offset:54272
	ds_read_b128 v[210:213], v175 offset:55296
	ds_read_b128 v[214:217], v175 offset:56320
	global_load_lds_dwordx4 v[168:169], off
	s_add_i32 m0, s52, 0x2000
	s_add_u32 s42, s42, 0x40080
	v_lshl_add_u64 v[168:169], v[218:219], 0, s[12:13]
	s_addc_u32 s43, s43, 0
	s_add_i32 s52, s79, s54
	global_load_lds_dwordx4 v[168:169], off
	v_lshl_add_u64 v[168:169], s[42:43], 0, v[146:147]
	s_mov_b32 m0, s52
	s_nop 0
	global_load_lds_dwordx4 v[168:169], off
	v_lshl_add_u64 v[168:169], s[42:43], 0, v[150:151]
	s_add_i32 m0, s52, 0x2000
	s_nop 0
	global_load_lds_dwordx4 v[168:169], off
	v_lshl_add_u64 v[168:169], v[220:221], 0, s[12:13]
	s_mov_b32 m0, s65
	s_nop 0
	global_load_lds_dwordx4 v[168:169], off
	v_lshl_add_u64 v[168:169], v[222:223], 0, s[12:13]
	s_mov_b32 m0, s68
	s_nop 0
	global_load_lds_dwordx4 v[168:169], off
	s_waitcnt vmcnt(8)
	s_waitcnt lgkmcnt(0)
	s_barrier
	s_waitcnt lgkmcnt(0)
	v_mfma_f32_16x16x32_bf16 v[60:63], v[128:131], v[186:189], v[60:63]
	v_mfma_f32_16x16x32_bf16 v[56:59], v[136:139], v[186:189], v[56:59]
	v_mfma_f32_16x16x32_bf16 v[44:47], v[128:131], v[194:197], v[44:47]
	v_mfma_f32_16x16x32_bf16 v[40:43], v[136:139], v[194:197], v[40:43]
	v_mfma_f32_16x16x32_bf16 v[28:31], v[128:131], v[202:205], v[28:31]
	v_mfma_f32_16x16x32_bf16 v[24:27], v[136:139], v[202:205], v[24:27]
	v_mfma_f32_16x16x32_bf16 v[12:15], v[128:131], v[210:213], v[12:15]
	v_mfma_f32_16x16x32_bf16 v[8:11], v[136:139], v[210:213], v[8:11]
	v_mfma_f32_16x16x32_bf16 v[60:63], v[132:135], v[190:193], v[60:63]
	v_mfma_f32_16x16x32_bf16 v[56:59], v[140:143], v[190:193], v[56:59]
	v_mfma_f32_16x16x32_bf16 v[44:47], v[132:135], v[198:201], v[44:47]
	v_mfma_f32_16x16x32_bf16 v[40:43], v[140:143], v[198:201], v[40:43]
	v_mfma_f32_16x16x32_bf16 v[28:31], v[132:135], v[206:209], v[28:31]
	v_mfma_f32_16x16x32_bf16 v[24:27], v[140:143], v[206:209], v[24:27]
	v_mfma_f32_16x16x32_bf16 v[12:15], v[132:135], v[214:217], v[12:15]
	v_mfma_f32_16x16x32_bf16 v[8:11], v[140:143], v[214:217], v[8:11]
	v_mfma_f32_16x16x32_bf16 v[52:55], v[160:163], v[186:189], v[52:55]
	v_mfma_f32_16x16x32_bf16 v[48:51], v[178:181], v[186:189], v[48:51]
	v_mfma_f32_16x16x32_bf16 v[36:39], v[160:163], v[194:197], v[36:39]
	v_mfma_f32_16x16x32_bf16 v[32:35], v[178:181], v[194:197], v[32:35]
	v_mfma_f32_16x16x32_bf16 v[20:23], v[160:163], v[202:205], v[20:23]
	v_mfma_f32_16x16x32_bf16 v[16:19], v[178:181], v[202:205], v[16:19]
	v_mfma_f32_16x16x32_bf16 v[4:7], v[160:163], v[210:213], v[4:7]
	v_mfma_f32_16x16x32_bf16 v[0:3], v[178:181], v[210:213], v[0:3]
	v_mfma_f32_16x16x32_bf16 v[52:55], v[164:167], v[190:193], v[52:55]
	v_mfma_f32_16x16x32_bf16 v[48:51], v[182:185], v[190:193], v[48:51]
	v_mfma_f32_16x16x32_bf16 v[36:39], v[164:167], v[198:201], v[36:39]
	v_mfma_f32_16x16x32_bf16 v[32:35], v[182:185], v[198:201], v[32:35]
	v_mfma_f32_16x16x32_bf16 v[20:23], v[164:167], v[206:209], v[20:23]
	v_mfma_f32_16x16x32_bf16 v[16:19], v[182:185], v[206:209], v[16:19]
	v_mfma_f32_16x16x32_bf16 v[4:7], v[164:167], v[214:217], v[4:7]
	v_mfma_f32_16x16x32_bf16 v[0:3], v[182:185], v[214:217], v[0:3]
	s_barrier
	s_add_i32 s77, s77, 2
	s_add_u32 s38, s38, 0x100
	s_addc_u32 s39, s39, 0
	s_add_u32 s75, s75, 0x100
	s_addc_u32 s76, s76, 0
	s_cmp_gt_u32 s77, 13
.LBB0_457:
	ds_read_b128 v[128:131], v173
	ds_read_b128 v[132:135], v173 offset:1024
	ds_read_b128 v[136:139], v173 offset:2048
	ds_read_b128 v[140:143], v173 offset:3072
	ds_read_b128 v[160:163], v174
	ds_read_b128 v[164:167], v174 offset:1024
	ds_read_b128 v[178:181], v174 offset:2048
	ds_read_b128 v[182:185], v174 offset:3072
	s_add_u32 s42, s38, 0xfffc0080
	s_addc_u32 s43, s39, -1
	s_cmp_eq_u32 s77, 12
	s_cselect_b32 s53, s1, s43
	s_cselect_b32 s52, s23, s42
	s_cselect_b32 s43, s19, s76
	s_cselect_b32 s42, s74, s75
	v_lshl_add_u64 v[168:169], s[38:39], 0, v[152:153]
	s_add_i32 m0, s35, 0xc000
	ds_read_b128 v[186:189], v175
	ds_read_b128 v[190:193], v175 offset:1024
	ds_read_b128 v[194:197], v175 offset:2048
	ds_read_b128 v[198:201], v175 offset:3072
	ds_read_b128 v[202:205], v175 offset:4096
	ds_read_b128 v[206:209], v175 offset:5120
	ds_read_b128 v[210:213], v175 offset:6144
	ds_read_b128 v[214:217], v175 offset:7168
	global_load_lds_dwordx4 v[168:169], off
	v_lshl_add_u64 v[168:169], s[38:39], 0, v[154:155]
	s_add_i32 m0, s35, 0xe000
	s_nop 0
	global_load_lds_dwordx4 v[168:169], off
	s_waitcnt vmcnt(8)
	s_waitcnt lgkmcnt(0)
	s_barrier
; #define PG8_STAGE(bufoff, gbase, voff) do { _Pragma("unroll") for (int _i = 0; _i < 2; ++_i) \
;         __builtin_amdgcn_global_load_lds((const unsigned*)((const char*)(gbase) + (voff)[_i]), (LAS unsigned*)(lds + (bufoff) + ldsw + _i * 8192), 16, 0, 0); } while (0)
; #define PG8_LDA(dst, b, h) do { _Pragma("unroll") for (int m = 0; m < 4; ++m) _Pragma("unroll") for (int k = 0; k < 2; ++k) dst[m][k] = *(const LAS bf16x8*)(lds + PG8_SA(b, h) + aoff + m * 2048 + k * 1024); } while (0)
; #define PG8_MMA(ai, bj, At, Bt) do { __builtin_amdgcn_s_setprio(1); _Pragma("unroll") for (int m = 0; m < 4; ++m) _Pragma("unroll") for (int n = 0; n < 2; ++n) _Pragma("unroll") for (int k = 0; k < 2; ++k) \
;         acc[ai][bj][m][n] = __builtin_amdgcn_mfma_f32_16x16x32_bf16(Bt[n][k], At[m][k], acc[ai][bj][m][n], 0, 0, 0); __builtin_amdgcn_s_setprio(0); } while (0)
; #define PG8_WAIT_V(n) asm volatile("s_waitcnt vmcnt(" #n ")" ::: "memory")
; #define PG8_WAIT_L(n) asm volatile("s_waitcnt lgkmcnt(" #n ")" ::: "memory")
; #define PG8_BAR __builtin_amdgcn_s_barrier()
; #define PG8_SCHED __builtin_amdgcn_sched_barrier(0)
; template <class Epi>
; __device__ __forceinline__ void gemm_phase(LAS unsigned char* lds, const Gemm g, const StaticOrder& S, const Epi& E) {
;     ...
;             PG8_WAIT_V(8); PG8_WAIT_L(0); PG8_BAR; PG8_MMA(0, 0, At, B0); PG8_MMA(0, 1, At, B1); PG8_BAR; PG8_SCHED;
;             PG8_LDA(At, 0, 1); PG8_STAGE(PG8_SB(0, 0), b2, voffB); PG8_STAGE(PG8_SB(0, 1), b2 + hstepB, voffB); PG8_STAGE(PG8_SA(0, 0), a2, voffA);
;             PG8_WAIT_V(8); PG8_WAIT_L(0); PG8_BAR; PG8_MMA(1, 0, At, B0); PG8_MMA(1, 1, At, B1); PG8_BAR; PG8_SCHED;
	s_waitcnt lgkmcnt(0)
	v_mfma_f32_16x16x32_bf16 v[124:127], v[128:131], v[186:189], v[124:127]
	v_mfma_f32_16x16x32_bf16 v[120:123], v[136:139], v[186:189], v[120:123]
	v_mfma_f32_16x16x32_bf16 v[108:111], v[128:131], v[194:197], v[108:111]
	v_mfma_f32_16x16x32_bf16 v[104:107], v[136:139], v[194:197], v[104:107]
	v_mfma_f32_16x16x32_bf16 v[92:95], v[128:131], v[202:205], v[92:95]
	v_mfma_f32_16x16x32_bf16 v[88:91], v[136:139], v[202:205], v[88:91]
	v_mfma_f32_16x16x32_bf16 v[76:79], v[128:131], v[210:213], v[76:79]
	v_mfma_f32_16x16x32_bf16 v[72:75], v[136:139], v[210:213], v[72:75]
	v_mfma_f32_16x16x32_bf16 v[124:127], v[132:135], v[190:193], v[124:127]
	v_mfma_f32_16x16x32_bf16 v[120:123], v[140:143], v[190:193], v[120:123]
	v_mfma_f32_16x16x32_bf16 v[108:111], v[132:135], v[198:201], v[108:111]
	v_mfma_f32_16x16x32_bf16 v[104:107], v[140:143], v[198:201], v[104:107]
	v_mfma_f32_16x16x32_bf16 v[92:95], v[132:135], v[206:209], v[92:95]
	v_mfma_f32_16x16x32_bf16 v[88:91], v[140:143], v[206:209], v[88:91]
	v_mfma_f32_16x16x32_bf16 v[76:79], v[132:135], v[214:217], v[76:79]
	v_mfma_f32_16x16x32_bf16 v[72:75], v[140:143], v[214:217], v[72:75]
	v_mfma_f32_16x16x32_bf16 v[116:119], v[160:163], v[186:189], v[116:119]
	v_mfma_f32_16x16x32_bf16 v[112:115], v[178:181], v[186:189], v[112:115]
	v_mfma_f32_16x16x32_bf16 v[100:103], v[160:163], v[194:197], v[100:103]
	v_mfma_f32_16x16x32_bf16 v[96:99], v[178:181], v[194:197], v[96:99]
	v_mfma_f32_16x16x32_bf16 v[84:87], v[160:163], v[202:205], v[84:87]
	v_mfma_f32_16x16x32_bf16 v[80:83], v[178:181], v[202:205], v[80:83]
	v_mfma_f32_16x16x32_bf16 v[68:71], v[160:163], v[210:213], v[68:71]
	v_mfma_f32_16x16x32_bf16 v[64:67], v[178:181], v[210:213], v[64:67]
	v_mfma_f32_16x16x32_bf16 v[116:119], v[164:167], v[190:193], v[116:119]
	v_mfma_f32_16x16x32_bf16 v[112:115], v[182:185], v[190:193], v[112:115]
	v_mfma_f32_16x16x32_bf16 v[100:103], v[164:167], v[198:201], v[100:103]
	v_mfma_f32_16x16x32_bf16 v[96:99], v[182:185], v[198:201], v[96:99]
	v_mfma_f32_16x16x32_bf16 v[84:87], v[164:167], v[206:209], v[84:87]
	v_mfma_f32_16x16x32_bf16 v[80:83], v[182:185], v[206:209], v[80:83]
	v_mfma_f32_16x16x32_bf16 v[68:71], v[164:167], v[214:217], v[68:71]
	v_mfma_f32_16x16x32_bf16 v[64:67], v[182:185], v[214:217], v[64:67]
	s_barrier
	s_add_i32 s78, s72, s54
	v_lshl_add_u64 v[168:169], s[42:43], 0, v[146:147]
	s_mov_b32 m0, s78
	ds_read_b128 v[186:189], v175 offset:16384
	ds_read_b128 v[190:193], v175 offset:17408
	ds_read_b128 v[194:197], v175 offset:18432
	ds_read_b128 v[198:201], v175 offset:19456
	ds_read_b128 v[202:205], v175 offset:20480
	ds_read_b128 v[206:209], v175 offset:21504
	ds_read_b128 v[210:213], v175 offset:22528
	ds_read_b128 v[214:217], v175 offset:23552
	global_load_lds_dwordx4 v[168:169], off
	s_add_i32 m0, s78, 0x2000
	s_add_u32 s78, s42, 0x40000
	v_lshl_add_u64 v[218:219], s[42:43], 0, v[150:151]
	s_addc_u32 s79, s43, 0
	s_add_i32 s80, s73, s54
	global_load_lds_dwordx4 v[218:219], off
	v_lshl_add_u64 v[220:221], s[78:79], 0, v[146:147]
	s_mov_b32 m0, s80
	v_lshl_add_u64 v[222:223], s[52:53], 0, v[148:149]
	global_load_lds_dwordx4 v[220:221], off
	v_lshl_add_u64 v[220:221], s[78:79], 0, v[150:151]
	s_add_i32 m0, s80, 0x2000
	s_nop 0
	global_load_lds_dwordx4 v[220:221], off
	v_lshl_add_u64 v[220:221], s[52:53], 0, v[144:145]
	s_mov_b32 m0, s35
	s_nop 0
	global_load_lds_dwordx4 v[220:221], off
	s_mov_b32 m0, s55
	s_nop 0
	global_load_lds_dwordx4 v[222:223], off
	s_waitcnt vmcnt(8)
	s_waitcnt lgkmcnt(0)
	s_barrier
	s_waitcnt lgkmcnt(0)
	v_mfma_f32_16x16x32_bf16 v[60:63], v[128:131], v[186:189], v[60:63]
	v_mfma_f32_16x16x32_bf16 v[56:59], v[136:139], v[186:189], v[56:59]
	v_mfma_f32_16x16x32_bf16 v[44:47], v[128:131], v[194:197], v[44:47]
	v_mfma_f32_16x16x32_bf16 v[40:43], v[136:139], v[194:197], v[40:43]
	v_mfma_f32_16x16x32_bf16 v[28:31], v[128:131], v[202:205], v[28:31]
	v_mfma_f32_16x16x32_bf16 v[24:27], v[136:139], v[202:205], v[24:27]
	v_mfma_f32_16x16x32_bf16 v[12:15], v[128:131], v[210:213], v[12:15]
	v_mfma_f32_16x16x32_bf16 v[8:11], v[136:139], v[210:213], v[8:11]
	v_mfma_f32_16x16x32_bf16 v[60:63], v[132:135], v[190:193], v[60:63]
	v_mfma_f32_16x16x32_bf16 v[56:59], v[140:143], v[190:193], v[56:59]
	v_mfma_f32_16x16x32_bf16 v[44:47], v[132:135], v[198:201], v[44:47]
	v_mfma_f32_16x16x32_bf16 v[40:43], v[140:143], v[198:201], v[40:43]
	v_mfma_f32_16x16x32_bf16 v[28:31], v[132:135], v[206:209], v[28:31]
	v_mfma_f32_16x16x32_bf16 v[24:27], v[140:143], v[206:209], v[24:27]
	v_mfma_f32_16x16x32_bf16 v[12:15], v[132:135], v[214:217], v[12:15]
	v_mfma_f32_16x16x32_bf16 v[8:11], v[140:143], v[214:217], v[8:11]
	v_mfma_f32_16x16x32_bf16 v[52:55], v[160:163], v[186:189], v[52:55]
	v_mfma_f32_16x16x32_bf16 v[48:51], v[178:181], v[186:189], v[48:51]
	v_mfma_f32_16x16x32_bf16 v[36:39], v[160:163], v[194:197], v[36:39]
	v_mfma_f32_16x16x32_bf16 v[32:35], v[178:181], v[194:197], v[32:35]
	v_mfma_f32_16x16x32_bf16 v[20:23], v[160:163], v[202:205], v[20:23]
	v_mfma_f32_16x16x32_bf16 v[16:19], v[178:181], v[202:205], v[16:19]
	v_mfma_f32_16x16x32_bf16 v[4:7], v[160:163], v[210:213], v[4:7]
	v_mfma_f32_16x16x32_bf16 v[0:3], v[178:181], v[210:213], v[0:3]
	v_mfma_f32_16x16x32_bf16 v[52:55], v[164:167], v[190:193], v[52:55]
	v_mfma_f32_16x16x32_bf16 v[48:51], v[182:185], v[190:193], v[48:51]
	v_mfma_f32_16x16x32_bf16 v[36:39], v[164:167], v[198:201], v[36:39]
	v_mfma_f32_16x16x32_bf16 v[32:35], v[182:185], v[198:201], v[32:35]
	v_mfma_f32_16x16x32_bf16 v[20:23], v[164:167], v[206:209], v[20:23]
	v_mfma_f32_16x16x32_bf16 v[16:19], v[182:185], v[206:209], v[16:19]
	v_mfma_f32_16x16x32_bf16 v[4:7], v[164:167], v[214:217], v[4:7]
	v_mfma_f32_16x16x32_bf16 v[0:3], v[182:185], v[214:217], v[0:3]
	s_barrier
; #define PG8_STAGE(bufoff, gbase, voff) do { _Pragma("unroll") for (int _i = 0; _i < 2; ++_i) \
;         __builtin_amdgcn_global_load_lds((const unsigned*)((const char*)(gbase) + (voff)[_i]), (LAS unsigned*)(lds + (bufoff) + ldsw + _i * 8192), 16, 0, 0); } while (0)
; #define PG8_LDA(dst, b, h) do { _Pragma("unroll") for (int m = 0; m < 4; ++m) _Pragma("unroll") for (int k = 0; k < 2; ++k) dst[m][k] = *(const LAS bf16x8*)(lds + PG8_SA(b, h) + aoff + m * 2048 + k * 1024); } while (0)
; #define PG8_LDB(dst, b, h) do { _Pragma("unroll") for (int n = 0; n < 2; ++n) _Pragma("unroll") for (int k = 0; k < 2; ++k) dst[n][k] = *(const LAS bf16x8*)(lds + PG8_SB(b, h) + boff + n * 2048 + k * 1024); } while (0)
; #define PG8_MMA(ai, bj, At, Bt) do { __builtin_amdgcn_s_setprio(1); _Pragma("unroll") for (int m = 0; m < 4; ++m) _Pragma("unroll") for (int n = 0; n < 2; ++n) _Pragma("unroll") for (int k = 0; k < 2; ++k) \
;         acc[ai][bj][m][n] = __builtin_amdgcn_mfma_f32_16x16x32_bf16(Bt[n][k], At[m][k], acc[ai][bj][m][n], 0, 0, 0); __builtin_amdgcn_s_setprio(0); } while (0)
; #define PG8_WAIT_V(n) asm volatile("s_waitcnt vmcnt(" #n ")" ::: "memory")
; #define PG8_WAIT_L(n) asm volatile("s_waitcnt lgkmcnt(" #n ")" ::: "memory")
; #define PG8_BAR __builtin_amdgcn_s_barrier()
; #define PG8_SCHED __builtin_amdgcn_sched_barrier(0)
; template <class Epi>
; __device__ __forceinline__ void gemm_phase(LAS unsigned char* lds, const Gemm g, const StaticOrder& S, const Epi& E) {
;     ...
;             PG8_LDB(B0, 1, 0); PG8_LDB(B1, 1, 1); PG8_SCHED; PG8_LDA(At, 1, 0); PG8_STAGE(PG8_SA(0, 1), a2 + hstepA, voffA);
;             PG8_WAIT_V(8); PG8_WAIT_L(0); PG8_BAR; PG8_MMA(0, 0, At, B0); PG8_MMA(0, 1, At, B1); PG8_BAR; PG8_SCHED;
	s_add_i32 s78, 0, 0x18000
	s_add_i32 s79, 0, 0x1c000
	v_add_u32_e32 v140, s78, v172
	v_add_u32_e32 v182, s79, v172
	ds_read_b128 v[128:131], v140
	ds_read_b128 v[132:135], v140 offset:1024
	ds_read_b128 v[136:139], v140 offset:2048
	ds_read_b128 v[140:143], v140 offset:3072
	ds_read_b128 v[160:163], v182
	ds_read_b128 v[164:167], v182 offset:1024
	ds_read_b128 v[178:181], v182 offset:2048
	ds_read_b128 v[182:185], v182 offset:3072
	s_add_u32 s52, s52, 0x40000
	s_addc_u32 s53, s53, 0
	s_mov_b32 m0, s56
	v_lshl_add_u64 v[226:227], s[52:53], 0, v[144:145]
	ds_read_b128 v[186:189], v175 offset:32768
	ds_read_b128 v[190:193], v175 offset:33792
	ds_read_b128 v[194:197], v175 offset:34816
	ds_read_b128 v[198:201], v175 offset:35840
	ds_read_b128 v[202:205], v175 offset:36864
	ds_read_b128 v[206:209], v175 offset:37888
	ds_read_b128 v[210:213], v175 offset:38912
	ds_read_b128 v[214:217], v175 offset:39936
	global_load_lds_dwordx4 v[226:227], off
	v_lshl_add_u64 v[226:227], s[52:53], 0, v[148:149]
	s_mov_b32 m0, s57
	s_nop 0
	global_load_lds_dwordx4 v[226:227], off
	s_waitcnt vmcnt(8)
	s_waitcnt lgkmcnt(0)
	s_barrier
	s_waitcnt lgkmcnt(0)
	v_mfma_f32_16x16x32_bf16 v[124:127], v[128:131], v[186:189], v[124:127]
	v_mfma_f32_16x16x32_bf16 v[120:123], v[136:139], v[186:189], v[120:123]
	v_mfma_f32_16x16x32_bf16 v[108:111], v[128:131], v[194:197], v[108:111]
	v_mfma_f32_16x16x32_bf16 v[104:107], v[136:139], v[194:197], v[104:107]
	v_mfma_f32_16x16x32_bf16 v[92:95], v[128:131], v[202:205], v[92:95]
	v_mfma_f32_16x16x32_bf16 v[88:91], v[136:139], v[202:205], v[88:91]
	v_mfma_f32_16x16x32_bf16 v[76:79], v[128:131], v[210:213], v[76:79]
	v_mfma_f32_16x16x32_bf16 v[72:75], v[136:139], v[210:213], v[72:75]
	v_mfma_f32_16x16x32_bf16 v[124:127], v[132:135], v[190:193], v[124:127]
	v_mfma_f32_16x16x32_bf16 v[120:123], v[140:143], v[190:193], v[120:123]
	v_mfma_f32_16x16x32_bf16 v[108:111], v[132:135], v[198:201], v[108:111]
	v_mfma_f32_16x16x32_bf16 v[104:107], v[140:143], v[198:201], v[104:107]
	v_mfma_f32_16x16x32_bf16 v[92:95], v[132:135], v[206:209], v[92:95]
	v_mfma_f32_16x16x32_bf16 v[88:91], v[140:143], v[206:209], v[88:91]
	v_mfma_f32_16x16x32_bf16 v[76:79], v[132:135], v[214:217], v[76:79]
	v_mfma_f32_16x16x32_bf16 v[72:75], v[140:143], v[214:217], v[72:75]
	v_mfma_f32_16x16x32_bf16 v[116:119], v[160:163], v[186:189], v[116:119]
	v_mfma_f32_16x16x32_bf16 v[112:115], v[178:181], v[186:189], v[112:115]
	v_mfma_f32_16x16x32_bf16 v[100:103], v[160:163], v[194:197], v[100:103]
	v_mfma_f32_16x16x32_bf16 v[96:99], v[178:181], v[194:197], v[96:99]
	v_mfma_f32_16x16x32_bf16 v[84:87], v[160:163], v[202:205], v[84:87]
	v_mfma_f32_16x16x32_bf16 v[80:83], v[178:181], v[202:205], v[80:83]
	v_mfma_f32_16x16x32_bf16 v[68:71], v[160:163], v[210:213], v[68:71]
	v_mfma_f32_16x16x32_bf16 v[64:67], v[178:181], v[210:213], v[64:67]
	v_mfma_f32_16x16x32_bf16 v[116:119], v[164:167], v[190:193], v[116:119]
	v_mfma_f32_16x16x32_bf16 v[112:115], v[182:185], v[190:193], v[112:115]
	v_mfma_f32_16x16x32_bf16 v[100:103], v[164:167], v[198:201], v[100:103]
	v_mfma_f32_16x16x32_bf16 v[96:99], v[182:185], v[198:201], v[96:99]
	v_mfma_f32_16x16x32_bf16 v[84:87], v[164:167], v[206:209], v[84:87]
	v_mfma_f32_16x16x32_bf16 v[80:83], v[182:185], v[206:209], v[80:83]
	v_mfma_f32_16x16x32_bf16 v[68:71], v[164:167], v[214:217], v[68:71]
	v_mfma_f32_16x16x32_bf16 v[64:67], v[182:185], v[214:217], v[64:67]
	s_barrier
; #define PG8_STAGE(bufoff, gbase, voff) do { _Pragma("unroll") for (int _i = 0; _i < 2; ++_i) \
;         __builtin_amdgcn_global_load_lds((const unsigned*)((const char*)(gbase) + (voff)[_i]), (LAS unsigned*)(lds + (bufoff) + ldsw + _i * 8192), 16, 0, 0); } while (0)
; #define PG8_LDA(dst, b, h) do { _Pragma("unroll") for (int m = 0; m < 4; ++m) _Pragma("unroll") for (int k = 0; k < 2; ++k) dst[m][k] = *(const LAS bf16x8*)(lds + PG8_SA(b, h) + aoff + m * 2048 + k * 1024); } while (0)
; #define PG8_MMA(ai, bj, At, Bt) do { __builtin_amdgcn_s_setprio(1); _Pragma("unroll") for (int m = 0; m < 4; ++m) _Pragma("unroll") for (int n = 0; n < 2; ++n) _Pragma("unroll") for (int k = 0; k < 2; ++k) \
;         acc[ai][bj][m][n] = __builtin_amdgcn_mfma_f32_16x16x32_bf16(Bt[n][k], At[m][k], acc[ai][bj][m][n], 0, 0, 0); __builtin_amdgcn_s_setprio(0); } while (0)
; #define PG8_WAIT_V(n) asm volatile("s_waitcnt vmcnt(" #n ")" ::: "memory")
; #define PG8_WAIT_L(n) asm volatile("s_waitcnt lgkmcnt(" #n ")" ::: "memory")
; #define PG8_BAR __builtin_amdgcn_s_barrier()
; #define PG8_SCHED __builtin_amdgcn_sched_barrier(0)
; template <class Epi>
; __device__ __forceinline__ void gemm_phase(LAS unsigned char* lds, const Gemm g, const StaticOrder& S, const Epi& E) {
;     ...
;             PG8_LDA(At, 1, 1); PG8_STAGE(PG8_SB(1, 0), b3, voffB); PG8_STAGE(PG8_SB(1, 1), b3 + hstepB, voffB); PG8_STAGE(PG8_SA(1, 0), a3, voffA);
;             PG8_WAIT_V(8); PG8_WAIT_L(0); PG8_BAR; PG8_MMA(1, 0, At, B0); PG8_MMA(1, 1, At, B1); PG8_BAR; PG8_SCHED;
;         }
;         if (wr == 0) PG8_BAR;
	s_add_i32 s52, s78, s54
	v_lshl_add_u64 v[168:169], v[168:169], 0, s[12:13]
	s_mov_b32 m0, s52
	ds_read_b128 v[186:189], v175 offset:49152
	ds_read_b128 v[190:193], v175 offset:50176
	ds_read_b128 v[194:197], v175 offset:51200
	ds_read_b128 v[198:201], v175 offset:52224
	ds_read_b128 v[202:205], v175 offset:53248
	ds_read_b128 v[206:209], v175 offset:54272
	ds_read_b128 v[210:213], v175 offset:55296
	ds_read_b128 v[214:217], v175 offset:56320
	global_load_lds_dwordx4 v[168:169], off
	s_add_i32 m0, s52, 0x2000
	s_add_u32 s42, s42, 0x40080
	v_lshl_add_u64 v[168:169], v[218:219], 0, s[12:13]
	s_addc_u32 s43, s43, 0
	s_add_i32 s52, s79, s54
	global_load_lds_dwordx4 v[168:169], off
	v_lshl_add_u64 v[168:169], s[42:43], 0, v[146:147]
	s_mov_b32 m0, s52
	s_nop 0
	global_load_lds_dwordx4 v[168:169], off
	v_lshl_add_u64 v[168:169], s[42:43], 0, v[150:151]
	s_add_i32 m0, s52, 0x2000
	s_nop 0
	global_load_lds_dwordx4 v[168:169], off
	v_lshl_add_u64 v[168:169], v[220:221], 0, s[12:13]
	s_mov_b32 m0, s65
	s_nop 0
	global_load_lds_dwordx4 v[168:169], off
	v_lshl_add_u64 v[168:169], v[222:223], 0, s[12:13]
	s_mov_b32 m0, s68
	s_nop 0
	global_load_lds_dwordx4 v[168:169], off
	s_waitcnt vmcnt(8)
	s_waitcnt lgkmcnt(0)
	s_barrier
	s_waitcnt lgkmcnt(0)
	v_mfma_f32_16x16x32_bf16 v[60:63], v[128:131], v[186:189], v[60:63]
	v_mfma_f32_16x16x32_bf16 v[56:59], v[136:139], v[186:189], v[56:59]
	v_mfma_f32_16x16x32_bf16 v[44:47], v[128:131], v[194:197], v[44:47]
	v_mfma_f32_16x16x32_bf16 v[40:43], v[136:139], v[194:197], v[40:43]
	v_mfma_f32_16x16x32_bf16 v[28:31], v[128:131], v[202:205], v[28:31]
	v_mfma_f32_16x16x32_bf16 v[24:27], v[136:139], v[202:205], v[24:27]
	v_mfma_f32_16x16x32_bf16 v[12:15], v[128:131], v[210:213], v[12:15]
	v_mfma_f32_16x16x32_bf16 v[8:11], v[136:139], v[210:213], v[8:11]
	v_mfma_f32_16x16x32_bf16 v[60:63], v[132:135], v[190:193], v[60:63]
	v_mfma_f32_16x16x32_bf16 v[56:59], v[140:143], v[190:193], v[56:59]
	v_mfma_f32_16x16x32_bf16 v[44:47], v[132:135], v[198:201], v[44:47]
	v_mfma_f32_16x16x32_bf16 v[40:43], v[140:143], v[198:201], v[40:43]
	v_mfma_f32_16x16x32_bf16 v[28:31], v[132:135], v[206:209], v[28:31]
	v_mfma_f32_16x16x32_bf16 v[24:27], v[140:143], v[206:209], v[24:27]
	v_mfma_f32_16x16x32_bf16 v[12:15], v[132:135], v[214:217], v[12:15]
	v_mfma_f32_16x16x32_bf16 v[8:11], v[140:143], v[214:217], v[8:11]
	v_mfma_f32_16x16x32_bf16 v[52:55], v[160:163], v[186:189], v[52:55]
	v_mfma_f32_16x16x32_bf16 v[48:51], v[178:181], v[186:189], v[48:51]
	v_mfma_f32_16x16x32_bf16 v[36:39], v[160:163], v[194:197], v[36:39]
	v_mfma_f32_16x16x32_bf16 v[32:35], v[178:181], v[194:197], v[32:35]
	v_mfma_f32_16x16x32_bf16 v[20:23], v[160:163], v[202:205], v[20:23]
	v_mfma_f32_16x16x32_bf16 v[16:19], v[178:181], v[202:205], v[16:19]
	v_mfma_f32_16x16x32_bf16 v[4:7], v[160:163], v[210:213], v[4:7]
	v_mfma_f32_16x16x32_bf16 v[0:3], v[178:181], v[210:213], v[0:3]
	v_mfma_f32_16x16x32_bf16 v[52:55], v[164:167], v[190:193], v[52:55]
	v_mfma_f32_16x16x32_bf16 v[48:51], v[182:185], v[190:193], v[48:51]
	v_mfma_f32_16x16x32_bf16 v[36:39], v[164:167], v[198:201], v[36:39]
	v_mfma_f32_16x16x32_bf16 v[32:35], v[182:185], v[198:201], v[32:35]
	v_mfma_f32_16x16x32_bf16 v[20:23], v[164:167], v[206:209], v[20:23]
	v_mfma_f32_16x16x32_bf16 v[16:19], v[182:185], v[206:209], v[16:19]
	v_mfma_f32_16x16x32_bf16 v[4:7], v[164:167], v[214:217], v[4:7]
	v_mfma_f32_16x16x32_bf16 v[0:3], v[182:185], v[214:217], v[0:3]
	s_barrier
	s_add_i32 s77, s77, 2
	s_add_u32 s38, s38, 0x100
	s_addc_u32 s39, s39, 0
	s_add_u32 s75, s75, 0x100
	s_addc_u32 s76, s76, 0
	s_cmp_gt_u32 s77, 13
	s_cbranch_scc0 .LBB0_457
	s_and_b64 vcc, exec, s[14:15]
	s_cbranch_vccz .LBB0_460
	s_barrier

; #define PG8_STAGE(bufoff, gbase, voff) do { _Pragma("unroll") for (int _i = 0; _i < 2; ++_i) \
;         __builtin_amdgcn_global_load_lds((const unsigned*)((const char*)(gbase) + (voff)[_i]), (LAS unsigned*)(lds + (bufoff) + ldsw + _i * 8192), 16, 0, 0); } while (0)
; #define PG8_LDA(dst, b, h) do { _Pragma("unroll") for (int m = 0; m < 4; ++m) _Pragma("unroll") for (int k = 0; k < 2; ++k) dst[m][k] = *(const LAS bf16x8*)(lds + PG8_SA(b, h) + aoff + m * 2048 + k * 1024); } while (0)
; #define PG8_LDB(dst, b, h) do { _Pragma("unroll") for (int n = 0; n < 2; ++n) _Pragma("unroll") for (int k = 0; k < 2; ++k) dst[n][k] = *(const LAS bf16x8*)(lds + PG8_SB(b, h) + boff + n * 2048 + k * 1024); } while (0)
; #define PG8_MMA(ai, bj, At, Bt) do { __builtin_amdgcn_s_setprio(1); _Pragma("unroll") for (int m = 0; m < 4; ++m) _Pragma("unroll") for (int n = 0; n < 2; ++n) _Pragma("unroll") for (int k = 0; k < 2; ++k) \
;         acc[ai][bj][m][n] = __builtin_amdgcn_mfma_f32_16x16x32_bf16(Bt[n][k], At[m][k], acc[ai][bj][m][n], 0, 0, 0); __builtin_amdgcn_s_setprio(0); } while (0)
; #define PG8_WAIT_V(n) asm volatile("s_waitcnt vmcnt(" #n ")" ::: "memory")
; #define PG8_WAIT_L(n) asm volatile("s_waitcnt lgkmcnt(" #n ")" ::: "memory")
; template <class Epi>
; __device__ __forceinline__ void gemm_phase(LAS unsigned char* lds, const Gemm g, const StaticOrder& S, const Epi& E) {
;     ...
;         const bool has_next = S.next(ui + 1, nxt);
;         const char* nA = has_next ? (const char*)g.A + (size_t)nxt.pm * tstepA : cA; const char* nB = has_next ? (const char*)g.Bt + (size_t)nxt.pn * tstepB : cB;
; #pragma nounroll
;         for (int t = 0; t < nt; t += 2) {
;             const bool last = (t == nt - 2);
;             const char* a1 = cA + (size_t)(t + 1) * kstep;
;             const char* a2 = last ? nA : cA + (size_t)(t + 2) * kstep; const char* b2 = last ? nB : cB + (size_t)(t + 2) * kstep;
;             const char* a3 = a2 + kstep; const char* b3 = b2 + kstep;
;             PG8_LDB(B0, 0, 0); PG8_LDB(B1, 0, 1); PG8_SCHED; PG8_LDA(At, 0, 0); PG8_STAGE(PG8_SA(1, 1), a1 + hstepA, voffA);
;             PG8_WAIT_V(8); PG8_WAIT_L(0); PG8_BAR; PG8_MMA(0, 0, At, B0); PG8_MMA(0, 1, At, B1); PG8_BAR; PG8_SCHED;
;             PG8_LDA(At, 0, 1); PG8_STAGE(PG8_SB(0, 0), b2, voffB); PG8_STAGE(PG8_SB(0, 1), b2 + hstepB, voffB); PG8_STAGE(PG8_SA(0, 0), a2, voffA);
.LBB0_545:
	s_ashr_i32 s71, s70, 31
	s_lshl_b64 s[12:13], s[70:71], 19
	s_add_u32 s72, s24, s12
	s_addc_u32 s73, s25, s13
	s_and_b64 s[12:13], s[4:5], exec
	s_cselect_b32 s1, s73, s9
	s_cselect_b32 s7, s72, s8
	s_ashr_i32 s69, s68, 31
	s_lshl_b64 s[12:13], s[68:69], 19
	s_add_u32 s74, s3, s12
	s_addc_u32 s75, s33, s13
	s_and_b64 s[12:13], s[4:5], exec
	s_cselect_b32 s69, s75, s11
	s_cselect_b32 s71, s74, s10
	s_add_u32 s8, s8, 0x40080
	s_addc_u32 s9, s9, 0
	s_add_u32 s76, s10, 0x100
	s_addc_u32 s77, s11, 0
	s_mov_b32 s89, -2
	s_nop 0
	v_lshl_add_u32 v248, s6, 8, v151
	v_add_u32_e32 v248, s65, v248
	v_ashrrev_i32_e32 v249, 31, v248
	v_lshl_add_u64 v[248:249], v[248:249], 2, s[22:23]
	global_load_dword v240, v[248:249], off
	global_load_dword v241, v[248:249], off offset:64
	global_load_dword v242, v[248:249], off offset:128
	global_load_dword v243, v[248:249], off offset:192
	global_load_dword v244, v[248:249], off offset:512
	global_load_dword v245, v[248:249], off offset:576
	global_load_dword v246, v[248:249], off offset:640
	global_load_dword v247, v[248:249], off offset:704
	ds_read_b128 v[146:149], v162
	ds_read_b128 v[166:169], v162 offset:1024
	ds_read_b128 v[170:173], v162 offset:2048
	ds_read_b128 v[178:181], v162 offset:3072
	ds_read_b128 v[182:185], v163
	ds_read_b128 v[186:189], v163 offset:1024
	ds_read_b128 v[190:193], v163 offset:2048
	ds_read_b128 v[194:197], v163 offset:3072
	s_add_u32 s10, s8, 0xfffc0080
	s_addc_u32 s11, s9, -1
	s_cmp_eq_u32 s89, 12
	s_cselect_b32 s13, s1, s11
	s_cselect_b32 s12, s7, s10
	s_cselect_b32 s11, s69, s77
	s_cselect_b32 s10, s71, s76
	v_lshl_add_u64 v[174:175], s[8:9], 0, v[138:139]
	s_add_i32 m0, s43, 0xc000
	ds_read_b128 v[198:201], v164
	ds_read_b128 v[202:205], v164 offset:1024
	ds_read_b128 v[206:209], v164 offset:2048
	ds_read_b128 v[210:213], v164 offset:3072
	ds_read_b128 v[214:217], v164 offset:4096
	ds_read_b128 v[218:221], v164 offset:5120
	ds_read_b128 v[226:229], v164 offset:6144
	ds_read_b128 v[230:233], v164 offset:7168
	global_load_lds_dwordx4 v[174:175], off
	v_lshl_add_u64 v[174:175], s[8:9], 0, v[140:141]
	s_add_i32 m0, s43, 0xe000
	s_nop 0
	global_load_lds_dwordx4 v[174:175], off
	s_waitcnt vmcnt(8)
	s_waitcnt lgkmcnt(0)
	s_barrier
	s_waitcnt lgkmcnt(0)
	v_mfma_f32_16x16x32_bf16 v[124:127], v[146:149], v[198:201], 0
	v_mfma_f32_16x16x32_bf16 v[120:123], v[170:173], v[198:201], 0
	v_mfma_f32_16x16x32_bf16 v[112:115], v[146:149], v[206:209], 0
	v_mfma_f32_16x16x32_bf16 v[104:107], v[170:173], v[206:209], 0
	v_mfma_f32_16x16x32_bf16 v[100:103], v[146:149], v[214:217], 0
	v_mfma_f32_16x16x32_bf16 v[92:95], v[170:173], v[214:217], 0
	v_mfma_f32_16x16x32_bf16 v[84:87], v[146:149], v[226:229], 0
	v_mfma_f32_16x16x32_bf16 v[76:79], v[170:173], v[226:229], 0
	v_mfma_f32_16x16x32_bf16 v[124:127], v[166:169], v[202:205], v[124:127]
	v_mfma_f32_16x16x32_bf16 v[120:123], v[178:181], v[202:205], v[120:123]
	v_mfma_f32_16x16x32_bf16 v[112:115], v[166:169], v[210:213], v[112:115]
	v_mfma_f32_16x16x32_bf16 v[104:107], v[178:181], v[210:213], v[104:107]
	v_mfma_f32_16x16x32_bf16 v[100:103], v[166:169], v[218:221], v[100:103]
	v_mfma_f32_16x16x32_bf16 v[92:95], v[178:181], v[218:221], v[92:95]
	v_mfma_f32_16x16x32_bf16 v[84:87], v[166:169], v[230:233], v[84:87]
	v_mfma_f32_16x16x32_bf16 v[76:79], v[178:181], v[230:233], v[76:79]
	v_mfma_f32_16x16x32_bf16 v[116:119], v[182:185], v[198:201], 0
	v_mfma_f32_16x16x32_bf16 v[108:111], v[190:193], v[198:201], 0
	v_mfma_f32_16x16x32_bf16 v[96:99], v[182:185], v[206:209], 0
	v_mfma_f32_16x16x32_bf16 v[88:91], v[190:193], v[206:209], 0
	v_mfma_f32_16x16x32_bf16 v[80:83], v[182:185], v[214:217], 0
	v_mfma_f32_16x16x32_bf16 v[72:75], v[190:193], v[214:217], 0
	v_mfma_f32_16x16x32_bf16 v[68:71], v[182:185], v[226:229], 0
	v_mfma_f32_16x16x32_bf16 v[64:67], v[190:193], v[226:229], 0
	v_mfma_f32_16x16x32_bf16 v[116:119], v[186:189], v[202:205], v[116:119]
	v_mfma_f32_16x16x32_bf16 v[108:111], v[194:197], v[202:205], v[108:111]
	v_mfma_f32_16x16x32_bf16 v[96:99], v[186:189], v[210:213], v[96:99]
	v_mfma_f32_16x16x32_bf16 v[88:91], v[194:197], v[210:213], v[88:91]
	v_mfma_f32_16x16x32_bf16 v[80:83], v[186:189], v[218:221], v[80:83]
	v_mfma_f32_16x16x32_bf16 v[72:75], v[194:197], v[218:221], v[72:75]
	v_mfma_f32_16x16x32_bf16 v[68:71], v[186:189], v[230:233], v[68:71]
	v_mfma_f32_16x16x32_bf16 v[64:67], v[194:197], v[230:233], v[64:67]
	s_barrier
	s_add_i32 s90, s85, s39
	v_lshl_add_u64 v[174:175], s[10:11], 0, v[130:131]
	s_mov_b32 m0, s90
	ds_read_b128 v[198:201], v164 offset:16384
	ds_read_b128 v[202:205], v164 offset:17408
	ds_read_b128 v[206:209], v164 offset:18432
	ds_read_b128 v[210:213], v164 offset:19456
	ds_read_b128 v[214:217], v164 offset:20480
	ds_read_b128 v[218:221], v164 offset:21504
	ds_read_b128 v[226:229], v164 offset:22528
	ds_read_b128 v[230:233], v164 offset:23552
	global_load_lds_dwordx4 v[174:175], off
	s_add_i32 m0, s90, 0x2000
	s_add_u32 s90, s10, 0x40000
	v_lshl_add_u64 v[222:223], s[10:11], 0, v[134:135]
	s_addc_u32 s91, s11, 0
	s_add_i32 s92, s86, s39
	global_load_lds_dwordx4 v[222:223], off
	v_lshl_add_u64 v[234:235], s[90:91], 0, v[130:131]
	s_mov_b32 m0, s92
	v_lshl_add_u64 v[236:237], s[12:13], 0, v[132:133]
	global_load_lds_dwordx4 v[234:235], off
	v_lshl_add_u64 v[234:235], s[90:91], 0, v[134:135]
	s_add_i32 m0, s92, 0x2000
	s_nop 0
	global_load_lds_dwordx4 v[234:235], off
	v_lshl_add_u64 v[234:235], s[12:13], 0, v[128:129]
	s_mov_b32 m0, s43
	s_nop 0
	global_load_lds_dwordx4 v[234:235], off
	s_mov_b32 m0, s53
	s_nop 0
	global_load_lds_dwordx4 v[236:237], off
	s_waitcnt vmcnt(8)
	s_waitcnt lgkmcnt(0)
	s_barrier
; #define PG8_STAGE(bufoff, gbase, voff) do { _Pragma("unroll") for (int _i = 0; _i < 2; ++_i) \
;         __builtin_amdgcn_global_load_lds((const unsigned*)((const char*)(gbase) + (voff)[_i]), (LAS unsigned*)(lds + (bufoff) + ldsw + _i * 8192), 16, 0, 0); } while (0)
; #define PG8_LDA(dst, b, h) do { _Pragma("unroll") for (int m = 0; m < 4; ++m) _Pragma("unroll") for (int k = 0; k < 2; ++k) dst[m][k] = *(const LAS bf16x8*)(lds + PG8_SA(b, h) + aoff + m * 2048 + k * 1024); } while (0)
; #define PG8_LDB(dst, b, h) do { _Pragma("unroll") for (int n = 0; n < 2; ++n) _Pragma("unroll") for (int k = 0; k < 2; ++k) dst[n][k] = *(const LAS bf16x8*)(lds + PG8_SB(b, h) + boff + n * 2048 + k * 1024); } while (0)
; #define PG8_MMA(ai, bj, At, Bt) do { __builtin_amdgcn_s_setprio(1); _Pragma("unroll") for (int m = 0; m < 4; ++m) _Pragma("unroll") for (int n = 0; n < 2; ++n) _Pragma("unroll") for (int k = 0; k < 2; ++k) \
;         acc[ai][bj][m][n] = __builtin_amdgcn_mfma_f32_16x16x32_bf16(Bt[n][k], At[m][k], acc[ai][bj][m][n], 0, 0, 0); __builtin_amdgcn_s_setprio(0); } while (0)
; #define PG8_WAIT_V(n) asm volatile("s_waitcnt vmcnt(" #n ")" ::: "memory")
; #define PG8_WAIT_L(n) asm volatile("s_waitcnt lgkmcnt(" #n ")" ::: "memory")
; #define PG8_BAR __builtin_amdgcn_s_barrier()
; #define PG8_SCHED __builtin_amdgcn_sched_barrier(0)
; template <class Epi>
; __device__ __forceinline__ void gemm_phase(LAS unsigned char* lds, const Gemm g, const StaticOrder& S, const Epi& E) {
;     ...
;             PG8_WAIT_V(8); PG8_WAIT_L(0); PG8_BAR; PG8_MMA(1, 0, At, B0); PG8_MMA(1, 1, At, B1); PG8_BAR; PG8_SCHED;
;             PG8_LDB(B0, 1, 0); PG8_LDB(B1, 1, 1); PG8_SCHED; PG8_LDA(At, 1, 0); PG8_STAGE(PG8_SA(0, 1), a2 + hstepA, voffA);
;             PG8_WAIT_V(8); PG8_WAIT_L(0); PG8_BAR; PG8_MMA(0, 0, At, B0); PG8_MMA(0, 1, At, B1); PG8_BAR; PG8_SCHED;
	s_waitcnt lgkmcnt(0)
	v_mfma_f32_16x16x32_bf16 v[60:63], v[146:149], v[198:201], 0
	v_mfma_f32_16x16x32_bf16 v[56:59], v[170:173], v[198:201], 0
	v_mfma_f32_16x16x32_bf16 v[52:55], v[146:149], v[206:209], 0
	v_mfma_f32_16x16x32_bf16 v[44:47], v[170:173], v[206:209], 0
	v_mfma_f32_16x16x32_bf16 v[36:39], v[146:149], v[214:217], 0
	v_mfma_f32_16x16x32_bf16 v[28:31], v[170:173], v[214:217], 0
	v_mfma_f32_16x16x32_bf16 v[20:23], v[146:149], v[226:229], 0
	v_mfma_f32_16x16x32_bf16 v[12:15], v[170:173], v[226:229], 0
	v_mfma_f32_16x16x32_bf16 v[60:63], v[166:169], v[202:205], v[60:63]
	v_mfma_f32_16x16x32_bf16 v[56:59], v[178:181], v[202:205], v[56:59]
	v_mfma_f32_16x16x32_bf16 v[52:55], v[166:169], v[210:213], v[52:55]
	v_mfma_f32_16x16x32_bf16 v[44:47], v[178:181], v[210:213], v[44:47]
	v_mfma_f32_16x16x32_bf16 v[36:39], v[166:169], v[218:221], v[36:39]
	v_mfma_f32_16x16x32_bf16 v[28:31], v[178:181], v[218:221], v[28:31]
	v_mfma_f32_16x16x32_bf16 v[20:23], v[166:169], v[230:233], v[20:23]
	v_mfma_f32_16x16x32_bf16 v[12:15], v[178:181], v[230:233], v[12:15]
	v_mfma_f32_16x16x32_bf16 v[48:51], v[182:185], v[198:201], 0
	v_mfma_f32_16x16x32_bf16 v[40:43], v[190:193], v[198:201], 0
	v_mfma_f32_16x16x32_bf16 v[32:35], v[182:185], v[206:209], 0
	v_mfma_f32_16x16x32_bf16 v[24:27], v[190:193], v[206:209], 0
	v_mfma_f32_16x16x32_bf16 v[16:19], v[182:185], v[214:217], 0
	v_mfma_f32_16x16x32_bf16 v[8:11], v[190:193], v[214:217], 0
	v_mfma_f32_16x16x32_bf16 v[4:7], v[182:185], v[226:229], 0
	v_mfma_f32_16x16x32_bf16 v[0:3], v[190:193], v[226:229], 0
	v_mfma_f32_16x16x32_bf16 v[48:51], v[186:189], v[202:205], v[48:51]
	v_mfma_f32_16x16x32_bf16 v[40:43], v[194:197], v[202:205], v[40:43]
	v_mfma_f32_16x16x32_bf16 v[32:35], v[186:189], v[210:213], v[32:35]
	v_mfma_f32_16x16x32_bf16 v[24:27], v[194:197], v[210:213], v[24:27]
	v_mfma_f32_16x16x32_bf16 v[16:19], v[186:189], v[218:221], v[16:19]
	v_mfma_f32_16x16x32_bf16 v[8:11], v[194:197], v[218:221], v[8:11]
	v_mfma_f32_16x16x32_bf16 v[4:7], v[186:189], v[230:233], v[4:7]
	v_mfma_f32_16x16x32_bf16 v[0:3], v[194:197], v[230:233], v[0:3]
	s_barrier
	s_add_i32 s90, 0, 0x18000
	v_add_u32_e32 v136, s90, v161
	s_add_i32 s91, 0, 0x1c000
	ds_read_b128 v[146:149], v136
	ds_read_b128 v[166:169], v136 offset:1024
	ds_read_b128 v[170:173], v136 offset:2048
	ds_read_b128 v[178:181], v136 offset:3072
	v_add_u32_e32 v136, s91, v161
	ds_read_b128 v[182:185], v136
	ds_read_b128 v[186:189], v136 offset:1024
	ds_read_b128 v[190:193], v136 offset:2048
	ds_read_b128 v[194:197], v136 offset:3072
	s_add_u32 s12, s12, 0x40000
	s_addc_u32 s13, s13, 0
	s_mov_b32 m0, s55
	v_lshl_add_u64 v[238:239], s[12:13], 0, v[128:129]
	ds_read_b128 v[198:201], v164 offset:32768
	ds_read_b128 v[202:205], v164 offset:33792
	ds_read_b128 v[206:209], v164 offset:34816
	ds_read_b128 v[210:213], v164 offset:35840
	ds_read_b128 v[214:217], v164 offset:36864
	ds_read_b128 v[218:221], v164 offset:37888
	ds_read_b128 v[226:229], v164 offset:38912
	ds_read_b128 v[230:233], v164 offset:39936
	global_load_lds_dwordx4 v[238:239], off
	v_lshl_add_u64 v[238:239], s[12:13], 0, v[132:133]
	s_mov_b32 m0, s57
	s_nop 0
	global_load_lds_dwordx4 v[238:239], off
	s_waitcnt vmcnt(8)
	s_waitcnt lgkmcnt(0)
	s_barrier
	s_waitcnt lgkmcnt(0)
	v_mfma_f32_16x16x32_bf16 v[124:127], v[146:149], v[198:201], v[124:127]
	v_mfma_f32_16x16x32_bf16 v[120:123], v[170:173], v[198:201], v[120:123]
	v_mfma_f32_16x16x32_bf16 v[112:115], v[146:149], v[206:209], v[112:115]
	v_mfma_f32_16x16x32_bf16 v[104:107], v[170:173], v[206:209], v[104:107]
	v_mfma_f32_16x16x32_bf16 v[100:103], v[146:149], v[214:217], v[100:103]
	v_mfma_f32_16x16x32_bf16 v[92:95], v[170:173], v[214:217], v[92:95]
	v_mfma_f32_16x16x32_bf16 v[84:87], v[146:149], v[226:229], v[84:87]
	v_mfma_f32_16x16x32_bf16 v[76:79], v[170:173], v[226:229], v[76:79]
	v_mfma_f32_16x16x32_bf16 v[124:127], v[166:169], v[202:205], v[124:127]
	v_mfma_f32_16x16x32_bf16 v[120:123], v[178:181], v[202:205], v[120:123]
	v_mfma_f32_16x16x32_bf16 v[112:115], v[166:169], v[210:213], v[112:115]
	v_mfma_f32_16x16x32_bf16 v[104:107], v[178:181], v[210:213], v[104:107]
	v_mfma_f32_16x16x32_bf16 v[100:103], v[166:169], v[218:221], v[100:103]
	v_mfma_f32_16x16x32_bf16 v[92:95], v[178:181], v[218:221], v[92:95]
	v_mfma_f32_16x16x32_bf16 v[84:87], v[166:169], v[230:233], v[84:87]
	v_mfma_f32_16x16x32_bf16 v[76:79], v[178:181], v[230:233], v[76:79]
	v_mfma_f32_16x16x32_bf16 v[116:119], v[182:185], v[198:201], v[116:119]
	v_mfma_f32_16x16x32_bf16 v[108:111], v[190:193], v[198:201], v[108:111]
	v_mfma_f32_16x16x32_bf16 v[96:99], v[182:185], v[206:209], v[96:99]
	v_mfma_f32_16x16x32_bf16 v[88:91], v[190:193], v[206:209], v[88:91]
	v_mfma_f32_16x16x32_bf16 v[80:83], v[182:185], v[214:217], v[80:83]
	v_mfma_f32_16x16x32_bf16 v[72:75], v[190:193], v[214:217], v[72:75]
	v_mfma_f32_16x16x32_bf16 v[68:71], v[182:185], v[226:229], v[68:71]
	v_mfma_f32_16x16x32_bf16 v[64:67], v[190:193], v[226:229], v[64:67]
	v_mfma_f32_16x16x32_bf16 v[116:119], v[186:189], v[202:205], v[116:119]
	v_mfma_f32_16x16x32_bf16 v[108:111], v[194:197], v[202:205], v[108:111]
	v_mfma_f32_16x16x32_bf16 v[96:99], v[186:189], v[210:213], v[96:99]
	v_mfma_f32_16x16x32_bf16 v[88:91], v[194:197], v[210:213], v[88:91]
	v_mfma_f32_16x16x32_bf16 v[80:83], v[186:189], v[218:221], v[80:83]
	v_mfma_f32_16x16x32_bf16 v[72:75], v[194:197], v[218:221], v[72:75]
	v_mfma_f32_16x16x32_bf16 v[68:71], v[186:189], v[230:233], v[68:71]
	v_mfma_f32_16x16x32_bf16 v[64:67], v[194:197], v[230:233], v[64:67]
	s_barrier
; #define PG8_STAGE(bufoff, gbase, voff) do { _Pragma("unroll") for (int _i = 0; _i < 2; ++_i) \
;         __builtin_amdgcn_global_load_lds((const unsigned*)((const char*)(gbase) + (voff)[_i]), (LAS unsigned*)(lds + (bufoff) + ldsw + _i * 8192), 16, 0, 0); } while (0)
; #define PG8_LDA(dst, b, h) do { _Pragma("unroll") for (int m = 0; m < 4; ++m) _Pragma("unroll") for (int k = 0; k < 2; ++k) dst[m][k] = *(const LAS bf16x8*)(lds + PG8_SA(b, h) + aoff + m * 2048 + k * 1024); } while (0)
; #define PG8_LDB(dst, b, h) do { _Pragma("unroll") for (int n = 0; n < 2; ++n) _Pragma("unroll") for (int k = 0; k < 2; ++k) dst[n][k] = *(const LAS bf16x8*)(lds + PG8_SB(b, h) + boff + n * 2048 + k * 1024); } while (0)
; #define PG8_WAIT_V(n) asm volatile("s_waitcnt vmcnt(" #n ")" ::: "memory")
; #define PG8_WAIT_L(n) asm volatile("s_waitcnt lgkmcnt(" #n ")" ::: "memory")
; template <class Epi>
; __device__ __forceinline__ void gemm_phase(LAS unsigned char* lds, const Gemm g, const StaticOrder& S, const Epi& E) {
;     ...
;         for (int t = 0; t < nt; t += 2) {
;             const bool last = (t == nt - 2);
;             const char* a1 = cA + (size_t)(t + 1) * kstep;
;             const char* a2 = last ? nA : cA + (size_t)(t + 2) * kstep; const char* b2 = last ? nB : cB + (size_t)(t + 2) * kstep;
;             const char* a3 = a2 + kstep; const char* b3 = b2 + kstep;
;             PG8_LDB(B0, 0, 0); PG8_LDB(B1, 0, 1); PG8_SCHED; PG8_LDA(At, 0, 0); PG8_STAGE(PG8_SA(1, 1), a1 + hstepA, voffA);
;             PG8_WAIT_V(8); PG8_WAIT_L(0); PG8_BAR; PG8_MMA(0, 0, At, B0); PG8_MMA(0, 1, At, B1); PG8_BAR; PG8_SCHED;
;             PG8_LDA(At, 0, 1); PG8_STAGE(PG8_SB(0, 0), b2, voffB); PG8_STAGE(PG8_SB(0, 1), b2 + hstepB, voffB); PG8_STAGE(PG8_SA(0, 0), a2, voffA);
;             PG8_WAIT_V(8); PG8_WAIT_L(0); PG8_BAR; PG8_MMA(1, 0, At, B0); PG8_MMA(1, 1, At, B1); PG8_BAR; PG8_SCHED;
;             PG8_LDB(B0, 1, 0); PG8_LDB(B1, 1, 1); PG8_SCHED; PG8_LDA(At, 1, 0); PG8_STAGE(PG8_SA(0, 1), a2 + hstepA, voffA);
;             PG8_WAIT_V(8); PG8_WAIT_L(0); PG8_BAR; PG8_MMA(0, 0, At, B0); PG8_MMA(0, 1, At, B1); PG8_BAR; PG8_SCHED;
;             PG8_LDA(At, 1, 1); PG8_STAGE(PG8_SB(1, 0), b3, voffB); PG8_STAGE(PG8_SB(1, 1), b3 + hstepB, voffB); PG8_STAGE(PG8_SA(1, 0), a3, voffA);
;             PG8_WAIT_V(8); PG8_WAIT_L(0); PG8_BAR; PG8_MMA(1, 0, At, B0); PG8_MMA(1, 1, At, B1); PG8_BAR; PG8_SCHED;
	s_add_i32 s12, s90, s39
	v_lshl_add_u64 v[174:175], v[174:175], 0, s[30:31]
	s_mov_b32 m0, s12
	ds_read_b128 v[198:201], v164 offset:49152
	ds_read_b128 v[202:205], v164 offset:50176
	ds_read_b128 v[206:209], v164 offset:51200
	ds_read_b128 v[210:213], v164 offset:52224
	ds_read_b128 v[214:217], v164 offset:53248
	ds_read_b128 v[218:221], v164 offset:54272
	ds_read_b128 v[226:229], v164 offset:55296
	ds_read_b128 v[230:233], v164 offset:56320
	global_load_lds_dwordx4 v[174:175], off
	s_add_i32 m0, s12, 0x2000
	s_add_u32 s10, s10, 0x40080
	v_lshl_add_u64 v[174:175], v[222:223], 0, s[30:31]
	s_addc_u32 s11, s11, 0
	s_add_i32 s12, s91, s39
	global_load_lds_dwordx4 v[174:175], off
	v_lshl_add_u64 v[174:175], s[10:11], 0, v[130:131]
	s_mov_b32 m0, s12
	s_nop 0
	global_load_lds_dwordx4 v[174:175], off
	v_lshl_add_u64 v[174:175], s[10:11], 0, v[134:135]
	s_add_i32 m0, s12, 0x2000
	s_nop 0
	global_load_lds_dwordx4 v[174:175], off
	v_lshl_add_u64 v[174:175], v[234:235], 0, s[30:31]
	s_mov_b32 m0, s79
	s_nop 0
	global_load_lds_dwordx4 v[174:175], off
	v_lshl_add_u64 v[174:175], v[236:237], 0, s[30:31]
	s_mov_b32 m0, s80
	s_nop 0
	global_load_lds_dwordx4 v[174:175], off
	s_waitcnt vmcnt(8)
	s_waitcnt lgkmcnt(0)
	s_barrier
	s_waitcnt lgkmcnt(0)
	v_mfma_f32_16x16x32_bf16 v[60:63], v[146:149], v[198:201], v[60:63]
	v_mfma_f32_16x16x32_bf16 v[56:59], v[170:173], v[198:201], v[56:59]
	v_mfma_f32_16x16x32_bf16 v[52:55], v[146:149], v[206:209], v[52:55]
	v_mfma_f32_16x16x32_bf16 v[44:47], v[170:173], v[206:209], v[44:47]
	v_mfma_f32_16x16x32_bf16 v[36:39], v[146:149], v[214:217], v[36:39]
	v_mfma_f32_16x16x32_bf16 v[28:31], v[170:173], v[214:217], v[28:31]
	v_mfma_f32_16x16x32_bf16 v[20:23], v[146:149], v[226:229], v[20:23]
	v_mfma_f32_16x16x32_bf16 v[12:15], v[170:173], v[226:229], v[12:15]
	v_mfma_f32_16x16x32_bf16 v[60:63], v[166:169], v[202:205], v[60:63]
	v_mfma_f32_16x16x32_bf16 v[56:59], v[178:181], v[202:205], v[56:59]
	v_mfma_f32_16x16x32_bf16 v[52:55], v[166:169], v[210:213], v[52:55]
	v_mfma_f32_16x16x32_bf16 v[44:47], v[178:181], v[210:213], v[44:47]
	v_mfma_f32_16x16x32_bf16 v[36:39], v[166:169], v[218:221], v[36:39]
	v_mfma_f32_16x16x32_bf16 v[28:31], v[178:181], v[218:221], v[28:31]
	v_mfma_f32_16x16x32_bf16 v[20:23], v[166:169], v[230:233], v[20:23]
	v_mfma_f32_16x16x32_bf16 v[12:15], v[178:181], v[230:233], v[12:15]
	v_mfma_f32_16x16x32_bf16 v[48:51], v[182:185], v[198:201], v[48:51]
	v_mfma_f32_16x16x32_bf16 v[40:43], v[190:193], v[198:201], v[40:43]
	v_mfma_f32_16x16x32_bf16 v[32:35], v[182:185], v[206:209], v[32:35]
	v_mfma_f32_16x16x32_bf16 v[24:27], v[190:193], v[206:209], v[24:27]
	v_mfma_f32_16x16x32_bf16 v[16:19], v[182:185], v[214:217], v[16:19]
	v_mfma_f32_16x16x32_bf16 v[8:11], v[190:193], v[214:217], v[8:11]
	v_mfma_f32_16x16x32_bf16 v[4:7], v[182:185], v[226:229], v[4:7]
	v_mfma_f32_16x16x32_bf16 v[0:3], v[190:193], v[226:229], v[0:3]
	v_mfma_f32_16x16x32_bf16 v[48:51], v[186:189], v[202:205], v[48:51]
	v_mfma_f32_16x16x32_bf16 v[40:43], v[194:197], v[202:205], v[40:43]
	v_mfma_f32_16x16x32_bf16 v[32:35], v[186:189], v[210:213], v[32:35]
	v_mfma_f32_16x16x32_bf16 v[24:27], v[194:197], v[210:213], v[24:27]
	v_mfma_f32_16x16x32_bf16 v[16:19], v[186:189], v[218:221], v[16:19]
	v_mfma_f32_16x16x32_bf16 v[8:11], v[194:197], v[218:221], v[8:11]
	v_mfma_f32_16x16x32_bf16 v[4:7], v[186:189], v[230:233], v[4:7]
	v_mfma_f32_16x16x32_bf16 v[0:3], v[194:197], v[230:233], v[0:3]
	s_barrier
	s_add_i32 s89, s89, 2
	s_add_u32 s8, s8, 0x100
	s_addc_u32 s9, s9, 0
	s_add_u32 s76, s76, 0x100
	s_addc_u32 s77, s77, 0
	s_cmp_gt_u32 s89, 13
.LBB0_546:
	ds_read_b128 v[146:149], v162
	ds_read_b128 v[166:169], v162 offset:1024
	ds_read_b128 v[170:173], v162 offset:2048
	ds_read_b128 v[178:181], v162 offset:3072
	ds_read_b128 v[182:185], v163
	ds_read_b128 v[186:189], v163 offset:1024
	ds_read_b128 v[190:193], v163 offset:2048
	ds_read_b128 v[194:197], v163 offset:3072
	s_add_u32 s10, s8, 0xfffc0080
	s_addc_u32 s11, s9, -1
	s_cmp_eq_u32 s89, 12
	s_cselect_b32 s13, s1, s11
	s_cselect_b32 s12, s7, s10
	s_cselect_b32 s11, s69, s77
	s_cselect_b32 s10, s71, s76
	v_lshl_add_u64 v[174:175], s[8:9], 0, v[138:139]
	s_add_i32 m0, s43, 0xc000
	ds_read_b128 v[198:201], v164
	ds_read_b128 v[202:205], v164 offset:1024
	ds_read_b128 v[206:209], v164 offset:2048
	ds_read_b128 v[210:213], v164 offset:3072
	ds_read_b128 v[214:217], v164 offset:4096
	ds_read_b128 v[218:221], v164 offset:5120
	ds_read_b128 v[226:229], v164 offset:6144
	ds_read_b128 v[230:233], v164 offset:7168
	global_load_lds_dwordx4 v[174:175], off
	v_lshl_add_u64 v[174:175], s[8:9], 0, v[140:141]
	s_add_i32 m0, s43, 0xe000
	s_nop 0
	global_load_lds_dwordx4 v[174:175], off
	s_waitcnt vmcnt(8)
	s_waitcnt lgkmcnt(0)
	s_barrier
; #define PG8_STAGE(bufoff, gbase, voff) do { _Pragma("unroll") for (int _i = 0; _i < 2; ++_i) \
;         __builtin_amdgcn_global_load_lds((const unsigned*)((const char*)(gbase) + (voff)[_i]), (LAS unsigned*)(lds + (bufoff) + ldsw + _i * 8192), 16, 0, 0); } while (0)
; #define PG8_LDA(dst, b, h) do { _Pragma("unroll") for (int m = 0; m < 4; ++m) _Pragma("unroll") for (int k = 0; k < 2; ++k) dst[m][k] = *(const LAS bf16x8*)(lds + PG8_SA(b, h) + aoff + m * 2048 + k * 1024); } while (0)
; #define PG8_MMA(ai, bj, At, Bt) do { __builtin_amdgcn_s_setprio(1); _Pragma("unroll") for (int m = 0; m < 4; ++m) _Pragma("unroll") for (int n = 0; n < 2; ++n) _Pragma("unroll") for (int k = 0; k < 2; ++k) \
;         acc[ai][bj][m][n] = __builtin_amdgcn_mfma_f32_16x16x32_bf16(Bt[n][k], At[m][k], acc[ai][bj][m][n], 0, 0, 0); __builtin_amdgcn_s_setprio(0); } while (0)
; #define PG8_WAIT_V(n) asm volatile("s_waitcnt vmcnt(" #n ")" ::: "memory")
; #define PG8_WAIT_L(n) asm volatile("s_waitcnt lgkmcnt(" #n ")" ::: "memory")
; #define PG8_BAR __builtin_amdgcn_s_barrier()
; #define PG8_SCHED __builtin_amdgcn_sched_barrier(0)
; template <class Epi>
; __device__ __forceinline__ void gemm_phase(LAS unsigned char* lds, const Gemm g, const StaticOrder& S, const Epi& E) {
;     ...
;             PG8_WAIT_V(8); PG8_WAIT_L(0); PG8_BAR; PG8_MMA(0, 0, At, B0); PG8_MMA(0, 1, At, B1); PG8_BAR; PG8_SCHED;
;             PG8_LDA(At, 0, 1); PG8_STAGE(PG8_SB(0, 0), b2, voffB); PG8_STAGE(PG8_SB(0, 1), b2 + hstepB, voffB); PG8_STAGE(PG8_SA(0, 0), a2, voffA);
;             PG8_WAIT_V(8); PG8_WAIT_L(0); PG8_BAR; PG8_MMA(1, 0, At, B0); PG8_MMA(1, 1, At, B1); PG8_BAR; PG8_SCHED;
	s_waitcnt lgkmcnt(0)
	v_mfma_f32_16x16x32_bf16 v[124:127], v[146:149], v[198:201], v[124:127]
	v_mfma_f32_16x16x32_bf16 v[120:123], v[170:173], v[198:201], v[120:123]
	v_mfma_f32_16x16x32_bf16 v[112:115], v[146:149], v[206:209], v[112:115]
	v_mfma_f32_16x16x32_bf16 v[104:107], v[170:173], v[206:209], v[104:107]
	v_mfma_f32_16x16x32_bf16 v[100:103], v[146:149], v[214:217], v[100:103]
	v_mfma_f32_16x16x32_bf16 v[92:95], v[170:173], v[214:217], v[92:95]
	v_mfma_f32_16x16x32_bf16 v[84:87], v[146:149], v[226:229], v[84:87]
	v_mfma_f32_16x16x32_bf16 v[76:79], v[170:173], v[226:229], v[76:79]
	v_mfma_f32_16x16x32_bf16 v[124:127], v[166:169], v[202:205], v[124:127]
	v_mfma_f32_16x16x32_bf16 v[120:123], v[178:181], v[202:205], v[120:123]
	v_mfma_f32_16x16x32_bf16 v[112:115], v[166:169], v[210:213], v[112:115]
	v_mfma_f32_16x16x32_bf16 v[104:107], v[178:181], v[210:213], v[104:107]
	v_mfma_f32_16x16x32_bf16 v[100:103], v[166:169], v[218:221], v[100:103]
	v_mfma_f32_16x16x32_bf16 v[92:95], v[178:181], v[218:221], v[92:95]
	v_mfma_f32_16x16x32_bf16 v[84:87], v[166:169], v[230:233], v[84:87]
	v_mfma_f32_16x16x32_bf16 v[76:79], v[178:181], v[230:233], v[76:79]
	v_mfma_f32_16x16x32_bf16 v[116:119], v[182:185], v[198:201], v[116:119]
	v_mfma_f32_16x16x32_bf16 v[108:111], v[190:193], v[198:201], v[108:111]
	v_mfma_f32_16x16x32_bf16 v[96:99], v[182:185], v[206:209], v[96:99]
	v_mfma_f32_16x16x32_bf16 v[88:91], v[190:193], v[206:209], v[88:91]
	v_mfma_f32_16x16x32_bf16 v[80:83], v[182:185], v[214:217], v[80:83]
	v_mfma_f32_16x16x32_bf16 v[72:75], v[190:193], v[214:217], v[72:75]
	v_mfma_f32_16x16x32_bf16 v[68:71], v[182:185], v[226:229], v[68:71]
	v_mfma_f32_16x16x32_bf16 v[64:67], v[190:193], v[226:229], v[64:67]
	v_mfma_f32_16x16x32_bf16 v[116:119], v[186:189], v[202:205], v[116:119]
	v_mfma_f32_16x16x32_bf16 v[108:111], v[194:197], v[202:205], v[108:111]
	v_mfma_f32_16x16x32_bf16 v[96:99], v[186:189], v[210:213], v[96:99]
	v_mfma_f32_16x16x32_bf16 v[88:91], v[194:197], v[210:213], v[88:91]
	v_mfma_f32_16x16x32_bf16 v[80:83], v[186:189], v[218:221], v[80:83]
	v_mfma_f32_16x16x32_bf16 v[72:75], v[194:197], v[218:221], v[72:75]
	v_mfma_f32_16x16x32_bf16 v[68:71], v[186:189], v[230:233], v[68:71]
	v_mfma_f32_16x16x32_bf16 v[64:67], v[194:197], v[230:233], v[64:67]
	s_barrier
	s_add_i32 s90, s85, s39
	v_lshl_add_u64 v[174:175], s[10:11], 0, v[130:131]
	s_mov_b32 m0, s90
	ds_read_b128 v[198:201], v164 offset:16384
	ds_read_b128 v[202:205], v164 offset:17408
	ds_read_b128 v[206:209], v164 offset:18432
	ds_read_b128 v[210:213], v164 offset:19456
	ds_read_b128 v[214:217], v164 offset:20480
	ds_read_b128 v[218:221], v164 offset:21504
	ds_read_b128 v[226:229], v164 offset:22528
	ds_read_b128 v[230:233], v164 offset:23552
	global_load_lds_dwordx4 v[174:175], off
	s_add_i32 m0, s90, 0x2000
	s_add_u32 s90, s10, 0x40000
	v_lshl_add_u64 v[222:223], s[10:11], 0, v[134:135]
	s_addc_u32 s91, s11, 0
	s_add_i32 s92, s86, s39
	global_load_lds_dwordx4 v[222:223], off
	v_lshl_add_u64 v[234:235], s[90:91], 0, v[130:131]
	s_mov_b32 m0, s92
	v_lshl_add_u64 v[236:237], s[12:13], 0, v[132:133]
	global_load_lds_dwordx4 v[234:235], off
	v_lshl_add_u64 v[234:235], s[90:91], 0, v[134:135]
	s_add_i32 m0, s92, 0x2000
	s_nop 0
	global_load_lds_dwordx4 v[234:235], off
	v_lshl_add_u64 v[234:235], s[12:13], 0, v[128:129]
	s_mov_b32 m0, s43
	s_nop 0
	global_load_lds_dwordx4 v[234:235], off
	s_mov_b32 m0, s53
	s_nop 0
	global_load_lds_dwordx4 v[236:237], off
	s_waitcnt vmcnt(8)
	s_waitcnt lgkmcnt(0)
	s_barrier
	s_waitcnt lgkmcnt(0)
	v_mfma_f32_16x16x32_bf16 v[60:63], v[146:149], v[198:201], v[60:63]
	v_mfma_f32_16x16x32_bf16 v[56:59], v[170:173], v[198:201], v[56:59]
	v_mfma_f32_16x16x32_bf16 v[52:55], v[146:149], v[206:209], v[52:55]
	v_mfma_f32_16x16x32_bf16 v[44:47], v[170:173], v[206:209], v[44:47]
	v_mfma_f32_16x16x32_bf16 v[36:39], v[146:149], v[214:217], v[36:39]
	v_mfma_f32_16x16x32_bf16 v[28:31], v[170:173], v[214:217], v[28:31]
	v_mfma_f32_16x16x32_bf16 v[20:23], v[146:149], v[226:229], v[20:23]
	v_mfma_f32_16x16x32_bf16 v[12:15], v[170:173], v[226:229], v[12:15]
	v_mfma_f32_16x16x32_bf16 v[60:63], v[166:169], v[202:205], v[60:63]
	v_mfma_f32_16x16x32_bf16 v[56:59], v[178:181], v[202:205], v[56:59]
	v_mfma_f32_16x16x32_bf16 v[52:55], v[166:169], v[210:213], v[52:55]
	v_mfma_f32_16x16x32_bf16 v[44:47], v[178:181], v[210:213], v[44:47]
	v_mfma_f32_16x16x32_bf16 v[36:39], v[166:169], v[218:221], v[36:39]
	v_mfma_f32_16x16x32_bf16 v[28:31], v[178:181], v[218:221], v[28:31]
	v_mfma_f32_16x16x32_bf16 v[20:23], v[166:169], v[230:233], v[20:23]
	v_mfma_f32_16x16x32_bf16 v[12:15], v[178:181], v[230:233], v[12:15]
	v_mfma_f32_16x16x32_bf16 v[48:51], v[182:185], v[198:201], v[48:51]
	v_mfma_f32_16x16x32_bf16 v[40:43], v[190:193], v[198:201], v[40:43]
	v_mfma_f32_16x16x32_bf16 v[32:35], v[182:185], v[206:209], v[32:35]
	v_mfma_f32_16x16x32_bf16 v[24:27], v[190:193], v[206:209], v[24:27]
	v_mfma_f32_16x16x32_bf16 v[16:19], v[182:185], v[214:217], v[16:19]
	v_mfma_f32_16x16x32_bf16 v[8:11], v[190:193], v[214:217], v[8:11]
	v_mfma_f32_16x16x32_bf16 v[4:7], v[182:185], v[226:229], v[4:7]
	v_mfma_f32_16x16x32_bf16 v[0:3], v[190:193], v[226:229], v[0:3]
	v_mfma_f32_16x16x32_bf16 v[48:51], v[186:189], v[202:205], v[48:51]
	v_mfma_f32_16x16x32_bf16 v[40:43], v[194:197], v[202:205], v[40:43]
	v_mfma_f32_16x16x32_bf16 v[32:35], v[186:189], v[210:213], v[32:35]
	v_mfma_f32_16x16x32_bf16 v[24:27], v[194:197], v[210:213], v[24:27]
	v_mfma_f32_16x16x32_bf16 v[16:19], v[186:189], v[218:221], v[16:19]
	v_mfma_f32_16x16x32_bf16 v[8:11], v[194:197], v[218:221], v[8:11]
	v_mfma_f32_16x16x32_bf16 v[4:7], v[186:189], v[230:233], v[4:7]
	v_mfma_f32_16x16x32_bf16 v[0:3], v[194:197], v[230:233], v[0:3]
	s_barrier
; #define PG8_STAGE(bufoff, gbase, voff) do { _Pragma("unroll") for (int _i = 0; _i < 2; ++_i) \
;         __builtin_amdgcn_global_load_lds((const unsigned*)((const char*)(gbase) + (voff)[_i]), (LAS unsigned*)(lds + (bufoff) + ldsw + _i * 8192), 16, 0, 0); } while (0)
; #define PG8_LDA(dst, b, h) do { _Pragma("unroll") for (int m = 0; m < 4; ++m) _Pragma("unroll") for (int k = 0; k < 2; ++k) dst[m][k] = *(const LAS bf16x8*)(lds + PG8_SA(b, h) + aoff + m * 2048 + k * 1024); } while (0)
; #define PG8_LDB(dst, b, h) do { _Pragma("unroll") for (int n = 0; n < 2; ++n) _Pragma("unroll") for (int k = 0; k < 2; ++k) dst[n][k] = *(const LAS bf16x8*)(lds + PG8_SB(b, h) + boff + n * 2048 + k * 1024); } while (0)
; #define PG8_MMA(ai, bj, At, Bt) do { __builtin_amdgcn_s_setprio(1); _Pragma("unroll") for (int m = 0; m < 4; ++m) _Pragma("unroll") for (int n = 0; n < 2; ++n) _Pragma("unroll") for (int k = 0; k < 2; ++k) \
;         acc[ai][bj][m][n] = __builtin_amdgcn_mfma_f32_16x16x32_bf16(Bt[n][k], At[m][k], acc[ai][bj][m][n], 0, 0, 0); __builtin_amdgcn_s_setprio(0); } while (0)
; #define PG8_WAIT_V(n) asm volatile("s_waitcnt vmcnt(" #n ")" ::: "memory")
; #define PG8_WAIT_L(n) asm volatile("s_waitcnt lgkmcnt(" #n ")" ::: "memory")
; #define PG8_BAR __builtin_amdgcn_s_barrier()
; #define PG8_SCHED __builtin_amdgcn_sched_barrier(0)
; template <class Epi>
; __device__ __forceinline__ void gemm_phase(LAS unsigned char* lds, const Gemm g, const StaticOrder& S, const Epi& E) {
;     ...
;             PG8_LDB(B0, 1, 0); PG8_LDB(B1, 1, 1); PG8_SCHED; PG8_LDA(At, 1, 0); PG8_STAGE(PG8_SA(0, 1), a2 + hstepA, voffA);
;             PG8_WAIT_V(8); PG8_WAIT_L(0); PG8_BAR; PG8_MMA(0, 0, At, B0); PG8_MMA(0, 1, At, B1); PG8_BAR; PG8_SCHED;
	s_add_i32 s90, 0, 0x18000
	v_add_u32_e32 v136, s90, v161
	s_add_i32 s91, 0, 0x1c000
	ds_read_b128 v[146:149], v136
	ds_read_b128 v[166:169], v136 offset:1024
	ds_read_b128 v[170:173], v136 offset:2048
	ds_read_b128 v[178:181], v136 offset:3072
	v_add_u32_e32 v136, s91, v161
	ds_read_b128 v[182:185], v136
	ds_read_b128 v[186:189], v136 offset:1024
	ds_read_b128 v[190:193], v136 offset:2048
	ds_read_b128 v[194:197], v136 offset:3072
	s_add_u32 s12, s12, 0x40000
	s_addc_u32 s13, s13, 0
	s_mov_b32 m0, s55
	v_lshl_add_u64 v[238:239], s[12:13], 0, v[128:129]
	ds_read_b128 v[198:201], v164 offset:32768
	ds_read_b128 v[202:205], v164 offset:33792
	ds_read_b128 v[206:209], v164 offset:34816
	ds_read_b128 v[210:213], v164 offset:35840
	ds_read_b128 v[214:217], v164 offset:36864
	ds_read_b128 v[218:221], v164 offset:37888
	ds_read_b128 v[226:229], v164 offset:38912
	ds_read_b128 v[230:233], v164 offset:39936
	global_load_lds_dwordx4 v[238:239], off
	v_lshl_add_u64 v[238:239], s[12:13], 0, v[132:133]
	s_mov_b32 m0, s57
	s_nop 0
	global_load_lds_dwordx4 v[238:239], off
	s_waitcnt vmcnt(8)
	s_waitcnt lgkmcnt(0)
	s_barrier
	s_waitcnt lgkmcnt(0)
	v_mfma_f32_16x16x32_bf16 v[124:127], v[146:149], v[198:201], v[124:127]
	v_mfma_f32_16x16x32_bf16 v[120:123], v[170:173], v[198:201], v[120:123]
	v_mfma_f32_16x16x32_bf16 v[112:115], v[146:149], v[206:209], v[112:115]
	v_mfma_f32_16x16x32_bf16 v[104:107], v[170:173], v[206:209], v[104:107]
	v_mfma_f32_16x16x32_bf16 v[100:103], v[146:149], v[214:217], v[100:103]
	v_mfma_f32_16x16x32_bf16 v[92:95], v[170:173], v[214:217], v[92:95]
	v_mfma_f32_16x16x32_bf16 v[84:87], v[146:149], v[226:229], v[84:87]
	v_mfma_f32_16x16x32_bf16 v[76:79], v[170:173], v[226:229], v[76:79]
	v_mfma_f32_16x16x32_bf16 v[124:127], v[166:169], v[202:205], v[124:127]
	v_mfma_f32_16x16x32_bf16 v[120:123], v[178:181], v[202:205], v[120:123]
	v_mfma_f32_16x16x32_bf16 v[112:115], v[166:169], v[210:213], v[112:115]
	v_mfma_f32_16x16x32_bf16 v[104:107], v[178:181], v[210:213], v[104:107]
	v_mfma_f32_16x16x32_bf16 v[100:103], v[166:169], v[218:221], v[100:103]
	v_mfma_f32_16x16x32_bf16 v[92:95], v[178:181], v[218:221], v[92:95]
	v_mfma_f32_16x16x32_bf16 v[84:87], v[166:169], v[230:233], v[84:87]
	v_mfma_f32_16x16x32_bf16 v[76:79], v[178:181], v[230:233], v[76:79]
	v_mfma_f32_16x16x32_bf16 v[116:119], v[182:185], v[198:201], v[116:119]
	v_mfma_f32_16x16x32_bf16 v[108:111], v[190:193], v[198:201], v[108:111]
	v_mfma_f32_16x16x32_bf16 v[96:99], v[182:185], v[206:209], v[96:99]
	v_mfma_f32_16x16x32_bf16 v[88:91], v[190:193], v[206:209], v[88:91]
	v_mfma_f32_16x16x32_bf16 v[80:83], v[182:185], v[214:217], v[80:83]
	v_mfma_f32_16x16x32_bf16 v[72:75], v[190:193], v[214:217], v[72:75]
	v_mfma_f32_16x16x32_bf16 v[68:71], v[182:185], v[226:229], v[68:71]
	v_mfma_f32_16x16x32_bf16 v[64:67], v[190:193], v[226:229], v[64:67]
	v_mfma_f32_16x16x32_bf16 v[116:119], v[186:189], v[202:205], v[116:119]
	v_mfma_f32_16x16x32_bf16 v[108:111], v[194:197], v[202:205], v[108:111]
	v_mfma_f32_16x16x32_bf16 v[96:99], v[186:189], v[210:213], v[96:99]
	v_mfma_f32_16x16x32_bf16 v[88:91], v[194:197], v[210:213], v[88:91]
	v_mfma_f32_16x16x32_bf16 v[80:83], v[186:189], v[218:221], v[80:83]
	v_mfma_f32_16x16x32_bf16 v[72:75], v[194:197], v[218:221], v[72:75]
	v_mfma_f32_16x16x32_bf16 v[68:71], v[186:189], v[230:233], v[68:71]
	v_mfma_f32_16x16x32_bf16 v[64:67], v[194:197], v[230:233], v[64:67]
	s_barrier
; #define PG8_STAGE(bufoff, gbase, voff) do { _Pragma("unroll") for (int _i = 0; _i < 2; ++_i) \
;         __builtin_amdgcn_global_load_lds((const unsigned*)((const char*)(gbase) + (voff)[_i]), (LAS unsigned*)(lds + (bufoff) + ldsw + _i * 8192), 16, 0, 0); } while (0)
; #define PG8_LDA(dst, b, h) do { _Pragma("unroll") for (int m = 0; m < 4; ++m) _Pragma("unroll") for (int k = 0; k < 2; ++k) dst[m][k] = *(const LAS bf16x8*)(lds + PG8_SA(b, h) + aoff + m * 2048 + k * 1024); } while (0)
; #define PG8_MMA(ai, bj, At, Bt) do { __builtin_amdgcn_s_setprio(1); _Pragma("unroll") for (int m = 0; m < 4; ++m) _Pragma("unroll") for (int n = 0; n < 2; ++n) _Pragma("unroll") for (int k = 0; k < 2; ++k) \
;         acc[ai][bj][m][n] = __builtin_amdgcn_mfma_f32_16x16x32_bf16(Bt[n][k], At[m][k], acc[ai][bj][m][n], 0, 0, 0); __builtin_amdgcn_s_setprio(0); } while (0)
; #define PG8_WAIT_V(n) asm volatile("s_waitcnt vmcnt(" #n ")" ::: "memory")
; #define PG8_WAIT_L(n) asm volatile("s_waitcnt lgkmcnt(" #n ")" ::: "memory")
; #define PG8_BAR __builtin_amdgcn_s_barrier()
; #define PG8_SCHED __builtin_amdgcn_sched_barrier(0)
; template <class Epi>
; __device__ __forceinline__ void gemm_phase(LAS unsigned char* lds, const Gemm g, const StaticOrder& S, const Epi& E) {
;     ...
;             PG8_LDA(At, 1, 1); PG8_STAGE(PG8_SB(1, 0), b3, voffB); PG8_STAGE(PG8_SB(1, 1), b3 + hstepB, voffB); PG8_STAGE(PG8_SA(1, 0), a3, voffA);
;             PG8_WAIT_V(8); PG8_WAIT_L(0); PG8_BAR; PG8_MMA(1, 0, At, B0); PG8_MMA(1, 1, At, B1); PG8_BAR; PG8_SCHED;
;         }
;         if (wr == 0) PG8_BAR;
	s_add_i32 s12, s90, s39
	v_lshl_add_u64 v[174:175], v[174:175], 0, s[30:31]
	s_mov_b32 m0, s12
	ds_read_b128 v[198:201], v164 offset:49152
	ds_read_b128 v[202:205], v164 offset:50176
	ds_read_b128 v[206:209], v164 offset:51200
	ds_read_b128 v[210:213], v164 offset:52224
	ds_read_b128 v[214:217], v164 offset:53248
	ds_read_b128 v[218:221], v164 offset:54272
	ds_read_b128 v[226:229], v164 offset:55296
	ds_read_b128 v[230:233], v164 offset:56320
	global_load_lds_dwordx4 v[174:175], off
	s_add_i32 m0, s12, 0x2000
	s_add_u32 s10, s10, 0x40080
	v_lshl_add_u64 v[174:175], v[222:223], 0, s[30:31]
	s_addc_u32 s11, s11, 0
	s_add_i32 s12, s91, s39
	global_load_lds_dwordx4 v[174:175], off
	v_lshl_add_u64 v[174:175], s[10:11], 0, v[130:131]
	s_mov_b32 m0, s12
	s_nop 0
	global_load_lds_dwordx4 v[174:175], off
	v_lshl_add_u64 v[174:175], s[10:11], 0, v[134:135]
	s_add_i32 m0, s12, 0x2000
	s_nop 0
	global_load_lds_dwordx4 v[174:175], off
	v_lshl_add_u64 v[174:175], v[234:235], 0, s[30:31]
	s_mov_b32 m0, s79
	s_nop 0
	global_load_lds_dwordx4 v[174:175], off
	v_lshl_add_u64 v[174:175], v[236:237], 0, s[30:31]
	s_mov_b32 m0, s80
	s_nop 0
	global_load_lds_dwordx4 v[174:175], off
	s_waitcnt vmcnt(8)
	s_waitcnt lgkmcnt(0)
	s_barrier
	s_waitcnt lgkmcnt(0)
	v_mfma_f32_16x16x32_bf16 v[60:63], v[146:149], v[198:201], v[60:63]
	v_mfma_f32_16x16x32_bf16 v[56:59], v[170:173], v[198:201], v[56:59]
	v_mfma_f32_16x16x32_bf16 v[52:55], v[146:149], v[206:209], v[52:55]
	v_mfma_f32_16x16x32_bf16 v[44:47], v[170:173], v[206:209], v[44:47]
	v_mfma_f32_16x16x32_bf16 v[36:39], v[146:149], v[214:217], v[36:39]
	v_mfma_f32_16x16x32_bf16 v[28:31], v[170:173], v[214:217], v[28:31]
	v_mfma_f32_16x16x32_bf16 v[20:23], v[146:149], v[226:229], v[20:23]
	v_mfma_f32_16x16x32_bf16 v[12:15], v[170:173], v[226:229], v[12:15]
	v_mfma_f32_16x16x32_bf16 v[60:63], v[166:169], v[202:205], v[60:63]
	v_mfma_f32_16x16x32_bf16 v[56:59], v[178:181], v[202:205], v[56:59]
	v_mfma_f32_16x16x32_bf16 v[52:55], v[166:169], v[210:213], v[52:55]
	v_mfma_f32_16x16x32_bf16 v[44:47], v[178:181], v[210:213], v[44:47]
	v_mfma_f32_16x16x32_bf16 v[36:39], v[166:169], v[218:221], v[36:39]
	v_mfma_f32_16x16x32_bf16 v[28:31], v[178:181], v[218:221], v[28:31]
	v_mfma_f32_16x16x32_bf16 v[20:23], v[166:169], v[230:233], v[20:23]
	v_mfma_f32_16x16x32_bf16 v[12:15], v[178:181], v[230:233], v[12:15]
	v_mfma_f32_16x16x32_bf16 v[48:51], v[182:185], v[198:201], v[48:51]
	v_mfma_f32_16x16x32_bf16 v[40:43], v[190:193], v[198:201], v[40:43]
	v_mfma_f32_16x16x32_bf16 v[32:35], v[182:185], v[206:209], v[32:35]
	v_mfma_f32_16x16x32_bf16 v[24:27], v[190:193], v[206:209], v[24:27]
	v_mfma_f32_16x16x32_bf16 v[16:19], v[182:185], v[214:217], v[16:19]
	v_mfma_f32_16x16x32_bf16 v[8:11], v[190:193], v[214:217], v[8:11]
	v_mfma_f32_16x16x32_bf16 v[4:7], v[182:185], v[226:229], v[4:7]
	v_mfma_f32_16x16x32_bf16 v[0:3], v[190:193], v[226:229], v[0:3]
	v_mfma_f32_16x16x32_bf16 v[48:51], v[186:189], v[202:205], v[48:51]
	v_mfma_f32_16x16x32_bf16 v[40:43], v[194:197], v[202:205], v[40:43]
	v_mfma_f32_16x16x32_bf16 v[32:35], v[186:189], v[210:213], v[32:35]
	v_mfma_f32_16x16x32_bf16 v[24:27], v[194:197], v[210:213], v[24:27]
	v_mfma_f32_16x16x32_bf16 v[16:19], v[186:189], v[218:221], v[16:19]
	v_mfma_f32_16x16x32_bf16 v[8:11], v[194:197], v[218:221], v[8:11]
	v_mfma_f32_16x16x32_bf16 v[4:7], v[186:189], v[230:233], v[4:7]
	v_mfma_f32_16x16x32_bf16 v[0:3], v[194:197], v[230:233], v[0:3]
	s_barrier
	s_add_i32 s89, s89, 2
	s_add_u32 s8, s8, 0x100
	s_addc_u32 s9, s9, 0
	s_add_u32 s76, s76, 0x100
	s_addc_u32 s77, s77, 0
	s_cmp_gt_u32 s89, 13
	s_cbranch_scc0 .LBB0_546
	s_and_b64 vcc, exec, s[34:35]
	s_cbranch_vccz .LBB0_549
	s_barrier

; #define PG8_STAGE(bufoff, gbase, voff) do { _Pragma("unroll") for (int _i = 0; _i < 2; ++_i) \
;         __builtin_amdgcn_global_load_lds((const unsigned*)((const char*)(gbase) + (voff)[_i]), (LAS unsigned*)(lds + (bufoff) + ldsw + _i * 8192), 16, 0, 0); } while (0)
; #define PG8_LDA(dst, b, h) do { _Pragma("unroll") for (int m = 0; m < 4; ++m) _Pragma("unroll") for (int k = 0; k < 2; ++k) dst[m][k] = *(const LAS bf16x8*)(lds + PG8_SA(b, h) + aoff + m * 2048 + k * 1024); } while (0)
; #define PG8_LDB(dst, b, h) do { _Pragma("unroll") for (int n = 0; n < 2; ++n) _Pragma("unroll") for (int k = 0; k < 2; ++k) dst[n][k] = *(const LAS bf16x8*)(lds + PG8_SB(b, h) + boff + n * 2048 + k * 1024); } while (0)
; #define PG8_MMA(ai, bj, At, Bt) do { __builtin_amdgcn_s_setprio(1); _Pragma("unroll") for (int m = 0; m < 4; ++m) _Pragma("unroll") for (int n = 0; n < 2; ++n) _Pragma("unroll") for (int k = 0; k < 2; ++k) \
;         acc[ai][bj][m][n] = __builtin_amdgcn_mfma_f32_16x16x32_bf16(Bt[n][k], At[m][k], acc[ai][bj][m][n], 0, 0, 0); __builtin_amdgcn_s_setprio(0); } while (0)
; #define PG8_WAIT_V(n) asm volatile("s_waitcnt vmcnt(" #n ")" ::: "memory")
; #define PG8_WAIT_L(n) asm volatile("s_waitcnt lgkmcnt(" #n ")" ::: "memory")
; #define PG8_BAR __builtin_amdgcn_s_barrier()
; #define PG8_SCHED __builtin_amdgcn_sched_barrier(0)
; template <class Epi>
; __device__ __forceinline__ void gemm_phase(LAS unsigned char* lds, const Gemm g, const StaticOrder& S, const Epi& E) {
;     ...
;             const bool last = (t == nt - 2);
;             const char* a1 = cA + (size_t)(t + 1) * kstep;
;             const char* a2 = last ? nA : cA + (size_t)(t + 2) * kstep; const char* b2 = last ? nB : cB + (size_t)(t + 2) * kstep;
;             const char* a3 = a2 + kstep; const char* b3 = b2 + kstep;
;             PG8_LDB(B0, 0, 0); PG8_LDB(B1, 0, 1); PG8_SCHED; PG8_LDA(At, 0, 0); PG8_STAGE(PG8_SA(1, 1), a1 + hstepA, voffA);
;             PG8_WAIT_V(8); PG8_WAIT_L(0); PG8_BAR; PG8_MMA(0, 0, At, B0); PG8_MMA(0, 1, At, B1); PG8_BAR; PG8_SCHED;
;             PG8_LDA(At, 0, 1); PG8_STAGE(PG8_SB(0, 0), b2, voffB); PG8_STAGE(PG8_SB(0, 1), b2 + hstepB, voffB); PG8_STAGE(PG8_SA(0, 0), a2, voffA);
.LBB0_612:
	s_add_u32 s68, s42, s56
	s_addc_u32 s69, s43, s57
	s_add_u32 s64, s68, 0x100
	s_addc_u32 s65, s69, 0
	s_and_b64 s[62:63], s[54:55], exec
	s_cselect_b32 s63, s1, s65
	s_cselect_b32 s62, s19, s64
	s_add_u32 s56, s38, s56
	s_addc_u32 s57, s39, s57
	s_add_u32 s56, s56, 0x100
	s_addc_u32 s57, s57, 0
	s_and_b64 s[54:55], s[54:55], exec
	s_cselect_b32 s65, s13, s57
	s_cselect_b32 s64, s88, s56
	s_add_u32 s70, s68, 0x10080
	ds_read_b128 v[140:143], v145
	ds_read_b128 v[154:157], v145 offset:1024
	ds_read_b128 v[158:161], v145 offset:2048
	ds_read_b128 v[162:165], v145 offset:3072
	ds_read_b128 v[166:169], v146
	ds_read_b128 v[170:173], v146 offset:1024
	ds_read_b128 v[178:181], v146 offset:2048
	ds_read_b128 v[182:185], v146 offset:3072
	s_addc_u32 s71, s69, 0
	s_add_i32 vcc_lo, s86, s72
	s_add_i32 m0, s35, 0xc000
	s_add_i32 vcc_hi, s35, 0xe000
	s_add_i32 s95, vcc_lo, 0x2000
	s_add_u32 s68, s64, 0x10000
	s_addc_u32 s69, s65, 0
	s_add_i32 s97, s87, s72
	s_add_i32 s96, s97, 0x2000
	s_add_i32 s94, 0, 0x18000
	s_add_i32 s93, 0, 0x1c000
	s_add_u32 s56, s62, 0x10000
	s_addc_u32 s57, s63, 0
	s_add_i32 s92, s94, s72
	s_add_i32 s90, s92, 0x2000
	s_add_u32 s54, s64, 0x10080
	s_addc_u32 s55, s65, 0
	s_add_i32 s91, s93, s72
	s_add_i32 s89, s91, 0x2000
	v_lshl_add_u64 v[174:175], s[70:71], 0, v[128:129]
	ds_read_b128 v[186:189], v147
	ds_read_b128 v[190:193], v147 offset:1024
	ds_read_b128 v[194:197], v147 offset:2048
	ds_read_b128 v[198:201], v147 offset:3072
	ds_read_b128 v[202:205], v147 offset:4096
	ds_read_b128 v[206:209], v147 offset:5120
	ds_read_b128 v[210:213], v147 offset:6144
	ds_read_b128 v[214:217], v147 offset:7168
	global_load_lds_dwordx4 v[174:175], off
	v_lshl_add_u64 v[174:175], s[70:71], 0, v[132:133]
	s_mov_b32 m0, vcc_hi
	s_nop 0
	global_load_lds_dwordx4 v[174:175], off
	s_waitcnt vmcnt(8)
	s_waitcnt lgkmcnt(0)
	s_barrier
	s_waitcnt lgkmcnt(0)
	v_mfma_f32_16x16x32_bf16 v[124:127], v[140:143], v[186:189], v[124:127]
	v_mfma_f32_16x16x32_bf16 v[120:123], v[158:161], v[186:189], v[120:123]
	v_mfma_f32_16x16x32_bf16 v[108:111], v[140:143], v[194:197], v[108:111]
	v_mfma_f32_16x16x32_bf16 v[104:107], v[158:161], v[194:197], v[104:107]
	v_mfma_f32_16x16x32_bf16 v[92:95], v[140:143], v[202:205], v[92:95]
	v_mfma_f32_16x16x32_bf16 v[88:91], v[158:161], v[202:205], v[88:91]
	v_mfma_f32_16x16x32_bf16 v[76:79], v[140:143], v[210:213], v[76:79]
	v_mfma_f32_16x16x32_bf16 v[72:75], v[158:161], v[210:213], v[72:75]
	v_mfma_f32_16x16x32_bf16 v[124:127], v[154:157], v[190:193], v[124:127]
	v_mfma_f32_16x16x32_bf16 v[120:123], v[162:165], v[190:193], v[120:123]
	v_mfma_f32_16x16x32_bf16 v[108:111], v[154:157], v[198:201], v[108:111]
	v_mfma_f32_16x16x32_bf16 v[104:107], v[162:165], v[198:201], v[104:107]
	v_mfma_f32_16x16x32_bf16 v[92:95], v[154:157], v[206:209], v[92:95]
	v_mfma_f32_16x16x32_bf16 v[88:91], v[162:165], v[206:209], v[88:91]
	v_mfma_f32_16x16x32_bf16 v[76:79], v[154:157], v[214:217], v[76:79]
	v_mfma_f32_16x16x32_bf16 v[72:75], v[162:165], v[214:217], v[72:75]
	v_mfma_f32_16x16x32_bf16 v[116:119], v[166:169], v[186:189], v[116:119]
	v_mfma_f32_16x16x32_bf16 v[112:115], v[178:181], v[186:189], v[112:115]
	v_mfma_f32_16x16x32_bf16 v[100:103], v[166:169], v[194:197], v[100:103]
	v_mfma_f32_16x16x32_bf16 v[96:99], v[178:181], v[194:197], v[96:99]
	v_mfma_f32_16x16x32_bf16 v[84:87], v[166:169], v[202:205], v[84:87]
	v_mfma_f32_16x16x32_bf16 v[80:83], v[178:181], v[202:205], v[80:83]
	v_mfma_f32_16x16x32_bf16 v[68:71], v[166:169], v[210:213], v[68:71]
	v_mfma_f32_16x16x32_bf16 v[64:67], v[178:181], v[210:213], v[64:67]
	v_mfma_f32_16x16x32_bf16 v[116:119], v[170:173], v[190:193], v[116:119]
	v_mfma_f32_16x16x32_bf16 v[112:115], v[182:185], v[190:193], v[112:115]
	v_mfma_f32_16x16x32_bf16 v[100:103], v[170:173], v[198:201], v[100:103]
	v_mfma_f32_16x16x32_bf16 v[96:99], v[182:185], v[198:201], v[96:99]
	v_mfma_f32_16x16x32_bf16 v[84:87], v[170:173], v[206:209], v[84:87]
	v_mfma_f32_16x16x32_bf16 v[80:83], v[182:185], v[206:209], v[80:83]
	v_mfma_f32_16x16x32_bf16 v[68:71], v[170:173], v[214:217], v[68:71]
	v_mfma_f32_16x16x32_bf16 v[64:67], v[182:185], v[214:217], v[64:67]
	s_barrier
	s_mov_b32 m0, vcc_lo
	v_lshl_add_u64 v[174:175], s[64:65], 0, v[130:131]
	ds_read_b128 v[186:189], v147 offset:16384
	ds_read_b128 v[190:193], v147 offset:17408
	ds_read_b128 v[194:197], v147 offset:18432
	ds_read_b128 v[198:201], v147 offset:19456
	ds_read_b128 v[202:205], v147 offset:20480
	ds_read_b128 v[206:209], v147 offset:21504
	ds_read_b128 v[210:213], v147 offset:22528
	ds_read_b128 v[214:217], v147 offset:23552
	global_load_lds_dwordx4 v[174:175], off
	v_lshl_add_u64 v[218:219], s[64:65], 0, v[134:135]
	s_mov_b32 m0, s95
	v_lshl_add_u64 v[220:221], s[68:69], 0, v[130:131]
	global_load_lds_dwordx4 v[218:219], off
	s_mov_b32 m0, s97
	v_lshl_add_u64 v[222:223], s[62:63], 0, v[132:133]
	global_load_lds_dwordx4 v[220:221], off
	v_lshl_add_u64 v[220:221], s[68:69], 0, v[134:135]
	s_mov_b32 m0, s96
	s_nop 0
	global_load_lds_dwordx4 v[220:221], off
	v_lshl_add_u64 v[220:221], s[62:63], 0, v[128:129]
	s_mov_b32 m0, s35
	s_nop 0
	global_load_lds_dwordx4 v[220:221], off
	s_mov_b32 m0, s75
	s_nop 0
	global_load_lds_dwordx4 v[222:223], off
	s_waitcnt vmcnt(8)
	s_waitcnt lgkmcnt(0)
	s_barrier
; #define PG8_STAGE(bufoff, gbase, voff) do { _Pragma("unroll") for (int _i = 0; _i < 2; ++_i) \
;         __builtin_amdgcn_global_load_lds((const unsigned*)((const char*)(gbase) + (voff)[_i]), (LAS unsigned*)(lds + (bufoff) + ldsw + _i * 8192), 16, 0, 0); } while (0)
; #define PG8_LDA(dst, b, h) do { _Pragma("unroll") for (int m = 0; m < 4; ++m) _Pragma("unroll") for (int k = 0; k < 2; ++k) dst[m][k] = *(const LAS bf16x8*)(lds + PG8_SA(b, h) + aoff + m * 2048 + k * 1024); } while (0)
; #define PG8_LDB(dst, b, h) do { _Pragma("unroll") for (int n = 0; n < 2; ++n) _Pragma("unroll") for (int k = 0; k < 2; ++k) dst[n][k] = *(const LAS bf16x8*)(lds + PG8_SB(b, h) + boff + n * 2048 + k * 1024); } while (0)
; #define PG8_MMA(ai, bj, At, Bt) do { __builtin_amdgcn_s_setprio(1); _Pragma("unroll") for (int m = 0; m < 4; ++m) _Pragma("unroll") for (int n = 0; n < 2; ++n) _Pragma("unroll") for (int k = 0; k < 2; ++k) \
;         acc[ai][bj][m][n] = __builtin_amdgcn_mfma_f32_16x16x32_bf16(Bt[n][k], At[m][k], acc[ai][bj][m][n], 0, 0, 0); __builtin_amdgcn_s_setprio(0); } while (0)
; #define PG8_WAIT_V(n) asm volatile("s_waitcnt vmcnt(" #n ")" ::: "memory")
; #define PG8_WAIT_L(n) asm volatile("s_waitcnt lgkmcnt(" #n ")" ::: "memory")
; #define PG8_BAR __builtin_amdgcn_s_barrier()
; #define PG8_SCHED __builtin_amdgcn_sched_barrier(0)
; template <class Epi>
; __device__ __forceinline__ void gemm_phase(LAS unsigned char* lds, const Gemm g, const StaticOrder& S, const Epi& E) {
;     ...
;             PG8_WAIT_V(8); PG8_WAIT_L(0); PG8_BAR; PG8_MMA(1, 0, At, B0); PG8_MMA(1, 1, At, B1); PG8_BAR; PG8_SCHED;
;             PG8_LDB(B0, 1, 0); PG8_LDB(B1, 1, 1); PG8_SCHED; PG8_LDA(At, 1, 0); PG8_STAGE(PG8_SA(0, 1), a2 + hstepA, voffA);
;             PG8_WAIT_V(8); PG8_WAIT_L(0); PG8_BAR; PG8_MMA(0, 0, At, B0); PG8_MMA(0, 1, At, B1); PG8_BAR; PG8_SCHED;
	s_waitcnt lgkmcnt(0)
	v_mfma_f32_16x16x32_bf16 v[60:63], v[140:143], v[186:189], v[60:63]
	v_mfma_f32_16x16x32_bf16 v[56:59], v[158:161], v[186:189], v[56:59]
	v_mfma_f32_16x16x32_bf16 v[44:47], v[140:143], v[194:197], v[44:47]
	v_mfma_f32_16x16x32_bf16 v[40:43], v[158:161], v[194:197], v[40:43]
	v_mfma_f32_16x16x32_bf16 v[28:31], v[140:143], v[202:205], v[28:31]
	v_mfma_f32_16x16x32_bf16 v[24:27], v[158:161], v[202:205], v[24:27]
	v_mfma_f32_16x16x32_bf16 v[12:15], v[140:143], v[210:213], v[12:15]
	v_mfma_f32_16x16x32_bf16 v[8:11], v[158:161], v[210:213], v[8:11]
	v_mfma_f32_16x16x32_bf16 v[60:63], v[154:157], v[190:193], v[60:63]
	v_mfma_f32_16x16x32_bf16 v[56:59], v[162:165], v[190:193], v[56:59]
	v_mfma_f32_16x16x32_bf16 v[44:47], v[154:157], v[198:201], v[44:47]
	v_mfma_f32_16x16x32_bf16 v[40:43], v[162:165], v[198:201], v[40:43]
	v_mfma_f32_16x16x32_bf16 v[28:31], v[154:157], v[206:209], v[28:31]
	v_mfma_f32_16x16x32_bf16 v[24:27], v[162:165], v[206:209], v[24:27]
	v_mfma_f32_16x16x32_bf16 v[12:15], v[154:157], v[214:217], v[12:15]
	v_mfma_f32_16x16x32_bf16 v[8:11], v[162:165], v[214:217], v[8:11]
	v_mfma_f32_16x16x32_bf16 v[52:55], v[166:169], v[186:189], v[52:55]
	v_mfma_f32_16x16x32_bf16 v[48:51], v[178:181], v[186:189], v[48:51]
	v_mfma_f32_16x16x32_bf16 v[36:39], v[166:169], v[194:197], v[36:39]
	v_mfma_f32_16x16x32_bf16 v[32:35], v[178:181], v[194:197], v[32:35]
	v_mfma_f32_16x16x32_bf16 v[20:23], v[166:169], v[202:205], v[20:23]
	v_mfma_f32_16x16x32_bf16 v[16:19], v[178:181], v[202:205], v[16:19]
	v_mfma_f32_16x16x32_bf16 v[4:7], v[166:169], v[210:213], v[4:7]
	v_mfma_f32_16x16x32_bf16 v[0:3], v[178:181], v[210:213], v[0:3]
	v_mfma_f32_16x16x32_bf16 v[52:55], v[170:173], v[190:193], v[52:55]
	v_mfma_f32_16x16x32_bf16 v[48:51], v[182:185], v[190:193], v[48:51]
	v_mfma_f32_16x16x32_bf16 v[36:39], v[170:173], v[198:201], v[36:39]
	v_mfma_f32_16x16x32_bf16 v[32:35], v[182:185], v[198:201], v[32:35]
	v_mfma_f32_16x16x32_bf16 v[20:23], v[170:173], v[206:209], v[20:23]
	v_mfma_f32_16x16x32_bf16 v[16:19], v[182:185], v[206:209], v[16:19]
	v_mfma_f32_16x16x32_bf16 v[4:7], v[170:173], v[214:217], v[4:7]
	v_mfma_f32_16x16x32_bf16 v[0:3], v[182:185], v[214:217], v[0:3]
	s_barrier
	v_add_u32_e32 v149, s94, v144
	ds_read_b128 v[140:143], v149
	ds_read_b128 v[154:157], v149 offset:1024
	ds_read_b128 v[158:161], v149 offset:2048
	ds_read_b128 v[162:165], v149 offset:3072
	v_add_u32_e32 v149, s93, v144
	ds_read_b128 v[166:169], v149
	ds_read_b128 v[170:173], v149 offset:1024
	ds_read_b128 v[178:181], v149 offset:2048
	ds_read_b128 v[182:185], v149 offset:3072
	s_mov_b32 m0, s76
	v_lshl_add_u64 v[226:227], s[56:57], 0, v[128:129]
	ds_read_b128 v[186:189], v147 offset:32768
	ds_read_b128 v[190:193], v147 offset:33792
	ds_read_b128 v[194:197], v147 offset:34816
	ds_read_b128 v[198:201], v147 offset:35840
	ds_read_b128 v[202:205], v147 offset:36864
	ds_read_b128 v[206:209], v147 offset:37888
	ds_read_b128 v[210:213], v147 offset:38912
	ds_read_b128 v[214:217], v147 offset:39936
	global_load_lds_dwordx4 v[226:227], off
	v_lshl_add_u64 v[226:227], s[56:57], 0, v[132:133]
	s_mov_b32 m0, s77
	s_nop 0
	global_load_lds_dwordx4 v[226:227], off
	s_waitcnt vmcnt(8)
	s_waitcnt lgkmcnt(0)
	s_barrier
	s_waitcnt lgkmcnt(0)
	v_mfma_f32_16x16x32_bf16 v[124:127], v[140:143], v[186:189], v[124:127]
	v_mfma_f32_16x16x32_bf16 v[120:123], v[158:161], v[186:189], v[120:123]
	v_mfma_f32_16x16x32_bf16 v[108:111], v[140:143], v[194:197], v[108:111]
	v_mfma_f32_16x16x32_bf16 v[104:107], v[158:161], v[194:197], v[104:107]
	v_mfma_f32_16x16x32_bf16 v[92:95], v[140:143], v[202:205], v[92:95]
	v_mfma_f32_16x16x32_bf16 v[88:91], v[158:161], v[202:205], v[88:91]
	v_mfma_f32_16x16x32_bf16 v[76:79], v[140:143], v[210:213], v[76:79]
	v_mfma_f32_16x16x32_bf16 v[72:75], v[158:161], v[210:213], v[72:75]
	v_mfma_f32_16x16x32_bf16 v[124:127], v[154:157], v[190:193], v[124:127]
	v_mfma_f32_16x16x32_bf16 v[120:123], v[162:165], v[190:193], v[120:123]
	v_mfma_f32_16x16x32_bf16 v[108:111], v[154:157], v[198:201], v[108:111]
	v_mfma_f32_16x16x32_bf16 v[104:107], v[162:165], v[198:201], v[104:107]
	v_mfma_f32_16x16x32_bf16 v[92:95], v[154:157], v[206:209], v[92:95]
	v_mfma_f32_16x16x32_bf16 v[88:91], v[162:165], v[206:209], v[88:91]
	v_mfma_f32_16x16x32_bf16 v[76:79], v[154:157], v[214:217], v[76:79]
	v_mfma_f32_16x16x32_bf16 v[72:75], v[162:165], v[214:217], v[72:75]
	v_mfma_f32_16x16x32_bf16 v[116:119], v[166:169], v[186:189], v[116:119]
	v_mfma_f32_16x16x32_bf16 v[112:115], v[178:181], v[186:189], v[112:115]
	v_mfma_f32_16x16x32_bf16 v[100:103], v[166:169], v[194:197], v[100:103]
	v_mfma_f32_16x16x32_bf16 v[96:99], v[178:181], v[194:197], v[96:99]
	v_mfma_f32_16x16x32_bf16 v[84:87], v[166:169], v[202:205], v[84:87]
	v_mfma_f32_16x16x32_bf16 v[80:83], v[178:181], v[202:205], v[80:83]
	v_mfma_f32_16x16x32_bf16 v[68:71], v[166:169], v[210:213], v[68:71]
	v_mfma_f32_16x16x32_bf16 v[64:67], v[178:181], v[210:213], v[64:67]
	v_mfma_f32_16x16x32_bf16 v[116:119], v[170:173], v[190:193], v[116:119]
	v_mfma_f32_16x16x32_bf16 v[112:115], v[182:185], v[190:193], v[112:115]
	v_mfma_f32_16x16x32_bf16 v[100:103], v[170:173], v[198:201], v[100:103]
	v_mfma_f32_16x16x32_bf16 v[96:99], v[182:185], v[198:201], v[96:99]
	v_mfma_f32_16x16x32_bf16 v[84:87], v[170:173], v[206:209], v[84:87]
	v_mfma_f32_16x16x32_bf16 v[80:83], v[182:185], v[206:209], v[80:83]
	v_mfma_f32_16x16x32_bf16 v[68:71], v[170:173], v[214:217], v[68:71]
	v_mfma_f32_16x16x32_bf16 v[64:67], v[182:185], v[214:217], v[64:67]
	s_barrier
; #define PG8_STAGE(bufoff, gbase, voff) do { _Pragma("unroll") for (int _i = 0; _i < 2; ++_i) \
;         __builtin_amdgcn_global_load_lds((const unsigned*)((const char*)(gbase) + (voff)[_i]), (LAS unsigned*)(lds + (bufoff) + ldsw + _i * 8192), 16, 0, 0); } while (0)
; #define PG8_LDA(dst, b, h) do { _Pragma("unroll") for (int m = 0; m < 4; ++m) _Pragma("unroll") for (int k = 0; k < 2; ++k) dst[m][k] = *(const LAS bf16x8*)(lds + PG8_SA(b, h) + aoff + m * 2048 + k * 1024); } while (0)
; #define PG8_MMA(ai, bj, At, Bt) do { __builtin_amdgcn_s_setprio(1); _Pragma("unroll") for (int m = 0; m < 4; ++m) _Pragma("unroll") for (int n = 0; n < 2; ++n) _Pragma("unroll") for (int k = 0; k < 2; ++k) \
;         acc[ai][bj][m][n] = __builtin_amdgcn_mfma_f32_16x16x32_bf16(Bt[n][k], At[m][k], acc[ai][bj][m][n], 0, 0, 0); __builtin_amdgcn_s_setprio(0); } while (0)
; #define PG8_WAIT_V(n) asm volatile("s_waitcnt vmcnt(" #n ")" ::: "memory")
; #define PG8_WAIT_L(n) asm volatile("s_waitcnt lgkmcnt(" #n ")" ::: "memory")
; #define PG8_BAR __builtin_amdgcn_s_barrier()
; #define PG8_SCHED __builtin_amdgcn_sched_barrier(0)
; template <class Epi>
; __device__ __forceinline__ void gemm_phase(LAS unsigned char* lds, const Gemm g, const StaticOrder& S, const Epi& E) {
;     ...
;             PG8_LDA(At, 1, 1); PG8_STAGE(PG8_SB(1, 0), b3, voffB); PG8_STAGE(PG8_SB(1, 1), b3 + hstepB, voffB); PG8_STAGE(PG8_SA(1, 0), a3, voffA);
;             PG8_WAIT_V(8); PG8_WAIT_L(0); PG8_BAR; PG8_MMA(1, 0, At, B0); PG8_MMA(1, 1, At, B1); PG8_BAR; PG8_SCHED;
;         }
;         if (wr == 0) PG8_BAR;
	s_mov_b32 m0, s92
	v_lshl_add_u64 v[174:175], v[174:175], 0, s[8:9]
	ds_read_b128 v[186:189], v147 offset:49152
	ds_read_b128 v[190:193], v147 offset:50176
	ds_read_b128 v[194:197], v147 offset:51200
	ds_read_b128 v[198:201], v147 offset:52224
	ds_read_b128 v[202:205], v147 offset:53248
	ds_read_b128 v[206:209], v147 offset:54272
	ds_read_b128 v[210:213], v147 offset:55296
	ds_read_b128 v[214:217], v147 offset:56320
	global_load_lds_dwordx4 v[174:175], off
	v_lshl_add_u64 v[174:175], v[218:219], 0, s[8:9]
	s_mov_b32 m0, s90
	s_nop 0
	global_load_lds_dwordx4 v[174:175], off
	v_lshl_add_u64 v[174:175], s[54:55], 0, v[130:131]
	s_mov_b32 m0, s91
	s_nop 0
	global_load_lds_dwordx4 v[174:175], off
	v_lshl_add_u64 v[174:175], s[54:55], 0, v[134:135]
	s_mov_b32 m0, s89
	s_nop 0
	global_load_lds_dwordx4 v[174:175], off
	v_lshl_add_u64 v[174:175], v[220:221], 0, s[8:9]
	s_mov_b32 m0, s81
	s_nop 0
	global_load_lds_dwordx4 v[174:175], off
	v_lshl_add_u64 v[174:175], v[222:223], 0, s[8:9]
	s_mov_b32 m0, s82
	s_nop 0
	global_load_lds_dwordx4 v[174:175], off
	s_waitcnt vmcnt(8)
	s_waitcnt lgkmcnt(0)
	s_barrier
	s_waitcnt lgkmcnt(0)
	v_mfma_f32_16x16x32_bf16 v[60:63], v[140:143], v[186:189], v[60:63]
	v_mfma_f32_16x16x32_bf16 v[56:59], v[158:161], v[186:189], v[56:59]
	v_mfma_f32_16x16x32_bf16 v[44:47], v[140:143], v[194:197], v[44:47]
	v_mfma_f32_16x16x32_bf16 v[40:43], v[158:161], v[194:197], v[40:43]
	v_mfma_f32_16x16x32_bf16 v[28:31], v[140:143], v[202:205], v[28:31]
	v_mfma_f32_16x16x32_bf16 v[24:27], v[158:161], v[202:205], v[24:27]
	v_mfma_f32_16x16x32_bf16 v[12:15], v[140:143], v[210:213], v[12:15]
	v_mfma_f32_16x16x32_bf16 v[8:11], v[158:161], v[210:213], v[8:11]
	v_mfma_f32_16x16x32_bf16 v[60:63], v[154:157], v[190:193], v[60:63]
	v_mfma_f32_16x16x32_bf16 v[56:59], v[162:165], v[190:193], v[56:59]
	v_mfma_f32_16x16x32_bf16 v[44:47], v[154:157], v[198:201], v[44:47]
	v_mfma_f32_16x16x32_bf16 v[40:43], v[162:165], v[198:201], v[40:43]
	v_mfma_f32_16x16x32_bf16 v[28:31], v[154:157], v[206:209], v[28:31]
	v_mfma_f32_16x16x32_bf16 v[24:27], v[162:165], v[206:209], v[24:27]
	v_mfma_f32_16x16x32_bf16 v[12:15], v[154:157], v[214:217], v[12:15]
	v_mfma_f32_16x16x32_bf16 v[8:11], v[162:165], v[214:217], v[8:11]
	v_mfma_f32_16x16x32_bf16 v[52:55], v[166:169], v[186:189], v[52:55]
	v_mfma_f32_16x16x32_bf16 v[48:51], v[178:181], v[186:189], v[48:51]
	v_mfma_f32_16x16x32_bf16 v[36:39], v[166:169], v[194:197], v[36:39]
	v_mfma_f32_16x16x32_bf16 v[32:35], v[178:181], v[194:197], v[32:35]
	v_mfma_f32_16x16x32_bf16 v[20:23], v[166:169], v[202:205], v[20:23]
	v_mfma_f32_16x16x32_bf16 v[16:19], v[178:181], v[202:205], v[16:19]
	v_mfma_f32_16x16x32_bf16 v[4:7], v[166:169], v[210:213], v[4:7]
	v_mfma_f32_16x16x32_bf16 v[0:3], v[178:181], v[210:213], v[0:3]
	v_mfma_f32_16x16x32_bf16 v[52:55], v[170:173], v[190:193], v[52:55]
	v_mfma_f32_16x16x32_bf16 v[48:51], v[182:185], v[190:193], v[48:51]
	v_mfma_f32_16x16x32_bf16 v[36:39], v[170:173], v[198:201], v[36:39]
	v_mfma_f32_16x16x32_bf16 v[32:35], v[182:185], v[198:201], v[32:35]
	v_mfma_f32_16x16x32_bf16 v[20:23], v[170:173], v[206:209], v[20:23]
	v_mfma_f32_16x16x32_bf16 v[16:19], v[182:185], v[206:209], v[16:19]
	v_mfma_f32_16x16x32_bf16 v[4:7], v[170:173], v[214:217], v[4:7]
	v_mfma_f32_16x16x32_bf16 v[0:3], v[182:185], v[214:217], v[0:3]
	s_barrier
	s_andn2_b64 vcc, exec, s[52:53]
	s_mov_b64 s[54:55], -1
	s_mov_b64 s[52:53], 0
	s_mov_b64 s[56:57], 0x100
	s_cbranch_vccz .LBB0_612
	s_and_b64 vcc, exec, s[10:11]
	s_cbranch_vccz .LBB0_615
	s_barrier

; #define PG8_STAGE(bufoff, gbase, voff) do { _Pragma("unroll") for (int _i = 0; _i < 2; ++_i) \
;         __builtin_amdgcn_global_load_lds((const unsigned*)((const char*)(gbase) + (voff)[_i]), (LAS unsigned*)(lds + (bufoff) + ldsw + _i * 8192), 16, 0, 0); } while (0)
; #define PG8_LDA(dst, b, h) do { _Pragma("unroll") for (int m = 0; m < 4; ++m) _Pragma("unroll") for (int k = 0; k < 2; ++k) dst[m][k] = *(const LAS bf16x8*)(lds + PG8_SA(b, h) + aoff + m * 2048 + k * 1024); } while (0)
; #define PG8_LDB(dst, b, h) do { _Pragma("unroll") for (int n = 0; n < 2; ++n) _Pragma("unroll") for (int k = 0; k < 2; ++k) dst[n][k] = *(const LAS bf16x8*)(lds + PG8_SB(b, h) + boff + n * 2048 + k * 1024); } while (0)
; #define PG8_MMA(ai, bj, At, Bt) do { __builtin_amdgcn_s_setprio(1); _Pragma("unroll") for (int m = 0; m < 4; ++m) _Pragma("unroll") for (int n = 0; n < 2; ++n) _Pragma("unroll") for (int k = 0; k < 2; ++k) \
;         acc[ai][bj][m][n] = __builtin_amdgcn_mfma_f32_16x16x32_bf16(Bt[n][k], At[m][k], acc[ai][bj][m][n], 0, 0, 0); __builtin_amdgcn_s_setprio(0); } while (0)
; #define PG8_WAIT_V(n) asm volatile("s_waitcnt vmcnt(" #n ")" ::: "memory")
; #define PG8_WAIT_L(n) asm volatile("s_waitcnt lgkmcnt(" #n ")" ::: "memory")
; template <class Epi>
; __device__ __forceinline__ void gemm_phase(LAS unsigned char* lds, const Gemm g, const StaticOrder& S, const Epi& E) {
;     ...
;         const bool has_next = S.next(ui + 1, nxt);
;         const char* nA = has_next ? (const char*)g.A + (size_t)nxt.pm * tstepA : cA; const char* nB = has_next ? (const char*)g.Bt + (size_t)nxt.pn * tstepB : cB;
; #pragma nounroll
;         for (int t = 0; t < nt; t += 2) {
;             const bool last = (t == nt - 2);
;             const char* a1 = cA + (size_t)(t + 1) * kstep;
;             const char* a2 = last ? nA : cA + (size_t)(t + 2) * kstep; const char* b2 = last ? nB : cB + (size_t)(t + 2) * kstep;
;             const char* a3 = a2 + kstep; const char* b3 = b2 + kstep;
;             PG8_LDB(B0, 0, 0); PG8_LDB(B1, 0, 1); PG8_SCHED; PG8_LDA(At, 0, 0); PG8_STAGE(PG8_SA(1, 1), a1 + hstepA, voffA);
;             PG8_WAIT_V(8); PG8_WAIT_L(0); PG8_BAR; PG8_MMA(0, 0, At, B0); PG8_MMA(0, 1, At, B1); PG8_BAR; PG8_SCHED;
;             PG8_LDA(At, 0, 1); PG8_STAGE(PG8_SB(0, 0), b2, voffB); PG8_STAGE(PG8_SB(0, 1), b2 + hstepB, voffB); PG8_STAGE(PG8_SA(0, 0), a2, voffA);
.LBB0_791:
	s_add_u32 s0, s0, 0xb0080
	s_addc_u32 s1, s1, 0
	s_add_u32 s75, s34, 0x100
	s_addc_u32 s76, s35, 0
	s_mov_b32 s77, -2
	s_waitcnt lgkmcnt(0)
	s_nop 0
	ds_read_b128 v[128:131], v182
	ds_read_b128 v[132:135], v182 offset:1024
	ds_read_b128 v[136:139], v182 offset:2048
	ds_read_b128 v[140:143], v182 offset:3072
	ds_read_b128 v[160:163], v183
	ds_read_b128 v[164:167], v183 offset:1024
	ds_read_b128 v[168:171], v183 offset:2048
	ds_read_b128 v[172:175], v183 offset:3072
	s_add_u32 s34, s0, 0xfff50080
	s_addc_u32 s35, s1, -1
	s_cmp_eq_u32 s77, 40
	s_cselect_b32 s39, s7, s35
	s_cselect_b32 s38, s6, s34
	s_cselect_b32 s35, s23, s76
	s_cselect_b32 s34, s22, s75
	v_lshl_add_u64 v[178:179], s[0:1], 0, v[152:153]
	s_add_i32 m0, s43, 0xc000
	ds_read_b128 v[186:189], v184
	ds_read_b128 v[190:193], v184 offset:1024
	ds_read_b128 v[194:197], v184 offset:2048
	ds_read_b128 v[198:201], v184 offset:3072
	ds_read_b128 v[202:205], v184 offset:4096
	ds_read_b128 v[206:209], v184 offset:5120
	ds_read_b128 v[210:213], v184 offset:6144
	ds_read_b128 v[214:217], v184 offset:7168
	global_load_lds_dwordx4 v[178:179], off
	v_lshl_add_u64 v[178:179], s[0:1], 0, v[154:155]
	s_add_i32 m0, s43, 0xe000
	s_nop 0
	global_load_lds_dwordx4 v[178:179], off
	s_waitcnt vmcnt(8)
	s_waitcnt lgkmcnt(0)
	s_barrier
	s_waitcnt lgkmcnt(0)
	v_mfma_f32_16x16x32_bf16 v[124:127], v[128:131], v[186:189], 0
	v_mfma_f32_16x16x32_bf16 v[120:123], v[136:139], v[186:189], 0
	v_mfma_f32_16x16x32_bf16 v[108:111], v[128:131], v[194:197], 0
	v_mfma_f32_16x16x32_bf16 v[104:107], v[136:139], v[194:197], 0
	v_mfma_f32_16x16x32_bf16 v[92:95], v[128:131], v[202:205], 0
	v_mfma_f32_16x16x32_bf16 v[88:91], v[136:139], v[202:205], 0
	v_mfma_f32_16x16x32_bf16 v[76:79], v[128:131], v[210:213], 0
	v_mfma_f32_16x16x32_bf16 v[72:75], v[136:139], v[210:213], 0
	v_mfma_f32_16x16x32_bf16 v[124:127], v[132:135], v[190:193], v[124:127]
	v_mfma_f32_16x16x32_bf16 v[120:123], v[140:143], v[190:193], v[120:123]
	v_mfma_f32_16x16x32_bf16 v[108:111], v[132:135], v[198:201], v[108:111]
	v_mfma_f32_16x16x32_bf16 v[104:107], v[140:143], v[198:201], v[104:107]
	v_mfma_f32_16x16x32_bf16 v[92:95], v[132:135], v[206:209], v[92:95]
	v_mfma_f32_16x16x32_bf16 v[88:91], v[140:143], v[206:209], v[88:91]
	v_mfma_f32_16x16x32_bf16 v[76:79], v[132:135], v[214:217], v[76:79]
	v_mfma_f32_16x16x32_bf16 v[72:75], v[140:143], v[214:217], v[72:75]
	v_mfma_f32_16x16x32_bf16 v[116:119], v[160:163], v[186:189], 0
	v_mfma_f32_16x16x32_bf16 v[112:115], v[168:171], v[186:189], 0
	v_mfma_f32_16x16x32_bf16 v[100:103], v[160:163], v[194:197], 0
	v_mfma_f32_16x16x32_bf16 v[96:99], v[168:171], v[194:197], 0
	v_mfma_f32_16x16x32_bf16 v[84:87], v[160:163], v[202:205], 0
	v_mfma_f32_16x16x32_bf16 v[80:83], v[168:171], v[202:205], 0
	v_mfma_f32_16x16x32_bf16 v[68:71], v[160:163], v[210:213], 0
	v_mfma_f32_16x16x32_bf16 v[64:67], v[168:171], v[210:213], 0
	v_mfma_f32_16x16x32_bf16 v[116:119], v[164:167], v[190:193], v[116:119]
	v_mfma_f32_16x16x32_bf16 v[112:115], v[172:175], v[190:193], v[112:115]
	v_mfma_f32_16x16x32_bf16 v[100:103], v[164:167], v[198:201], v[100:103]
	v_mfma_f32_16x16x32_bf16 v[96:99], v[172:175], v[198:201], v[96:99]
	v_mfma_f32_16x16x32_bf16 v[84:87], v[164:167], v[206:209], v[84:87]
	v_mfma_f32_16x16x32_bf16 v[80:83], v[172:175], v[206:209], v[80:83]
	v_mfma_f32_16x16x32_bf16 v[68:71], v[164:167], v[214:217], v[68:71]
	v_mfma_f32_16x16x32_bf16 v[64:67], v[172:175], v[214:217], v[64:67]
	s_barrier
	s_add_i32 s78, s69, s42
	v_lshl_add_u64 v[178:179], s[34:35], 0, v[146:147]
	s_mov_b32 m0, s78
	ds_read_b128 v[186:189], v184 offset:16384
	ds_read_b128 v[190:193], v184 offset:17408
	ds_read_b128 v[194:197], v184 offset:18432
	ds_read_b128 v[198:201], v184 offset:19456
	ds_read_b128 v[202:205], v184 offset:20480
	ds_read_b128 v[206:209], v184 offset:21504
	ds_read_b128 v[210:213], v184 offset:22528
	ds_read_b128 v[214:217], v184 offset:23552
	global_load_lds_dwordx4 v[178:179], off
	s_add_i32 m0, s78, 0x2000
	s_add_u32 s78, s34, 0xb0000
	v_lshl_add_u64 v[218:219], s[34:35], 0, v[150:151]
	s_addc_u32 s79, s35, 0
	s_add_i32 s80, s70, s42
	global_load_lds_dwordx4 v[218:219], off
	v_lshl_add_u64 v[220:221], s[78:79], 0, v[146:147]
	s_mov_b32 m0, s80
	v_lshl_add_u64 v[222:223], s[38:39], 0, v[148:149]
	global_load_lds_dwordx4 v[220:221], off
	v_lshl_add_u64 v[220:221], s[78:79], 0, v[150:151]
	s_add_i32 m0, s80, 0x2000
	s_nop 0
	global_load_lds_dwordx4 v[220:221], off
	v_lshl_add_u64 v[220:221], s[38:39], 0, v[144:145]
	s_mov_b32 m0, s43
	s_nop 0
	global_load_lds_dwordx4 v[220:221], off
	s_mov_b32 m0, s52
	s_nop 0
	global_load_lds_dwordx4 v[222:223], off
	s_waitcnt vmcnt(8)
	s_waitcnt lgkmcnt(0)
	s_barrier
; #define PG8_STAGE(bufoff, gbase, voff) do { _Pragma("unroll") for (int _i = 0; _i < 2; ++_i) \
;         __builtin_amdgcn_global_load_lds((const unsigned*)((const char*)(gbase) + (voff)[_i]), (LAS unsigned*)(lds + (bufoff) + ldsw + _i * 8192), 16, 0, 0); } while (0)
; #define PG8_LDA(dst, b, h) do { _Pragma("unroll") for (int m = 0; m < 4; ++m) _Pragma("unroll") for (int k = 0; k < 2; ++k) dst[m][k] = *(const LAS bf16x8*)(lds + PG8_SA(b, h) + aoff + m * 2048 + k * 1024); } while (0)
; #define PG8_LDB(dst, b, h) do { _Pragma("unroll") for (int n = 0; n < 2; ++n) _Pragma("unroll") for (int k = 0; k < 2; ++k) dst[n][k] = *(const LAS bf16x8*)(lds + PG8_SB(b, h) + boff + n * 2048 + k * 1024); } while (0)
; #define PG8_MMA(ai, bj, At, Bt) do { __builtin_amdgcn_s_setprio(1); _Pragma("unroll") for (int m = 0; m < 4; ++m) _Pragma("unroll") for (int n = 0; n < 2; ++n) _Pragma("unroll") for (int k = 0; k < 2; ++k) \
;         acc[ai][bj][m][n] = __builtin_amdgcn_mfma_f32_16x16x32_bf16(Bt[n][k], At[m][k], acc[ai][bj][m][n], 0, 0, 0); __builtin_amdgcn_s_setprio(0); } while (0)
; #define PG8_WAIT_V(n) asm volatile("s_waitcnt vmcnt(" #n ")" ::: "memory")
; #define PG8_WAIT_L(n) asm volatile("s_waitcnt lgkmcnt(" #n ")" ::: "memory")
; #define PG8_BAR __builtin_amdgcn_s_barrier()
; #define PG8_SCHED __builtin_amdgcn_sched_barrier(0)
; template <class Epi>
; __device__ __forceinline__ void gemm_phase(LAS unsigned char* lds, const Gemm g, const StaticOrder& S, const Epi& E) {
;     ...
;             PG8_WAIT_V(8); PG8_WAIT_L(0); PG8_BAR; PG8_MMA(1, 0, At, B0); PG8_MMA(1, 1, At, B1); PG8_BAR; PG8_SCHED;
;             PG8_LDB(B0, 1, 0); PG8_LDB(B1, 1, 1); PG8_SCHED; PG8_LDA(At, 1, 0); PG8_STAGE(PG8_SA(0, 1), a2 + hstepA, voffA);
;             PG8_WAIT_V(8); PG8_WAIT_L(0); PG8_BAR; PG8_MMA(0, 0, At, B0); PG8_MMA(0, 1, At, B1); PG8_BAR; PG8_SCHED;
	s_waitcnt lgkmcnt(0)
	v_mfma_f32_16x16x32_bf16 v[60:63], v[128:131], v[186:189], 0
	v_mfma_f32_16x16x32_bf16 v[56:59], v[136:139], v[186:189], 0
	v_mfma_f32_16x16x32_bf16 v[44:47], v[128:131], v[194:197], 0
	v_mfma_f32_16x16x32_bf16 v[40:43], v[136:139], v[194:197], 0
	v_mfma_f32_16x16x32_bf16 v[28:31], v[128:131], v[202:205], 0
	v_mfma_f32_16x16x32_bf16 v[24:27], v[136:139], v[202:205], 0
	v_mfma_f32_16x16x32_bf16 v[12:15], v[128:131], v[210:213], 0
	v_mfma_f32_16x16x32_bf16 v[8:11], v[136:139], v[210:213], 0
	v_mfma_f32_16x16x32_bf16 v[60:63], v[132:135], v[190:193], v[60:63]
	v_mfma_f32_16x16x32_bf16 v[56:59], v[140:143], v[190:193], v[56:59]
	v_mfma_f32_16x16x32_bf16 v[44:47], v[132:135], v[198:201], v[44:47]
	v_mfma_f32_16x16x32_bf16 v[40:43], v[140:143], v[198:201], v[40:43]
	v_mfma_f32_16x16x32_bf16 v[28:31], v[132:135], v[206:209], v[28:31]
	v_mfma_f32_16x16x32_bf16 v[24:27], v[140:143], v[206:209], v[24:27]
	v_mfma_f32_16x16x32_bf16 v[12:15], v[132:135], v[214:217], v[12:15]
	v_mfma_f32_16x16x32_bf16 v[8:11], v[140:143], v[214:217], v[8:11]
	v_mfma_f32_16x16x32_bf16 v[52:55], v[160:163], v[186:189], 0
	v_mfma_f32_16x16x32_bf16 v[48:51], v[168:171], v[186:189], 0
	v_mfma_f32_16x16x32_bf16 v[36:39], v[160:163], v[194:197], 0
	v_mfma_f32_16x16x32_bf16 v[32:35], v[168:171], v[194:197], 0
	v_mfma_f32_16x16x32_bf16 v[20:23], v[160:163], v[202:205], 0
	v_mfma_f32_16x16x32_bf16 v[16:19], v[168:171], v[202:205], 0
	v_mfma_f32_16x16x32_bf16 v[4:7], v[160:163], v[210:213], 0
	v_mfma_f32_16x16x32_bf16 v[0:3], v[168:171], v[210:213], 0
	v_mfma_f32_16x16x32_bf16 v[52:55], v[164:167], v[190:193], v[52:55]
	v_mfma_f32_16x16x32_bf16 v[48:51], v[172:175], v[190:193], v[48:51]
	v_mfma_f32_16x16x32_bf16 v[36:39], v[164:167], v[198:201], v[36:39]
	v_mfma_f32_16x16x32_bf16 v[32:35], v[172:175], v[198:201], v[32:35]
	v_mfma_f32_16x16x32_bf16 v[20:23], v[164:167], v[206:209], v[20:23]
	v_mfma_f32_16x16x32_bf16 v[16:19], v[172:175], v[206:209], v[16:19]
	v_mfma_f32_16x16x32_bf16 v[4:7], v[164:167], v[214:217], v[4:7]
	v_mfma_f32_16x16x32_bf16 v[0:3], v[172:175], v[214:217], v[0:3]
	s_barrier
	s_add_i32 s78, 0, 0x18000
	s_add_i32 s79, 0, 0x1c000
	v_add_u32_e32 v140, s78, v181
	v_add_u32_e32 v172, s79, v181
	ds_read_b128 v[128:131], v140
	ds_read_b128 v[132:135], v140 offset:1024
	ds_read_b128 v[136:139], v140 offset:2048
	ds_read_b128 v[140:143], v140 offset:3072
	ds_read_b128 v[160:163], v172
	ds_read_b128 v[164:167], v172 offset:1024
	ds_read_b128 v[168:171], v172 offset:2048
	ds_read_b128 v[172:175], v172 offset:3072
	s_add_u32 s38, s38, 0xb0000
	s_addc_u32 s39, s39, 0
	s_mov_b32 m0, s53
	v_lshl_add_u64 v[226:227], s[38:39], 0, v[144:145]
	ds_read_b128 v[186:189], v184 offset:32768
	ds_read_b128 v[190:193], v184 offset:33792
	ds_read_b128 v[194:197], v184 offset:34816
	ds_read_b128 v[198:201], v184 offset:35840
	ds_read_b128 v[202:205], v184 offset:36864
	ds_read_b128 v[206:209], v184 offset:37888
	ds_read_b128 v[210:213], v184 offset:38912
	ds_read_b128 v[214:217], v184 offset:39936
	global_load_lds_dwordx4 v[226:227], off
	v_lshl_add_u64 v[226:227], s[38:39], 0, v[148:149]
	s_mov_b32 m0, s54
	s_nop 0
	global_load_lds_dwordx4 v[226:227], off
	s_waitcnt vmcnt(8)
	s_waitcnt lgkmcnt(0)
	s_barrier
	s_waitcnt lgkmcnt(0)
	v_mfma_f32_16x16x32_bf16 v[124:127], v[128:131], v[186:189], v[124:127]
	v_mfma_f32_16x16x32_bf16 v[120:123], v[136:139], v[186:189], v[120:123]
	v_mfma_f32_16x16x32_bf16 v[108:111], v[128:131], v[194:197], v[108:111]
	v_mfma_f32_16x16x32_bf16 v[104:107], v[136:139], v[194:197], v[104:107]
	v_mfma_f32_16x16x32_bf16 v[92:95], v[128:131], v[202:205], v[92:95]
	v_mfma_f32_16x16x32_bf16 v[88:91], v[136:139], v[202:205], v[88:91]
	v_mfma_f32_16x16x32_bf16 v[76:79], v[128:131], v[210:213], v[76:79]
	v_mfma_f32_16x16x32_bf16 v[72:75], v[136:139], v[210:213], v[72:75]
	v_mfma_f32_16x16x32_bf16 v[124:127], v[132:135], v[190:193], v[124:127]
	v_mfma_f32_16x16x32_bf16 v[120:123], v[140:143], v[190:193], v[120:123]
	v_mfma_f32_16x16x32_bf16 v[108:111], v[132:135], v[198:201], v[108:111]
	v_mfma_f32_16x16x32_bf16 v[104:107], v[140:143], v[198:201], v[104:107]
	v_mfma_f32_16x16x32_bf16 v[92:95], v[132:135], v[206:209], v[92:95]
	v_mfma_f32_16x16x32_bf16 v[88:91], v[140:143], v[206:209], v[88:91]
	v_mfma_f32_16x16x32_bf16 v[76:79], v[132:135], v[214:217], v[76:79]
	v_mfma_f32_16x16x32_bf16 v[72:75], v[140:143], v[214:217], v[72:75]
	v_mfma_f32_16x16x32_bf16 v[116:119], v[160:163], v[186:189], v[116:119]
	v_mfma_f32_16x16x32_bf16 v[112:115], v[168:171], v[186:189], v[112:115]
	v_mfma_f32_16x16x32_bf16 v[100:103], v[160:163], v[194:197], v[100:103]
	v_mfma_f32_16x16x32_bf16 v[96:99], v[168:171], v[194:197], v[96:99]
	v_mfma_f32_16x16x32_bf16 v[84:87], v[160:163], v[202:205], v[84:87]
	v_mfma_f32_16x16x32_bf16 v[80:83], v[168:171], v[202:205], v[80:83]
	v_mfma_f32_16x16x32_bf16 v[68:71], v[160:163], v[210:213], v[68:71]
	v_mfma_f32_16x16x32_bf16 v[64:67], v[168:171], v[210:213], v[64:67]
	v_mfma_f32_16x16x32_bf16 v[116:119], v[164:167], v[190:193], v[116:119]
	v_mfma_f32_16x16x32_bf16 v[112:115], v[172:175], v[190:193], v[112:115]
	v_mfma_f32_16x16x32_bf16 v[100:103], v[164:167], v[198:201], v[100:103]
	v_mfma_f32_16x16x32_bf16 v[96:99], v[172:175], v[198:201], v[96:99]
	v_mfma_f32_16x16x32_bf16 v[84:87], v[164:167], v[206:209], v[84:87]
	v_mfma_f32_16x16x32_bf16 v[80:83], v[172:175], v[206:209], v[80:83]
	v_mfma_f32_16x16x32_bf16 v[68:71], v[164:167], v[214:217], v[68:71]
	v_mfma_f32_16x16x32_bf16 v[64:67], v[172:175], v[214:217], v[64:67]
	s_barrier
; #define PG8_STAGE(bufoff, gbase, voff) do { _Pragma("unroll") for (int _i = 0; _i < 2; ++_i) \
;         __builtin_amdgcn_global_load_lds((const unsigned*)((const char*)(gbase) + (voff)[_i]), (LAS unsigned*)(lds + (bufoff) + ldsw + _i * 8192), 16, 0, 0); } while (0)
; #define PG8_LDA(dst, b, h) do { _Pragma("unroll") for (int m = 0; m < 4; ++m) _Pragma("unroll") for (int k = 0; k < 2; ++k) dst[m][k] = *(const LAS bf16x8*)(lds + PG8_SA(b, h) + aoff + m * 2048 + k * 1024); } while (0)
; #define PG8_LDB(dst, b, h) do { _Pragma("unroll") for (int n = 0; n < 2; ++n) _Pragma("unroll") for (int k = 0; k < 2; ++k) dst[n][k] = *(const LAS bf16x8*)(lds + PG8_SB(b, h) + boff + n * 2048 + k * 1024); } while (0)
; #define PG8_WAIT_V(n) asm volatile("s_waitcnt vmcnt(" #n ")" ::: "memory")
; #define PG8_WAIT_L(n) asm volatile("s_waitcnt lgkmcnt(" #n ")" ::: "memory")
; template <class Epi>
; __device__ __forceinline__ void gemm_phase(LAS unsigned char* lds, const Gemm g, const StaticOrder& S, const Epi& E) {
;     ...
;         for (int t = 0; t < nt; t += 2) {
;             const bool last = (t == nt - 2);
;             const char* a1 = cA + (size_t)(t + 1) * kstep;
;             const char* a2 = last ? nA : cA + (size_t)(t + 2) * kstep; const char* b2 = last ? nB : cB + (size_t)(t + 2) * kstep;
;             const char* a3 = a2 + kstep; const char* b3 = b2 + kstep;
;             PG8_LDB(B0, 0, 0); PG8_LDB(B1, 0, 1); PG8_SCHED; PG8_LDA(At, 0, 0); PG8_STAGE(PG8_SA(1, 1), a1 + hstepA, voffA);
;             PG8_WAIT_V(8); PG8_WAIT_L(0); PG8_BAR; PG8_MMA(0, 0, At, B0); PG8_MMA(0, 1, At, B1); PG8_BAR; PG8_SCHED;
;             PG8_LDA(At, 0, 1); PG8_STAGE(PG8_SB(0, 0), b2, voffB); PG8_STAGE(PG8_SB(0, 1), b2 + hstepB, voffB); PG8_STAGE(PG8_SA(0, 0), a2, voffA);
;             PG8_WAIT_V(8); PG8_WAIT_L(0); PG8_BAR; PG8_MMA(1, 0, At, B0); PG8_MMA(1, 1, At, B1); PG8_BAR; PG8_SCHED;
;             PG8_LDB(B0, 1, 0); PG8_LDB(B1, 1, 1); PG8_SCHED; PG8_LDA(At, 1, 0); PG8_STAGE(PG8_SA(0, 1), a2 + hstepA, voffA);
;             PG8_WAIT_V(8); PG8_WAIT_L(0); PG8_BAR; PG8_MMA(0, 0, At, B0); PG8_MMA(0, 1, At, B1); PG8_BAR; PG8_SCHED;
;             PG8_LDA(At, 1, 1); PG8_STAGE(PG8_SB(1, 0), b3, voffB); PG8_STAGE(PG8_SB(1, 1), b3 + hstepB, voffB); PG8_STAGE(PG8_SA(1, 0), a3, voffA);
;             PG8_WAIT_V(8); PG8_WAIT_L(0); PG8_BAR; PG8_MMA(1, 0, At, B0); PG8_MMA(1, 1, At, B1); PG8_BAR; PG8_SCHED;
	s_add_i32 s38, s78, s42
	v_lshl_add_u64 v[178:179], v[178:179], 0, s[16:17]
	s_mov_b32 m0, s38
	ds_read_b128 v[186:189], v184 offset:49152
	ds_read_b128 v[190:193], v184 offset:50176
	ds_read_b128 v[194:197], v184 offset:51200
	ds_read_b128 v[198:201], v184 offset:52224
	ds_read_b128 v[202:205], v184 offset:53248
	ds_read_b128 v[206:209], v184 offset:54272
	ds_read_b128 v[210:213], v184 offset:55296
	ds_read_b128 v[214:217], v184 offset:56320
	global_load_lds_dwordx4 v[178:179], off
	s_add_i32 m0, s38, 0x2000
	s_add_u32 s34, s34, 0xb0080
	v_lshl_add_u64 v[178:179], v[218:219], 0, s[16:17]
	s_addc_u32 s35, s35, 0
	s_add_i32 s38, s79, s42
	global_load_lds_dwordx4 v[178:179], off
	v_lshl_add_u64 v[178:179], s[34:35], 0, v[146:147]
	s_mov_b32 m0, s38
	s_nop 0
	global_load_lds_dwordx4 v[178:179], off
	v_lshl_add_u64 v[178:179], s[34:35], 0, v[150:151]
	s_add_i32 m0, s38, 0x2000
	s_nop 0
	global_load_lds_dwordx4 v[178:179], off
	v_lshl_add_u64 v[178:179], v[220:221], 0, s[16:17]
	s_mov_b32 m0, s62
	s_nop 0
	global_load_lds_dwordx4 v[178:179], off
	v_lshl_add_u64 v[178:179], v[222:223], 0, s[16:17]
	s_mov_b32 m0, s63
	s_nop 0
	global_load_lds_dwordx4 v[178:179], off
	s_waitcnt vmcnt(8)
	s_waitcnt lgkmcnt(0)
	s_barrier
	s_waitcnt lgkmcnt(0)
	v_mfma_f32_16x16x32_bf16 v[60:63], v[128:131], v[186:189], v[60:63]
	v_mfma_f32_16x16x32_bf16 v[56:59], v[136:139], v[186:189], v[56:59]
	v_mfma_f32_16x16x32_bf16 v[44:47], v[128:131], v[194:197], v[44:47]
	v_mfma_f32_16x16x32_bf16 v[40:43], v[136:139], v[194:197], v[40:43]
	v_mfma_f32_16x16x32_bf16 v[28:31], v[128:131], v[202:205], v[28:31]
	v_mfma_f32_16x16x32_bf16 v[24:27], v[136:139], v[202:205], v[24:27]
	v_mfma_f32_16x16x32_bf16 v[12:15], v[128:131], v[210:213], v[12:15]
	v_mfma_f32_16x16x32_bf16 v[8:11], v[136:139], v[210:213], v[8:11]
	v_mfma_f32_16x16x32_bf16 v[60:63], v[132:135], v[190:193], v[60:63]
	v_mfma_f32_16x16x32_bf16 v[56:59], v[140:143], v[190:193], v[56:59]
	v_mfma_f32_16x16x32_bf16 v[44:47], v[132:135], v[198:201], v[44:47]
	v_mfma_f32_16x16x32_bf16 v[40:43], v[140:143], v[198:201], v[40:43]
	v_mfma_f32_16x16x32_bf16 v[28:31], v[132:135], v[206:209], v[28:31]
	v_mfma_f32_16x16x32_bf16 v[24:27], v[140:143], v[206:209], v[24:27]
	v_mfma_f32_16x16x32_bf16 v[12:15], v[132:135], v[214:217], v[12:15]
	v_mfma_f32_16x16x32_bf16 v[8:11], v[140:143], v[214:217], v[8:11]
	v_mfma_f32_16x16x32_bf16 v[52:55], v[160:163], v[186:189], v[52:55]
	v_mfma_f32_16x16x32_bf16 v[48:51], v[168:171], v[186:189], v[48:51]
	v_mfma_f32_16x16x32_bf16 v[36:39], v[160:163], v[194:197], v[36:39]
	v_mfma_f32_16x16x32_bf16 v[32:35], v[168:171], v[194:197], v[32:35]
	v_mfma_f32_16x16x32_bf16 v[20:23], v[160:163], v[202:205], v[20:23]
	v_mfma_f32_16x16x32_bf16 v[16:19], v[168:171], v[202:205], v[16:19]
	v_mfma_f32_16x16x32_bf16 v[4:7], v[160:163], v[210:213], v[4:7]
	v_mfma_f32_16x16x32_bf16 v[0:3], v[168:171], v[210:213], v[0:3]
	v_mfma_f32_16x16x32_bf16 v[52:55], v[164:167], v[190:193], v[52:55]
	v_mfma_f32_16x16x32_bf16 v[48:51], v[172:175], v[190:193], v[48:51]
	v_mfma_f32_16x16x32_bf16 v[36:39], v[164:167], v[198:201], v[36:39]
	v_mfma_f32_16x16x32_bf16 v[32:35], v[172:175], v[198:201], v[32:35]
	v_mfma_f32_16x16x32_bf16 v[20:23], v[164:167], v[206:209], v[20:23]
	v_mfma_f32_16x16x32_bf16 v[16:19], v[172:175], v[206:209], v[16:19]
	v_mfma_f32_16x16x32_bf16 v[4:7], v[164:167], v[214:217], v[4:7]
	v_mfma_f32_16x16x32_bf16 v[0:3], v[172:175], v[214:217], v[0:3]
	s_barrier
	s_add_i32 s77, s77, 2
	s_add_u32 s0, s0, 0x100
	s_addc_u32 s1, s1, 0
	s_add_u32 s75, s75, 0x100
	s_addc_u32 s76, s76, 0
	s_cmp_gt_u32 s77, 41
.LBB0_792:
	ds_read_b128 v[128:131], v182
	ds_read_b128 v[132:135], v182 offset:1024
	ds_read_b128 v[136:139], v182 offset:2048
	ds_read_b128 v[140:143], v182 offset:3072
	ds_read_b128 v[160:163], v183
	ds_read_b128 v[164:167], v183 offset:1024
	ds_read_b128 v[168:171], v183 offset:2048
	ds_read_b128 v[172:175], v183 offset:3072
	s_add_u32 s34, s0, 0xfff50080
	s_addc_u32 s35, s1, -1
	s_cmp_eq_u32 s77, 40
	s_cselect_b32 s39, s7, s35
	s_cselect_b32 s38, s6, s34
	s_cselect_b32 s35, s23, s76
	s_cselect_b32 s34, s22, s75
	v_lshl_add_u64 v[178:179], s[0:1], 0, v[152:153]
	s_add_i32 m0, s43, 0xc000
	ds_read_b128 v[186:189], v184
	ds_read_b128 v[190:193], v184 offset:1024
	ds_read_b128 v[194:197], v184 offset:2048
	ds_read_b128 v[198:201], v184 offset:3072
	ds_read_b128 v[202:205], v184 offset:4096
	ds_read_b128 v[206:209], v184 offset:5120
	ds_read_b128 v[210:213], v184 offset:6144
	ds_read_b128 v[214:217], v184 offset:7168
	global_load_lds_dwordx4 v[178:179], off
	v_lshl_add_u64 v[178:179], s[0:1], 0, v[154:155]
	s_add_i32 m0, s43, 0xe000
	s_nop 0
	global_load_lds_dwordx4 v[178:179], off
	s_waitcnt vmcnt(8)
	s_waitcnt lgkmcnt(0)
	s_barrier
; #define PG8_STAGE(bufoff, gbase, voff) do { _Pragma("unroll") for (int _i = 0; _i < 2; ++_i) \
;         __builtin_amdgcn_global_load_lds((const unsigned*)((const char*)(gbase) + (voff)[_i]), (LAS unsigned*)(lds + (bufoff) + ldsw + _i * 8192), 16, 0, 0); } while (0)
; #define PG8_LDA(dst, b, h) do { _Pragma("unroll") for (int m = 0; m < 4; ++m) _Pragma("unroll") for (int k = 0; k < 2; ++k) dst[m][k] = *(const LAS bf16x8*)(lds + PG8_SA(b, h) + aoff + m * 2048 + k * 1024); } while (0)
; #define PG8_MMA(ai, bj, At, Bt) do { __builtin_amdgcn_s_setprio(1); _Pragma("unroll") for (int m = 0; m < 4; ++m) _Pragma("unroll") for (int n = 0; n < 2; ++n) _Pragma("unroll") for (int k = 0; k < 2; ++k) \
;         acc[ai][bj][m][n] = __builtin_amdgcn_mfma_f32_16x16x32_bf16(Bt[n][k], At[m][k], acc[ai][bj][m][n], 0, 0, 0); __builtin_amdgcn_s_setprio(0); } while (0)
; #define PG8_WAIT_V(n) asm volatile("s_waitcnt vmcnt(" #n ")" ::: "memory")
; #define PG8_WAIT_L(n) asm volatile("s_waitcnt lgkmcnt(" #n ")" ::: "memory")
; #define PG8_BAR __builtin_amdgcn_s_barrier()
; #define PG8_SCHED __builtin_amdgcn_sched_barrier(0)
; template <class Epi>
; __device__ __forceinline__ void gemm_phase(LAS unsigned char* lds, const Gemm g, const StaticOrder& S, const Epi& E) {
;     ...
;             PG8_WAIT_V(8); PG8_WAIT_L(0); PG8_BAR; PG8_MMA(0, 0, At, B0); PG8_MMA(0, 1, At, B1); PG8_BAR; PG8_SCHED;
;             PG8_LDA(At, 0, 1); PG8_STAGE(PG8_SB(0, 0), b2, voffB); PG8_STAGE(PG8_SB(0, 1), b2 + hstepB, voffB); PG8_STAGE(PG8_SA(0, 0), a2, voffA);
;             PG8_WAIT_V(8); PG8_WAIT_L(0); PG8_BAR; PG8_MMA(1, 0, At, B0); PG8_MMA(1, 1, At, B1); PG8_BAR; PG8_SCHED;
	s_waitcnt lgkmcnt(0)
	v_mfma_f32_16x16x32_bf16 v[124:127], v[128:131], v[186:189], v[124:127]
	v_mfma_f32_16x16x32_bf16 v[120:123], v[136:139], v[186:189], v[120:123]
	v_mfma_f32_16x16x32_bf16 v[108:111], v[128:131], v[194:197], v[108:111]
	v_mfma_f32_16x16x32_bf16 v[104:107], v[136:139], v[194:197], v[104:107]
	v_mfma_f32_16x16x32_bf16 v[92:95], v[128:131], v[202:205], v[92:95]
	v_mfma_f32_16x16x32_bf16 v[88:91], v[136:139], v[202:205], v[88:91]
	v_mfma_f32_16x16x32_bf16 v[76:79], v[128:131], v[210:213], v[76:79]
	v_mfma_f32_16x16x32_bf16 v[72:75], v[136:139], v[210:213], v[72:75]
	v_mfma_f32_16x16x32_bf16 v[124:127], v[132:135], v[190:193], v[124:127]
	v_mfma_f32_16x16x32_bf16 v[120:123], v[140:143], v[190:193], v[120:123]
	v_mfma_f32_16x16x32_bf16 v[108:111], v[132:135], v[198:201], v[108:111]
	v_mfma_f32_16x16x32_bf16 v[104:107], v[140:143], v[198:201], v[104:107]
	v_mfma_f32_16x16x32_bf16 v[92:95], v[132:135], v[206:209], v[92:95]
	v_mfma_f32_16x16x32_bf16 v[88:91], v[140:143], v[206:209], v[88:91]
	v_mfma_f32_16x16x32_bf16 v[76:79], v[132:135], v[214:217], v[76:79]
	v_mfma_f32_16x16x32_bf16 v[72:75], v[140:143], v[214:217], v[72:75]
	v_mfma_f32_16x16x32_bf16 v[116:119], v[160:163], v[186:189], v[116:119]
	v_mfma_f32_16x16x32_bf16 v[112:115], v[168:171], v[186:189], v[112:115]
	v_mfma_f32_16x16x32_bf16 v[100:103], v[160:163], v[194:197], v[100:103]
	v_mfma_f32_16x16x32_bf16 v[96:99], v[168:171], v[194:197], v[96:99]
	v_mfma_f32_16x16x32_bf16 v[84:87], v[160:163], v[202:205], v[84:87]
	v_mfma_f32_16x16x32_bf16 v[80:83], v[168:171], v[202:205], v[80:83]
	v_mfma_f32_16x16x32_bf16 v[68:71], v[160:163], v[210:213], v[68:71]
	v_mfma_f32_16x16x32_bf16 v[64:67], v[168:171], v[210:213], v[64:67]
	v_mfma_f32_16x16x32_bf16 v[116:119], v[164:167], v[190:193], v[116:119]
	v_mfma_f32_16x16x32_bf16 v[112:115], v[172:175], v[190:193], v[112:115]
	v_mfma_f32_16x16x32_bf16 v[100:103], v[164:167], v[198:201], v[100:103]
	v_mfma_f32_16x16x32_bf16 v[96:99], v[172:175], v[198:201], v[96:99]
	v_mfma_f32_16x16x32_bf16 v[84:87], v[164:167], v[206:209], v[84:87]
	v_mfma_f32_16x16x32_bf16 v[80:83], v[172:175], v[206:209], v[80:83]
	v_mfma_f32_16x16x32_bf16 v[68:71], v[164:167], v[214:217], v[68:71]
	v_mfma_f32_16x16x32_bf16 v[64:67], v[172:175], v[214:217], v[64:67]
	s_barrier
	s_add_i32 s78, s69, s42
	v_lshl_add_u64 v[178:179], s[34:35], 0, v[146:147]
	s_mov_b32 m0, s78
	ds_read_b128 v[186:189], v184 offset:16384
	ds_read_b128 v[190:193], v184 offset:17408
	ds_read_b128 v[194:197], v184 offset:18432
	ds_read_b128 v[198:201], v184 offset:19456
	ds_read_b128 v[202:205], v184 offset:20480
	ds_read_b128 v[206:209], v184 offset:21504
	ds_read_b128 v[210:213], v184 offset:22528
	ds_read_b128 v[214:217], v184 offset:23552
	global_load_lds_dwordx4 v[178:179], off
	s_add_i32 m0, s78, 0x2000
	s_add_u32 s78, s34, 0xb0000
	v_lshl_add_u64 v[218:219], s[34:35], 0, v[150:151]
	s_addc_u32 s79, s35, 0
	s_add_i32 s80, s70, s42
	global_load_lds_dwordx4 v[218:219], off
	v_lshl_add_u64 v[220:221], s[78:79], 0, v[146:147]
	s_mov_b32 m0, s80
	v_lshl_add_u64 v[222:223], s[38:39], 0, v[148:149]
	global_load_lds_dwordx4 v[220:221], off
	v_lshl_add_u64 v[220:221], s[78:79], 0, v[150:151]
	s_add_i32 m0, s80, 0x2000
	s_nop 0
	global_load_lds_dwordx4 v[220:221], off
	v_lshl_add_u64 v[220:221], s[38:39], 0, v[144:145]
	s_mov_b32 m0, s43
	s_nop 0
	global_load_lds_dwordx4 v[220:221], off
	s_mov_b32 m0, s52
	s_nop 0
	global_load_lds_dwordx4 v[222:223], off
	s_waitcnt vmcnt(8)
	s_waitcnt lgkmcnt(0)
	s_barrier
	s_waitcnt lgkmcnt(0)
	v_mfma_f32_16x16x32_bf16 v[60:63], v[128:131], v[186:189], v[60:63]
	v_mfma_f32_16x16x32_bf16 v[56:59], v[136:139], v[186:189], v[56:59]
	v_mfma_f32_16x16x32_bf16 v[44:47], v[128:131], v[194:197], v[44:47]
	v_mfma_f32_16x16x32_bf16 v[40:43], v[136:139], v[194:197], v[40:43]
	v_mfma_f32_16x16x32_bf16 v[28:31], v[128:131], v[202:205], v[28:31]
	v_mfma_f32_16x16x32_bf16 v[24:27], v[136:139], v[202:205], v[24:27]
	v_mfma_f32_16x16x32_bf16 v[12:15], v[128:131], v[210:213], v[12:15]
	v_mfma_f32_16x16x32_bf16 v[8:11], v[136:139], v[210:213], v[8:11]
	v_mfma_f32_16x16x32_bf16 v[60:63], v[132:135], v[190:193], v[60:63]
	v_mfma_f32_16x16x32_bf16 v[56:59], v[140:143], v[190:193], v[56:59]
	v_mfma_f32_16x16x32_bf16 v[44:47], v[132:135], v[198:201], v[44:47]
	v_mfma_f32_16x16x32_bf16 v[40:43], v[140:143], v[198:201], v[40:43]
	v_mfma_f32_16x16x32_bf16 v[28:31], v[132:135], v[206:209], v[28:31]
	v_mfma_f32_16x16x32_bf16 v[24:27], v[140:143], v[206:209], v[24:27]
	v_mfma_f32_16x16x32_bf16 v[12:15], v[132:135], v[214:217], v[12:15]
	v_mfma_f32_16x16x32_bf16 v[8:11], v[140:143], v[214:217], v[8:11]
	v_mfma_f32_16x16x32_bf16 v[52:55], v[160:163], v[186:189], v[52:55]
	v_mfma_f32_16x16x32_bf16 v[48:51], v[168:171], v[186:189], v[48:51]
	v_mfma_f32_16x16x32_bf16 v[36:39], v[160:163], v[194:197], v[36:39]
	v_mfma_f32_16x16x32_bf16 v[32:35], v[168:171], v[194:197], v[32:35]
	v_mfma_f32_16x16x32_bf16 v[20:23], v[160:163], v[202:205], v[20:23]
	v_mfma_f32_16x16x32_bf16 v[16:19], v[168:171], v[202:205], v[16:19]
	v_mfma_f32_16x16x32_bf16 v[4:7], v[160:163], v[210:213], v[4:7]
	v_mfma_f32_16x16x32_bf16 v[0:3], v[168:171], v[210:213], v[0:3]
	v_mfma_f32_16x16x32_bf16 v[52:55], v[164:167], v[190:193], v[52:55]
	v_mfma_f32_16x16x32_bf16 v[48:51], v[172:175], v[190:193], v[48:51]
	v_mfma_f32_16x16x32_bf16 v[36:39], v[164:167], v[198:201], v[36:39]
	v_mfma_f32_16x16x32_bf16 v[32:35], v[172:175], v[198:201], v[32:35]
	v_mfma_f32_16x16x32_bf16 v[20:23], v[164:167], v[206:209], v[20:23]
	v_mfma_f32_16x16x32_bf16 v[16:19], v[172:175], v[206:209], v[16:19]
	v_mfma_f32_16x16x32_bf16 v[4:7], v[164:167], v[214:217], v[4:7]
	v_mfma_f32_16x16x32_bf16 v[0:3], v[172:175], v[214:217], v[0:3]
	s_barrier
; #define PG8_STAGE(bufoff, gbase, voff) do { _Pragma("unroll") for (int _i = 0; _i < 2; ++_i) \
;         __builtin_amdgcn_global_load_lds((const unsigned*)((const char*)(gbase) + (voff)[_i]), (LAS unsigned*)(lds + (bufoff) + ldsw + _i * 8192), 16, 0, 0); } while (0)
; #define PG8_LDA(dst, b, h) do { _Pragma("unroll") for (int m = 0; m < 4; ++m) _Pragma("unroll") for (int k = 0; k < 2; ++k) dst[m][k] = *(const LAS bf16x8*)(lds + PG8_SA(b, h) + aoff + m * 2048 + k * 1024); } while (0)
; #define PG8_LDB(dst, b, h) do { _Pragma("unroll") for (int n = 0; n < 2; ++n) _Pragma("unroll") for (int k = 0; k < 2; ++k) dst[n][k] = *(const LAS bf16x8*)(lds + PG8_SB(b, h) + boff + n * 2048 + k * 1024); } while (0)
; #define PG8_MMA(ai, bj, At, Bt) do { __builtin_amdgcn_s_setprio(1); _Pragma("unroll") for (int m = 0; m < 4; ++m) _Pragma("unroll") for (int n = 0; n < 2; ++n) _Pragma("unroll") for (int k = 0; k < 2; ++k) \
;         acc[ai][bj][m][n] = __builtin_amdgcn_mfma_f32_16x16x32_bf16(Bt[n][k], At[m][k], acc[ai][bj][m][n], 0, 0, 0); __builtin_amdgcn_s_setprio(0); } while (0)
; #define PG8_WAIT_V(n) asm volatile("s_waitcnt vmcnt(" #n ")" ::: "memory")
; #define PG8_WAIT_L(n) asm volatile("s_waitcnt lgkmcnt(" #n ")" ::: "memory")
; #define PG8_BAR __builtin_amdgcn_s_barrier()
; #define PG8_SCHED __builtin_amdgcn_sched_barrier(0)
; template <class Epi>
; __device__ __forceinline__ void gemm_phase(LAS unsigned char* lds, const Gemm g, const StaticOrder& S, const Epi& E) {
;     ...
;             PG8_LDB(B0, 1, 0); PG8_LDB(B1, 1, 1); PG8_SCHED; PG8_LDA(At, 1, 0); PG8_STAGE(PG8_SA(0, 1), a2 + hstepA, voffA);
;             PG8_WAIT_V(8); PG8_WAIT_L(0); PG8_BAR; PG8_MMA(0, 0, At, B0); PG8_MMA(0, 1, At, B1); PG8_BAR; PG8_SCHED;
	s_add_i32 s78, 0, 0x18000
	s_add_i32 s79, 0, 0x1c000
	v_add_u32_e32 v140, s78, v181
	v_add_u32_e32 v172, s79, v181
	ds_read_b128 v[128:131], v140
	ds_read_b128 v[132:135], v140 offset:1024
	ds_read_b128 v[136:139], v140 offset:2048
	ds_read_b128 v[140:143], v140 offset:3072
	ds_read_b128 v[160:163], v172
	ds_read_b128 v[164:167], v172 offset:1024
	ds_read_b128 v[168:171], v172 offset:2048
	ds_read_b128 v[172:175], v172 offset:3072
	s_add_u32 s38, s38, 0xb0000
	s_addc_u32 s39, s39, 0
	s_mov_b32 m0, s53
	v_lshl_add_u64 v[226:227], s[38:39], 0, v[144:145]
	ds_read_b128 v[186:189], v184 offset:32768
	ds_read_b128 v[190:193], v184 offset:33792
	ds_read_b128 v[194:197], v184 offset:34816
	ds_read_b128 v[198:201], v184 offset:35840
	ds_read_b128 v[202:205], v184 offset:36864
	ds_read_b128 v[206:209], v184 offset:37888
	ds_read_b128 v[210:213], v184 offset:38912
	ds_read_b128 v[214:217], v184 offset:39936
	global_load_lds_dwordx4 v[226:227], off
	v_lshl_add_u64 v[226:227], s[38:39], 0, v[148:149]
	s_mov_b32 m0, s54
	s_nop 0
	global_load_lds_dwordx4 v[226:227], off
	s_waitcnt vmcnt(8)
	s_waitcnt lgkmcnt(0)
	s_barrier
	s_waitcnt lgkmcnt(0)
	v_mfma_f32_16x16x32_bf16 v[124:127], v[128:131], v[186:189], v[124:127]
	v_mfma_f32_16x16x32_bf16 v[120:123], v[136:139], v[186:189], v[120:123]
	v_mfma_f32_16x16x32_bf16 v[108:111], v[128:131], v[194:197], v[108:111]
	v_mfma_f32_16x16x32_bf16 v[104:107], v[136:139], v[194:197], v[104:107]
	v_mfma_f32_16x16x32_bf16 v[92:95], v[128:131], v[202:205], v[92:95]
	v_mfma_f32_16x16x32_bf16 v[88:91], v[136:139], v[202:205], v[88:91]
	v_mfma_f32_16x16x32_bf16 v[76:79], v[128:131], v[210:213], v[76:79]
	v_mfma_f32_16x16x32_bf16 v[72:75], v[136:139], v[210:213], v[72:75]
	v_mfma_f32_16x16x32_bf16 v[124:127], v[132:135], v[190:193], v[124:127]
	v_mfma_f32_16x16x32_bf16 v[120:123], v[140:143], v[190:193], v[120:123]
	v_mfma_f32_16x16x32_bf16 v[108:111], v[132:135], v[198:201], v[108:111]
	v_mfma_f32_16x16x32_bf16 v[104:107], v[140:143], v[198:201], v[104:107]
	v_mfma_f32_16x16x32_bf16 v[92:95], v[132:135], v[206:209], v[92:95]
	v_mfma_f32_16x16x32_bf16 v[88:91], v[140:143], v[206:209], v[88:91]
	v_mfma_f32_16x16x32_bf16 v[76:79], v[132:135], v[214:217], v[76:79]
	v_mfma_f32_16x16x32_bf16 v[72:75], v[140:143], v[214:217], v[72:75]
	v_mfma_f32_16x16x32_bf16 v[116:119], v[160:163], v[186:189], v[116:119]
	v_mfma_f32_16x16x32_bf16 v[112:115], v[168:171], v[186:189], v[112:115]
	v_mfma_f32_16x16x32_bf16 v[100:103], v[160:163], v[194:197], v[100:103]
	v_mfma_f32_16x16x32_bf16 v[96:99], v[168:171], v[194:197], v[96:99]
	v_mfma_f32_16x16x32_bf16 v[84:87], v[160:163], v[202:205], v[84:87]
	v_mfma_f32_16x16x32_bf16 v[80:83], v[168:171], v[202:205], v[80:83]
	v_mfma_f32_16x16x32_bf16 v[68:71], v[160:163], v[210:213], v[68:71]
	v_mfma_f32_16x16x32_bf16 v[64:67], v[168:171], v[210:213], v[64:67]
	v_mfma_f32_16x16x32_bf16 v[116:119], v[164:167], v[190:193], v[116:119]
	v_mfma_f32_16x16x32_bf16 v[112:115], v[172:175], v[190:193], v[112:115]
	v_mfma_f32_16x16x32_bf16 v[100:103], v[164:167], v[198:201], v[100:103]
	v_mfma_f32_16x16x32_bf16 v[96:99], v[172:175], v[198:201], v[96:99]
	v_mfma_f32_16x16x32_bf16 v[84:87], v[164:167], v[206:209], v[84:87]
	v_mfma_f32_16x16x32_bf16 v[80:83], v[172:175], v[206:209], v[80:83]
	v_mfma_f32_16x16x32_bf16 v[68:71], v[164:167], v[214:217], v[68:71]
	v_mfma_f32_16x16x32_bf16 v[64:67], v[172:175], v[214:217], v[64:67]
	s_barrier
; #define PG8_STAGE(bufoff, gbase, voff) do { _Pragma("unroll") for (int _i = 0; _i < 2; ++_i) \
;         __builtin_amdgcn_global_load_lds((const unsigned*)((const char*)(gbase) + (voff)[_i]), (LAS unsigned*)(lds + (bufoff) + ldsw + _i * 8192), 16, 0, 0); } while (0)
; #define PG8_LDA(dst, b, h) do { _Pragma("unroll") for (int m = 0; m < 4; ++m) _Pragma("unroll") for (int k = 0; k < 2; ++k) dst[m][k] = *(const LAS bf16x8*)(lds + PG8_SA(b, h) + aoff + m * 2048 + k * 1024); } while (0)
; #define PG8_MMA(ai, bj, At, Bt) do { __builtin_amdgcn_s_setprio(1); _Pragma("unroll") for (int m = 0; m < 4; ++m) _Pragma("unroll") for (int n = 0; n < 2; ++n) _Pragma("unroll") for (int k = 0; k < 2; ++k) \
;         acc[ai][bj][m][n] = __builtin_amdgcn_mfma_f32_16x16x32_bf16(Bt[n][k], At[m][k], acc[ai][bj][m][n], 0, 0, 0); __builtin_amdgcn_s_setprio(0); } while (0)
; #define PG8_WAIT_V(n) asm volatile("s_waitcnt vmcnt(" #n ")" ::: "memory")
; #define PG8_WAIT_L(n) asm volatile("s_waitcnt lgkmcnt(" #n ")" ::: "memory")
; #define PG8_BAR __builtin_amdgcn_s_barrier()
; #define PG8_SCHED __builtin_amdgcn_sched_barrier(0)
; template <class Epi>
; __device__ __forceinline__ void gemm_phase(LAS unsigned char* lds, const Gemm g, const StaticOrder& S, const Epi& E) {
;     ...
;             PG8_LDA(At, 1, 1); PG8_STAGE(PG8_SB(1, 0), b3, voffB); PG8_STAGE(PG8_SB(1, 1), b3 + hstepB, voffB); PG8_STAGE(PG8_SA(1, 0), a3, voffA);
;             PG8_WAIT_V(8); PG8_WAIT_L(0); PG8_BAR; PG8_MMA(1, 0, At, B0); PG8_MMA(1, 1, At, B1); PG8_BAR; PG8_SCHED;
;         }
;         if (wr == 0) PG8_BAR;
	s_add_i32 s38, s78, s42
	v_lshl_add_u64 v[178:179], v[178:179], 0, s[16:17]
	s_mov_b32 m0, s38
	ds_read_b128 v[186:189], v184 offset:49152
	ds_read_b128 v[190:193], v184 offset:50176
	ds_read_b128 v[194:197], v184 offset:51200
	ds_read_b128 v[198:201], v184 offset:52224
	ds_read_b128 v[202:205], v184 offset:53248
	ds_read_b128 v[206:209], v184 offset:54272
	ds_read_b128 v[210:213], v184 offset:55296
	ds_read_b128 v[214:217], v184 offset:56320
	global_load_lds_dwordx4 v[178:179], off
	s_add_i32 m0, s38, 0x2000
	s_add_u32 s34, s34, 0xb0080
	v_lshl_add_u64 v[178:179], v[218:219], 0, s[16:17]
	s_addc_u32 s35, s35, 0
	s_add_i32 s38, s79, s42
	global_load_lds_dwordx4 v[178:179], off
	v_lshl_add_u64 v[178:179], s[34:35], 0, v[146:147]
	s_mov_b32 m0, s38
	s_nop 0
	global_load_lds_dwordx4 v[178:179], off
	v_lshl_add_u64 v[178:179], s[34:35], 0, v[150:151]
	s_add_i32 m0, s38, 0x2000
	s_nop 0
	global_load_lds_dwordx4 v[178:179], off
	v_lshl_add_u64 v[178:179], v[220:221], 0, s[16:17]
	s_mov_b32 m0, s62
	s_nop 0
	global_load_lds_dwordx4 v[178:179], off
	v_lshl_add_u64 v[178:179], v[222:223], 0, s[16:17]
	s_mov_b32 m0, s63
	s_nop 0
	global_load_lds_dwordx4 v[178:179], off
	s_waitcnt vmcnt(8)
	s_waitcnt lgkmcnt(0)
	s_barrier
	s_waitcnt lgkmcnt(0)
	v_mfma_f32_16x16x32_bf16 v[60:63], v[128:131], v[186:189], v[60:63]
	v_mfma_f32_16x16x32_bf16 v[56:59], v[136:139], v[186:189], v[56:59]
	v_mfma_f32_16x16x32_bf16 v[44:47], v[128:131], v[194:197], v[44:47]
	v_mfma_f32_16x16x32_bf16 v[40:43], v[136:139], v[194:197], v[40:43]
	v_mfma_f32_16x16x32_bf16 v[28:31], v[128:131], v[202:205], v[28:31]
	v_mfma_f32_16x16x32_bf16 v[24:27], v[136:139], v[202:205], v[24:27]
	v_mfma_f32_16x16x32_bf16 v[12:15], v[128:131], v[210:213], v[12:15]
	v_mfma_f32_16x16x32_bf16 v[8:11], v[136:139], v[210:213], v[8:11]
	v_mfma_f32_16x16x32_bf16 v[60:63], v[132:135], v[190:193], v[60:63]
	v_mfma_f32_16x16x32_bf16 v[56:59], v[140:143], v[190:193], v[56:59]
	v_mfma_f32_16x16x32_bf16 v[44:47], v[132:135], v[198:201], v[44:47]
	v_mfma_f32_16x16x32_bf16 v[40:43], v[140:143], v[198:201], v[40:43]
	v_mfma_f32_16x16x32_bf16 v[28:31], v[132:135], v[206:209], v[28:31]
	v_mfma_f32_16x16x32_bf16 v[24:27], v[140:143], v[206:209], v[24:27]
	v_mfma_f32_16x16x32_bf16 v[12:15], v[132:135], v[214:217], v[12:15]
	v_mfma_f32_16x16x32_bf16 v[8:11], v[140:143], v[214:217], v[8:11]
	v_mfma_f32_16x16x32_bf16 v[52:55], v[160:163], v[186:189], v[52:55]
	v_mfma_f32_16x16x32_bf16 v[48:51], v[168:171], v[186:189], v[48:51]
	v_mfma_f32_16x16x32_bf16 v[36:39], v[160:163], v[194:197], v[36:39]
	v_mfma_f32_16x16x32_bf16 v[32:35], v[168:171], v[194:197], v[32:35]
	v_mfma_f32_16x16x32_bf16 v[20:23], v[160:163], v[202:205], v[20:23]
	v_mfma_f32_16x16x32_bf16 v[16:19], v[168:171], v[202:205], v[16:19]
	v_mfma_f32_16x16x32_bf16 v[4:7], v[160:163], v[210:213], v[4:7]
	v_mfma_f32_16x16x32_bf16 v[0:3], v[168:171], v[210:213], v[0:3]
	v_mfma_f32_16x16x32_bf16 v[52:55], v[164:167], v[190:193], v[52:55]
	v_mfma_f32_16x16x32_bf16 v[48:51], v[172:175], v[190:193], v[48:51]
	v_mfma_f32_16x16x32_bf16 v[36:39], v[164:167], v[198:201], v[36:39]
	v_mfma_f32_16x16x32_bf16 v[32:35], v[172:175], v[198:201], v[32:35]
	v_mfma_f32_16x16x32_bf16 v[20:23], v[164:167], v[206:209], v[20:23]
	v_mfma_f32_16x16x32_bf16 v[16:19], v[172:175], v[206:209], v[16:19]
	v_mfma_f32_16x16x32_bf16 v[4:7], v[164:167], v[214:217], v[4:7]
	v_mfma_f32_16x16x32_bf16 v[0:3], v[172:175], v[214:217], v[0:3]
	s_barrier
	s_add_i32 s77, s77, 2
	s_add_u32 s0, s0, 0x100
	s_addc_u32 s1, s1, 0
	s_add_u32 s75, s75, 0x100
	s_addc_u32 s76, s76, 0
	s_cmp_gt_u32 s77, 41
	s_cbranch_scc0 .LBB0_792
	s_and_b64 vcc, exec, s[18:19]
	s_cbranch_vccz .LBB0_795
	s_barrier

; #define PG8_STAGE(bufoff, gbase, voff) do { _Pragma("unroll") for (int _i = 0; _i < 2; ++_i) \
;         __builtin_amdgcn_global_load_lds((const unsigned*)((const char*)(gbase) + (voff)[_i]), (LAS unsigned*)(lds + (bufoff) + ldsw + _i * 8192), 16, 0, 0); } while (0)
; #define PG8_LDA(dst, b, h) do { _Pragma("unroll") for (int m = 0; m < 4; ++m) _Pragma("unroll") for (int k = 0; k < 2; ++k) dst[m][k] = *(const LAS bf16x8*)(lds + PG8_SA(b, h) + aoff + m * 2048 + k * 1024); } while (0)
; #define PG8_LDB(dst, b, h) do { _Pragma("unroll") for (int n = 0; n < 2; ++n) _Pragma("unroll") for (int k = 0; k < 2; ++k) dst[n][k] = *(const LAS bf16x8*)(lds + PG8_SB(b, h) + boff + n * 2048 + k * 1024); } while (0)
; #define PG8_MMA(ai, bj, At, Bt) do { __builtin_amdgcn_s_setprio(1); _Pragma("unroll") for (int m = 0; m < 4; ++m) _Pragma("unroll") for (int n = 0; n < 2; ++n) _Pragma("unroll") for (int k = 0; k < 2; ++k) \
;         acc[ai][bj][m][n] = __builtin_amdgcn_mfma_f32_16x16x32_bf16(Bt[n][k], At[m][k], acc[ai][bj][m][n], 0, 0, 0); __builtin_amdgcn_s_setprio(0); } while (0)
; #define PG8_BAR __builtin_amdgcn_s_barrier()
; template <class Epi>
; __device__ __forceinline__ void gemm_phase(LAS unsigned char* lds, const Gemm g, const StaticOrder& S, const Epi& E) {
;     ...
;         const bool has_next = S.next(ui + 1, nxt);
;         const char* nA = has_next ? (const char*)g.A + (size_t)nxt.pm * tstepA : cA; const char* nB = has_next ? (const char*)g.Bt + (size_t)nxt.pn * tstepB : cB;
; #pragma nounroll
;         for (int t = 0; t < nt; t += 2) {
;             const bool last = (t == nt - 2);
;             const char* a1 = cA + (size_t)(t + 1) * kstep;
;             const char* a2 = last ? nA : cA + (size_t)(t + 2) * kstep; const char* b2 = last ? nB : cB + (size_t)(t + 2) * kstep;
;             const char* a3 = a2 + kstep; const char* b3 = b2 + kstep;
;             PG8_LDB(B0, 0, 0); PG8_LDB(B1, 0, 1); PG8_SCHED; PG8_LDA(At, 0, 0); PG8_STAGE(PG8_SA(1, 1), a1 + hstepA, voffA);
;             PG8_WAIT_V(8); PG8_WAIT_L(0); PG8_BAR; PG8_MMA(0, 0, At, B0); PG8_MMA(0, 1, At, B1); PG8_BAR; PG8_SCHED;
;             PG8_LDA(At, 0, 1); PG8_STAGE(PG8_SB(0, 0), b2, voffB); PG8_STAGE(PG8_SB(0, 1), b2 + hstepB, voffB); PG8_STAGE(PG8_SA(0, 0), a2, voffA);
;             PG8_WAIT_V(8); PG8_WAIT_L(0); PG8_BAR; PG8_MMA(1, 0, At, B0); PG8_MMA(1, 1, At, B1); PG8_BAR; PG8_SCHED;
.LBB0_888:
	s_ashr_i32 s43, s42, 31
	s_lshl_b64 s[52:53], s[42:43], 19
	s_add_u32 s52, s30, s52
	s_addc_u32 s53, s31, s53
	s_and_b64 s[54:55], s[4:5], exec
	s_cselect_b32 s7, s53, s57
	s_cselect_b32 s9, s52, s56
	s_ashr_i32 s39, s38, 31
	s_lshl_b64 s[54:55], s[38:39], 19
	s_add_u32 s54, s3, s54
	s_addc_u32 s55, s33, s55
	s_and_b64 s[64:65], s[4:5], exec
	s_cselect_b32 s39, s55, s63
	s_cselect_b32 s43, s54, s62
	s_add_u32 s56, s56, 0x40080
	s_addc_u32 s57, s57, 0
	s_add_u32 s83, s62, 0x100
	s_addc_u32 s84, s63, 0
	s_mov_b32 s85, -2
	s_waitcnt lgkmcnt(0)
	s_nop 0
	ds_read_b128 v[40:43], v208
	ds_read_b128 v[44:47], v208 offset:1024
	ds_read_b128 v[56:59], v208 offset:2048
	ds_read_b128 v[60:63], v208 offset:3072
	ds_read_b128 v[144:147], v209
	ds_read_b128 v[148:151], v209 offset:1024
	ds_read_b128 v[152:155], v209 offset:2048
	ds_read_b128 v[156:159], v209 offset:3072
	s_add_u32 s62, s56, 0xfffc0080
	s_addc_u32 s63, s57, -1
	s_cmp_eq_u32 s85, 12
	s_cselect_b32 s65, s7, s63
	s_cselect_b32 s64, s9, s62
	s_cselect_b32 s63, s39, s84
	s_cselect_b32 s62, s43, s83
	v_lshl_add_u64 v[218:219], s[56:57], 0, v[178:179]
	s_add_i32 m0, s69, 0xc000
	ds_read_b128 v[160:163], v210
	ds_read_b128 v[164:167], v210 offset:1024
	ds_read_b128 v[186:189], v210 offset:2048
	ds_read_b128 v[190:193], v210 offset:3072
	ds_read_b128 v[194:197], v210 offset:4096
	ds_read_b128 v[198:201], v210 offset:5120
	ds_read_b128 v[202:205], v210 offset:6144
	ds_read_b128 v[214:217], v210 offset:7168
	global_load_lds_dwordx4 v[218:219], off
	v_lshl_add_u64 v[218:219], s[56:57], 0, v[180:181]
	s_add_i32 m0, s69, 0xe000
	s_nop 0
	global_load_lds_dwordx4 v[218:219], off
	s_waitcnt vmcnt(8)
	s_waitcnt lgkmcnt(0)
	s_barrier
	s_waitcnt lgkmcnt(0)
	v_mfma_f32_16x16x32_bf16 v[140:143], v[40:43], v[160:163], 0
	v_mfma_f32_16x16x32_bf16 v[136:139], v[56:59], v[160:163], 0
	v_mfma_f32_16x16x32_bf16 v[124:127], v[40:43], v[186:189], 0
	v_mfma_f32_16x16x32_bf16 v[120:123], v[56:59], v[186:189], 0
	v_mfma_f32_16x16x32_bf16 v[108:111], v[40:43], v[194:197], 0
	v_mfma_f32_16x16x32_bf16 v[104:107], v[56:59], v[194:197], 0
	v_mfma_f32_16x16x32_bf16 v[92:95], v[40:43], v[202:205], 0
	v_mfma_f32_16x16x32_bf16 v[88:91], v[56:59], v[202:205], 0
	v_mfma_f32_16x16x32_bf16 v[140:143], v[44:47], v[164:167], v[140:143]
	v_mfma_f32_16x16x32_bf16 v[136:139], v[60:63], v[164:167], v[136:139]
	v_mfma_f32_16x16x32_bf16 v[124:127], v[44:47], v[190:193], v[124:127]
	v_mfma_f32_16x16x32_bf16 v[120:123], v[60:63], v[190:193], v[120:123]
	v_mfma_f32_16x16x32_bf16 v[108:111], v[44:47], v[198:201], v[108:111]
	v_mfma_f32_16x16x32_bf16 v[104:107], v[60:63], v[198:201], v[104:107]
	v_mfma_f32_16x16x32_bf16 v[92:95], v[44:47], v[214:217], v[92:95]
	v_mfma_f32_16x16x32_bf16 v[88:91], v[60:63], v[214:217], v[88:91]
	v_mfma_f32_16x16x32_bf16 v[132:135], v[144:147], v[160:163], 0
	v_mfma_f32_16x16x32_bf16 v[128:131], v[152:155], v[160:163], 0
	v_mfma_f32_16x16x32_bf16 v[116:119], v[144:147], v[186:189], 0
	v_mfma_f32_16x16x32_bf16 v[112:115], v[152:155], v[186:189], 0
	v_mfma_f32_16x16x32_bf16 v[100:103], v[144:147], v[194:197], 0
	v_mfma_f32_16x16x32_bf16 v[96:99], v[152:155], v[194:197], 0
	v_mfma_f32_16x16x32_bf16 v[84:87], v[144:147], v[202:205], 0
	v_mfma_f32_16x16x32_bf16 v[80:83], v[152:155], v[202:205], 0
	v_mfma_f32_16x16x32_bf16 v[132:135], v[148:151], v[164:167], v[132:135]
	v_mfma_f32_16x16x32_bf16 v[128:131], v[156:159], v[164:167], v[128:131]
	v_mfma_f32_16x16x32_bf16 v[116:119], v[148:151], v[190:193], v[116:119]
	v_mfma_f32_16x16x32_bf16 v[112:115], v[156:159], v[190:193], v[112:115]
	v_mfma_f32_16x16x32_bf16 v[100:103], v[148:151], v[198:201], v[100:103]
	v_mfma_f32_16x16x32_bf16 v[96:99], v[156:159], v[198:201], v[96:99]
	v_mfma_f32_16x16x32_bf16 v[84:87], v[148:151], v[214:217], v[84:87]
	v_mfma_f32_16x16x32_bf16 v[80:83], v[156:159], v[214:217], v[80:83]
	s_barrier
	s_add_i32 s86, s81, s68
	v_lshl_add_u64 v[218:219], s[62:63], 0, v[170:171]
	s_mov_b32 m0, s86
	ds_read_b128 v[160:163], v210 offset:16384
	ds_read_b128 v[164:167], v210 offset:17408
	ds_read_b128 v[186:189], v210 offset:18432
	ds_read_b128 v[190:193], v210 offset:19456
	ds_read_b128 v[194:197], v210 offset:20480
	ds_read_b128 v[198:201], v210 offset:21504
	ds_read_b128 v[202:205], v210 offset:22528
	ds_read_b128 v[214:217], v210 offset:23552
	global_load_lds_dwordx4 v[218:219], off
	s_add_i32 m0, s86, 0x2000
	s_add_u32 s86, s62, 0x40000
	v_lshl_add_u64 v[220:221], s[62:63], 0, v[174:175]
	s_addc_u32 s87, s63, 0
	s_add_i32 s88, s82, s68
	global_load_lds_dwordx4 v[220:221], off
	v_lshl_add_u64 v[222:223], s[86:87], 0, v[170:171]
	s_mov_b32 m0, s88
	v_lshl_add_u64 v[226:227], s[64:65], 0, v[172:173]
	global_load_lds_dwordx4 v[222:223], off
	v_lshl_add_u64 v[222:223], s[86:87], 0, v[174:175]
	s_add_i32 m0, s88, 0x2000
	s_nop 0
	global_load_lds_dwordx4 v[222:223], off
	v_lshl_add_u64 v[222:223], s[64:65], 0, v[168:169]
	s_mov_b32 m0, s69
	s_nop 0
	global_load_lds_dwordx4 v[222:223], off
	s_mov_b32 m0, s70
	s_nop 0
	global_load_lds_dwordx4 v[226:227], off
	s_waitcnt vmcnt(8)
	s_waitcnt lgkmcnt(0)
	s_barrier
; #define PG8_STAGE(bufoff, gbase, voff) do { _Pragma("unroll") for (int _i = 0; _i < 2; ++_i) \
;         __builtin_amdgcn_global_load_lds((const unsigned*)((const char*)(gbase) + (voff)[_i]), (LAS unsigned*)(lds + (bufoff) + ldsw + _i * 8192), 16, 0, 0); } while (0)
; #define PG8_LDA(dst, b, h) do { _Pragma("unroll") for (int m = 0; m < 4; ++m) _Pragma("unroll") for (int k = 0; k < 2; ++k) dst[m][k] = *(const LAS bf16x8*)(lds + PG8_SA(b, h) + aoff + m * 2048 + k * 1024); } while (0)
; #define PG8_LDB(dst, b, h) do { _Pragma("unroll") for (int n = 0; n < 2; ++n) _Pragma("unroll") for (int k = 0; k < 2; ++k) dst[n][k] = *(const LAS bf16x8*)(lds + PG8_SB(b, h) + boff + n * 2048 + k * 1024); } while (0)
; #define PG8_MMA(ai, bj, At, Bt) do { __builtin_amdgcn_s_setprio(1); _Pragma("unroll") for (int m = 0; m < 4; ++m) _Pragma("unroll") for (int n = 0; n < 2; ++n) _Pragma("unroll") for (int k = 0; k < 2; ++k) \
;         acc[ai][bj][m][n] = __builtin_amdgcn_mfma_f32_16x16x32_bf16(Bt[n][k], At[m][k], acc[ai][bj][m][n], 0, 0, 0); __builtin_amdgcn_s_setprio(0); } while (0)
; #define PG8_WAIT_V(n) asm volatile("s_waitcnt vmcnt(" #n ")" ::: "memory")
; #define PG8_WAIT_L(n) asm volatile("s_waitcnt lgkmcnt(" #n ")" ::: "memory")
; #define PG8_BAR __builtin_amdgcn_s_barrier()
; #define PG8_SCHED __builtin_amdgcn_sched_barrier(0)
; template <class Epi>
; __device__ __forceinline__ void gemm_phase(LAS unsigned char* lds, const Gemm g, const StaticOrder& S, const Epi& E) {
;     ...
;             PG8_WAIT_V(8); PG8_WAIT_L(0); PG8_BAR; PG8_MMA(1, 0, At, B0); PG8_MMA(1, 1, At, B1); PG8_BAR; PG8_SCHED;
;             PG8_LDB(B0, 1, 0); PG8_LDB(B1, 1, 1); PG8_SCHED; PG8_LDA(At, 1, 0); PG8_STAGE(PG8_SA(0, 1), a2 + hstepA, voffA);
;             PG8_WAIT_V(8); PG8_WAIT_L(0); PG8_BAR; PG8_MMA(0, 0, At, B0); PG8_MMA(0, 1, At, B1); PG8_BAR; PG8_SCHED;
;             PG8_LDA(At, 1, 1); PG8_STAGE(PG8_SB(1, 0), b3, voffB); PG8_STAGE(PG8_SB(1, 1), b3 + hstepB, voffB); PG8_STAGE(PG8_SA(1, 0), a3, voffA);
;             PG8_WAIT_V(8); PG8_WAIT_L(0); PG8_BAR; PG8_MMA(1, 0, At, B0); PG8_MMA(1, 1, At, B1); PG8_BAR; PG8_SCHED;
	s_waitcnt lgkmcnt(0)
	v_mfma_f32_16x16x32_bf16 v[76:79], v[40:43], v[160:163], 0
	v_mfma_f32_16x16x32_bf16 v[72:75], v[56:59], v[160:163], 0
	v_mfma_f32_16x16x32_bf16 v[52:55], v[40:43], v[186:189], 0
	v_mfma_f32_16x16x32_bf16 v[48:51], v[56:59], v[186:189], 0
	v_mfma_f32_16x16x32_bf16 v[28:31], v[40:43], v[194:197], 0
	v_mfma_f32_16x16x32_bf16 v[24:27], v[56:59], v[194:197], 0
	v_mfma_f32_16x16x32_bf16 v[12:15], v[40:43], v[202:205], 0
	v_mfma_f32_16x16x32_bf16 v[8:11], v[56:59], v[202:205], 0
	v_mfma_f32_16x16x32_bf16 v[76:79], v[44:47], v[164:167], v[76:79]
	v_mfma_f32_16x16x32_bf16 v[72:75], v[60:63], v[164:167], v[72:75]
	v_mfma_f32_16x16x32_bf16 v[52:55], v[44:47], v[190:193], v[52:55]
	v_mfma_f32_16x16x32_bf16 v[48:51], v[60:63], v[190:193], v[48:51]
	v_mfma_f32_16x16x32_bf16 v[28:31], v[44:47], v[198:201], v[28:31]
	v_mfma_f32_16x16x32_bf16 v[24:27], v[60:63], v[198:201], v[24:27]
	v_mfma_f32_16x16x32_bf16 v[12:15], v[44:47], v[214:217], v[12:15]
	v_mfma_f32_16x16x32_bf16 v[8:11], v[60:63], v[214:217], v[8:11]
	v_mfma_f32_16x16x32_bf16 v[36:39], v[144:147], v[186:189], 0
	v_mfma_f32_16x16x32_bf16 v[32:35], v[152:155], v[186:189], 0
	v_mfma_f32_16x16x32_bf16 v[20:23], v[144:147], v[194:197], 0
	v_mfma_f32_16x16x32_bf16 v[16:19], v[152:155], v[194:197], 0
	v_mfma_f32_16x16x32_bf16 v[4:7], v[144:147], v[202:205], 0
	v_mfma_f32_16x16x32_bf16 v[0:3], v[152:155], v[202:205], 0
	v_mfma_f32_16x16x32_bf16 v[40:43], v[144:147], v[160:163], 0
	v_mfma_f32_16x16x32_bf16 v[44:47], v[152:155], v[160:163], 0
	v_mfma_f32_16x16x32_bf16 v[36:39], v[148:151], v[190:193], v[36:39]
	v_mfma_f32_16x16x32_bf16 v[32:35], v[156:159], v[190:193], v[32:35]
	v_mfma_f32_16x16x32_bf16 v[20:23], v[148:151], v[198:201], v[20:23]
	v_mfma_f32_16x16x32_bf16 v[16:19], v[156:159], v[198:201], v[16:19]
	v_mfma_f32_16x16x32_bf16 v[4:7], v[148:151], v[214:217], v[4:7]
	v_mfma_f32_16x16x32_bf16 v[0:3], v[156:159], v[214:217], v[0:3]
	v_mfma_f32_16x16x32_bf16 v[40:43], v[148:151], v[164:167], v[40:43]
	v_mfma_f32_16x16x32_bf16 v[44:47], v[156:159], v[164:167], v[44:47]
	s_barrier
	s_add_i32 s86, 0, 0x18000
	s_add_i32 s87, 0, 0x1c000
	v_add_u32_e32 v68, s86, v207
	v_add_u32_e32 v156, s87, v207
	ds_read_b128 v[56:59], v68
	ds_read_b128 v[60:63], v68 offset:1024
	ds_read_b128 v[64:67], v68 offset:2048
	ds_read_b128 v[68:71], v68 offset:3072
	ds_read_b128 v[144:147], v156
	ds_read_b128 v[148:151], v156 offset:1024
	ds_read_b128 v[152:155], v156 offset:2048
	ds_read_b128 v[156:159], v156 offset:3072
	s_add_u32 s64, s64, 0x40000
	s_addc_u32 s65, s65, 0
	s_mov_b32 m0, s71
	v_lshl_add_u64 v[228:229], s[64:65], 0, v[168:169]
	ds_read_b128 v[160:163], v210 offset:32768
	ds_read_b128 v[164:167], v210 offset:33792
	ds_read_b128 v[186:189], v210 offset:34816
	ds_read_b128 v[190:193], v210 offset:35840
	ds_read_b128 v[194:197], v210 offset:36864
	ds_read_b128 v[198:201], v210 offset:37888
	ds_read_b128 v[202:205], v210 offset:38912
	ds_read_b128 v[214:217], v210 offset:39936
	global_load_lds_dwordx4 v[228:229], off
	v_lshl_add_u64 v[228:229], s[64:65], 0, v[172:173]
	s_mov_b32 m0, s72
	s_nop 0
	global_load_lds_dwordx4 v[228:229], off
	s_waitcnt vmcnt(8)
	s_waitcnt lgkmcnt(0)
	s_barrier
	s_waitcnt lgkmcnt(0)
	v_mfma_f32_16x16x32_bf16 v[140:143], v[56:59], v[160:163], v[140:143]
	v_mfma_f32_16x16x32_bf16 v[136:139], v[64:67], v[160:163], v[136:139]
	v_mfma_f32_16x16x32_bf16 v[124:127], v[56:59], v[186:189], v[124:127]
	v_mfma_f32_16x16x32_bf16 v[120:123], v[64:67], v[186:189], v[120:123]
	v_mfma_f32_16x16x32_bf16 v[108:111], v[56:59], v[194:197], v[108:111]
	v_mfma_f32_16x16x32_bf16 v[104:107], v[64:67], v[194:197], v[104:107]
	v_mfma_f32_16x16x32_bf16 v[92:95], v[56:59], v[202:205], v[92:95]
	v_mfma_f32_16x16x32_bf16 v[88:91], v[64:67], v[202:205], v[88:91]
	v_mfma_f32_16x16x32_bf16 v[140:143], v[60:63], v[164:167], v[140:143]
	v_mfma_f32_16x16x32_bf16 v[136:139], v[68:71], v[164:167], v[136:139]
	v_mfma_f32_16x16x32_bf16 v[124:127], v[60:63], v[190:193], v[124:127]
	v_mfma_f32_16x16x32_bf16 v[120:123], v[68:71], v[190:193], v[120:123]
	v_mfma_f32_16x16x32_bf16 v[108:111], v[60:63], v[198:201], v[108:111]
	v_mfma_f32_16x16x32_bf16 v[104:107], v[68:71], v[198:201], v[104:107]
	v_mfma_f32_16x16x32_bf16 v[92:95], v[60:63], v[214:217], v[92:95]
	v_mfma_f32_16x16x32_bf16 v[88:91], v[68:71], v[214:217], v[88:91]
	v_mfma_f32_16x16x32_bf16 v[132:135], v[144:147], v[160:163], v[132:135]
	v_mfma_f32_16x16x32_bf16 v[128:131], v[152:155], v[160:163], v[128:131]
	v_mfma_f32_16x16x32_bf16 v[116:119], v[144:147], v[186:189], v[116:119]
	v_mfma_f32_16x16x32_bf16 v[112:115], v[152:155], v[186:189], v[112:115]
	v_mfma_f32_16x16x32_bf16 v[100:103], v[144:147], v[194:197], v[100:103]
	v_mfma_f32_16x16x32_bf16 v[96:99], v[152:155], v[194:197], v[96:99]
	v_mfma_f32_16x16x32_bf16 v[84:87], v[144:147], v[202:205], v[84:87]
	v_mfma_f32_16x16x32_bf16 v[80:83], v[152:155], v[202:205], v[80:83]
	v_mfma_f32_16x16x32_bf16 v[132:135], v[148:151], v[164:167], v[132:135]
	v_mfma_f32_16x16x32_bf16 v[128:131], v[156:159], v[164:167], v[128:131]
	v_mfma_f32_16x16x32_bf16 v[116:119], v[148:151], v[190:193], v[116:119]
	v_mfma_f32_16x16x32_bf16 v[112:115], v[156:159], v[190:193], v[112:115]
	v_mfma_f32_16x16x32_bf16 v[100:103], v[148:151], v[198:201], v[100:103]
	v_mfma_f32_16x16x32_bf16 v[96:99], v[156:159], v[198:201], v[96:99]
	v_mfma_f32_16x16x32_bf16 v[84:87], v[148:151], v[214:217], v[84:87]
	v_mfma_f32_16x16x32_bf16 v[80:83], v[156:159], v[214:217], v[80:83]
	s_barrier
; #define PG8_STAGE(bufoff, gbase, voff) do { _Pragma("unroll") for (int _i = 0; _i < 2; ++_i) \
;         __builtin_amdgcn_global_load_lds((const unsigned*)((const char*)(gbase) + (voff)[_i]), (LAS unsigned*)(lds + (bufoff) + ldsw + _i * 8192), 16, 0, 0); } while (0)
; #define PG8_LDA(dst, b, h) do { _Pragma("unroll") for (int m = 0; m < 4; ++m) _Pragma("unroll") for (int k = 0; k < 2; ++k) dst[m][k] = *(const LAS bf16x8*)(lds + PG8_SA(b, h) + aoff + m * 2048 + k * 1024); } while (0)
; #define PG8_LDB(dst, b, h) do { _Pragma("unroll") for (int n = 0; n < 2; ++n) _Pragma("unroll") for (int k = 0; k < 2; ++k) dst[n][k] = *(const LAS bf16x8*)(lds + PG8_SB(b, h) + boff + n * 2048 + k * 1024); } while (0)
; #define PG8_MMA(ai, bj, At, Bt) do { __builtin_amdgcn_s_setprio(1); _Pragma("unroll") for (int m = 0; m < 4; ++m) _Pragma("unroll") for (int n = 0; n < 2; ++n) _Pragma("unroll") for (int k = 0; k < 2; ++k) \
;         acc[ai][bj][m][n] = __builtin_amdgcn_mfma_f32_16x16x32_bf16(Bt[n][k], At[m][k], acc[ai][bj][m][n], 0, 0, 0); __builtin_amdgcn_s_setprio(0); } while (0)
; #define PG8_WAIT_V(n) asm volatile("s_waitcnt vmcnt(" #n ")" ::: "memory")
; #define PG8_WAIT_L(n) asm volatile("s_waitcnt lgkmcnt(" #n ")" ::: "memory")
; template <class Epi>
; __device__ __forceinline__ void gemm_phase(LAS unsigned char* lds, const Gemm g, const StaticOrder& S, const Epi& E) {
;     ...
;         for (int t = 0; t < nt; t += 2) {
;             const bool last = (t == nt - 2);
;             const char* a1 = cA + (size_t)(t + 1) * kstep;
;             const char* a2 = last ? nA : cA + (size_t)(t + 2) * kstep; const char* b2 = last ? nB : cB + (size_t)(t + 2) * kstep;
;             const char* a3 = a2 + kstep; const char* b3 = b2 + kstep;
;             PG8_LDB(B0, 0, 0); PG8_LDB(B1, 0, 1); PG8_SCHED; PG8_LDA(At, 0, 0); PG8_STAGE(PG8_SA(1, 1), a1 + hstepA, voffA);
;             PG8_WAIT_V(8); PG8_WAIT_L(0); PG8_BAR; PG8_MMA(0, 0, At, B0); PG8_MMA(0, 1, At, B1); PG8_BAR; PG8_SCHED;
;     ...
;             PG8_WAIT_V(8); PG8_WAIT_L(0); PG8_BAR; PG8_MMA(0, 0, At, B0); PG8_MMA(0, 1, At, B1); PG8_BAR; PG8_SCHED;
;             PG8_LDA(At, 1, 1); PG8_STAGE(PG8_SB(1, 0), b3, voffB); PG8_STAGE(PG8_SB(1, 1), b3 + hstepB, voffB); PG8_STAGE(PG8_SA(1, 0), a3, voffA);
;             PG8_WAIT_V(8); PG8_WAIT_L(0); PG8_BAR; PG8_MMA(1, 0, At, B0); PG8_MMA(1, 1, At, B1); PG8_BAR; PG8_SCHED;
	s_add_i32 s64, s86, s68
	v_lshl_add_u64 v[218:219], v[218:219], 0, s[18:19]
	s_mov_b32 m0, s64
	ds_read_b128 v[160:163], v210 offset:49152
	ds_read_b128 v[164:167], v210 offset:50176
	ds_read_b128 v[186:189], v210 offset:51200
	ds_read_b128 v[190:193], v210 offset:52224
	ds_read_b128 v[194:197], v210 offset:53248
	ds_read_b128 v[198:201], v210 offset:54272
	ds_read_b128 v[202:205], v210 offset:55296
	ds_read_b128 v[214:217], v210 offset:56320
	global_load_lds_dwordx4 v[218:219], off
	s_add_i32 m0, s64, 0x2000
	s_add_u32 s62, s62, 0x40080
	v_lshl_add_u64 v[218:219], v[220:221], 0, s[18:19]
	s_addc_u32 s63, s63, 0
	s_add_i32 s64, s87, s68
	global_load_lds_dwordx4 v[218:219], off
	v_lshl_add_u64 v[218:219], s[62:63], 0, v[170:171]
	s_mov_b32 m0, s64
	s_nop 0
	global_load_lds_dwordx4 v[218:219], off
	v_lshl_add_u64 v[218:219], s[62:63], 0, v[174:175]
	s_add_i32 m0, s64, 0x2000
	s_nop 0
	global_load_lds_dwordx4 v[218:219], off
	v_lshl_add_u64 v[218:219], v[222:223], 0, s[18:19]
	s_mov_b32 m0, s76
	s_nop 0
	global_load_lds_dwordx4 v[218:219], off
	v_lshl_add_u64 v[218:219], v[226:227], 0, s[18:19]
	s_mov_b32 m0, s77
	s_nop 0
	global_load_lds_dwordx4 v[218:219], off
	s_waitcnt vmcnt(8)
	s_waitcnt lgkmcnt(0)
	s_barrier
	s_waitcnt lgkmcnt(0)
	v_mfma_f32_16x16x32_bf16 v[76:79], v[56:59], v[160:163], v[76:79]
	v_mfma_f32_16x16x32_bf16 v[72:75], v[64:67], v[160:163], v[72:75]
	v_mfma_f32_16x16x32_bf16 v[52:55], v[56:59], v[186:189], v[52:55]
	v_mfma_f32_16x16x32_bf16 v[48:51], v[64:67], v[186:189], v[48:51]
	v_mfma_f32_16x16x32_bf16 v[28:31], v[56:59], v[194:197], v[28:31]
	v_mfma_f32_16x16x32_bf16 v[24:27], v[64:67], v[194:197], v[24:27]
	v_mfma_f32_16x16x32_bf16 v[12:15], v[56:59], v[202:205], v[12:15]
	v_mfma_f32_16x16x32_bf16 v[8:11], v[64:67], v[202:205], v[8:11]
	v_mfma_f32_16x16x32_bf16 v[76:79], v[60:63], v[164:167], v[76:79]
	v_mfma_f32_16x16x32_bf16 v[72:75], v[68:71], v[164:167], v[72:75]
	v_mfma_f32_16x16x32_bf16 v[52:55], v[60:63], v[190:193], v[52:55]
	v_mfma_f32_16x16x32_bf16 v[48:51], v[68:71], v[190:193], v[48:51]
	v_mfma_f32_16x16x32_bf16 v[28:31], v[60:63], v[198:201], v[28:31]
	v_mfma_f32_16x16x32_bf16 v[24:27], v[68:71], v[198:201], v[24:27]
	v_mfma_f32_16x16x32_bf16 v[12:15], v[60:63], v[214:217], v[12:15]
	v_mfma_f32_16x16x32_bf16 v[8:11], v[68:71], v[214:217], v[8:11]
	v_mfma_f32_16x16x32_bf16 v[40:43], v[144:147], v[160:163], v[40:43]
	v_mfma_f32_16x16x32_bf16 v[68:71], v[148:151], v[164:167], v[40:43]
	v_mfma_f32_16x16x32_bf16 v[40:43], v[152:155], v[160:163], v[44:47]
	v_mfma_f32_16x16x32_bf16 v[36:39], v[144:147], v[186:189], v[36:39]
	v_mfma_f32_16x16x32_bf16 v[32:35], v[152:155], v[186:189], v[32:35]
	v_mfma_f32_16x16x32_bf16 v[20:23], v[144:147], v[194:197], v[20:23]
	v_mfma_f32_16x16x32_bf16 v[16:19], v[152:155], v[194:197], v[16:19]
	v_mfma_f32_16x16x32_bf16 v[4:7], v[144:147], v[202:205], v[4:7]
	v_mfma_f32_16x16x32_bf16 v[0:3], v[152:155], v[202:205], v[0:3]
	v_mfma_f32_16x16x32_bf16 v[64:67], v[156:159], v[164:167], v[40:43]
	v_mfma_f32_16x16x32_bf16 v[36:39], v[148:151], v[190:193], v[36:39]
	v_mfma_f32_16x16x32_bf16 v[32:35], v[156:159], v[190:193], v[32:35]
	v_mfma_f32_16x16x32_bf16 v[20:23], v[148:151], v[198:201], v[20:23]
	v_mfma_f32_16x16x32_bf16 v[16:19], v[156:159], v[198:201], v[16:19]
	v_mfma_f32_16x16x32_bf16 v[4:7], v[148:151], v[214:217], v[4:7]
	v_mfma_f32_16x16x32_bf16 v[0:3], v[156:159], v[214:217], v[0:3]
	s_barrier
	s_add_i32 s85, s85, 2
	s_add_u32 s56, s56, 0x100
	s_addc_u32 s57, s57, 0
	s_add_u32 s83, s83, 0x100
	s_addc_u32 s84, s84, 0
	s_cmp_gt_u32 s85, 13
.LBB0_889:
	ds_read_b128 v[40:43], v208
	ds_read_b128 v[44:47], v208 offset:1024
	ds_read_b128 v[56:59], v208 offset:2048
	ds_read_b128 v[60:63], v208 offset:3072
	ds_read_b128 v[144:147], v209
	ds_read_b128 v[148:151], v209 offset:1024
	ds_read_b128 v[152:155], v209 offset:2048
	ds_read_b128 v[156:159], v209 offset:3072
	s_add_u32 s62, s56, 0xfffc0080
	s_addc_u32 s63, s57, -1
	s_cmp_eq_u32 s85, 12
	s_cselect_b32 s65, s7, s63
	s_cselect_b32 s64, s9, s62
	s_cselect_b32 s63, s39, s84
	s_cselect_b32 s62, s43, s83
	v_lshl_add_u64 v[218:219], s[56:57], 0, v[178:179]
	s_add_i32 m0, s69, 0xc000
	ds_read_b128 v[160:163], v210
	ds_read_b128 v[164:167], v210 offset:1024
	ds_read_b128 v[186:189], v210 offset:2048
	ds_read_b128 v[190:193], v210 offset:3072
	ds_read_b128 v[194:197], v210 offset:4096
	ds_read_b128 v[198:201], v210 offset:5120
	ds_read_b128 v[202:205], v210 offset:6144
	ds_read_b128 v[214:217], v210 offset:7168
	global_load_lds_dwordx4 v[218:219], off
	v_lshl_add_u64 v[218:219], s[56:57], 0, v[180:181]
	s_add_i32 m0, s69, 0xe000
	s_nop 0
	global_load_lds_dwordx4 v[218:219], off
	s_waitcnt vmcnt(8)
	s_waitcnt lgkmcnt(0)
	s_barrier
; #define PG8_STAGE(bufoff, gbase, voff) do { _Pragma("unroll") for (int _i = 0; _i < 2; ++_i) \
;         __builtin_amdgcn_global_load_lds((const unsigned*)((const char*)(gbase) + (voff)[_i]), (LAS unsigned*)(lds + (bufoff) + ldsw + _i * 8192), 16, 0, 0); } while (0)
; #define PG8_LDA(dst, b, h) do { _Pragma("unroll") for (int m = 0; m < 4; ++m) _Pragma("unroll") for (int k = 0; k < 2; ++k) dst[m][k] = *(const LAS bf16x8*)(lds + PG8_SA(b, h) + aoff + m * 2048 + k * 1024); } while (0)
; #define PG8_LDB(dst, b, h) do { _Pragma("unroll") for (int n = 0; n < 2; ++n) _Pragma("unroll") for (int k = 0; k < 2; ++k) dst[n][k] = *(const LAS bf16x8*)(lds + PG8_SB(b, h) + boff + n * 2048 + k * 1024); } while (0)
; #define PG8_MMA(ai, bj, At, Bt) do { __builtin_amdgcn_s_setprio(1); _Pragma("unroll") for (int m = 0; m < 4; ++m) _Pragma("unroll") for (int n = 0; n < 2; ++n) _Pragma("unroll") for (int k = 0; k < 2; ++k) \
;         acc[ai][bj][m][n] = __builtin_amdgcn_mfma_f32_16x16x32_bf16(Bt[n][k], At[m][k], acc[ai][bj][m][n], 0, 0, 0); __builtin_amdgcn_s_setprio(0); } while (0)
; #define PG8_WAIT_V(n) asm volatile("s_waitcnt vmcnt(" #n ")" ::: "memory")
; #define PG8_WAIT_L(n) asm volatile("s_waitcnt lgkmcnt(" #n ")" ::: "memory")
; #define PG8_BAR __builtin_amdgcn_s_barrier()
; #define PG8_SCHED __builtin_amdgcn_sched_barrier(0)
; template <class Epi>
; __device__ __forceinline__ void gemm_phase(LAS unsigned char* lds, const Gemm g, const StaticOrder& S, const Epi& E) {
;     ...
;             PG8_WAIT_V(8); PG8_WAIT_L(0); PG8_BAR; PG8_MMA(0, 0, At, B0); PG8_MMA(0, 1, At, B1); PG8_BAR; PG8_SCHED;
;             PG8_LDA(At, 0, 1); PG8_STAGE(PG8_SB(0, 0), b2, voffB); PG8_STAGE(PG8_SB(0, 1), b2 + hstepB, voffB); PG8_STAGE(PG8_SA(0, 0), a2, voffA);
;             PG8_WAIT_V(8); PG8_WAIT_L(0); PG8_BAR; PG8_MMA(1, 0, At, B0); PG8_MMA(1, 1, At, B1); PG8_BAR; PG8_SCHED;
;             PG8_LDB(B0, 1, 0); PG8_LDB(B1, 1, 1); PG8_SCHED; PG8_LDA(At, 1, 0); PG8_STAGE(PG8_SA(0, 1), a2 + hstepA, voffA);
;             PG8_WAIT_V(8); PG8_WAIT_L(0); PG8_BAR; PG8_MMA(0, 0, At, B0); PG8_MMA(0, 1, At, B1); PG8_BAR; PG8_SCHED;
	s_waitcnt lgkmcnt(0)
	v_mfma_f32_16x16x32_bf16 v[140:143], v[40:43], v[160:163], v[140:143]
	v_mfma_f32_16x16x32_bf16 v[136:139], v[56:59], v[160:163], v[136:139]
	v_mfma_f32_16x16x32_bf16 v[124:127], v[40:43], v[186:189], v[124:127]
	v_mfma_f32_16x16x32_bf16 v[120:123], v[56:59], v[186:189], v[120:123]
	v_mfma_f32_16x16x32_bf16 v[108:111], v[40:43], v[194:197], v[108:111]
	v_mfma_f32_16x16x32_bf16 v[104:107], v[56:59], v[194:197], v[104:107]
	v_mfma_f32_16x16x32_bf16 v[92:95], v[40:43], v[202:205], v[92:95]
	v_mfma_f32_16x16x32_bf16 v[88:91], v[56:59], v[202:205], v[88:91]
	v_mfma_f32_16x16x32_bf16 v[140:143], v[44:47], v[164:167], v[140:143]
	v_mfma_f32_16x16x32_bf16 v[136:139], v[60:63], v[164:167], v[136:139]
	v_mfma_f32_16x16x32_bf16 v[124:127], v[44:47], v[190:193], v[124:127]
	v_mfma_f32_16x16x32_bf16 v[120:123], v[60:63], v[190:193], v[120:123]
	v_mfma_f32_16x16x32_bf16 v[108:111], v[44:47], v[198:201], v[108:111]
	v_mfma_f32_16x16x32_bf16 v[104:107], v[60:63], v[198:201], v[104:107]
	v_mfma_f32_16x16x32_bf16 v[92:95], v[44:47], v[214:217], v[92:95]
	v_mfma_f32_16x16x32_bf16 v[88:91], v[60:63], v[214:217], v[88:91]
	v_mfma_f32_16x16x32_bf16 v[132:135], v[144:147], v[160:163], v[132:135]
	v_mfma_f32_16x16x32_bf16 v[128:131], v[152:155], v[160:163], v[128:131]
	v_mfma_f32_16x16x32_bf16 v[116:119], v[144:147], v[186:189], v[116:119]
	v_mfma_f32_16x16x32_bf16 v[112:115], v[152:155], v[186:189], v[112:115]
	v_mfma_f32_16x16x32_bf16 v[100:103], v[144:147], v[194:197], v[100:103]
	v_mfma_f32_16x16x32_bf16 v[96:99], v[152:155], v[194:197], v[96:99]
	v_mfma_f32_16x16x32_bf16 v[84:87], v[144:147], v[202:205], v[84:87]
	v_mfma_f32_16x16x32_bf16 v[80:83], v[152:155], v[202:205], v[80:83]
	v_mfma_f32_16x16x32_bf16 v[132:135], v[148:151], v[164:167], v[132:135]
	v_mfma_f32_16x16x32_bf16 v[128:131], v[156:159], v[164:167], v[128:131]
	v_mfma_f32_16x16x32_bf16 v[116:119], v[148:151], v[190:193], v[116:119]
	v_mfma_f32_16x16x32_bf16 v[112:115], v[156:159], v[190:193], v[112:115]
	v_mfma_f32_16x16x32_bf16 v[100:103], v[148:151], v[198:201], v[100:103]
	v_mfma_f32_16x16x32_bf16 v[96:99], v[156:159], v[198:201], v[96:99]
	v_mfma_f32_16x16x32_bf16 v[84:87], v[148:151], v[214:217], v[84:87]
	v_mfma_f32_16x16x32_bf16 v[80:83], v[156:159], v[214:217], v[80:83]
	s_barrier
	s_add_i32 s86, s81, s68
	v_lshl_add_u64 v[218:219], s[62:63], 0, v[170:171]
	s_mov_b32 m0, s86
	ds_read_b128 v[160:163], v210 offset:16384
	ds_read_b128 v[164:167], v210 offset:17408
	ds_read_b128 v[186:189], v210 offset:18432
	ds_read_b128 v[190:193], v210 offset:19456
	ds_read_b128 v[194:197], v210 offset:20480
	ds_read_b128 v[198:201], v210 offset:21504
	ds_read_b128 v[202:205], v210 offset:22528
	ds_read_b128 v[214:217], v210 offset:23552
	global_load_lds_dwordx4 v[218:219], off
	s_add_i32 m0, s86, 0x2000
	s_add_u32 s86, s62, 0x40000
	v_lshl_add_u64 v[220:221], s[62:63], 0, v[174:175]
	s_addc_u32 s87, s63, 0
	s_add_i32 s88, s82, s68
	global_load_lds_dwordx4 v[220:221], off
	v_lshl_add_u64 v[222:223], s[86:87], 0, v[170:171]
	s_mov_b32 m0, s88
	v_lshl_add_u64 v[226:227], s[64:65], 0, v[172:173]
	global_load_lds_dwordx4 v[222:223], off
	v_lshl_add_u64 v[222:223], s[86:87], 0, v[174:175]
	s_add_i32 m0, s88, 0x2000
	s_nop 0
	global_load_lds_dwordx4 v[222:223], off
	v_lshl_add_u64 v[222:223], s[64:65], 0, v[168:169]
	s_mov_b32 m0, s69
	s_nop 0
	global_load_lds_dwordx4 v[222:223], off
	s_mov_b32 m0, s70
	s_nop 0
	global_load_lds_dwordx4 v[226:227], off
	s_waitcnt vmcnt(8)
	s_waitcnt lgkmcnt(0)
	s_barrier
	s_waitcnt lgkmcnt(0)
	v_mfma_f32_16x16x32_bf16 v[76:79], v[40:43], v[160:163], v[76:79]
	v_mfma_f32_16x16x32_bf16 v[72:75], v[56:59], v[160:163], v[72:75]
	v_mfma_f32_16x16x32_bf16 v[52:55], v[40:43], v[186:189], v[52:55]
	v_mfma_f32_16x16x32_bf16 v[48:51], v[56:59], v[186:189], v[48:51]
	v_mfma_f32_16x16x32_bf16 v[28:31], v[40:43], v[194:197], v[28:31]
	v_mfma_f32_16x16x32_bf16 v[24:27], v[56:59], v[194:197], v[24:27]
	v_mfma_f32_16x16x32_bf16 v[12:15], v[40:43], v[202:205], v[12:15]
	v_mfma_f32_16x16x32_bf16 v[8:11], v[56:59], v[202:205], v[8:11]
	v_mfma_f32_16x16x32_bf16 v[76:79], v[44:47], v[164:167], v[76:79]
	v_mfma_f32_16x16x32_bf16 v[72:75], v[60:63], v[164:167], v[72:75]
	v_mfma_f32_16x16x32_bf16 v[52:55], v[44:47], v[190:193], v[52:55]
	v_mfma_f32_16x16x32_bf16 v[48:51], v[60:63], v[190:193], v[48:51]
	v_mfma_f32_16x16x32_bf16 v[28:31], v[44:47], v[198:201], v[28:31]
	v_mfma_f32_16x16x32_bf16 v[24:27], v[60:63], v[198:201], v[24:27]
	v_mfma_f32_16x16x32_bf16 v[12:15], v[44:47], v[214:217], v[12:15]
	v_mfma_f32_16x16x32_bf16 v[8:11], v[60:63], v[214:217], v[8:11]
	v_mfma_f32_16x16x32_bf16 v[36:39], v[144:147], v[186:189], v[36:39]
	v_mfma_f32_16x16x32_bf16 v[32:35], v[152:155], v[186:189], v[32:35]
	v_mfma_f32_16x16x32_bf16 v[20:23], v[144:147], v[194:197], v[20:23]
	v_mfma_f32_16x16x32_bf16 v[16:19], v[152:155], v[194:197], v[16:19]
	v_mfma_f32_16x16x32_bf16 v[4:7], v[144:147], v[202:205], v[4:7]
	v_mfma_f32_16x16x32_bf16 v[0:3], v[152:155], v[202:205], v[0:3]
	v_mfma_f32_16x16x32_bf16 v[40:43], v[144:147], v[160:163], v[68:71]
	v_mfma_f32_16x16x32_bf16 v[44:47], v[152:155], v[160:163], v[64:67]
	v_mfma_f32_16x16x32_bf16 v[36:39], v[148:151], v[190:193], v[36:39]
	v_mfma_f32_16x16x32_bf16 v[32:35], v[156:159], v[190:193], v[32:35]
	v_mfma_f32_16x16x32_bf16 v[20:23], v[148:151], v[198:201], v[20:23]
	v_mfma_f32_16x16x32_bf16 v[16:19], v[156:159], v[198:201], v[16:19]
	v_mfma_f32_16x16x32_bf16 v[4:7], v[148:151], v[214:217], v[4:7]
	v_mfma_f32_16x16x32_bf16 v[0:3], v[156:159], v[214:217], v[0:3]
	v_mfma_f32_16x16x32_bf16 v[40:43], v[148:151], v[164:167], v[40:43]
	v_mfma_f32_16x16x32_bf16 v[44:47], v[156:159], v[164:167], v[44:47]
	s_barrier
; #define PG8_STAGE(bufoff, gbase, voff) do { _Pragma("unroll") for (int _i = 0; _i < 2; ++_i) \
;         __builtin_amdgcn_global_load_lds((const unsigned*)((const char*)(gbase) + (voff)[_i]), (LAS unsigned*)(lds + (bufoff) + ldsw + _i * 8192), 16, 0, 0); } while (0)
; #define PG8_LDA(dst, b, h) do { _Pragma("unroll") for (int m = 0; m < 4; ++m) _Pragma("unroll") for (int k = 0; k < 2; ++k) dst[m][k] = *(const LAS bf16x8*)(lds + PG8_SA(b, h) + aoff + m * 2048 + k * 1024); } while (0)
; #define PG8_MMA(ai, bj, At, Bt) do { __builtin_amdgcn_s_setprio(1); _Pragma("unroll") for (int m = 0; m < 4; ++m) _Pragma("unroll") for (int n = 0; n < 2; ++n) _Pragma("unroll") for (int k = 0; k < 2; ++k) \
;         acc[ai][bj][m][n] = __builtin_amdgcn_mfma_f32_16x16x32_bf16(Bt[n][k], At[m][k], acc[ai][bj][m][n], 0, 0, 0); __builtin_amdgcn_s_setprio(0); } while (0)
; #define PG8_WAIT_V(n) asm volatile("s_waitcnt vmcnt(" #n ")" ::: "memory")
; #define PG8_WAIT_L(n) asm volatile("s_waitcnt lgkmcnt(" #n ")" ::: "memory")
; #define PG8_BAR __builtin_amdgcn_s_barrier()
; #define PG8_SCHED __builtin_amdgcn_sched_barrier(0)
; template <class Epi>
; __device__ __forceinline__ void gemm_phase(LAS unsigned char* lds, const Gemm g, const StaticOrder& S, const Epi& E) {
;     ...
;             PG8_LDA(At, 1, 1); PG8_STAGE(PG8_SB(1, 0), b3, voffB); PG8_STAGE(PG8_SB(1, 1), b3 + hstepB, voffB); PG8_STAGE(PG8_SA(1, 0), a3, voffA);
;             PG8_WAIT_V(8); PG8_WAIT_L(0); PG8_BAR; PG8_MMA(1, 0, At, B0); PG8_MMA(1, 1, At, B1); PG8_BAR; PG8_SCHED;
	s_add_i32 s86, 0, 0x18000
	s_add_i32 s87, 0, 0x1c000
	v_add_u32_e32 v68, s86, v207
	v_add_u32_e32 v156, s87, v207
	ds_read_b128 v[56:59], v68
	ds_read_b128 v[60:63], v68 offset:1024
	ds_read_b128 v[64:67], v68 offset:2048
	ds_read_b128 v[68:71], v68 offset:3072
	ds_read_b128 v[144:147], v156
	ds_read_b128 v[148:151], v156 offset:1024
	ds_read_b128 v[152:155], v156 offset:2048
	ds_read_b128 v[156:159], v156 offset:3072
	s_add_u32 s64, s64, 0x40000
	s_addc_u32 s65, s65, 0
	s_mov_b32 m0, s71
	v_lshl_add_u64 v[228:229], s[64:65], 0, v[168:169]
	ds_read_b128 v[160:163], v210 offset:32768
	ds_read_b128 v[164:167], v210 offset:33792
	ds_read_b128 v[186:189], v210 offset:34816
	ds_read_b128 v[190:193], v210 offset:35840
	ds_read_b128 v[194:197], v210 offset:36864
	ds_read_b128 v[198:201], v210 offset:37888
	ds_read_b128 v[202:205], v210 offset:38912
	ds_read_b128 v[214:217], v210 offset:39936
	global_load_lds_dwordx4 v[228:229], off
	v_lshl_add_u64 v[228:229], s[64:65], 0, v[172:173]
	s_mov_b32 m0, s72
	s_nop 0
	global_load_lds_dwordx4 v[228:229], off
	s_waitcnt vmcnt(8)
	s_waitcnt lgkmcnt(0)
	s_barrier
	s_waitcnt lgkmcnt(0)
	v_mfma_f32_16x16x32_bf16 v[140:143], v[56:59], v[160:163], v[140:143]
	v_mfma_f32_16x16x32_bf16 v[136:139], v[64:67], v[160:163], v[136:139]
	v_mfma_f32_16x16x32_bf16 v[124:127], v[56:59], v[186:189], v[124:127]
	v_mfma_f32_16x16x32_bf16 v[120:123], v[64:67], v[186:189], v[120:123]
	v_mfma_f32_16x16x32_bf16 v[108:111], v[56:59], v[194:197], v[108:111]
	v_mfma_f32_16x16x32_bf16 v[104:107], v[64:67], v[194:197], v[104:107]
	v_mfma_f32_16x16x32_bf16 v[92:95], v[56:59], v[202:205], v[92:95]
	v_mfma_f32_16x16x32_bf16 v[88:91], v[64:67], v[202:205], v[88:91]
	v_mfma_f32_16x16x32_bf16 v[140:143], v[60:63], v[164:167], v[140:143]
	v_mfma_f32_16x16x32_bf16 v[136:139], v[68:71], v[164:167], v[136:139]
	v_mfma_f32_16x16x32_bf16 v[124:127], v[60:63], v[190:193], v[124:127]
	v_mfma_f32_16x16x32_bf16 v[120:123], v[68:71], v[190:193], v[120:123]
	v_mfma_f32_16x16x32_bf16 v[108:111], v[60:63], v[198:201], v[108:111]
	v_mfma_f32_16x16x32_bf16 v[104:107], v[68:71], v[198:201], v[104:107]
	v_mfma_f32_16x16x32_bf16 v[92:95], v[60:63], v[214:217], v[92:95]
	v_mfma_f32_16x16x32_bf16 v[88:91], v[68:71], v[214:217], v[88:91]
	v_mfma_f32_16x16x32_bf16 v[132:135], v[144:147], v[160:163], v[132:135]
	v_mfma_f32_16x16x32_bf16 v[128:131], v[152:155], v[160:163], v[128:131]
	v_mfma_f32_16x16x32_bf16 v[116:119], v[144:147], v[186:189], v[116:119]
	v_mfma_f32_16x16x32_bf16 v[112:115], v[152:155], v[186:189], v[112:115]
	v_mfma_f32_16x16x32_bf16 v[100:103], v[144:147], v[194:197], v[100:103]
	v_mfma_f32_16x16x32_bf16 v[96:99], v[152:155], v[194:197], v[96:99]
	v_mfma_f32_16x16x32_bf16 v[84:87], v[144:147], v[202:205], v[84:87]
	v_mfma_f32_16x16x32_bf16 v[80:83], v[152:155], v[202:205], v[80:83]
	v_mfma_f32_16x16x32_bf16 v[132:135], v[148:151], v[164:167], v[132:135]
	v_mfma_f32_16x16x32_bf16 v[128:131], v[156:159], v[164:167], v[128:131]
	v_mfma_f32_16x16x32_bf16 v[116:119], v[148:151], v[190:193], v[116:119]
	v_mfma_f32_16x16x32_bf16 v[112:115], v[156:159], v[190:193], v[112:115]
	v_mfma_f32_16x16x32_bf16 v[100:103], v[148:151], v[198:201], v[100:103]
	v_mfma_f32_16x16x32_bf16 v[96:99], v[156:159], v[198:201], v[96:99]
	v_mfma_f32_16x16x32_bf16 v[84:87], v[148:151], v[214:217], v[84:87]
	v_mfma_f32_16x16x32_bf16 v[80:83], v[156:159], v[214:217], v[80:83]
	s_barrier
; #define PG8_MMA(ai, bj, At, Bt) do { __builtin_amdgcn_s_setprio(1); _Pragma("unroll") for (int m = 0; m < 4; ++m) _Pragma("unroll") for (int n = 0; n < 2; ++n) _Pragma("unroll") for (int k = 0; k < 2; ++k) \
;         acc[ai][bj][m][n] = __builtin_amdgcn_mfma_f32_16x16x32_bf16(Bt[n][k], At[m][k], acc[ai][bj][m][n], 0, 0, 0); __builtin_amdgcn_s_setprio(0); } while (0)
; #define PG8_WAIT_V(n) asm volatile("s_waitcnt vmcnt(" #n ")" ::: "memory")
; #define PG8_WAIT_L(n) asm volatile("s_waitcnt lgkmcnt(" #n ")" ::: "memory")
; #define PG8_BAR __builtin_amdgcn_s_barrier()
; #define PG8_SCHED __builtin_amdgcn_sched_barrier(0)
; template <class Epi>
; __device__ __forceinline__ void gemm_phase(LAS unsigned char* lds, const Gemm g, const StaticOrder& S, const Epi& E) {
;     ...
;             PG8_WAIT_V(8); PG8_WAIT_L(0); PG8_BAR; PG8_MMA(1, 0, At, B0); PG8_MMA(1, 1, At, B1); PG8_BAR; PG8_SCHED;
;         }
;         if (wr == 0) PG8_BAR;
	s_add_i32 s64, s86, s68
	v_lshl_add_u64 v[218:219], v[218:219], 0, s[18:19]
	s_mov_b32 m0, s64
	ds_read_b128 v[160:163], v210 offset:49152
	ds_read_b128 v[164:167], v210 offset:50176
	ds_read_b128 v[186:189], v210 offset:51200
	ds_read_b128 v[190:193], v210 offset:52224
	ds_read_b128 v[194:197], v210 offset:53248
	ds_read_b128 v[198:201], v210 offset:54272
	ds_read_b128 v[202:205], v210 offset:55296
	ds_read_b128 v[214:217], v210 offset:56320
	global_load_lds_dwordx4 v[218:219], off
	s_add_i32 m0, s64, 0x2000
	s_add_u32 s62, s62, 0x40080
	v_lshl_add_u64 v[218:219], v[220:221], 0, s[18:19]
	s_addc_u32 s63, s63, 0
	s_add_i32 s64, s87, s68
	global_load_lds_dwordx4 v[218:219], off
	v_lshl_add_u64 v[218:219], s[62:63], 0, v[170:171]
	s_mov_b32 m0, s64
	s_nop 0
	global_load_lds_dwordx4 v[218:219], off
	v_lshl_add_u64 v[218:219], s[62:63], 0, v[174:175]
	s_add_i32 m0, s64, 0x2000
	s_nop 0
	global_load_lds_dwordx4 v[218:219], off
	v_lshl_add_u64 v[218:219], v[222:223], 0, s[18:19]
	s_mov_b32 m0, s76
	s_nop 0
	global_load_lds_dwordx4 v[218:219], off
	v_lshl_add_u64 v[218:219], v[226:227], 0, s[18:19]
	s_mov_b32 m0, s77
	s_nop 0
	global_load_lds_dwordx4 v[218:219], off
	s_waitcnt vmcnt(8)
	s_waitcnt lgkmcnt(0)
	s_barrier
	s_waitcnt lgkmcnt(0)
	v_mfma_f32_16x16x32_bf16 v[76:79], v[56:59], v[160:163], v[76:79]
	v_mfma_f32_16x16x32_bf16 v[72:75], v[64:67], v[160:163], v[72:75]
	v_mfma_f32_16x16x32_bf16 v[52:55], v[56:59], v[186:189], v[52:55]
	v_mfma_f32_16x16x32_bf16 v[48:51], v[64:67], v[186:189], v[48:51]
	v_mfma_f32_16x16x32_bf16 v[28:31], v[56:59], v[194:197], v[28:31]
	v_mfma_f32_16x16x32_bf16 v[24:27], v[64:67], v[194:197], v[24:27]
	v_mfma_f32_16x16x32_bf16 v[12:15], v[56:59], v[202:205], v[12:15]
	v_mfma_f32_16x16x32_bf16 v[8:11], v[64:67], v[202:205], v[8:11]
	v_mfma_f32_16x16x32_bf16 v[76:79], v[60:63], v[164:167], v[76:79]
	v_mfma_f32_16x16x32_bf16 v[72:75], v[68:71], v[164:167], v[72:75]
	v_mfma_f32_16x16x32_bf16 v[52:55], v[60:63], v[190:193], v[52:55]
	v_mfma_f32_16x16x32_bf16 v[48:51], v[68:71], v[190:193], v[48:51]
	v_mfma_f32_16x16x32_bf16 v[28:31], v[60:63], v[198:201], v[28:31]
	v_mfma_f32_16x16x32_bf16 v[24:27], v[68:71], v[198:201], v[24:27]
	v_mfma_f32_16x16x32_bf16 v[12:15], v[60:63], v[214:217], v[12:15]
	v_mfma_f32_16x16x32_bf16 v[8:11], v[68:71], v[214:217], v[8:11]
	v_mfma_f32_16x16x32_bf16 v[40:43], v[144:147], v[160:163], v[40:43]
	v_mfma_f32_16x16x32_bf16 v[68:71], v[148:151], v[164:167], v[40:43]
	v_mfma_f32_16x16x32_bf16 v[40:43], v[152:155], v[160:163], v[44:47]
	v_mfma_f32_16x16x32_bf16 v[36:39], v[144:147], v[186:189], v[36:39]
	v_mfma_f32_16x16x32_bf16 v[32:35], v[152:155], v[186:189], v[32:35]
	v_mfma_f32_16x16x32_bf16 v[20:23], v[144:147], v[194:197], v[20:23]
	v_mfma_f32_16x16x32_bf16 v[16:19], v[152:155], v[194:197], v[16:19]
	v_mfma_f32_16x16x32_bf16 v[4:7], v[144:147], v[202:205], v[4:7]
	v_mfma_f32_16x16x32_bf16 v[0:3], v[152:155], v[202:205], v[0:3]
	v_mfma_f32_16x16x32_bf16 v[64:67], v[156:159], v[164:167], v[40:43]
	v_mfma_f32_16x16x32_bf16 v[36:39], v[148:151], v[190:193], v[36:39]
	v_mfma_f32_16x16x32_bf16 v[32:35], v[156:159], v[190:193], v[32:35]
	v_mfma_f32_16x16x32_bf16 v[20:23], v[148:151], v[198:201], v[20:23]
	v_mfma_f32_16x16x32_bf16 v[16:19], v[156:159], v[198:201], v[16:19]
	v_mfma_f32_16x16x32_bf16 v[4:7], v[148:151], v[214:217], v[4:7]
	v_mfma_f32_16x16x32_bf16 v[0:3], v[156:159], v[214:217], v[0:3]
	s_barrier
	s_add_i32 s85, s85, 2
	s_add_u32 s56, s56, 0x100
	s_addc_u32 s57, s57, 0
	s_add_u32 s83, s83, 0x100
	s_addc_u32 s84, s84, 0
	s_cmp_gt_u32 s85, 13
	s_cbranch_scc0 .LBB0_889
	s_and_b64 vcc, exec, s[22:23]
	s_cbranch_vccz .LBB0_892
	s_barrier

; #define PG8_STAGE(bufoff, gbase, voff) do { _Pragma("unroll") for (int _i = 0; _i < 2; ++_i) \
;         __builtin_amdgcn_global_load_lds((const unsigned*)((const char*)(gbase) + (voff)[_i]), (LAS unsigned*)(lds + (bufoff) + ldsw + _i * 8192), 16, 0, 0); } while (0)
; #define PG8_LDA(dst, b, h) do { _Pragma("unroll") for (int m = 0; m < 4; ++m) _Pragma("unroll") for (int k = 0; k < 2; ++k) dst[m][k] = *(const LAS bf16x8*)(lds + PG8_SA(b, h) + aoff + m * 2048 + k * 1024); } while (0)
; #define PG8_LDB(dst, b, h) do { _Pragma("unroll") for (int n = 0; n < 2; ++n) _Pragma("unroll") for (int k = 0; k < 2; ++k) dst[n][k] = *(const LAS bf16x8*)(lds + PG8_SB(b, h) + boff + n * 2048 + k * 1024); } while (0)
; #define PG8_MMA(ai, bj, At, Bt) do { __builtin_amdgcn_s_setprio(1); _Pragma("unroll") for (int m = 0; m < 4; ++m) _Pragma("unroll") for (int n = 0; n < 2; ++n) _Pragma("unroll") for (int k = 0; k < 2; ++k) \
;         acc[ai][bj][m][n] = __builtin_amdgcn_mfma_f32_16x16x32_bf16(Bt[n][k], At[m][k], acc[ai][bj][m][n], 0, 0, 0); __builtin_amdgcn_s_setprio(0); } while (0)
; #define PG8_BAR __builtin_amdgcn_s_barrier()
; template <class Epi>
; __device__ __forceinline__ void gemm_phase(LAS unsigned char* lds, const Gemm g, const StaticOrder& S, const Epi& E) {
;     ...
;         const bool has_next = S.next(ui + 1, nxt);
;         const char* nA = has_next ? (const char*)g.A + (size_t)nxt.pm * tstepA : cA; const char* nB = has_next ? (const char*)g.Bt + (size_t)nxt.pn * tstepB : cB;
; #pragma nounroll
;         for (int t = 0; t < nt; t += 2) {
;             const bool last = (t == nt - 2);
;             const char* a1 = cA + (size_t)(t + 1) * kstep;
;             const char* a2 = last ? nA : cA + (size_t)(t + 2) * kstep; const char* b2 = last ? nB : cB + (size_t)(t + 2) * kstep;
;             const char* a3 = a2 + kstep; const char* b3 = b2 + kstep;
;             PG8_LDB(B0, 0, 0); PG8_LDB(B1, 0, 1); PG8_SCHED; PG8_LDA(At, 0, 0); PG8_STAGE(PG8_SA(1, 1), a1 + hstepA, voffA);
;             PG8_WAIT_V(8); PG8_WAIT_L(0); PG8_BAR; PG8_MMA(0, 0, At, B0); PG8_MMA(0, 1, At, B1); PG8_BAR; PG8_SCHED;
;             PG8_LDA(At, 0, 1); PG8_STAGE(PG8_SB(0, 0), b2, voffB); PG8_STAGE(PG8_SB(0, 1), b2 + hstepB, voffB); PG8_STAGE(PG8_SA(0, 0), a2, voffA);
;             PG8_WAIT_V(8); PG8_WAIT_L(0); PG8_BAR; PG8_MMA(1, 0, At, B0); PG8_MMA(1, 1, At, B1); PG8_BAR; PG8_SCHED;
.LBB0_1017:
	s_ashr_i32 s35, s34, 31
	s_lshl_b64 s[38:39], s[34:35], 19
	s_add_u32 s38, s24, s38
	s_addc_u32 s39, s25, s39
	s_and_b64 s[42:43], s[4:5], exec
	s_cselect_b32 s7, s39, s55
	s_cselect_b32 s35, s38, s54
	s_ashr_i32 s23, s22, 31
	s_lshl_b64 s[42:43], s[22:23], 19
	s_add_u32 s42, s33, s42
	s_addc_u32 s43, s64, s43
	s_and_b64 s[62:63], s[4:5], exec
	s_cselect_b32 s23, s43, s57
	s_cselect_b32 s53, s42, s56
	s_add_u32 s54, s54, 0x40080
	s_addc_u32 s55, s55, 0
	s_add_u32 s83, s56, 0x100
	s_nop 0
	s_addc_u32 s84, s57, 0
	s_mov_b32 s85, -2
	v_lshl_add_u32 v248, s6, 8, v227
	v_add_u32_e32 v248, s74, v248
	v_ashrrev_i32_e32 v249, 31, v248
	v_lshl_add_u64 v[248:249], v[248:249], 2, s[10:11]
	global_load_dword v240, v[248:249], off
	global_load_dword v241, v[248:249], off offset:64
	global_load_dword v242, v[248:249], off offset:128
	global_load_dword v243, v[248:249], off offset:192
	global_load_dword v244, v[248:249], off offset:512
	global_load_dword v245, v[248:249], off offset:576
	global_load_dword v246, v[248:249], off offset:640
	global_load_dword v247, v[248:249], off offset:704
	ds_read_b128 v[0:3], v230
	ds_read_b128 v[4:7], v230 offset:1024
	ds_read_b128 v[8:11], v230 offset:2048
	ds_read_b128 v[12:15], v230 offset:3072
	ds_read_b128 v[144:147], v231
	ds_read_b128 v[148:151], v231 offset:1024
	ds_read_b128 v[152:155], v231 offset:2048
	ds_read_b128 v[156:159], v231 offset:3072
	s_add_u32 s56, s54, 0xfffc0080
	s_addc_u32 s57, s55, -1
	s_cmp_eq_u32 s85, 12
	s_cselect_b32 s63, s7, s57
	s_cselect_b32 s62, s35, s56
	s_cselect_b32 s57, s23, s84
	s_cselect_b32 s56, s53, s83
	v_lshl_add_u64 v[212:213], s[54:55], 0, v[188:189]
	s_add_i32 m0, s68, 0xc000
	ds_read_b128 v[160:163], v232
	ds_read_b128 v[164:167], v232 offset:1024
	ds_read_b128 v[168:171], v232 offset:2048
	ds_read_b128 v[172:175], v232 offset:3072
	ds_read_b128 v[196:199], v232 offset:4096
	ds_read_b128 v[200:203], v232 offset:5120
	ds_read_b128 v[204:207], v232 offset:6144
	ds_read_b128 v[208:211], v232 offset:7168
	global_load_lds_dwordx4 v[212:213], off
	v_lshl_add_u64 v[212:213], s[54:55], 0, v[190:191]
	s_add_i32 m0, s68, 0xe000
	s_nop 0
	global_load_lds_dwordx4 v[212:213], off
	s_waitcnt vmcnt(8)
	s_waitcnt lgkmcnt(0)
	s_barrier
	s_waitcnt lgkmcnt(0)
	v_mfma_f32_16x16x32_bf16 v[140:143], v[0:3], v[160:163], 0
	v_mfma_f32_16x16x32_bf16 v[132:135], v[8:11], v[160:163], 0
	v_mfma_f32_16x16x32_bf16 v[124:127], v[0:3], v[168:171], 0
	v_mfma_f32_16x16x32_bf16 v[120:123], v[8:11], v[168:171], 0
	v_mfma_f32_16x16x32_bf16 v[108:111], v[0:3], v[196:199], 0
	v_mfma_f32_16x16x32_bf16 v[104:107], v[8:11], v[196:199], 0
	v_mfma_f32_16x16x32_bf16 v[92:95], v[0:3], v[204:207], 0
	v_mfma_f32_16x16x32_bf16 v[88:91], v[8:11], v[204:207], 0
	v_mfma_f32_16x16x32_bf16 v[140:143], v[4:7], v[164:167], v[140:143]
	v_mfma_f32_16x16x32_bf16 v[132:135], v[12:15], v[164:167], v[132:135]
	v_mfma_f32_16x16x32_bf16 v[124:127], v[4:7], v[172:175], v[124:127]
	v_mfma_f32_16x16x32_bf16 v[120:123], v[12:15], v[172:175], v[120:123]
	v_mfma_f32_16x16x32_bf16 v[108:111], v[4:7], v[200:203], v[108:111]
	v_mfma_f32_16x16x32_bf16 v[104:107], v[12:15], v[200:203], v[104:107]
	v_mfma_f32_16x16x32_bf16 v[92:95], v[4:7], v[208:211], v[92:95]
	v_mfma_f32_16x16x32_bf16 v[88:91], v[12:15], v[208:211], v[88:91]
	v_mfma_f32_16x16x32_bf16 v[136:139], v[144:147], v[160:163], 0
	v_mfma_f32_16x16x32_bf16 v[128:131], v[152:155], v[160:163], 0
	v_mfma_f32_16x16x32_bf16 v[116:119], v[144:147], v[168:171], 0
	v_mfma_f32_16x16x32_bf16 v[112:115], v[152:155], v[168:171], 0
	v_mfma_f32_16x16x32_bf16 v[100:103], v[144:147], v[196:199], 0
	v_mfma_f32_16x16x32_bf16 v[96:99], v[152:155], v[196:199], 0
	v_mfma_f32_16x16x32_bf16 v[84:87], v[144:147], v[204:207], 0
	v_mfma_f32_16x16x32_bf16 v[80:83], v[152:155], v[204:207], 0
	v_mfma_f32_16x16x32_bf16 v[136:139], v[148:151], v[164:167], v[136:139]
	v_mfma_f32_16x16x32_bf16 v[128:131], v[156:159], v[164:167], v[128:131]
	v_mfma_f32_16x16x32_bf16 v[116:119], v[148:151], v[172:175], v[116:119]
	v_mfma_f32_16x16x32_bf16 v[112:115], v[156:159], v[172:175], v[112:115]
	v_mfma_f32_16x16x32_bf16 v[100:103], v[148:151], v[200:203], v[100:103]
	v_mfma_f32_16x16x32_bf16 v[96:99], v[156:159], v[200:203], v[96:99]
	v_mfma_f32_16x16x32_bf16 v[84:87], v[148:151], v[208:211], v[84:87]
	v_mfma_f32_16x16x32_bf16 v[80:83], v[156:159], v[208:211], v[80:83]
	s_barrier
	s_add_i32 s86, s81, s65
	v_lshl_add_u64 v[212:213], s[56:57], 0, v[180:181]
	s_mov_b32 m0, s86
	ds_read_b128 v[160:163], v232 offset:16384
	ds_read_b128 v[164:167], v232 offset:17408
	ds_read_b128 v[168:171], v232 offset:18432
	ds_read_b128 v[172:175], v232 offset:19456
	ds_read_b128 v[196:199], v232 offset:20480
	ds_read_b128 v[200:203], v232 offset:21504
	ds_read_b128 v[204:207], v232 offset:22528
	ds_read_b128 v[208:211], v232 offset:23552
	global_load_lds_dwordx4 v[212:213], off
	s_add_i32 m0, s86, 0x2000
	s_add_u32 s86, s56, 0x40000
	v_lshl_add_u64 v[214:215], s[56:57], 0, v[184:185]
	s_addc_u32 s87, s57, 0
	s_add_i32 s88, s82, s65
	global_load_lds_dwordx4 v[214:215], off
	v_lshl_add_u64 v[216:217], s[86:87], 0, v[180:181]
	s_mov_b32 m0, s88
	v_lshl_add_u64 v[218:219], s[62:63], 0, v[182:183]
	global_load_lds_dwordx4 v[216:217], off
	v_lshl_add_u64 v[216:217], s[86:87], 0, v[184:185]
	s_add_i32 m0, s88, 0x2000
	s_nop 0
	global_load_lds_dwordx4 v[216:217], off
	v_lshl_add_u64 v[216:217], s[62:63], 0, v[178:179]
	s_mov_b32 m0, s68
	s_nop 0
	global_load_lds_dwordx4 v[216:217], off
	s_mov_b32 m0, s69
	s_nop 0
	global_load_lds_dwordx4 v[218:219], off
	s_waitcnt vmcnt(8)
	s_waitcnt lgkmcnt(0)
	s_barrier
; #define PG8_STAGE(bufoff, gbase, voff) do { _Pragma("unroll") for (int _i = 0; _i < 2; ++_i) \
;         __builtin_amdgcn_global_load_lds((const unsigned*)((const char*)(gbase) + (voff)[_i]), (LAS unsigned*)(lds + (bufoff) + ldsw + _i * 8192), 16, 0, 0); } while (0)
; #define PG8_LDA(dst, b, h) do { _Pragma("unroll") for (int m = 0; m < 4; ++m) _Pragma("unroll") for (int k = 0; k < 2; ++k) dst[m][k] = *(const LAS bf16x8*)(lds + PG8_SA(b, h) + aoff + m * 2048 + k * 1024); } while (0)
; #define PG8_LDB(dst, b, h) do { _Pragma("unroll") for (int n = 0; n < 2; ++n) _Pragma("unroll") for (int k = 0; k < 2; ++k) dst[n][k] = *(const LAS bf16x8*)(lds + PG8_SB(b, h) + boff + n * 2048 + k * 1024); } while (0)
; #define PG8_MMA(ai, bj, At, Bt) do { __builtin_amdgcn_s_setprio(1); _Pragma("unroll") for (int m = 0; m < 4; ++m) _Pragma("unroll") for (int n = 0; n < 2; ++n) _Pragma("unroll") for (int k = 0; k < 2; ++k) \
;         acc[ai][bj][m][n] = __builtin_amdgcn_mfma_f32_16x16x32_bf16(Bt[n][k], At[m][k], acc[ai][bj][m][n], 0, 0, 0); __builtin_amdgcn_s_setprio(0); } while (0)
; #define PG8_WAIT_V(n) asm volatile("s_waitcnt vmcnt(" #n ")" ::: "memory")
; #define PG8_WAIT_L(n) asm volatile("s_waitcnt lgkmcnt(" #n ")" ::: "memory")
; #define PG8_BAR __builtin_amdgcn_s_barrier()
; #define PG8_SCHED __builtin_amdgcn_sched_barrier(0)
; template <class Epi>
; __device__ __forceinline__ void gemm_phase(LAS unsigned char* lds, const Gemm g, const StaticOrder& S, const Epi& E) {
;     ...
;             PG8_WAIT_V(8); PG8_WAIT_L(0); PG8_BAR; PG8_MMA(1, 0, At, B0); PG8_MMA(1, 1, At, B1); PG8_BAR; PG8_SCHED;
;             PG8_LDB(B0, 1, 0); PG8_LDB(B1, 1, 1); PG8_SCHED; PG8_LDA(At, 1, 0); PG8_STAGE(PG8_SA(0, 1), a2 + hstepA, voffA);
;             PG8_WAIT_V(8); PG8_WAIT_L(0); PG8_BAR; PG8_MMA(0, 0, At, B0); PG8_MMA(0, 1, At, B1); PG8_BAR; PG8_SCHED;
;             PG8_LDA(At, 1, 1); PG8_STAGE(PG8_SB(1, 0), b3, voffB); PG8_STAGE(PG8_SB(1, 1), b3 + hstepB, voffB); PG8_STAGE(PG8_SA(1, 0), a3, voffA);
;             PG8_WAIT_V(8); PG8_WAIT_L(0); PG8_BAR; PG8_MMA(1, 0, At, B0); PG8_MMA(1, 1, At, B1); PG8_BAR; PG8_SCHED;
	s_waitcnt lgkmcnt(0)
	v_mfma_f32_16x16x32_bf16 v[76:79], v[0:3], v[160:163], 0
	v_mfma_f32_16x16x32_bf16 v[72:75], v[8:11], v[160:163], 0
	v_mfma_f32_16x16x32_bf16 v[60:63], v[0:3], v[168:171], 0
	v_mfma_f32_16x16x32_bf16 v[56:59], v[8:11], v[168:171], 0
	v_mfma_f32_16x16x32_bf16 v[44:47], v[0:3], v[196:199], 0
	v_mfma_f32_16x16x32_bf16 v[40:43], v[8:11], v[196:199], 0
	v_mfma_f32_16x16x32_bf16 v[0:3], v[0:3], v[204:207], 0
	v_mfma_f32_16x16x32_bf16 v[76:79], v[4:7], v[164:167], v[76:79]
	v_mfma_f32_16x16x32_bf16 v[72:75], v[12:15], v[164:167], v[72:75]
	v_mfma_f32_16x16x32_bf16 v[60:63], v[4:7], v[172:175], v[60:63]
	v_mfma_f32_16x16x32_bf16 v[56:59], v[12:15], v[172:175], v[56:59]
	v_mfma_f32_16x16x32_bf16 v[44:47], v[4:7], v[200:203], v[44:47]
	v_mfma_f32_16x16x32_bf16 v[40:43], v[12:15], v[200:203], v[40:43]
	v_mfma_f32_16x16x32_bf16 v[0:3], v[4:7], v[208:211], v[0:3]
	v_mfma_f32_16x16x32_bf16 v[4:7], v[8:11], v[204:207], 0
	v_mfma_f32_16x16x32_bf16 v[4:7], v[12:15], v[208:211], v[4:7]
	v_mfma_f32_16x16x32_bf16 v[20:23], v[144:147], v[168:171], 0
	v_mfma_f32_16x16x32_bf16 v[52:55], v[148:151], v[172:175], v[20:23]
	v_mfma_f32_16x16x32_bf16 v[20:23], v[152:155], v[168:171], 0
	v_mfma_f32_16x16x32_bf16 v[48:51], v[156:159], v[172:175], v[20:23]
	v_mfma_f32_16x16x32_bf16 v[20:23], v[144:147], v[196:199], 0
	v_mfma_f32_16x16x32_bf16 v[36:39], v[148:151], v[200:203], v[20:23]
	v_mfma_f32_16x16x32_bf16 v[20:23], v[152:155], v[196:199], 0
	v_mfma_f32_16x16x32_bf16 v[32:35], v[156:159], v[200:203], v[20:23]
	v_mfma_f32_16x16x32_bf16 v[20:23], v[144:147], v[204:207], 0
	v_mfma_f32_16x16x32_bf16 v[16:19], v[152:155], v[204:207], 0
	v_mfma_f32_16x16x32_bf16 v[8:11], v[144:147], v[160:163], 0
	v_mfma_f32_16x16x32_bf16 v[12:15], v[152:155], v[160:163], 0
	v_mfma_f32_16x16x32_bf16 v[24:27], v[148:151], v[208:211], v[20:23]
	v_mfma_f32_16x16x32_bf16 v[16:19], v[156:159], v[208:211], v[16:19]
	v_mfma_f32_16x16x32_bf16 v[8:11], v[148:151], v[164:167], v[8:11]
	v_mfma_f32_16x16x32_bf16 v[12:15], v[156:159], v[164:167], v[12:15]
	s_barrier
	s_add_i32 s86, 0, 0x18000
	s_add_i32 s87, 0, 0x1c000
	v_add_u32_e32 v68, s86, v229
	v_add_u32_e32 v156, s87, v229
	ds_read_b128 v[20:23], v68
	ds_read_b128 v[28:31], v68 offset:1024
	ds_read_b128 v[64:67], v68 offset:2048
	ds_read_b128 v[68:71], v68 offset:3072
	ds_read_b128 v[144:147], v156
	ds_read_b128 v[148:151], v156 offset:1024
	ds_read_b128 v[152:155], v156 offset:2048
	ds_read_b128 v[156:159], v156 offset:3072
	s_add_u32 s62, s62, 0x40000
	s_addc_u32 s63, s63, 0
	s_mov_b32 m0, s70
	v_lshl_add_u64 v[220:221], s[62:63], 0, v[178:179]
	ds_read_b128 v[160:163], v232 offset:32768
	ds_read_b128 v[164:167], v232 offset:33792
	ds_read_b128 v[168:171], v232 offset:34816
	ds_read_b128 v[172:175], v232 offset:35840
	ds_read_b128 v[196:199], v232 offset:36864
	ds_read_b128 v[200:203], v232 offset:37888
	ds_read_b128 v[204:207], v232 offset:38912
	ds_read_b128 v[208:211], v232 offset:39936
	global_load_lds_dwordx4 v[220:221], off
	v_lshl_add_u64 v[220:221], s[62:63], 0, v[182:183]
	s_mov_b32 m0, s71
	s_nop 0
	global_load_lds_dwordx4 v[220:221], off
	s_waitcnt vmcnt(8)
	s_waitcnt lgkmcnt(0)
	s_barrier
	s_waitcnt lgkmcnt(0)
	v_mfma_f32_16x16x32_bf16 v[140:143], v[20:23], v[160:163], v[140:143]
	v_mfma_f32_16x16x32_bf16 v[132:135], v[64:67], v[160:163], v[132:135]
	v_mfma_f32_16x16x32_bf16 v[124:127], v[20:23], v[168:171], v[124:127]
	v_mfma_f32_16x16x32_bf16 v[120:123], v[64:67], v[168:171], v[120:123]
	v_mfma_f32_16x16x32_bf16 v[108:111], v[20:23], v[196:199], v[108:111]
	v_mfma_f32_16x16x32_bf16 v[104:107], v[64:67], v[196:199], v[104:107]
	v_mfma_f32_16x16x32_bf16 v[92:95], v[20:23], v[204:207], v[92:95]
	v_mfma_f32_16x16x32_bf16 v[88:91], v[64:67], v[204:207], v[88:91]
	v_mfma_f32_16x16x32_bf16 v[140:143], v[28:31], v[164:167], v[140:143]
	v_mfma_f32_16x16x32_bf16 v[132:135], v[68:71], v[164:167], v[132:135]
	v_mfma_f32_16x16x32_bf16 v[124:127], v[28:31], v[172:175], v[124:127]
	v_mfma_f32_16x16x32_bf16 v[120:123], v[68:71], v[172:175], v[120:123]
	v_mfma_f32_16x16x32_bf16 v[108:111], v[28:31], v[200:203], v[108:111]
	v_mfma_f32_16x16x32_bf16 v[104:107], v[68:71], v[200:203], v[104:107]
	v_mfma_f32_16x16x32_bf16 v[92:95], v[28:31], v[208:211], v[92:95]
	v_mfma_f32_16x16x32_bf16 v[88:91], v[68:71], v[208:211], v[88:91]
	v_mfma_f32_16x16x32_bf16 v[136:139], v[144:147], v[160:163], v[136:139]
	v_mfma_f32_16x16x32_bf16 v[128:131], v[152:155], v[160:163], v[128:131]
	v_mfma_f32_16x16x32_bf16 v[116:119], v[144:147], v[168:171], v[116:119]
	v_mfma_f32_16x16x32_bf16 v[112:115], v[152:155], v[168:171], v[112:115]
	v_mfma_f32_16x16x32_bf16 v[100:103], v[144:147], v[196:199], v[100:103]
	v_mfma_f32_16x16x32_bf16 v[96:99], v[152:155], v[196:199], v[96:99]
	v_mfma_f32_16x16x32_bf16 v[84:87], v[144:147], v[204:207], v[84:87]
	v_mfma_f32_16x16x32_bf16 v[80:83], v[152:155], v[204:207], v[80:83]
	v_mfma_f32_16x16x32_bf16 v[136:139], v[148:151], v[164:167], v[136:139]
	v_mfma_f32_16x16x32_bf16 v[128:131], v[156:159], v[164:167], v[128:131]
	v_mfma_f32_16x16x32_bf16 v[116:119], v[148:151], v[172:175], v[116:119]
	v_mfma_f32_16x16x32_bf16 v[112:115], v[156:159], v[172:175], v[112:115]
	v_mfma_f32_16x16x32_bf16 v[100:103], v[148:151], v[200:203], v[100:103]
	v_mfma_f32_16x16x32_bf16 v[96:99], v[156:159], v[200:203], v[96:99]
	v_mfma_f32_16x16x32_bf16 v[84:87], v[148:151], v[208:211], v[84:87]
	v_mfma_f32_16x16x32_bf16 v[80:83], v[156:159], v[208:211], v[80:83]
	s_barrier
; #define PG8_STAGE(bufoff, gbase, voff) do { _Pragma("unroll") for (int _i = 0; _i < 2; ++_i) \
;         __builtin_amdgcn_global_load_lds((const unsigned*)((const char*)(gbase) + (voff)[_i]), (LAS unsigned*)(lds + (bufoff) + ldsw + _i * 8192), 16, 0, 0); } while (0)
; #define PG8_LDA(dst, b, h) do { _Pragma("unroll") for (int m = 0; m < 4; ++m) _Pragma("unroll") for (int k = 0; k < 2; ++k) dst[m][k] = *(const LAS bf16x8*)(lds + PG8_SA(b, h) + aoff + m * 2048 + k * 1024); } while (0)
; #define PG8_LDB(dst, b, h) do { _Pragma("unroll") for (int n = 0; n < 2; ++n) _Pragma("unroll") for (int k = 0; k < 2; ++k) dst[n][k] = *(const LAS bf16x8*)(lds + PG8_SB(b, h) + boff + n * 2048 + k * 1024); } while (0)
; #define PG8_MMA(ai, bj, At, Bt) do { __builtin_amdgcn_s_setprio(1); _Pragma("unroll") for (int m = 0; m < 4; ++m) _Pragma("unroll") for (int n = 0; n < 2; ++n) _Pragma("unroll") for (int k = 0; k < 2; ++k) \
;         acc[ai][bj][m][n] = __builtin_amdgcn_mfma_f32_16x16x32_bf16(Bt[n][k], At[m][k], acc[ai][bj][m][n], 0, 0, 0); __builtin_amdgcn_s_setprio(0); } while (0)
; #define PG8_WAIT_V(n) asm volatile("s_waitcnt vmcnt(" #n ")" ::: "memory")
; #define PG8_WAIT_L(n) asm volatile("s_waitcnt lgkmcnt(" #n ")" ::: "memory")
; template <class Epi>
; __device__ __forceinline__ void gemm_phase(LAS unsigned char* lds, const Gemm g, const StaticOrder& S, const Epi& E) {
;     ...
;         for (int t = 0; t < nt; t += 2) {
;             const bool last = (t == nt - 2);
;             const char* a1 = cA + (size_t)(t + 1) * kstep;
;             const char* a2 = last ? nA : cA + (size_t)(t + 2) * kstep; const char* b2 = last ? nB : cB + (size_t)(t + 2) * kstep;
;             const char* a3 = a2 + kstep; const char* b3 = b2 + kstep;
;             PG8_LDB(B0, 0, 0); PG8_LDB(B1, 0, 1); PG8_SCHED; PG8_LDA(At, 0, 0); PG8_STAGE(PG8_SA(1, 1), a1 + hstepA, voffA);
;             PG8_WAIT_V(8); PG8_WAIT_L(0); PG8_BAR; PG8_MMA(0, 0, At, B0); PG8_MMA(0, 1, At, B1); PG8_BAR; PG8_SCHED;
;     ...
;             PG8_WAIT_V(8); PG8_WAIT_L(0); PG8_BAR; PG8_MMA(0, 0, At, B0); PG8_MMA(0, 1, At, B1); PG8_BAR; PG8_SCHED;
;             PG8_LDA(At, 1, 1); PG8_STAGE(PG8_SB(1, 0), b3, voffB); PG8_STAGE(PG8_SB(1, 1), b3 + hstepB, voffB); PG8_STAGE(PG8_SA(1, 0), a3, voffA);
;             PG8_WAIT_V(8); PG8_WAIT_L(0); PG8_BAR; PG8_MMA(1, 0, At, B0); PG8_MMA(1, 1, At, B1); PG8_BAR; PG8_SCHED;
	s_add_i32 s62, s86, s65
	v_lshl_add_u64 v[212:213], v[212:213], 0, s[16:17]
	s_mov_b32 m0, s62
	ds_read_b128 v[160:163], v232 offset:49152
	ds_read_b128 v[164:167], v232 offset:50176
	ds_read_b128 v[168:171], v232 offset:51200
	ds_read_b128 v[172:175], v232 offset:52224
	ds_read_b128 v[196:199], v232 offset:53248
	ds_read_b128 v[200:203], v232 offset:54272
	ds_read_b128 v[204:207], v232 offset:55296
	ds_read_b128 v[208:211], v232 offset:56320
	global_load_lds_dwordx4 v[212:213], off
	s_add_i32 m0, s62, 0x2000
	s_add_u32 s56, s56, 0x40080
	v_lshl_add_u64 v[212:213], v[214:215], 0, s[16:17]
	s_addc_u32 s57, s57, 0
	s_add_i32 s62, s87, s65
	global_load_lds_dwordx4 v[212:213], off
	v_lshl_add_u64 v[212:213], s[56:57], 0, v[180:181]
	s_mov_b32 m0, s62
	s_nop 0
	global_load_lds_dwordx4 v[212:213], off
	v_lshl_add_u64 v[212:213], s[56:57], 0, v[184:185]
	s_add_i32 m0, s62, 0x2000
	s_nop 0
	global_load_lds_dwordx4 v[212:213], off
	v_lshl_add_u64 v[212:213], v[216:217], 0, s[16:17]
	s_mov_b32 m0, s76
	s_nop 0
	global_load_lds_dwordx4 v[212:213], off
	v_lshl_add_u64 v[212:213], v[218:219], 0, s[16:17]
	s_mov_b32 m0, s77
	s_nop 0
	global_load_lds_dwordx4 v[212:213], off
	s_waitcnt vmcnt(8)
	s_waitcnt lgkmcnt(0)
	s_barrier
	s_waitcnt lgkmcnt(0)
	v_mfma_f32_16x16x32_bf16 v[76:79], v[20:23], v[160:163], v[76:79]
	v_mfma_f32_16x16x32_bf16 v[60:63], v[20:23], v[168:171], v[60:63]
	v_mfma_f32_16x16x32_bf16 v[44:47], v[20:23], v[196:199], v[44:47]
	v_mfma_f32_16x16x32_bf16 v[0:3], v[20:23], v[204:207], v[0:3]
	v_mfma_f32_16x16x32_bf16 v[76:79], v[28:31], v[164:167], v[76:79]
	v_mfma_f32_16x16x32_bf16 v[72:75], v[64:67], v[160:163], v[72:75]
	v_mfma_f32_16x16x32_bf16 v[60:63], v[28:31], v[172:175], v[60:63]
	v_mfma_f32_16x16x32_bf16 v[56:59], v[64:67], v[168:171], v[56:59]
	v_mfma_f32_16x16x32_bf16 v[44:47], v[28:31], v[200:203], v[44:47]
	v_mfma_f32_16x16x32_bf16 v[40:43], v[64:67], v[196:199], v[40:43]
	v_mfma_f32_16x16x32_bf16 v[28:31], v[28:31], v[208:211], v[0:3]
	v_mfma_f32_16x16x32_bf16 v[0:3], v[64:67], v[204:207], v[4:7]
	v_mfma_f32_16x16x32_bf16 v[72:75], v[68:71], v[164:167], v[72:75]
	v_mfma_f32_16x16x32_bf16 v[56:59], v[68:71], v[172:175], v[56:59]
	v_mfma_f32_16x16x32_bf16 v[40:43], v[68:71], v[200:203], v[40:43]
	v_mfma_f32_16x16x32_bf16 v[20:23], v[68:71], v[208:211], v[0:3]
	v_mfma_f32_16x16x32_bf16 v[0:3], v[144:147], v[160:163], v[8:11]
	v_mfma_f32_16x16x32_bf16 v[68:71], v[148:151], v[164:167], v[0:3]
	v_mfma_f32_16x16x32_bf16 v[0:3], v[152:155], v[160:163], v[12:15]
	v_mfma_f32_16x16x32_bf16 v[64:67], v[156:159], v[164:167], v[0:3]
	v_mfma_f32_16x16x32_bf16 v[0:3], v[144:147], v[168:171], v[52:55]
	v_mfma_f32_16x16x32_bf16 v[52:55], v[148:151], v[172:175], v[0:3]
	v_mfma_f32_16x16x32_bf16 v[0:3], v[152:155], v[168:171], v[48:51]
	v_mfma_f32_16x16x32_bf16 v[48:51], v[156:159], v[172:175], v[0:3]
	v_mfma_f32_16x16x32_bf16 v[0:3], v[144:147], v[196:199], v[36:39]
	v_mfma_f32_16x16x32_bf16 v[36:39], v[148:151], v[200:203], v[0:3]
	v_mfma_f32_16x16x32_bf16 v[0:3], v[152:155], v[196:199], v[32:35]
	v_mfma_f32_16x16x32_bf16 v[32:35], v[156:159], v[200:203], v[0:3]
	v_mfma_f32_16x16x32_bf16 v[0:3], v[144:147], v[204:207], v[24:27]
	v_mfma_f32_16x16x32_bf16 v[24:27], v[148:151], v[208:211], v[0:3]
	v_mfma_f32_16x16x32_bf16 v[0:3], v[152:155], v[204:207], v[16:19]
	v_mfma_f32_16x16x32_bf16 v[16:19], v[156:159], v[208:211], v[0:3]
	s_barrier
	s_add_i32 s85, s85, 2
	s_add_u32 s54, s54, 0x100
	s_addc_u32 s55, s55, 0
	s_add_u32 s83, s83, 0x100
	s_addc_u32 s84, s84, 0
	s_cmp_gt_u32 s85, 13
.LBB0_1018:
	ds_read_b128 v[0:3], v230
	ds_read_b128 v[4:7], v230 offset:1024
	ds_read_b128 v[8:11], v230 offset:2048
	ds_read_b128 v[12:15], v230 offset:3072
	ds_read_b128 v[144:147], v231
	ds_read_b128 v[148:151], v231 offset:1024
	ds_read_b128 v[152:155], v231 offset:2048
	ds_read_b128 v[156:159], v231 offset:3072
	s_add_u32 s56, s54, 0xfffc0080
	s_addc_u32 s57, s55, -1
	s_cmp_eq_u32 s85, 12
	s_cselect_b32 s63, s7, s57
	s_cselect_b32 s62, s35, s56
	s_cselect_b32 s57, s23, s84
	s_cselect_b32 s56, s53, s83
	v_lshl_add_u64 v[212:213], s[54:55], 0, v[188:189]
	s_add_i32 m0, s68, 0xc000
	ds_read_b128 v[160:163], v232
	ds_read_b128 v[164:167], v232 offset:1024
	ds_read_b128 v[168:171], v232 offset:2048
	ds_read_b128 v[172:175], v232 offset:3072
	ds_read_b128 v[196:199], v232 offset:4096
	ds_read_b128 v[200:203], v232 offset:5120
	ds_read_b128 v[204:207], v232 offset:6144
	ds_read_b128 v[208:211], v232 offset:7168
	global_load_lds_dwordx4 v[212:213], off
	v_lshl_add_u64 v[212:213], s[54:55], 0, v[190:191]
	s_add_i32 m0, s68, 0xe000
	s_nop 0
	global_load_lds_dwordx4 v[212:213], off
	s_waitcnt vmcnt(8)
	s_waitcnt lgkmcnt(0)
	s_barrier
; #define PG8_STAGE(bufoff, gbase, voff) do { _Pragma("unroll") for (int _i = 0; _i < 2; ++_i) \
;         __builtin_amdgcn_global_load_lds((const unsigned*)((const char*)(gbase) + (voff)[_i]), (LAS unsigned*)(lds + (bufoff) + ldsw + _i * 8192), 16, 0, 0); } while (0)
; #define PG8_LDA(dst, b, h) do { _Pragma("unroll") for (int m = 0; m < 4; ++m) _Pragma("unroll") for (int k = 0; k < 2; ++k) dst[m][k] = *(const LAS bf16x8*)(lds + PG8_SA(b, h) + aoff + m * 2048 + k * 1024); } while (0)
; #define PG8_LDB(dst, b, h) do { _Pragma("unroll") for (int n = 0; n < 2; ++n) _Pragma("unroll") for (int k = 0; k < 2; ++k) dst[n][k] = *(const LAS bf16x8*)(lds + PG8_SB(b, h) + boff + n * 2048 + k * 1024); } while (0)
; #define PG8_MMA(ai, bj, At, Bt) do { __builtin_amdgcn_s_setprio(1); _Pragma("unroll") for (int m = 0; m < 4; ++m) _Pragma("unroll") for (int n = 0; n < 2; ++n) _Pragma("unroll") for (int k = 0; k < 2; ++k) \
;         acc[ai][bj][m][n] = __builtin_amdgcn_mfma_f32_16x16x32_bf16(Bt[n][k], At[m][k], acc[ai][bj][m][n], 0, 0, 0); __builtin_amdgcn_s_setprio(0); } while (0)
; #define PG8_WAIT_V(n) asm volatile("s_waitcnt vmcnt(" #n ")" ::: "memory")
; #define PG8_WAIT_L(n) asm volatile("s_waitcnt lgkmcnt(" #n ")" ::: "memory")
; #define PG8_BAR __builtin_amdgcn_s_barrier()
; #define PG8_SCHED __builtin_amdgcn_sched_barrier(0)
; template <class Epi>
; __device__ __forceinline__ void gemm_phase(LAS unsigned char* lds, const Gemm g, const StaticOrder& S, const Epi& E) {
;     ...
;             PG8_WAIT_V(8); PG8_WAIT_L(0); PG8_BAR; PG8_MMA(0, 0, At, B0); PG8_MMA(0, 1, At, B1); PG8_BAR; PG8_SCHED;
;             PG8_LDA(At, 0, 1); PG8_STAGE(PG8_SB(0, 0), b2, voffB); PG8_STAGE(PG8_SB(0, 1), b2 + hstepB, voffB); PG8_STAGE(PG8_SA(0, 0), a2, voffA);
;             PG8_WAIT_V(8); PG8_WAIT_L(0); PG8_BAR; PG8_MMA(1, 0, At, B0); PG8_MMA(1, 1, At, B1); PG8_BAR; PG8_SCHED;
;             PG8_LDB(B0, 1, 0); PG8_LDB(B1, 1, 1); PG8_SCHED; PG8_LDA(At, 1, 0); PG8_STAGE(PG8_SA(0, 1), a2 + hstepA, voffA);
;             PG8_WAIT_V(8); PG8_WAIT_L(0); PG8_BAR; PG8_MMA(0, 0, At, B0); PG8_MMA(0, 1, At, B1); PG8_BAR; PG8_SCHED;
	s_waitcnt lgkmcnt(0)
	v_mfma_f32_16x16x32_bf16 v[140:143], v[0:3], v[160:163], v[140:143]
	v_mfma_f32_16x16x32_bf16 v[132:135], v[8:11], v[160:163], v[132:135]
	v_mfma_f32_16x16x32_bf16 v[124:127], v[0:3], v[168:171], v[124:127]
	v_mfma_f32_16x16x32_bf16 v[120:123], v[8:11], v[168:171], v[120:123]
	v_mfma_f32_16x16x32_bf16 v[108:111], v[0:3], v[196:199], v[108:111]
	v_mfma_f32_16x16x32_bf16 v[104:107], v[8:11], v[196:199], v[104:107]
	v_mfma_f32_16x16x32_bf16 v[92:95], v[0:3], v[204:207], v[92:95]
	v_mfma_f32_16x16x32_bf16 v[88:91], v[8:11], v[204:207], v[88:91]
	v_mfma_f32_16x16x32_bf16 v[140:143], v[4:7], v[164:167], v[140:143]
	v_mfma_f32_16x16x32_bf16 v[132:135], v[12:15], v[164:167], v[132:135]
	v_mfma_f32_16x16x32_bf16 v[124:127], v[4:7], v[172:175], v[124:127]
	v_mfma_f32_16x16x32_bf16 v[120:123], v[12:15], v[172:175], v[120:123]
	v_mfma_f32_16x16x32_bf16 v[108:111], v[4:7], v[200:203], v[108:111]
	v_mfma_f32_16x16x32_bf16 v[104:107], v[12:15], v[200:203], v[104:107]
	v_mfma_f32_16x16x32_bf16 v[92:95], v[4:7], v[208:211], v[92:95]
	v_mfma_f32_16x16x32_bf16 v[88:91], v[12:15], v[208:211], v[88:91]
	v_mfma_f32_16x16x32_bf16 v[136:139], v[144:147], v[160:163], v[136:139]
	v_mfma_f32_16x16x32_bf16 v[128:131], v[152:155], v[160:163], v[128:131]
	v_mfma_f32_16x16x32_bf16 v[116:119], v[144:147], v[168:171], v[116:119]
	v_mfma_f32_16x16x32_bf16 v[112:115], v[152:155], v[168:171], v[112:115]
	v_mfma_f32_16x16x32_bf16 v[100:103], v[144:147], v[196:199], v[100:103]
	v_mfma_f32_16x16x32_bf16 v[96:99], v[152:155], v[196:199], v[96:99]
	v_mfma_f32_16x16x32_bf16 v[84:87], v[144:147], v[204:207], v[84:87]
	v_mfma_f32_16x16x32_bf16 v[80:83], v[152:155], v[204:207], v[80:83]
	v_mfma_f32_16x16x32_bf16 v[136:139], v[148:151], v[164:167], v[136:139]
	v_mfma_f32_16x16x32_bf16 v[128:131], v[156:159], v[164:167], v[128:131]
	v_mfma_f32_16x16x32_bf16 v[116:119], v[148:151], v[172:175], v[116:119]
	v_mfma_f32_16x16x32_bf16 v[112:115], v[156:159], v[172:175], v[112:115]
	v_mfma_f32_16x16x32_bf16 v[100:103], v[148:151], v[200:203], v[100:103]
	v_mfma_f32_16x16x32_bf16 v[96:99], v[156:159], v[200:203], v[96:99]
	v_mfma_f32_16x16x32_bf16 v[84:87], v[148:151], v[208:211], v[84:87]
	v_mfma_f32_16x16x32_bf16 v[80:83], v[156:159], v[208:211], v[80:83]
	s_barrier
	s_add_i32 s86, s81, s65
	v_lshl_add_u64 v[212:213], s[56:57], 0, v[180:181]
	s_mov_b32 m0, s86
	ds_read_b128 v[160:163], v232 offset:16384
	ds_read_b128 v[164:167], v232 offset:17408
	ds_read_b128 v[168:171], v232 offset:18432
	ds_read_b128 v[172:175], v232 offset:19456
	ds_read_b128 v[196:199], v232 offset:20480
	ds_read_b128 v[200:203], v232 offset:21504
	ds_read_b128 v[204:207], v232 offset:22528
	ds_read_b128 v[208:211], v232 offset:23552
	global_load_lds_dwordx4 v[212:213], off
	s_add_i32 m0, s86, 0x2000
	s_add_u32 s86, s56, 0x40000
	v_lshl_add_u64 v[214:215], s[56:57], 0, v[184:185]
	s_addc_u32 s87, s57, 0
	s_add_i32 s88, s82, s65
	global_load_lds_dwordx4 v[214:215], off
	v_lshl_add_u64 v[216:217], s[86:87], 0, v[180:181]
	s_mov_b32 m0, s88
	v_lshl_add_u64 v[218:219], s[62:63], 0, v[182:183]
	global_load_lds_dwordx4 v[216:217], off
	v_lshl_add_u64 v[216:217], s[86:87], 0, v[184:185]
	s_add_i32 m0, s88, 0x2000
	s_nop 0
	global_load_lds_dwordx4 v[216:217], off
	v_lshl_add_u64 v[216:217], s[62:63], 0, v[178:179]
	s_mov_b32 m0, s68
	s_nop 0
	global_load_lds_dwordx4 v[216:217], off
	s_mov_b32 m0, s69
	s_nop 0
	global_load_lds_dwordx4 v[218:219], off
	s_waitcnt vmcnt(8)
	s_waitcnt lgkmcnt(0)
	s_barrier
	s_waitcnt lgkmcnt(0)
	v_mfma_f32_16x16x32_bf16 v[76:79], v[0:3], v[160:163], v[76:79]
	v_mfma_f32_16x16x32_bf16 v[72:75], v[8:11], v[160:163], v[72:75]
	v_mfma_f32_16x16x32_bf16 v[60:63], v[0:3], v[168:171], v[60:63]
	v_mfma_f32_16x16x32_bf16 v[56:59], v[8:11], v[168:171], v[56:59]
	v_mfma_f32_16x16x32_bf16 v[44:47], v[0:3], v[196:199], v[44:47]
	v_mfma_f32_16x16x32_bf16 v[40:43], v[8:11], v[196:199], v[40:43]
	v_mfma_f32_16x16x32_bf16 v[0:3], v[0:3], v[204:207], v[28:31]
	v_mfma_f32_16x16x32_bf16 v[76:79], v[4:7], v[164:167], v[76:79]
	v_mfma_f32_16x16x32_bf16 v[72:75], v[12:15], v[164:167], v[72:75]
	v_mfma_f32_16x16x32_bf16 v[60:63], v[4:7], v[172:175], v[60:63]
	v_mfma_f32_16x16x32_bf16 v[56:59], v[12:15], v[172:175], v[56:59]
	v_mfma_f32_16x16x32_bf16 v[44:47], v[4:7], v[200:203], v[44:47]
	v_mfma_f32_16x16x32_bf16 v[40:43], v[12:15], v[200:203], v[40:43]
	v_mfma_f32_16x16x32_bf16 v[0:3], v[4:7], v[208:211], v[0:3]
	v_mfma_f32_16x16x32_bf16 v[4:7], v[8:11], v[204:207], v[20:23]
	v_mfma_f32_16x16x32_bf16 v[4:7], v[12:15], v[208:211], v[4:7]
	v_mfma_f32_16x16x32_bf16 v[20:23], v[144:147], v[168:171], v[52:55]
	v_mfma_f32_16x16x32_bf16 v[52:55], v[148:151], v[172:175], v[20:23]
	v_mfma_f32_16x16x32_bf16 v[20:23], v[152:155], v[168:171], v[48:51]
	v_mfma_f32_16x16x32_bf16 v[48:51], v[156:159], v[172:175], v[20:23]
	v_mfma_f32_16x16x32_bf16 v[20:23], v[144:147], v[196:199], v[36:39]
	v_mfma_f32_16x16x32_bf16 v[36:39], v[148:151], v[200:203], v[20:23]
	v_mfma_f32_16x16x32_bf16 v[20:23], v[152:155], v[196:199], v[32:35]
	v_mfma_f32_16x16x32_bf16 v[32:35], v[156:159], v[200:203], v[20:23]
	v_mfma_f32_16x16x32_bf16 v[20:23], v[144:147], v[204:207], v[24:27]
	v_mfma_f32_16x16x32_bf16 v[16:19], v[152:155], v[204:207], v[16:19]
	v_mfma_f32_16x16x32_bf16 v[8:11], v[144:147], v[160:163], v[68:71]
	v_mfma_f32_16x16x32_bf16 v[12:15], v[152:155], v[160:163], v[64:67]
	v_mfma_f32_16x16x32_bf16 v[24:27], v[148:151], v[208:211], v[20:23]
	v_mfma_f32_16x16x32_bf16 v[16:19], v[156:159], v[208:211], v[16:19]
	v_mfma_f32_16x16x32_bf16 v[8:11], v[148:151], v[164:167], v[8:11]
	v_mfma_f32_16x16x32_bf16 v[12:15], v[156:159], v[164:167], v[12:15]
	s_barrier
; #define PG8_STAGE(bufoff, gbase, voff) do { _Pragma("unroll") for (int _i = 0; _i < 2; ++_i) \
;         __builtin_amdgcn_global_load_lds((const unsigned*)((const char*)(gbase) + (voff)[_i]), (LAS unsigned*)(lds + (bufoff) + ldsw + _i * 8192), 16, 0, 0); } while (0)
; #define PG8_LDA(dst, b, h) do { _Pragma("unroll") for (int m = 0; m < 4; ++m) _Pragma("unroll") for (int k = 0; k < 2; ++k) dst[m][k] = *(const LAS bf16x8*)(lds + PG8_SA(b, h) + aoff + m * 2048 + k * 1024); } while (0)
; #define PG8_MMA(ai, bj, At, Bt) do { __builtin_amdgcn_s_setprio(1); _Pragma("unroll") for (int m = 0; m < 4; ++m) _Pragma("unroll") for (int n = 0; n < 2; ++n) _Pragma("unroll") for (int k = 0; k < 2; ++k) \
;         acc[ai][bj][m][n] = __builtin_amdgcn_mfma_f32_16x16x32_bf16(Bt[n][k], At[m][k], acc[ai][bj][m][n], 0, 0, 0); __builtin_amdgcn_s_setprio(0); } while (0)
; #define PG8_WAIT_V(n) asm volatile("s_waitcnt vmcnt(" #n ")" ::: "memory")
; #define PG8_WAIT_L(n) asm volatile("s_waitcnt lgkmcnt(" #n ")" ::: "memory")
; #define PG8_BAR __builtin_amdgcn_s_barrier()
; #define PG8_SCHED __builtin_amdgcn_sched_barrier(0)
; template <class Epi>
; __device__ __forceinline__ void gemm_phase(LAS unsigned char* lds, const Gemm g, const StaticOrder& S, const Epi& E) {
;     ...
;             PG8_LDA(At, 1, 1); PG8_STAGE(PG8_SB(1, 0), b3, voffB); PG8_STAGE(PG8_SB(1, 1), b3 + hstepB, voffB); PG8_STAGE(PG8_SA(1, 0), a3, voffA);
;             PG8_WAIT_V(8); PG8_WAIT_L(0); PG8_BAR; PG8_MMA(1, 0, At, B0); PG8_MMA(1, 1, At, B1); PG8_BAR; PG8_SCHED;
;         }
;         if (wr == 0) PG8_BAR;
	s_add_i32 s86, 0, 0x18000
	s_add_i32 s87, 0, 0x1c000
	v_add_u32_e32 v68, s86, v229
	v_add_u32_e32 v156, s87, v229
	ds_read_b128 v[20:23], v68
	ds_read_b128 v[28:31], v68 offset:1024
	ds_read_b128 v[64:67], v68 offset:2048
	ds_read_b128 v[68:71], v68 offset:3072
	ds_read_b128 v[144:147], v156
	ds_read_b128 v[148:151], v156 offset:1024
	ds_read_b128 v[152:155], v156 offset:2048
	ds_read_b128 v[156:159], v156 offset:3072
	s_add_u32 s62, s62, 0x40000
	s_addc_u32 s63, s63, 0
	s_mov_b32 m0, s70
	v_lshl_add_u64 v[220:221], s[62:63], 0, v[178:179]
	ds_read_b128 v[160:163], v232 offset:32768
	ds_read_b128 v[164:167], v232 offset:33792
	ds_read_b128 v[168:171], v232 offset:34816
	ds_read_b128 v[172:175], v232 offset:35840
	ds_read_b128 v[196:199], v232 offset:36864
	ds_read_b128 v[200:203], v232 offset:37888
	ds_read_b128 v[204:207], v232 offset:38912
	ds_read_b128 v[208:211], v232 offset:39936
	global_load_lds_dwordx4 v[220:221], off
	v_lshl_add_u64 v[220:221], s[62:63], 0, v[182:183]
	s_mov_b32 m0, s71
	s_nop 0
	global_load_lds_dwordx4 v[220:221], off
	s_waitcnt vmcnt(8)
	s_waitcnt lgkmcnt(0)
	s_barrier
	s_waitcnt lgkmcnt(0)
	v_mfma_f32_16x16x32_bf16 v[140:143], v[20:23], v[160:163], v[140:143]
	v_mfma_f32_16x16x32_bf16 v[132:135], v[64:67], v[160:163], v[132:135]
	v_mfma_f32_16x16x32_bf16 v[124:127], v[20:23], v[168:171], v[124:127]
	v_mfma_f32_16x16x32_bf16 v[120:123], v[64:67], v[168:171], v[120:123]
	v_mfma_f32_16x16x32_bf16 v[108:111], v[20:23], v[196:199], v[108:111]
	v_mfma_f32_16x16x32_bf16 v[104:107], v[64:67], v[196:199], v[104:107]
	v_mfma_f32_16x16x32_bf16 v[92:95], v[20:23], v[204:207], v[92:95]
	v_mfma_f32_16x16x32_bf16 v[88:91], v[64:67], v[204:207], v[88:91]
	v_mfma_f32_16x16x32_bf16 v[140:143], v[28:31], v[164:167], v[140:143]
	v_mfma_f32_16x16x32_bf16 v[132:135], v[68:71], v[164:167], v[132:135]
	v_mfma_f32_16x16x32_bf16 v[124:127], v[28:31], v[172:175], v[124:127]
	v_mfma_f32_16x16x32_bf16 v[120:123], v[68:71], v[172:175], v[120:123]
	v_mfma_f32_16x16x32_bf16 v[108:111], v[28:31], v[200:203], v[108:111]
	v_mfma_f32_16x16x32_bf16 v[104:107], v[68:71], v[200:203], v[104:107]
	v_mfma_f32_16x16x32_bf16 v[92:95], v[28:31], v[208:211], v[92:95]
	v_mfma_f32_16x16x32_bf16 v[88:91], v[68:71], v[208:211], v[88:91]
	v_mfma_f32_16x16x32_bf16 v[136:139], v[144:147], v[160:163], v[136:139]
	v_mfma_f32_16x16x32_bf16 v[128:131], v[152:155], v[160:163], v[128:131]
	v_mfma_f32_16x16x32_bf16 v[116:119], v[144:147], v[168:171], v[116:119]
	v_mfma_f32_16x16x32_bf16 v[112:115], v[152:155], v[168:171], v[112:115]
	v_mfma_f32_16x16x32_bf16 v[100:103], v[144:147], v[196:199], v[100:103]
	v_mfma_f32_16x16x32_bf16 v[96:99], v[152:155], v[196:199], v[96:99]
	v_mfma_f32_16x16x32_bf16 v[84:87], v[144:147], v[204:207], v[84:87]
	v_mfma_f32_16x16x32_bf16 v[80:83], v[152:155], v[204:207], v[80:83]
	v_mfma_f32_16x16x32_bf16 v[136:139], v[148:151], v[164:167], v[136:139]
	v_mfma_f32_16x16x32_bf16 v[128:131], v[156:159], v[164:167], v[128:131]
	v_mfma_f32_16x16x32_bf16 v[116:119], v[148:151], v[172:175], v[116:119]
	v_mfma_f32_16x16x32_bf16 v[112:115], v[156:159], v[172:175], v[112:115]
	v_mfma_f32_16x16x32_bf16 v[100:103], v[148:151], v[200:203], v[100:103]
	v_mfma_f32_16x16x32_bf16 v[96:99], v[156:159], v[200:203], v[96:99]
	v_mfma_f32_16x16x32_bf16 v[84:87], v[148:151], v[208:211], v[84:87]
	v_mfma_f32_16x16x32_bf16 v[80:83], v[156:159], v[208:211], v[80:83]
	s_barrier
	s_add_i32 s62, s86, s65
	v_lshl_add_u64 v[212:213], v[212:213], 0, s[16:17]
	s_mov_b32 m0, s62
	ds_read_b128 v[160:163], v232 offset:49152
	ds_read_b128 v[164:167], v232 offset:50176
	ds_read_b128 v[168:171], v232 offset:51200
	ds_read_b128 v[172:175], v232 offset:52224
	ds_read_b128 v[196:199], v232 offset:53248
	ds_read_b128 v[200:203], v232 offset:54272
	ds_read_b128 v[204:207], v232 offset:55296
	ds_read_b128 v[208:211], v232 offset:56320
	global_load_lds_dwordx4 v[212:213], off
	s_add_i32 m0, s62, 0x2000
	s_add_u32 s56, s56, 0x40080
	v_lshl_add_u64 v[212:213], v[214:215], 0, s[16:17]
	s_addc_u32 s57, s57, 0
	s_add_i32 s62, s87, s65
	global_load_lds_dwordx4 v[212:213], off
	v_lshl_add_u64 v[212:213], s[56:57], 0, v[180:181]
	s_mov_b32 m0, s62
	s_nop 0
	global_load_lds_dwordx4 v[212:213], off
	v_lshl_add_u64 v[212:213], s[56:57], 0, v[184:185]
	s_add_i32 m0, s62, 0x2000
	s_nop 0
	global_load_lds_dwordx4 v[212:213], off
	v_lshl_add_u64 v[212:213], v[216:217], 0, s[16:17]
	s_mov_b32 m0, s76
	s_nop 0
	global_load_lds_dwordx4 v[212:213], off
	v_lshl_add_u64 v[212:213], v[218:219], 0, s[16:17]
	s_mov_b32 m0, s77
	s_nop 0
	global_load_lds_dwordx4 v[212:213], off
	s_waitcnt vmcnt(8)
	s_waitcnt lgkmcnt(0)
	s_barrier
	s_waitcnt lgkmcnt(0)
	v_mfma_f32_16x16x32_bf16 v[76:79], v[20:23], v[160:163], v[76:79]
	v_mfma_f32_16x16x32_bf16 v[60:63], v[20:23], v[168:171], v[60:63]
	v_mfma_f32_16x16x32_bf16 v[44:47], v[20:23], v[196:199], v[44:47]
	v_mfma_f32_16x16x32_bf16 v[0:3], v[20:23], v[204:207], v[0:3]
	v_mfma_f32_16x16x32_bf16 v[76:79], v[28:31], v[164:167], v[76:79]
	v_mfma_f32_16x16x32_bf16 v[72:75], v[64:67], v[160:163], v[72:75]
	v_mfma_f32_16x16x32_bf16 v[60:63], v[28:31], v[172:175], v[60:63]
	v_mfma_f32_16x16x32_bf16 v[56:59], v[64:67], v[168:171], v[56:59]
	v_mfma_f32_16x16x32_bf16 v[44:47], v[28:31], v[200:203], v[44:47]
	v_mfma_f32_16x16x32_bf16 v[40:43], v[64:67], v[196:199], v[40:43]
	v_mfma_f32_16x16x32_bf16 v[28:31], v[28:31], v[208:211], v[0:3]
	v_mfma_f32_16x16x32_bf16 v[0:3], v[64:67], v[204:207], v[4:7]
	v_mfma_f32_16x16x32_bf16 v[72:75], v[68:71], v[164:167], v[72:75]
	v_mfma_f32_16x16x32_bf16 v[56:59], v[68:71], v[172:175], v[56:59]
	v_mfma_f32_16x16x32_bf16 v[40:43], v[68:71], v[200:203], v[40:43]
	v_mfma_f32_16x16x32_bf16 v[20:23], v[68:71], v[208:211], v[0:3]
	v_mfma_f32_16x16x32_bf16 v[0:3], v[144:147], v[160:163], v[8:11]
	v_mfma_f32_16x16x32_bf16 v[68:71], v[148:151], v[164:167], v[0:3]
	v_mfma_f32_16x16x32_bf16 v[0:3], v[152:155], v[160:163], v[12:15]
	v_mfma_f32_16x16x32_bf16 v[64:67], v[156:159], v[164:167], v[0:3]
	v_mfma_f32_16x16x32_bf16 v[0:3], v[144:147], v[168:171], v[52:55]
	v_mfma_f32_16x16x32_bf16 v[52:55], v[148:151], v[172:175], v[0:3]
	v_mfma_f32_16x16x32_bf16 v[0:3], v[152:155], v[168:171], v[48:51]
	v_mfma_f32_16x16x32_bf16 v[48:51], v[156:159], v[172:175], v[0:3]
	v_mfma_f32_16x16x32_bf16 v[0:3], v[144:147], v[196:199], v[36:39]
	v_mfma_f32_16x16x32_bf16 v[36:39], v[148:151], v[200:203], v[0:3]
	v_mfma_f32_16x16x32_bf16 v[0:3], v[152:155], v[196:199], v[32:35]
	v_mfma_f32_16x16x32_bf16 v[32:35], v[156:159], v[200:203], v[0:3]
	v_mfma_f32_16x16x32_bf16 v[0:3], v[144:147], v[204:207], v[24:27]
	v_mfma_f32_16x16x32_bf16 v[24:27], v[148:151], v[208:211], v[0:3]
	v_mfma_f32_16x16x32_bf16 v[0:3], v[152:155], v[204:207], v[16:19]
	v_mfma_f32_16x16x32_bf16 v[16:19], v[156:159], v[208:211], v[0:3]
	s_barrier
	s_add_i32 s85, s85, 2
	s_add_u32 s54, s54, 0x100
	s_addc_u32 s55, s55, 0
	s_add_u32 s83, s83, 0x100
	s_addc_u32 s84, s84, 0
	s_cmp_gt_u32 s85, 13
	s_cbranch_scc0 .LBB0_1018
	s_and_b64 vcc, exec, s[18:19]
	s_cbranch_vccz .LBB0_1021
	s_barrier

; #define PG8_STAGE(bufoff, gbase, voff) do { _Pragma("unroll") for (int _i = 0; _i < 2; ++_i) \
;         __builtin_amdgcn_global_load_lds((const unsigned*)((const char*)(gbase) + (voff)[_i]), (LAS unsigned*)(lds + (bufoff) + ldsw + _i * 8192), 16, 0, 0); } while (0)
; #define PG8_LDA(dst, b, h) do { _Pragma("unroll") for (int m = 0; m < 4; ++m) _Pragma("unroll") for (int k = 0; k < 2; ++k) dst[m][k] = *(const LAS bf16x8*)(lds + PG8_SA(b, h) + aoff + m * 2048 + k * 1024); } while (0)
; #define PG8_LDB(dst, b, h) do { _Pragma("unroll") for (int n = 0; n < 2; ++n) _Pragma("unroll") for (int k = 0; k < 2; ++k) dst[n][k] = *(const LAS bf16x8*)(lds + PG8_SB(b, h) + boff + n * 2048 + k * 1024); } while (0)
; #define PG8_MMA(ai, bj, At, Bt) do { __builtin_amdgcn_s_setprio(1); _Pragma("unroll") for (int m = 0; m < 4; ++m) _Pragma("unroll") for (int n = 0; n < 2; ++n) _Pragma("unroll") for (int k = 0; k < 2; ++k) \
;         acc[ai][bj][m][n] = __builtin_amdgcn_mfma_f32_16x16x32_bf16(Bt[n][k], At[m][k], acc[ai][bj][m][n], 0, 0, 0); __builtin_amdgcn_s_setprio(0); } while (0)
; #define PG8_BAR __builtin_amdgcn_s_barrier()
; template <class Epi>
; __device__ __forceinline__ void gemm_phase(LAS unsigned char* lds, const Gemm g, const StaticOrder& S, const Epi& E) {
;     ...
;         const bool has_next = S.next(ui + 1, nxt);
;         const char* nA = has_next ? (const char*)g.A + (size_t)nxt.pm * tstepA : cA; const char* nB = has_next ? (const char*)g.Bt + (size_t)nxt.pn * tstepB : cB;
; #pragma nounroll
;         for (int t = 0; t < nt; t += 2) {
;             const bool last = (t == nt - 2);
;             const char* a1 = cA + (size_t)(t + 1) * kstep;
;             const char* a2 = last ? nA : cA + (size_t)(t + 2) * kstep; const char* b2 = last ? nB : cB + (size_t)(t + 2) * kstep;
;             const char* a3 = a2 + kstep; const char* b3 = b2 + kstep;
;             PG8_LDB(B0, 0, 0); PG8_LDB(B1, 0, 1); PG8_SCHED; PG8_LDA(At, 0, 0); PG8_STAGE(PG8_SA(1, 1), a1 + hstepA, voffA);
;             PG8_WAIT_V(8); PG8_WAIT_L(0); PG8_BAR; PG8_MMA(0, 0, At, B0); PG8_MMA(0, 1, At, B1); PG8_BAR; PG8_SCHED;
;             PG8_LDA(At, 0, 1); PG8_STAGE(PG8_SB(0, 0), b2, voffB); PG8_STAGE(PG8_SB(0, 1), b2 + hstepB, voffB); PG8_STAGE(PG8_SA(0, 0), a2, voffA);
;             PG8_WAIT_V(8); PG8_WAIT_L(0); PG8_BAR; PG8_MMA(1, 0, At, B0); PG8_MMA(1, 1, At, B1); PG8_BAR; PG8_SCHED;
.LBB0_1232:
	s_ashr_i32 s23, s22, 31
	s_lshl_b64 s[34:35], s[22:23], 19
	s_add_u32 s34, s24, s34
	s_addc_u32 s35, s25, s35
	s_and_b64 s[38:39], s[4:5], exec
	s_cselect_b32 s23, s35, s53
	s_cselect_b32 s76, s34, s52
	s_ashr_i32 s21, s20, 31
	s_lshl_b64 s[38:39], s[20:21], 19
	s_add_u32 s38, s19, s38
	s_addc_u32 s39, s33, s39
	s_and_b64 s[56:57], s[4:5], exec
	s_cselect_b32 s21, s39, s55
	s_cselect_b32 s77, s38, s54
	s_add_u32 s52, s52, 0x40080
	s_addc_u32 s53, s53, 0
	s_add_u32 s78, s54, 0x100
	s_addc_u32 s79, s55, 0
	s_mov_b32 s80, -2
	ds_read_b128 v[56:59], v189
	ds_read_b128 v[60:63], v189 offset:1024
	ds_read_b128 v[72:75], v189 offset:2048
	ds_read_b128 v[76:79], v189 offset:3072
	ds_read_b128 v[144:147], v195
	ds_read_b128 v[148:151], v195 offset:1024
	ds_read_b128 v[168:171], v195 offset:2048
	ds_read_b128 v[178:181], v195 offset:3072
	s_add_u32 s54, s52, 0xfffc0080
	s_addc_u32 s55, s53, -1
	s_cmp_eq_u32 s80, 12
	s_cselect_b32 s57, s23, s55
	s_cselect_b32 s56, s76, s54
	s_cselect_b32 s55, s21, s79
	s_cselect_b32 s54, s77, s78
	v_lshl_add_u64 v[174:175], s[52:53], 0, v[160:161]
	s_add_i32 m0, s43, 0xc000
	ds_read_b128 v[184:187], v201
	ds_read_b128 v[190:193], v201 offset:1024
	ds_read_b128 v[196:199], v201 offset:2048
	ds_read_b128 v[202:205], v201 offset:3072
	ds_read_b128 v[208:211], v201 offset:4096
	ds_read_b128 v[212:215], v201 offset:5120
	ds_read_b128 v[216:219], v201 offset:6144
	ds_read_b128 v[220:223], v201 offset:7168
	global_load_lds_dwordx4 v[174:175], off
	v_lshl_add_u64 v[174:175], s[52:53], 0, v[162:163]
	s_add_i32 m0, s43, 0xe000
	s_nop 0
	global_load_lds_dwordx4 v[174:175], off
	s_waitcnt vmcnt(8)
	s_waitcnt lgkmcnt(0)
	s_barrier
	s_waitcnt lgkmcnt(0)
	v_mfma_f32_16x16x32_bf16 v[140:143], v[56:59], v[184:187], 0
	v_mfma_f32_16x16x32_bf16 v[136:139], v[72:75], v[184:187], 0
	v_mfma_f32_16x16x32_bf16 v[124:127], v[56:59], v[196:199], 0
	v_mfma_f32_16x16x32_bf16 v[120:123], v[72:75], v[196:199], 0
	v_mfma_f32_16x16x32_bf16 v[108:111], v[56:59], v[208:211], 0
	v_mfma_f32_16x16x32_bf16 v[104:107], v[72:75], v[208:211], 0
	v_mfma_f32_16x16x32_bf16 v[92:95], v[56:59], v[216:219], 0
	v_mfma_f32_16x16x32_bf16 v[88:91], v[72:75], v[216:219], 0
	v_mfma_f32_16x16x32_bf16 v[140:143], v[60:63], v[190:193], v[140:143]
	v_mfma_f32_16x16x32_bf16 v[136:139], v[76:79], v[190:193], v[136:139]
	v_mfma_f32_16x16x32_bf16 v[124:127], v[60:63], v[202:205], v[124:127]
	v_mfma_f32_16x16x32_bf16 v[120:123], v[76:79], v[202:205], v[120:123]
	v_mfma_f32_16x16x32_bf16 v[108:111], v[60:63], v[212:215], v[108:111]
	v_mfma_f32_16x16x32_bf16 v[104:107], v[76:79], v[212:215], v[104:107]
	v_mfma_f32_16x16x32_bf16 v[92:95], v[60:63], v[220:223], v[92:95]
	v_mfma_f32_16x16x32_bf16 v[88:91], v[76:79], v[220:223], v[88:91]
	v_mfma_f32_16x16x32_bf16 v[132:135], v[144:147], v[184:187], 0
	v_mfma_f32_16x16x32_bf16 v[128:131], v[168:171], v[184:187], 0
	v_mfma_f32_16x16x32_bf16 v[116:119], v[144:147], v[196:199], 0
	v_mfma_f32_16x16x32_bf16 v[112:115], v[168:171], v[196:199], 0
	v_mfma_f32_16x16x32_bf16 v[100:103], v[144:147], v[208:211], 0
	v_mfma_f32_16x16x32_bf16 v[96:99], v[168:171], v[208:211], 0
	v_mfma_f32_16x16x32_bf16 v[84:87], v[144:147], v[216:219], 0
	v_mfma_f32_16x16x32_bf16 v[80:83], v[168:171], v[216:219], 0
	v_mfma_f32_16x16x32_bf16 v[132:135], v[148:151], v[190:193], v[132:135]
	v_mfma_f32_16x16x32_bf16 v[128:131], v[178:181], v[190:193], v[128:131]
	v_mfma_f32_16x16x32_bf16 v[116:119], v[148:151], v[202:205], v[116:119]
	v_mfma_f32_16x16x32_bf16 v[112:115], v[178:181], v[202:205], v[112:115]
	v_mfma_f32_16x16x32_bf16 v[100:103], v[148:151], v[212:215], v[100:103]
	v_mfma_f32_16x16x32_bf16 v[96:99], v[178:181], v[212:215], v[96:99]
	v_mfma_f32_16x16x32_bf16 v[84:87], v[148:151], v[220:223], v[84:87]
	v_mfma_f32_16x16x32_bf16 v[80:83], v[178:181], v[220:223], v[80:83]
	s_barrier
	s_add_i32 s81, s73, s58
	v_lshl_add_u64 v[174:175], s[54:55], 0, v[154:155]
	s_mov_b32 m0, s81
	ds_read_b128 v[184:187], v201 offset:16384
	ds_read_b128 v[190:193], v201 offset:17408
	ds_read_b128 v[196:199], v201 offset:18432
	ds_read_b128 v[202:205], v201 offset:19456
	ds_read_b128 v[208:211], v201 offset:20480
	ds_read_b128 v[212:215], v201 offset:21504
	ds_read_b128 v[216:219], v201 offset:22528
	ds_read_b128 v[220:223], v201 offset:23552
	global_load_lds_dwordx4 v[174:175], off
	s_add_i32 m0, s81, 0x2000
	s_add_u32 s82, s54, 0x40000
	v_lshl_add_u64 v[224:225], s[54:55], 0, v[158:159]
	s_addc_u32 s83, s55, 0
	s_add_i32 s81, s74, s58
	global_load_lds_dwordx4 v[224:225], off
	v_lshl_add_u64 v[226:227], s[82:83], 0, v[154:155]
	s_mov_b32 m0, s81
	v_lshl_add_u64 v[228:229], s[56:57], 0, v[156:157]
	global_load_lds_dwordx4 v[226:227], off
	v_lshl_add_u64 v[226:227], s[82:83], 0, v[158:159]
	s_add_i32 m0, s81, 0x2000
	s_nop 0
	global_load_lds_dwordx4 v[226:227], off
	v_lshl_add_u64 v[226:227], s[56:57], 0, v[152:153]
	s_mov_b32 m0, s43
	s_nop 0
	global_load_lds_dwordx4 v[226:227], off
	s_mov_b32 m0, s59
	s_nop 0
	global_load_lds_dwordx4 v[228:229], off
	s_waitcnt vmcnt(8)
	s_waitcnt lgkmcnt(0)
	s_barrier
; #define PG8_STAGE(bufoff, gbase, voff) do { _Pragma("unroll") for (int _i = 0; _i < 2; ++_i) \
;         __builtin_amdgcn_global_load_lds((const unsigned*)((const char*)(gbase) + (voff)[_i]), (LAS unsigned*)(lds + (bufoff) + ldsw + _i * 8192), 16, 0, 0); } while (0)
; #define PG8_LDA(dst, b, h) do { _Pragma("unroll") for (int m = 0; m < 4; ++m) _Pragma("unroll") for (int k = 0; k < 2; ++k) dst[m][k] = *(const LAS bf16x8*)(lds + PG8_SA(b, h) + aoff + m * 2048 + k * 1024); } while (0)
; #define PG8_LDB(dst, b, h) do { _Pragma("unroll") for (int n = 0; n < 2; ++n) _Pragma("unroll") for (int k = 0; k < 2; ++k) dst[n][k] = *(const LAS bf16x8*)(lds + PG8_SB(b, h) + boff + n * 2048 + k * 1024); } while (0)
; #define PG8_MMA(ai, bj, At, Bt) do { __builtin_amdgcn_s_setprio(1); _Pragma("unroll") for (int m = 0; m < 4; ++m) _Pragma("unroll") for (int n = 0; n < 2; ++n) _Pragma("unroll") for (int k = 0; k < 2; ++k) \
;         acc[ai][bj][m][n] = __builtin_amdgcn_mfma_f32_16x16x32_bf16(Bt[n][k], At[m][k], acc[ai][bj][m][n], 0, 0, 0); __builtin_amdgcn_s_setprio(0); } while (0)
; #define PG8_WAIT_V(n) asm volatile("s_waitcnt vmcnt(" #n ")" ::: "memory")
; #define PG8_WAIT_L(n) asm volatile("s_waitcnt lgkmcnt(" #n ")" ::: "memory")
; #define PG8_BAR __builtin_amdgcn_s_barrier()
; #define PG8_SCHED __builtin_amdgcn_sched_barrier(0)
; template <class Epi>
; __device__ __forceinline__ void gemm_phase(LAS unsigned char* lds, const Gemm g, const StaticOrder& S, const Epi& E) {
;     ...
;             PG8_WAIT_V(8); PG8_WAIT_L(0); PG8_BAR; PG8_MMA(1, 0, At, B0); PG8_MMA(1, 1, At, B1); PG8_BAR; PG8_SCHED;
;             PG8_LDB(B0, 1, 0); PG8_LDB(B1, 1, 1); PG8_SCHED; PG8_LDA(At, 1, 0); PG8_STAGE(PG8_SA(0, 1), a2 + hstepA, voffA);
;             PG8_WAIT_V(8); PG8_WAIT_L(0); PG8_BAR; PG8_MMA(0, 0, At, B0); PG8_MMA(0, 1, At, B1); PG8_BAR; PG8_SCHED;
;             PG8_LDA(At, 1, 1); PG8_STAGE(PG8_SB(1, 0), b3, voffB); PG8_STAGE(PG8_SB(1, 1), b3 + hstepB, voffB); PG8_STAGE(PG8_SA(1, 0), a3, voffA);
;             PG8_WAIT_V(8); PG8_WAIT_L(0); PG8_BAR; PG8_MMA(1, 0, At, B0); PG8_MMA(1, 1, At, B1); PG8_BAR; PG8_SCHED;
	s_waitcnt lgkmcnt(0)
	v_mfma_f32_16x16x32_bf16 v[68:71], v[56:59], v[184:187], 0
	v_mfma_f32_16x16x32_bf16 v[64:67], v[72:75], v[184:187], 0
	v_mfma_f32_16x16x32_bf16 v[44:47], v[56:59], v[196:199], 0
	v_mfma_f32_16x16x32_bf16 v[40:43], v[72:75], v[196:199], 0
	v_mfma_f32_16x16x32_bf16 v[28:31], v[56:59], v[208:211], 0
	v_mfma_f32_16x16x32_bf16 v[24:27], v[72:75], v[208:211], 0
	v_mfma_f32_16x16x32_bf16 v[12:15], v[56:59], v[216:219], 0
	v_mfma_f32_16x16x32_bf16 v[8:11], v[72:75], v[216:219], 0
	v_mfma_f32_16x16x32_bf16 v[68:71], v[60:63], v[190:193], v[68:71]
	v_mfma_f32_16x16x32_bf16 v[64:67], v[76:79], v[190:193], v[64:67]
	v_mfma_f32_16x16x32_bf16 v[44:47], v[60:63], v[202:205], v[44:47]
	v_mfma_f32_16x16x32_bf16 v[40:43], v[76:79], v[202:205], v[40:43]
	v_mfma_f32_16x16x32_bf16 v[28:31], v[60:63], v[212:215], v[28:31]
	v_mfma_f32_16x16x32_bf16 v[24:27], v[76:79], v[212:215], v[24:27]
	v_mfma_f32_16x16x32_bf16 v[12:15], v[60:63], v[220:223], v[12:15]
	v_mfma_f32_16x16x32_bf16 v[8:11], v[76:79], v[220:223], v[8:11]
	v_mfma_f32_16x16x32_bf16 v[52:55], v[144:147], v[184:187], 0
	v_mfma_f32_16x16x32_bf16 v[48:51], v[168:171], v[184:187], 0
	v_mfma_f32_16x16x32_bf16 v[36:39], v[144:147], v[196:199], 0
	v_mfma_f32_16x16x32_bf16 v[32:35], v[168:171], v[196:199], 0
	v_mfma_f32_16x16x32_bf16 v[20:23], v[144:147], v[208:211], 0
	v_mfma_f32_16x16x32_bf16 v[16:19], v[168:171], v[208:211], 0
	v_mfma_f32_16x16x32_bf16 v[4:7], v[144:147], v[216:219], 0
	v_mfma_f32_16x16x32_bf16 v[0:3], v[168:171], v[216:219], 0
	v_mfma_f32_16x16x32_bf16 v[52:55], v[148:151], v[190:193], v[52:55]
	v_mfma_f32_16x16x32_bf16 v[48:51], v[178:181], v[190:193], v[48:51]
	v_mfma_f32_16x16x32_bf16 v[36:39], v[148:151], v[202:205], v[36:39]
	v_mfma_f32_16x16x32_bf16 v[32:35], v[178:181], v[202:205], v[32:35]
	v_mfma_f32_16x16x32_bf16 v[20:23], v[148:151], v[212:215], v[20:23]
	v_mfma_f32_16x16x32_bf16 v[16:19], v[178:181], v[212:215], v[16:19]
	v_mfma_f32_16x16x32_bf16 v[4:7], v[148:151], v[220:223], v[4:7]
	v_mfma_f32_16x16x32_bf16 v[0:3], v[178:181], v[220:223], v[0:3]
	s_barrier
	s_add_i32 s81, 0, 0x18000
	s_add_i32 s82, 0, 0x1c000
	v_add_u32_e32 v76, s81, v183
	v_add_u32_e32 v172, s82, v183
	ds_read_b128 v[56:59], v76
	ds_read_b128 v[60:63], v76 offset:1024
	ds_read_b128 v[72:75], v76 offset:2048
	ds_read_b128 v[76:79], v76 offset:3072
	ds_read_b128 v[144:147], v172
	ds_read_b128 v[148:151], v172 offset:1024
	ds_read_b128 v[168:171], v172 offset:2048
	ds_read_b128 v[178:181], v172 offset:3072
	s_add_u32 s56, s56, 0x40000
	s_addc_u32 s57, s57, 0
	s_mov_b32 m0, s62
	v_lshl_add_u64 v[230:231], s[56:57], 0, v[152:153]
	ds_read_b128 v[184:187], v201 offset:32768
	ds_read_b128 v[190:193], v201 offset:33792
	ds_read_b128 v[196:199], v201 offset:34816
	ds_read_b128 v[202:205], v201 offset:35840
	ds_read_b128 v[208:211], v201 offset:36864
	ds_read_b128 v[212:215], v201 offset:37888
	ds_read_b128 v[216:219], v201 offset:38912
	ds_read_b128 v[220:223], v201 offset:39936
	global_load_lds_dwordx4 v[230:231], off
	v_lshl_add_u64 v[230:231], s[56:57], 0, v[156:157]
	s_mov_b32 m0, s63
	s_nop 0
	global_load_lds_dwordx4 v[230:231], off
	s_waitcnt vmcnt(8)
	s_waitcnt lgkmcnt(0)
	s_barrier
	s_waitcnt lgkmcnt(0)
	v_mfma_f32_16x16x32_bf16 v[140:143], v[56:59], v[184:187], v[140:143]
	v_mfma_f32_16x16x32_bf16 v[136:139], v[72:75], v[184:187], v[136:139]
	v_mfma_f32_16x16x32_bf16 v[124:127], v[56:59], v[196:199], v[124:127]
	v_mfma_f32_16x16x32_bf16 v[120:123], v[72:75], v[196:199], v[120:123]
	v_mfma_f32_16x16x32_bf16 v[108:111], v[56:59], v[208:211], v[108:111]
	v_mfma_f32_16x16x32_bf16 v[104:107], v[72:75], v[208:211], v[104:107]
	v_mfma_f32_16x16x32_bf16 v[92:95], v[56:59], v[216:219], v[92:95]
	v_mfma_f32_16x16x32_bf16 v[88:91], v[72:75], v[216:219], v[88:91]
	v_mfma_f32_16x16x32_bf16 v[140:143], v[60:63], v[190:193], v[140:143]
	v_mfma_f32_16x16x32_bf16 v[136:139], v[76:79], v[190:193], v[136:139]
	v_mfma_f32_16x16x32_bf16 v[124:127], v[60:63], v[202:205], v[124:127]
	v_mfma_f32_16x16x32_bf16 v[120:123], v[76:79], v[202:205], v[120:123]
	v_mfma_f32_16x16x32_bf16 v[108:111], v[60:63], v[212:215], v[108:111]
	v_mfma_f32_16x16x32_bf16 v[104:107], v[76:79], v[212:215], v[104:107]
	v_mfma_f32_16x16x32_bf16 v[92:95], v[60:63], v[220:223], v[92:95]
	v_mfma_f32_16x16x32_bf16 v[88:91], v[76:79], v[220:223], v[88:91]
	v_mfma_f32_16x16x32_bf16 v[132:135], v[144:147], v[184:187], v[132:135]
	v_mfma_f32_16x16x32_bf16 v[128:131], v[168:171], v[184:187], v[128:131]
	v_mfma_f32_16x16x32_bf16 v[116:119], v[144:147], v[196:199], v[116:119]
	v_mfma_f32_16x16x32_bf16 v[112:115], v[168:171], v[196:199], v[112:115]
	v_mfma_f32_16x16x32_bf16 v[100:103], v[144:147], v[208:211], v[100:103]
	v_mfma_f32_16x16x32_bf16 v[96:99], v[168:171], v[208:211], v[96:99]
	v_mfma_f32_16x16x32_bf16 v[84:87], v[144:147], v[216:219], v[84:87]
	v_mfma_f32_16x16x32_bf16 v[80:83], v[168:171], v[216:219], v[80:83]
	v_mfma_f32_16x16x32_bf16 v[132:135], v[148:151], v[190:193], v[132:135]
	v_mfma_f32_16x16x32_bf16 v[128:131], v[178:181], v[190:193], v[128:131]
	v_mfma_f32_16x16x32_bf16 v[116:119], v[148:151], v[202:205], v[116:119]
	v_mfma_f32_16x16x32_bf16 v[112:115], v[178:181], v[202:205], v[112:115]
	v_mfma_f32_16x16x32_bf16 v[100:103], v[148:151], v[212:215], v[100:103]
	v_mfma_f32_16x16x32_bf16 v[96:99], v[178:181], v[212:215], v[96:99]
	v_mfma_f32_16x16x32_bf16 v[84:87], v[148:151], v[220:223], v[84:87]
	v_mfma_f32_16x16x32_bf16 v[80:83], v[178:181], v[220:223], v[80:83]
	s_barrier
; #define PG8_STAGE(bufoff, gbase, voff) do { _Pragma("unroll") for (int _i = 0; _i < 2; ++_i) \
;         __builtin_amdgcn_global_load_lds((const unsigned*)((const char*)(gbase) + (voff)[_i]), (LAS unsigned*)(lds + (bufoff) + ldsw + _i * 8192), 16, 0, 0); } while (0)
; #define PG8_LDA(dst, b, h) do { _Pragma("unroll") for (int m = 0; m < 4; ++m) _Pragma("unroll") for (int k = 0; k < 2; ++k) dst[m][k] = *(const LAS bf16x8*)(lds + PG8_SA(b, h) + aoff + m * 2048 + k * 1024); } while (0)
; #define PG8_LDB(dst, b, h) do { _Pragma("unroll") for (int n = 0; n < 2; ++n) _Pragma("unroll") for (int k = 0; k < 2; ++k) dst[n][k] = *(const LAS bf16x8*)(lds + PG8_SB(b, h) + boff + n * 2048 + k * 1024); } while (0)
; #define PG8_MMA(ai, bj, At, Bt) do { __builtin_amdgcn_s_setprio(1); _Pragma("unroll") for (int m = 0; m < 4; ++m) _Pragma("unroll") for (int n = 0; n < 2; ++n) _Pragma("unroll") for (int k = 0; k < 2; ++k) \
;         acc[ai][bj][m][n] = __builtin_amdgcn_mfma_f32_16x16x32_bf16(Bt[n][k], At[m][k], acc[ai][bj][m][n], 0, 0, 0); __builtin_amdgcn_s_setprio(0); } while (0)
; #define PG8_WAIT_V(n) asm volatile("s_waitcnt vmcnt(" #n ")" ::: "memory")
; #define PG8_WAIT_L(n) asm volatile("s_waitcnt lgkmcnt(" #n ")" ::: "memory")
; template <class Epi>
; __device__ __forceinline__ void gemm_phase(LAS unsigned char* lds, const Gemm g, const StaticOrder& S, const Epi& E) {
;     ...
;         for (int t = 0; t < nt; t += 2) {
;             const bool last = (t == nt - 2);
;             const char* a1 = cA + (size_t)(t + 1) * kstep;
;             const char* a2 = last ? nA : cA + (size_t)(t + 2) * kstep; const char* b2 = last ? nB : cB + (size_t)(t + 2) * kstep;
;             const char* a3 = a2 + kstep; const char* b3 = b2 + kstep;
;             PG8_LDB(B0, 0, 0); PG8_LDB(B1, 0, 1); PG8_SCHED; PG8_LDA(At, 0, 0); PG8_STAGE(PG8_SA(1, 1), a1 + hstepA, voffA);
;             PG8_WAIT_V(8); PG8_WAIT_L(0); PG8_BAR; PG8_MMA(0, 0, At, B0); PG8_MMA(0, 1, At, B1); PG8_BAR; PG8_SCHED;
;     ...
;             PG8_WAIT_V(8); PG8_WAIT_L(0); PG8_BAR; PG8_MMA(0, 0, At, B0); PG8_MMA(0, 1, At, B1); PG8_BAR; PG8_SCHED;
;             PG8_LDA(At, 1, 1); PG8_STAGE(PG8_SB(1, 0), b3, voffB); PG8_STAGE(PG8_SB(1, 1), b3 + hstepB, voffB); PG8_STAGE(PG8_SA(1, 0), a3, voffA);
;             PG8_WAIT_V(8); PG8_WAIT_L(0); PG8_BAR; PG8_MMA(1, 0, At, B0); PG8_MMA(1, 1, At, B1); PG8_BAR; PG8_SCHED;
	s_add_i32 s56, s81, s58
	v_lshl_add_u64 v[174:175], v[174:175], 0, s[12:13]
	s_mov_b32 m0, s56
	ds_read_b128 v[184:187], v201 offset:49152
	ds_read_b128 v[190:193], v201 offset:50176
	ds_read_b128 v[196:199], v201 offset:51200
	ds_read_b128 v[202:205], v201 offset:52224
	ds_read_b128 v[208:211], v201 offset:53248
	ds_read_b128 v[212:215], v201 offset:54272
	ds_read_b128 v[216:219], v201 offset:55296
	ds_read_b128 v[220:223], v201 offset:56320
	global_load_lds_dwordx4 v[174:175], off
	s_add_i32 m0, s56, 0x2000
	s_add_u32 s54, s54, 0x40080
	v_lshl_add_u64 v[174:175], v[224:225], 0, s[12:13]
	s_addc_u32 s55, s55, 0
	s_add_i32 s56, s82, s58
	global_load_lds_dwordx4 v[174:175], off
	v_lshl_add_u64 v[174:175], s[54:55], 0, v[154:155]
	s_mov_b32 m0, s56
	s_nop 0
	global_load_lds_dwordx4 v[174:175], off
	v_lshl_add_u64 v[174:175], s[54:55], 0, v[158:159]
	s_add_i32 m0, s56, 0x2000
	s_nop 0
	global_load_lds_dwordx4 v[174:175], off
	v_lshl_add_u64 v[174:175], v[226:227], 0, s[12:13]
	s_mov_b32 m0, s69
	s_nop 0
	global_load_lds_dwordx4 v[174:175], off
	v_lshl_add_u64 v[174:175], v[228:229], 0, s[12:13]
	s_mov_b32 m0, s70
	s_nop 0
	global_load_lds_dwordx4 v[174:175], off
	s_waitcnt vmcnt(8)
	s_waitcnt lgkmcnt(0)
	s_barrier
	s_waitcnt lgkmcnt(0)
	v_mfma_f32_16x16x32_bf16 v[68:71], v[56:59], v[184:187], v[68:71]
	v_mfma_f32_16x16x32_bf16 v[64:67], v[72:75], v[184:187], v[64:67]
	v_mfma_f32_16x16x32_bf16 v[44:47], v[56:59], v[196:199], v[44:47]
	v_mfma_f32_16x16x32_bf16 v[40:43], v[72:75], v[196:199], v[40:43]
	v_mfma_f32_16x16x32_bf16 v[28:31], v[56:59], v[208:211], v[28:31]
	v_mfma_f32_16x16x32_bf16 v[24:27], v[72:75], v[208:211], v[24:27]
	v_mfma_f32_16x16x32_bf16 v[12:15], v[56:59], v[216:219], v[12:15]
	v_mfma_f32_16x16x32_bf16 v[8:11], v[72:75], v[216:219], v[8:11]
	v_mfma_f32_16x16x32_bf16 v[68:71], v[60:63], v[190:193], v[68:71]
	v_mfma_f32_16x16x32_bf16 v[64:67], v[76:79], v[190:193], v[64:67]
	v_mfma_f32_16x16x32_bf16 v[44:47], v[60:63], v[202:205], v[44:47]
	v_mfma_f32_16x16x32_bf16 v[40:43], v[76:79], v[202:205], v[40:43]
	v_mfma_f32_16x16x32_bf16 v[28:31], v[60:63], v[212:215], v[28:31]
	v_mfma_f32_16x16x32_bf16 v[24:27], v[76:79], v[212:215], v[24:27]
	v_mfma_f32_16x16x32_bf16 v[12:15], v[60:63], v[220:223], v[12:15]
	v_mfma_f32_16x16x32_bf16 v[8:11], v[76:79], v[220:223], v[8:11]
	v_mfma_f32_16x16x32_bf16 v[52:55], v[144:147], v[184:187], v[52:55]
	v_mfma_f32_16x16x32_bf16 v[48:51], v[168:171], v[184:187], v[48:51]
	v_mfma_f32_16x16x32_bf16 v[36:39], v[144:147], v[196:199], v[36:39]
	v_mfma_f32_16x16x32_bf16 v[32:35], v[168:171], v[196:199], v[32:35]
	v_mfma_f32_16x16x32_bf16 v[20:23], v[144:147], v[208:211], v[20:23]
	v_mfma_f32_16x16x32_bf16 v[16:19], v[168:171], v[208:211], v[16:19]
	v_mfma_f32_16x16x32_bf16 v[4:7], v[144:147], v[216:219], v[4:7]
	v_mfma_f32_16x16x32_bf16 v[0:3], v[168:171], v[216:219], v[0:3]
	v_mfma_f32_16x16x32_bf16 v[52:55], v[148:151], v[190:193], v[52:55]
	v_mfma_f32_16x16x32_bf16 v[48:51], v[178:181], v[190:193], v[48:51]
	v_mfma_f32_16x16x32_bf16 v[36:39], v[148:151], v[202:205], v[36:39]
	v_mfma_f32_16x16x32_bf16 v[32:35], v[178:181], v[202:205], v[32:35]
	v_mfma_f32_16x16x32_bf16 v[20:23], v[148:151], v[212:215], v[20:23]
	v_mfma_f32_16x16x32_bf16 v[16:19], v[178:181], v[212:215], v[16:19]
	v_mfma_f32_16x16x32_bf16 v[4:7], v[148:151], v[220:223], v[4:7]
	v_mfma_f32_16x16x32_bf16 v[0:3], v[178:181], v[220:223], v[0:3]
	s_barrier
	s_add_i32 s80, s80, 2
	s_add_u32 s52, s52, 0x100
	s_addc_u32 s53, s53, 0
	s_add_u32 s78, s78, 0x100
	s_addc_u32 s79, s79, 0
	s_cmp_gt_u32 s80, 13
.LBB0_1233:
	ds_read_b128 v[56:59], v189
	ds_read_b128 v[60:63], v189 offset:1024
	ds_read_b128 v[72:75], v189 offset:2048
	ds_read_b128 v[76:79], v189 offset:3072
	ds_read_b128 v[144:147], v195
	ds_read_b128 v[148:151], v195 offset:1024
	ds_read_b128 v[168:171], v195 offset:2048
	ds_read_b128 v[178:181], v195 offset:3072
	s_add_u32 s54, s52, 0xfffc0080
	s_addc_u32 s55, s53, -1
	s_cmp_eq_u32 s80, 12
	s_cselect_b32 s57, s23, s55
	s_cselect_b32 s56, s76, s54
	s_cselect_b32 s55, s21, s79
	s_cselect_b32 s54, s77, s78
	v_lshl_add_u64 v[174:175], s[52:53], 0, v[160:161]
	s_add_i32 m0, s43, 0xc000
	ds_read_b128 v[184:187], v201
	ds_read_b128 v[190:193], v201 offset:1024
	ds_read_b128 v[196:199], v201 offset:2048
	ds_read_b128 v[202:205], v201 offset:3072
	ds_read_b128 v[208:211], v201 offset:4096
	ds_read_b128 v[212:215], v201 offset:5120
	ds_read_b128 v[216:219], v201 offset:6144
	ds_read_b128 v[220:223], v201 offset:7168
	global_load_lds_dwordx4 v[174:175], off
	v_lshl_add_u64 v[174:175], s[52:53], 0, v[162:163]
	s_add_i32 m0, s43, 0xe000
	s_nop 0
	global_load_lds_dwordx4 v[174:175], off
	s_waitcnt vmcnt(8)
	s_waitcnt lgkmcnt(0)
	s_barrier
; #define PG8_STAGE(bufoff, gbase, voff) do { _Pragma("unroll") for (int _i = 0; _i < 2; ++_i) \
;         __builtin_amdgcn_global_load_lds((const unsigned*)((const char*)(gbase) + (voff)[_i]), (LAS unsigned*)(lds + (bufoff) + ldsw + _i * 8192), 16, 0, 0); } while (0)
; #define PG8_LDA(dst, b, h) do { _Pragma("unroll") for (int m = 0; m < 4; ++m) _Pragma("unroll") for (int k = 0; k < 2; ++k) dst[m][k] = *(const LAS bf16x8*)(lds + PG8_SA(b, h) + aoff + m * 2048 + k * 1024); } while (0)
; #define PG8_LDB(dst, b, h) do { _Pragma("unroll") for (int n = 0; n < 2; ++n) _Pragma("unroll") for (int k = 0; k < 2; ++k) dst[n][k] = *(const LAS bf16x8*)(lds + PG8_SB(b, h) + boff + n * 2048 + k * 1024); } while (0)
; #define PG8_MMA(ai, bj, At, Bt) do { __builtin_amdgcn_s_setprio(1); _Pragma("unroll") for (int m = 0; m < 4; ++m) _Pragma("unroll") for (int n = 0; n < 2; ++n) _Pragma("unroll") for (int k = 0; k < 2; ++k) \
;         acc[ai][bj][m][n] = __builtin_amdgcn_mfma_f32_16x16x32_bf16(Bt[n][k], At[m][k], acc[ai][bj][m][n], 0, 0, 0); __builtin_amdgcn_s_setprio(0); } while (0)
; #define PG8_WAIT_V(n) asm volatile("s_waitcnt vmcnt(" #n ")" ::: "memory")
; #define PG8_WAIT_L(n) asm volatile("s_waitcnt lgkmcnt(" #n ")" ::: "memory")
; #define PG8_BAR __builtin_amdgcn_s_barrier()
; #define PG8_SCHED __builtin_amdgcn_sched_barrier(0)
; template <class Epi>
; __device__ __forceinline__ void gemm_phase(LAS unsigned char* lds, const Gemm g, const StaticOrder& S, const Epi& E) {
;     ...
;             PG8_WAIT_V(8); PG8_WAIT_L(0); PG8_BAR; PG8_MMA(0, 0, At, B0); PG8_MMA(0, 1, At, B1); PG8_BAR; PG8_SCHED;
;             PG8_LDA(At, 0, 1); PG8_STAGE(PG8_SB(0, 0), b2, voffB); PG8_STAGE(PG8_SB(0, 1), b2 + hstepB, voffB); PG8_STAGE(PG8_SA(0, 0), a2, voffA);
;             PG8_WAIT_V(8); PG8_WAIT_L(0); PG8_BAR; PG8_MMA(1, 0, At, B0); PG8_MMA(1, 1, At, B1); PG8_BAR; PG8_SCHED;
;             PG8_LDB(B0, 1, 0); PG8_LDB(B1, 1, 1); PG8_SCHED; PG8_LDA(At, 1, 0); PG8_STAGE(PG8_SA(0, 1), a2 + hstepA, voffA);
;             PG8_WAIT_V(8); PG8_WAIT_L(0); PG8_BAR; PG8_MMA(0, 0, At, B0); PG8_MMA(0, 1, At, B1); PG8_BAR; PG8_SCHED;
	s_waitcnt lgkmcnt(0)
	v_mfma_f32_16x16x32_bf16 v[140:143], v[56:59], v[184:187], v[140:143]
	v_mfma_f32_16x16x32_bf16 v[136:139], v[72:75], v[184:187], v[136:139]
	v_mfma_f32_16x16x32_bf16 v[124:127], v[56:59], v[196:199], v[124:127]
	v_mfma_f32_16x16x32_bf16 v[120:123], v[72:75], v[196:199], v[120:123]
	v_mfma_f32_16x16x32_bf16 v[108:111], v[56:59], v[208:211], v[108:111]
	v_mfma_f32_16x16x32_bf16 v[104:107], v[72:75], v[208:211], v[104:107]
	v_mfma_f32_16x16x32_bf16 v[92:95], v[56:59], v[216:219], v[92:95]
	v_mfma_f32_16x16x32_bf16 v[88:91], v[72:75], v[216:219], v[88:91]
	v_mfma_f32_16x16x32_bf16 v[140:143], v[60:63], v[190:193], v[140:143]
	v_mfma_f32_16x16x32_bf16 v[136:139], v[76:79], v[190:193], v[136:139]
	v_mfma_f32_16x16x32_bf16 v[124:127], v[60:63], v[202:205], v[124:127]
	v_mfma_f32_16x16x32_bf16 v[120:123], v[76:79], v[202:205], v[120:123]
	v_mfma_f32_16x16x32_bf16 v[108:111], v[60:63], v[212:215], v[108:111]
	v_mfma_f32_16x16x32_bf16 v[104:107], v[76:79], v[212:215], v[104:107]
	v_mfma_f32_16x16x32_bf16 v[92:95], v[60:63], v[220:223], v[92:95]
	v_mfma_f32_16x16x32_bf16 v[88:91], v[76:79], v[220:223], v[88:91]
	v_mfma_f32_16x16x32_bf16 v[132:135], v[144:147], v[184:187], v[132:135]
	v_mfma_f32_16x16x32_bf16 v[128:131], v[168:171], v[184:187], v[128:131]
	v_mfma_f32_16x16x32_bf16 v[116:119], v[144:147], v[196:199], v[116:119]
	v_mfma_f32_16x16x32_bf16 v[112:115], v[168:171], v[196:199], v[112:115]
	v_mfma_f32_16x16x32_bf16 v[100:103], v[144:147], v[208:211], v[100:103]
	v_mfma_f32_16x16x32_bf16 v[96:99], v[168:171], v[208:211], v[96:99]
	v_mfma_f32_16x16x32_bf16 v[84:87], v[144:147], v[216:219], v[84:87]
	v_mfma_f32_16x16x32_bf16 v[80:83], v[168:171], v[216:219], v[80:83]
	v_mfma_f32_16x16x32_bf16 v[132:135], v[148:151], v[190:193], v[132:135]
	v_mfma_f32_16x16x32_bf16 v[128:131], v[178:181], v[190:193], v[128:131]
	v_mfma_f32_16x16x32_bf16 v[116:119], v[148:151], v[202:205], v[116:119]
	v_mfma_f32_16x16x32_bf16 v[112:115], v[178:181], v[202:205], v[112:115]
	v_mfma_f32_16x16x32_bf16 v[100:103], v[148:151], v[212:215], v[100:103]
	v_mfma_f32_16x16x32_bf16 v[96:99], v[178:181], v[212:215], v[96:99]
	v_mfma_f32_16x16x32_bf16 v[84:87], v[148:151], v[220:223], v[84:87]
	v_mfma_f32_16x16x32_bf16 v[80:83], v[178:181], v[220:223], v[80:83]
	s_barrier
	s_add_i32 s81, s73, s58
	v_lshl_add_u64 v[174:175], s[54:55], 0, v[154:155]
	s_mov_b32 m0, s81
	ds_read_b128 v[184:187], v201 offset:16384
	ds_read_b128 v[190:193], v201 offset:17408
	ds_read_b128 v[196:199], v201 offset:18432
	ds_read_b128 v[202:205], v201 offset:19456
	ds_read_b128 v[208:211], v201 offset:20480
	ds_read_b128 v[212:215], v201 offset:21504
	ds_read_b128 v[216:219], v201 offset:22528
	ds_read_b128 v[220:223], v201 offset:23552
	global_load_lds_dwordx4 v[174:175], off
	s_add_i32 m0, s81, 0x2000
	s_add_u32 s82, s54, 0x40000
	v_lshl_add_u64 v[224:225], s[54:55], 0, v[158:159]
	s_addc_u32 s83, s55, 0
	s_add_i32 s81, s74, s58
	global_load_lds_dwordx4 v[224:225], off
	v_lshl_add_u64 v[226:227], s[82:83], 0, v[154:155]
	s_mov_b32 m0, s81
	v_lshl_add_u64 v[228:229], s[56:57], 0, v[156:157]
	global_load_lds_dwordx4 v[226:227], off
	v_lshl_add_u64 v[226:227], s[82:83], 0, v[158:159]
	s_add_i32 m0, s81, 0x2000
	s_nop 0
	global_load_lds_dwordx4 v[226:227], off
	v_lshl_add_u64 v[226:227], s[56:57], 0, v[152:153]
	s_mov_b32 m0, s43
	s_nop 0
	global_load_lds_dwordx4 v[226:227], off
	s_mov_b32 m0, s59
	s_nop 0
	global_load_lds_dwordx4 v[228:229], off
	s_waitcnt vmcnt(8)
	s_waitcnt lgkmcnt(0)
	s_barrier
	s_waitcnt lgkmcnt(0)
	v_mfma_f32_16x16x32_bf16 v[68:71], v[56:59], v[184:187], v[68:71]
	v_mfma_f32_16x16x32_bf16 v[64:67], v[72:75], v[184:187], v[64:67]
	v_mfma_f32_16x16x32_bf16 v[44:47], v[56:59], v[196:199], v[44:47]
	v_mfma_f32_16x16x32_bf16 v[40:43], v[72:75], v[196:199], v[40:43]
	v_mfma_f32_16x16x32_bf16 v[28:31], v[56:59], v[208:211], v[28:31]
	v_mfma_f32_16x16x32_bf16 v[24:27], v[72:75], v[208:211], v[24:27]
	v_mfma_f32_16x16x32_bf16 v[12:15], v[56:59], v[216:219], v[12:15]
	v_mfma_f32_16x16x32_bf16 v[8:11], v[72:75], v[216:219], v[8:11]
	v_mfma_f32_16x16x32_bf16 v[68:71], v[60:63], v[190:193], v[68:71]
	v_mfma_f32_16x16x32_bf16 v[64:67], v[76:79], v[190:193], v[64:67]
	v_mfma_f32_16x16x32_bf16 v[44:47], v[60:63], v[202:205], v[44:47]
	v_mfma_f32_16x16x32_bf16 v[40:43], v[76:79], v[202:205], v[40:43]
	v_mfma_f32_16x16x32_bf16 v[28:31], v[60:63], v[212:215], v[28:31]
	v_mfma_f32_16x16x32_bf16 v[24:27], v[76:79], v[212:215], v[24:27]
	v_mfma_f32_16x16x32_bf16 v[12:15], v[60:63], v[220:223], v[12:15]
	v_mfma_f32_16x16x32_bf16 v[8:11], v[76:79], v[220:223], v[8:11]
	v_mfma_f32_16x16x32_bf16 v[52:55], v[144:147], v[184:187], v[52:55]
	v_mfma_f32_16x16x32_bf16 v[48:51], v[168:171], v[184:187], v[48:51]
	v_mfma_f32_16x16x32_bf16 v[36:39], v[144:147], v[196:199], v[36:39]
	v_mfma_f32_16x16x32_bf16 v[32:35], v[168:171], v[196:199], v[32:35]
	v_mfma_f32_16x16x32_bf16 v[20:23], v[144:147], v[208:211], v[20:23]
	v_mfma_f32_16x16x32_bf16 v[16:19], v[168:171], v[208:211], v[16:19]
	v_mfma_f32_16x16x32_bf16 v[4:7], v[144:147], v[216:219], v[4:7]
	v_mfma_f32_16x16x32_bf16 v[0:3], v[168:171], v[216:219], v[0:3]
	v_mfma_f32_16x16x32_bf16 v[52:55], v[148:151], v[190:193], v[52:55]
	v_mfma_f32_16x16x32_bf16 v[48:51], v[178:181], v[190:193], v[48:51]
	v_mfma_f32_16x16x32_bf16 v[36:39], v[148:151], v[202:205], v[36:39]
	v_mfma_f32_16x16x32_bf16 v[32:35], v[178:181], v[202:205], v[32:35]
	v_mfma_f32_16x16x32_bf16 v[20:23], v[148:151], v[212:215], v[20:23]
	v_mfma_f32_16x16x32_bf16 v[16:19], v[178:181], v[212:215], v[16:19]
	v_mfma_f32_16x16x32_bf16 v[4:7], v[148:151], v[220:223], v[4:7]
	v_mfma_f32_16x16x32_bf16 v[0:3], v[178:181], v[220:223], v[0:3]
	s_barrier
; #define PG8_STAGE(bufoff, gbase, voff) do { _Pragma("unroll") for (int _i = 0; _i < 2; ++_i) \
;         __builtin_amdgcn_global_load_lds((const unsigned*)((const char*)(gbase) + (voff)[_i]), (LAS unsigned*)(lds + (bufoff) + ldsw + _i * 8192), 16, 0, 0); } while (0)
; #define PG8_LDA(dst, b, h) do { _Pragma("unroll") for (int m = 0; m < 4; ++m) _Pragma("unroll") for (int k = 0; k < 2; ++k) dst[m][k] = *(const LAS bf16x8*)(lds + PG8_SA(b, h) + aoff + m * 2048 + k * 1024); } while (0)
; #define PG8_MMA(ai, bj, At, Bt) do { __builtin_amdgcn_s_setprio(1); _Pragma("unroll") for (int m = 0; m < 4; ++m) _Pragma("unroll") for (int n = 0; n < 2; ++n) _Pragma("unroll") for (int k = 0; k < 2; ++k) \
;         acc[ai][bj][m][n] = __builtin_amdgcn_mfma_f32_16x16x32_bf16(Bt[n][k], At[m][k], acc[ai][bj][m][n], 0, 0, 0); __builtin_amdgcn_s_setprio(0); } while (0)
; #define PG8_WAIT_V(n) asm volatile("s_waitcnt vmcnt(" #n ")" ::: "memory")
; #define PG8_WAIT_L(n) asm volatile("s_waitcnt lgkmcnt(" #n ")" ::: "memory")
; #define PG8_BAR __builtin_amdgcn_s_barrier()
; #define PG8_SCHED __builtin_amdgcn_sched_barrier(0)
; template <class Epi>
; __device__ __forceinline__ void gemm_phase(LAS unsigned char* lds, const Gemm g, const StaticOrder& S, const Epi& E) {
;     ...
;             PG8_LDA(At, 1, 1); PG8_STAGE(PG8_SB(1, 0), b3, voffB); PG8_STAGE(PG8_SB(1, 1), b3 + hstepB, voffB); PG8_STAGE(PG8_SA(1, 0), a3, voffA);
;             PG8_WAIT_V(8); PG8_WAIT_L(0); PG8_BAR; PG8_MMA(1, 0, At, B0); PG8_MMA(1, 1, At, B1); PG8_BAR; PG8_SCHED;
	s_add_i32 s81, 0, 0x18000
	s_add_i32 s82, 0, 0x1c000
	v_add_u32_e32 v76, s81, v183
	v_add_u32_e32 v172, s82, v183
	ds_read_b128 v[56:59], v76
	ds_read_b128 v[60:63], v76 offset:1024
	ds_read_b128 v[72:75], v76 offset:2048
	ds_read_b128 v[76:79], v76 offset:3072
	ds_read_b128 v[144:147], v172
	ds_read_b128 v[148:151], v172 offset:1024
	ds_read_b128 v[168:171], v172 offset:2048
	ds_read_b128 v[178:181], v172 offset:3072
	s_add_u32 s56, s56, 0x40000
	s_addc_u32 s57, s57, 0
	s_mov_b32 m0, s62
	v_lshl_add_u64 v[230:231], s[56:57], 0, v[152:153]
	ds_read_b128 v[184:187], v201 offset:32768
	ds_read_b128 v[190:193], v201 offset:33792
	ds_read_b128 v[196:199], v201 offset:34816
	ds_read_b128 v[202:205], v201 offset:35840
	ds_read_b128 v[208:211], v201 offset:36864
	ds_read_b128 v[212:215], v201 offset:37888
	ds_read_b128 v[216:219], v201 offset:38912
	ds_read_b128 v[220:223], v201 offset:39936
	global_load_lds_dwordx4 v[230:231], off
	v_lshl_add_u64 v[230:231], s[56:57], 0, v[156:157]
	s_mov_b32 m0, s63
	s_nop 0
	global_load_lds_dwordx4 v[230:231], off
	s_waitcnt vmcnt(8)
	s_waitcnt lgkmcnt(0)
	s_barrier
	s_waitcnt lgkmcnt(0)
	v_mfma_f32_16x16x32_bf16 v[140:143], v[56:59], v[184:187], v[140:143]
	v_mfma_f32_16x16x32_bf16 v[136:139], v[72:75], v[184:187], v[136:139]
	v_mfma_f32_16x16x32_bf16 v[124:127], v[56:59], v[196:199], v[124:127]
	v_mfma_f32_16x16x32_bf16 v[120:123], v[72:75], v[196:199], v[120:123]
	v_mfma_f32_16x16x32_bf16 v[108:111], v[56:59], v[208:211], v[108:111]
	v_mfma_f32_16x16x32_bf16 v[104:107], v[72:75], v[208:211], v[104:107]
	v_mfma_f32_16x16x32_bf16 v[92:95], v[56:59], v[216:219], v[92:95]
	v_mfma_f32_16x16x32_bf16 v[88:91], v[72:75], v[216:219], v[88:91]
	v_mfma_f32_16x16x32_bf16 v[140:143], v[60:63], v[190:193], v[140:143]
	v_mfma_f32_16x16x32_bf16 v[136:139], v[76:79], v[190:193], v[136:139]
	v_mfma_f32_16x16x32_bf16 v[124:127], v[60:63], v[202:205], v[124:127]
	v_mfma_f32_16x16x32_bf16 v[120:123], v[76:79], v[202:205], v[120:123]
	v_mfma_f32_16x16x32_bf16 v[108:111], v[60:63], v[212:215], v[108:111]
	v_mfma_f32_16x16x32_bf16 v[104:107], v[76:79], v[212:215], v[104:107]
	v_mfma_f32_16x16x32_bf16 v[92:95], v[60:63], v[220:223], v[92:95]
	v_mfma_f32_16x16x32_bf16 v[88:91], v[76:79], v[220:223], v[88:91]
	v_mfma_f32_16x16x32_bf16 v[132:135], v[144:147], v[184:187], v[132:135]
	v_mfma_f32_16x16x32_bf16 v[128:131], v[168:171], v[184:187], v[128:131]
	v_mfma_f32_16x16x32_bf16 v[116:119], v[144:147], v[196:199], v[116:119]
	v_mfma_f32_16x16x32_bf16 v[112:115], v[168:171], v[196:199], v[112:115]
	v_mfma_f32_16x16x32_bf16 v[100:103], v[144:147], v[208:211], v[100:103]
	v_mfma_f32_16x16x32_bf16 v[96:99], v[168:171], v[208:211], v[96:99]
	v_mfma_f32_16x16x32_bf16 v[84:87], v[144:147], v[216:219], v[84:87]
	v_mfma_f32_16x16x32_bf16 v[80:83], v[168:171], v[216:219], v[80:83]
	v_mfma_f32_16x16x32_bf16 v[132:135], v[148:151], v[190:193], v[132:135]
	v_mfma_f32_16x16x32_bf16 v[128:131], v[178:181], v[190:193], v[128:131]
	v_mfma_f32_16x16x32_bf16 v[116:119], v[148:151], v[202:205], v[116:119]
	v_mfma_f32_16x16x32_bf16 v[112:115], v[178:181], v[202:205], v[112:115]
	v_mfma_f32_16x16x32_bf16 v[100:103], v[148:151], v[212:215], v[100:103]
	v_mfma_f32_16x16x32_bf16 v[96:99], v[178:181], v[212:215], v[96:99]
	v_mfma_f32_16x16x32_bf16 v[84:87], v[148:151], v[220:223], v[84:87]
	v_mfma_f32_16x16x32_bf16 v[80:83], v[178:181], v[220:223], v[80:83]
	s_barrier
; #define PG8_MMA(ai, bj, At, Bt) do { __builtin_amdgcn_s_setprio(1); _Pragma("unroll") for (int m = 0; m < 4; ++m) _Pragma("unroll") for (int n = 0; n < 2; ++n) _Pragma("unroll") for (int k = 0; k < 2; ++k) \
;         acc[ai][bj][m][n] = __builtin_amdgcn_mfma_f32_16x16x32_bf16(Bt[n][k], At[m][k], acc[ai][bj][m][n], 0, 0, 0); __builtin_amdgcn_s_setprio(0); } while (0)
; #define PG8_WAIT_V(n) asm volatile("s_waitcnt vmcnt(" #n ")" ::: "memory")
; #define PG8_WAIT_L(n) asm volatile("s_waitcnt lgkmcnt(" #n ")" ::: "memory")
; #define PG8_BAR __builtin_amdgcn_s_barrier()
; #define PG8_SCHED __builtin_amdgcn_sched_barrier(0)
; template <class Epi>
; __device__ __forceinline__ void gemm_phase(LAS unsigned char* lds, const Gemm g, const StaticOrder& S, const Epi& E) {
;     ...
;             PG8_WAIT_V(8); PG8_WAIT_L(0); PG8_BAR; PG8_MMA(1, 0, At, B0); PG8_MMA(1, 1, At, B1); PG8_BAR; PG8_SCHED;
;         }
;         if (wr == 0) PG8_BAR;
	s_add_i32 s56, s81, s58
	v_lshl_add_u64 v[174:175], v[174:175], 0, s[12:13]
	s_mov_b32 m0, s56
	ds_read_b128 v[184:187], v201 offset:49152
	ds_read_b128 v[190:193], v201 offset:50176
	ds_read_b128 v[196:199], v201 offset:51200
	ds_read_b128 v[202:205], v201 offset:52224
	ds_read_b128 v[208:211], v201 offset:53248
	ds_read_b128 v[212:215], v201 offset:54272
	ds_read_b128 v[216:219], v201 offset:55296
	ds_read_b128 v[220:223], v201 offset:56320
	global_load_lds_dwordx4 v[174:175], off
	s_add_i32 m0, s56, 0x2000
	s_add_u32 s54, s54, 0x40080
	v_lshl_add_u64 v[174:175], v[224:225], 0, s[12:13]
	s_addc_u32 s55, s55, 0
	s_add_i32 s56, s82, s58
	global_load_lds_dwordx4 v[174:175], off
	v_lshl_add_u64 v[174:175], s[54:55], 0, v[154:155]
	s_mov_b32 m0, s56
	s_nop 0
	global_load_lds_dwordx4 v[174:175], off
	v_lshl_add_u64 v[174:175], s[54:55], 0, v[158:159]
	s_add_i32 m0, s56, 0x2000
	s_nop 0
	global_load_lds_dwordx4 v[174:175], off
	v_lshl_add_u64 v[174:175], v[226:227], 0, s[12:13]
	s_mov_b32 m0, s69
	s_nop 0
	global_load_lds_dwordx4 v[174:175], off
	v_lshl_add_u64 v[174:175], v[228:229], 0, s[12:13]
	s_mov_b32 m0, s70
	s_nop 0
	global_load_lds_dwordx4 v[174:175], off
	s_waitcnt vmcnt(8)
	s_waitcnt lgkmcnt(0)
	s_barrier
	s_waitcnt lgkmcnt(0)
	v_mfma_f32_16x16x32_bf16 v[68:71], v[56:59], v[184:187], v[68:71]
	v_mfma_f32_16x16x32_bf16 v[64:67], v[72:75], v[184:187], v[64:67]
	v_mfma_f32_16x16x32_bf16 v[44:47], v[56:59], v[196:199], v[44:47]
	v_mfma_f32_16x16x32_bf16 v[40:43], v[72:75], v[196:199], v[40:43]
	v_mfma_f32_16x16x32_bf16 v[28:31], v[56:59], v[208:211], v[28:31]
	v_mfma_f32_16x16x32_bf16 v[24:27], v[72:75], v[208:211], v[24:27]
	v_mfma_f32_16x16x32_bf16 v[12:15], v[56:59], v[216:219], v[12:15]
	v_mfma_f32_16x16x32_bf16 v[8:11], v[72:75], v[216:219], v[8:11]
	v_mfma_f32_16x16x32_bf16 v[68:71], v[60:63], v[190:193], v[68:71]
	v_mfma_f32_16x16x32_bf16 v[64:67], v[76:79], v[190:193], v[64:67]
	v_mfma_f32_16x16x32_bf16 v[44:47], v[60:63], v[202:205], v[44:47]
	v_mfma_f32_16x16x32_bf16 v[40:43], v[76:79], v[202:205], v[40:43]
	v_mfma_f32_16x16x32_bf16 v[28:31], v[60:63], v[212:215], v[28:31]
	v_mfma_f32_16x16x32_bf16 v[24:27], v[76:79], v[212:215], v[24:27]
	v_mfma_f32_16x16x32_bf16 v[12:15], v[60:63], v[220:223], v[12:15]
	v_mfma_f32_16x16x32_bf16 v[8:11], v[76:79], v[220:223], v[8:11]
	v_mfma_f32_16x16x32_bf16 v[52:55], v[144:147], v[184:187], v[52:55]
	v_mfma_f32_16x16x32_bf16 v[48:51], v[168:171], v[184:187], v[48:51]
	v_mfma_f32_16x16x32_bf16 v[36:39], v[144:147], v[196:199], v[36:39]
	v_mfma_f32_16x16x32_bf16 v[32:35], v[168:171], v[196:199], v[32:35]
	v_mfma_f32_16x16x32_bf16 v[20:23], v[144:147], v[208:211], v[20:23]
	v_mfma_f32_16x16x32_bf16 v[16:19], v[168:171], v[208:211], v[16:19]
	v_mfma_f32_16x16x32_bf16 v[4:7], v[144:147], v[216:219], v[4:7]
	v_mfma_f32_16x16x32_bf16 v[0:3], v[168:171], v[216:219], v[0:3]
	v_mfma_f32_16x16x32_bf16 v[52:55], v[148:151], v[190:193], v[52:55]
	v_mfma_f32_16x16x32_bf16 v[48:51], v[178:181], v[190:193], v[48:51]
	v_mfma_f32_16x16x32_bf16 v[36:39], v[148:151], v[202:205], v[36:39]
	v_mfma_f32_16x16x32_bf16 v[32:35], v[178:181], v[202:205], v[32:35]
	v_mfma_f32_16x16x32_bf16 v[20:23], v[148:151], v[212:215], v[20:23]
	v_mfma_f32_16x16x32_bf16 v[16:19], v[178:181], v[212:215], v[16:19]
	v_mfma_f32_16x16x32_bf16 v[4:7], v[148:151], v[220:223], v[4:7]
	v_mfma_f32_16x16x32_bf16 v[0:3], v[178:181], v[220:223], v[0:3]
	s_barrier
	s_add_i32 s80, s80, 2
	s_add_u32 s52, s52, 0x100
	s_addc_u32 s53, s53, 0
	s_add_u32 s78, s78, 0x100
	s_addc_u32 s79, s79, 0
	s_cmp_gt_u32 s80, 13
	s_cbranch_scc0 .LBB0_1233
	s_and_b64 vcc, exec, s[14:15]
	s_cbranch_vccz .LBB0_1236
	s_barrier

; #define PG8_STAGE(bufoff, gbase, voff) do { _Pragma("unroll") for (int _i = 0; _i < 2; ++_i) \
;         __builtin_amdgcn_global_load_lds((const unsigned*)((const char*)(gbase) + (voff)[_i]), (LAS unsigned*)(lds + (bufoff) + ldsw + _i * 8192), 16, 0, 0); } while (0)
; #define PG8_LDA(dst, b, h) do { _Pragma("unroll") for (int m = 0; m < 4; ++m) _Pragma("unroll") for (int k = 0; k < 2; ++k) dst[m][k] = *(const LAS bf16x8*)(lds + PG8_SA(b, h) + aoff + m * 2048 + k * 1024); } while (0)
; #define PG8_LDB(dst, b, h) do { _Pragma("unroll") for (int n = 0; n < 2; ++n) _Pragma("unroll") for (int k = 0; k < 2; ++k) dst[n][k] = *(const LAS bf16x8*)(lds + PG8_SB(b, h) + boff + n * 2048 + k * 1024); } while (0)
; #define PG8_MMA(ai, bj, At, Bt) do { __builtin_amdgcn_s_setprio(1); _Pragma("unroll") for (int m = 0; m < 4; ++m) _Pragma("unroll") for (int n = 0; n < 2; ++n) _Pragma("unroll") for (int k = 0; k < 2; ++k) \
;         acc[ai][bj][m][n] = __builtin_amdgcn_mfma_f32_16x16x32_bf16(Bt[n][k], At[m][k], acc[ai][bj][m][n], 0, 0, 0); __builtin_amdgcn_s_setprio(0); } while (0)
; #define PG8_BAR __builtin_amdgcn_s_barrier()
; template <class Epi>
; __device__ __forceinline__ void gemm_phase(LAS unsigned char* lds, const Gemm g, const StaticOrder& S, const Epi& E) {
;     ...
;         const bool has_next = S.next(ui + 1, nxt);
;         const char* nA = has_next ? (const char*)g.A + (size_t)nxt.pm * tstepA : cA; const char* nB = has_next ? (const char*)g.Bt + (size_t)nxt.pn * tstepB : cB;
; #pragma nounroll
;         for (int t = 0; t < nt; t += 2) {
;             const bool last = (t == nt - 2);
;             const char* a1 = cA + (size_t)(t + 1) * kstep;
;             const char* a2 = last ? nA : cA + (size_t)(t + 2) * kstep; const char* b2 = last ? nB : cB + (size_t)(t + 2) * kstep;
;             const char* a3 = a2 + kstep; const char* b3 = b2 + kstep;
;             PG8_LDB(B0, 0, 0); PG8_LDB(B1, 0, 1); PG8_SCHED; PG8_LDA(At, 0, 0); PG8_STAGE(PG8_SA(1, 1), a1 + hstepA, voffA);
;             PG8_WAIT_V(8); PG8_WAIT_L(0); PG8_BAR; PG8_MMA(0, 0, At, B0); PG8_MMA(0, 1, At, B1); PG8_BAR; PG8_SCHED;
;             PG8_LDA(At, 0, 1); PG8_STAGE(PG8_SB(0, 0), b2, voffB); PG8_STAGE(PG8_SB(0, 1), b2 + hstepB, voffB); PG8_STAGE(PG8_SA(0, 0), a2, voffA);
;             PG8_WAIT_V(8); PG8_WAIT_L(0); PG8_BAR; PG8_MMA(1, 0, At, B0); PG8_MMA(1, 1, At, B1); PG8_BAR; PG8_SCHED;
.LBB0_1313:
	s_ashr_i32 s19, s18, 31
	s_lshl_b64 s[20:21], s[18:19], 21
	s_add_u32 s20, s26, s20
	s_addc_u32 s21, s27, s21
	s_and_b64 s[22:23], s[4:5], exec
	s_cselect_b32 s1, s21, s39
	s_cselect_b32 s19, s20, s38
	s_ashr_i32 s17, s16, 31
	s_lshl_b64 s[22:23], s[16:17], 20
	s_add_u32 s22, s3, s22
	s_addc_u32 s23, s33, s23
	s_and_b64 s[52:53], s[4:5], exec
	s_cselect_b32 s17, s23, s43
	s_cselect_b32 s70, s22, s42
	s_add_u32 s38, s38, 0x100080
	s_addc_u32 s39, s39, 0
	s_add_u32 s71, s42, 0x100
	s_addc_u32 s72, s43, 0
	s_mov_b32 s73, -2
	s_waitcnt lgkmcnt(0)
	ds_read_b128 v[128:131], v182
	ds_read_b128 v[132:135], v182 offset:1024
	ds_read_b128 v[136:139], v182 offset:2048
	ds_read_b128 v[140:143], v182 offset:3072
	ds_read_b128 v[160:163], v183
	ds_read_b128 v[164:167], v183 offset:1024
	ds_read_b128 v[168:171], v183 offset:2048
	ds_read_b128 v[172:175], v183 offset:3072
	s_add_u32 s42, s38, 0xfff00080
	s_addc_u32 s43, s39, -1
	s_cmp_eq_u32 s73, 28
	s_cselect_b32 s53, s1, s43
	s_cselect_b32 s52, s19, s42
	s_cselect_b32 s43, s17, s72
	s_cselect_b32 s42, s70, s71
	v_lshl_add_u64 v[178:179], s[38:39], 0, v[152:153]
	s_add_i32 m0, s35, 0xc000
	ds_read_b128 v[186:189], v184
	ds_read_b128 v[190:193], v184 offset:1024
	ds_read_b128 v[194:197], v184 offset:2048
	ds_read_b128 v[198:201], v184 offset:3072
	ds_read_b128 v[202:205], v184 offset:4096
	ds_read_b128 v[206:209], v184 offset:5120
	ds_read_b128 v[210:213], v184 offset:6144
	ds_read_b128 v[214:217], v184 offset:7168
	global_load_lds_dwordx4 v[178:179], off
	v_lshl_add_u64 v[178:179], s[38:39], 0, v[154:155]
	s_add_i32 m0, s35, 0xe000
	s_nop 0
	global_load_lds_dwordx4 v[178:179], off
	s_waitcnt vmcnt(8)
	s_waitcnt lgkmcnt(0)
	s_barrier
	s_waitcnt lgkmcnt(0)
	v_mfma_f32_16x16x32_bf16 v[124:127], v[128:131], v[186:189], 0
	v_mfma_f32_16x16x32_bf16 v[120:123], v[136:139], v[186:189], 0
	v_mfma_f32_16x16x32_bf16 v[108:111], v[128:131], v[194:197], 0
	v_mfma_f32_16x16x32_bf16 v[104:107], v[136:139], v[194:197], 0
	v_mfma_f32_16x16x32_bf16 v[92:95], v[128:131], v[202:205], 0
	v_mfma_f32_16x16x32_bf16 v[88:91], v[136:139], v[202:205], 0
	v_mfma_f32_16x16x32_bf16 v[76:79], v[128:131], v[210:213], 0
	v_mfma_f32_16x16x32_bf16 v[72:75], v[136:139], v[210:213], 0
	v_mfma_f32_16x16x32_bf16 v[124:127], v[132:135], v[190:193], v[124:127]
	v_mfma_f32_16x16x32_bf16 v[120:123], v[140:143], v[190:193], v[120:123]
	v_mfma_f32_16x16x32_bf16 v[108:111], v[132:135], v[198:201], v[108:111]
	v_mfma_f32_16x16x32_bf16 v[104:107], v[140:143], v[198:201], v[104:107]
	v_mfma_f32_16x16x32_bf16 v[92:95], v[132:135], v[206:209], v[92:95]
	v_mfma_f32_16x16x32_bf16 v[88:91], v[140:143], v[206:209], v[88:91]
	v_mfma_f32_16x16x32_bf16 v[76:79], v[132:135], v[214:217], v[76:79]
	v_mfma_f32_16x16x32_bf16 v[72:75], v[140:143], v[214:217], v[72:75]
	v_mfma_f32_16x16x32_bf16 v[116:119], v[160:163], v[186:189], 0
	v_mfma_f32_16x16x32_bf16 v[112:115], v[168:171], v[186:189], 0
	v_mfma_f32_16x16x32_bf16 v[100:103], v[160:163], v[194:197], 0
	v_mfma_f32_16x16x32_bf16 v[96:99], v[168:171], v[194:197], 0
	v_mfma_f32_16x16x32_bf16 v[84:87], v[160:163], v[202:205], 0
	v_mfma_f32_16x16x32_bf16 v[80:83], v[168:171], v[202:205], 0
	v_mfma_f32_16x16x32_bf16 v[68:71], v[160:163], v[210:213], 0
	v_mfma_f32_16x16x32_bf16 v[64:67], v[168:171], v[210:213], 0
	v_mfma_f32_16x16x32_bf16 v[116:119], v[164:167], v[190:193], v[116:119]
	v_mfma_f32_16x16x32_bf16 v[112:115], v[172:175], v[190:193], v[112:115]
	v_mfma_f32_16x16x32_bf16 v[100:103], v[164:167], v[198:201], v[100:103]
	v_mfma_f32_16x16x32_bf16 v[96:99], v[172:175], v[198:201], v[96:99]
	v_mfma_f32_16x16x32_bf16 v[84:87], v[164:167], v[206:209], v[84:87]
	v_mfma_f32_16x16x32_bf16 v[80:83], v[172:175], v[206:209], v[80:83]
	v_mfma_f32_16x16x32_bf16 v[68:71], v[164:167], v[214:217], v[68:71]
	v_mfma_f32_16x16x32_bf16 v[64:67], v[172:175], v[214:217], v[64:67]
	s_barrier
	s_add_i32 s74, s68, s54
	v_lshl_add_u64 v[178:179], s[42:43], 0, v[146:147]
	s_mov_b32 m0, s74
	ds_read_b128 v[186:189], v184 offset:16384
	ds_read_b128 v[190:193], v184 offset:17408
	ds_read_b128 v[194:197], v184 offset:18432
	ds_read_b128 v[198:201], v184 offset:19456
	ds_read_b128 v[202:205], v184 offset:20480
	ds_read_b128 v[206:209], v184 offset:21504
	ds_read_b128 v[210:213], v184 offset:22528
	ds_read_b128 v[214:217], v184 offset:23552
	global_load_lds_dwordx4 v[178:179], off
	s_add_i32 m0, s74, 0x2000
	s_add_u32 s74, s42, 0x80000
	v_lshl_add_u64 v[218:219], s[42:43], 0, v[150:151]
	s_addc_u32 s75, s43, 0
	s_add_i32 s76, s69, s54
	global_load_lds_dwordx4 v[218:219], off
	v_lshl_add_u64 v[220:221], s[74:75], 0, v[146:147]
	s_mov_b32 m0, s76
	v_lshl_add_u64 v[222:223], s[52:53], 0, v[148:149]
	global_load_lds_dwordx4 v[220:221], off
	v_lshl_add_u64 v[220:221], s[74:75], 0, v[150:151]
	s_add_i32 m0, s76, 0x2000
	s_nop 0
	global_load_lds_dwordx4 v[220:221], off
	v_lshl_add_u64 v[220:221], s[52:53], 0, v[144:145]
	s_mov_b32 m0, s35
	s_nop 0
	global_load_lds_dwordx4 v[220:221], off
	s_mov_b32 m0, s55
	s_nop 0
	global_load_lds_dwordx4 v[222:223], off
	s_waitcnt vmcnt(8)
	s_waitcnt lgkmcnt(0)
	s_barrier
; #define PG8_STAGE(bufoff, gbase, voff) do { _Pragma("unroll") for (int _i = 0; _i < 2; ++_i) \
;         __builtin_amdgcn_global_load_lds((const unsigned*)((const char*)(gbase) + (voff)[_i]), (LAS unsigned*)(lds + (bufoff) + ldsw + _i * 8192), 16, 0, 0); } while (0)
; #define PG8_LDA(dst, b, h) do { _Pragma("unroll") for (int m = 0; m < 4; ++m) _Pragma("unroll") for (int k = 0; k < 2; ++k) dst[m][k] = *(const LAS bf16x8*)(lds + PG8_SA(b, h) + aoff + m * 2048 + k * 1024); } while (0)
; #define PG8_LDB(dst, b, h) do { _Pragma("unroll") for (int n = 0; n < 2; ++n) _Pragma("unroll") for (int k = 0; k < 2; ++k) dst[n][k] = *(const LAS bf16x8*)(lds + PG8_SB(b, h) + boff + n * 2048 + k * 1024); } while (0)
; #define PG8_MMA(ai, bj, At, Bt) do { __builtin_amdgcn_s_setprio(1); _Pragma("unroll") for (int m = 0; m < 4; ++m) _Pragma("unroll") for (int n = 0; n < 2; ++n) _Pragma("unroll") for (int k = 0; k < 2; ++k) \
;         acc[ai][bj][m][n] = __builtin_amdgcn_mfma_f32_16x16x32_bf16(Bt[n][k], At[m][k], acc[ai][bj][m][n], 0, 0, 0); __builtin_amdgcn_s_setprio(0); } while (0)
; #define PG8_WAIT_V(n) asm volatile("s_waitcnt vmcnt(" #n ")" ::: "memory")
; #define PG8_WAIT_L(n) asm volatile("s_waitcnt lgkmcnt(" #n ")" ::: "memory")
; #define PG8_BAR __builtin_amdgcn_s_barrier()
; #define PG8_SCHED __builtin_amdgcn_sched_barrier(0)
; template <class Epi>
; __device__ __forceinline__ void gemm_phase(LAS unsigned char* lds, const Gemm g, const StaticOrder& S, const Epi& E) {
;     ...
;             PG8_WAIT_V(8); PG8_WAIT_L(0); PG8_BAR; PG8_MMA(1, 0, At, B0); PG8_MMA(1, 1, At, B1); PG8_BAR; PG8_SCHED;
;             PG8_LDB(B0, 1, 0); PG8_LDB(B1, 1, 1); PG8_SCHED; PG8_LDA(At, 1, 0); PG8_STAGE(PG8_SA(0, 1), a2 + hstepA, voffA);
;             PG8_WAIT_V(8); PG8_WAIT_L(0); PG8_BAR; PG8_MMA(0, 0, At, B0); PG8_MMA(0, 1, At, B1); PG8_BAR; PG8_SCHED;
;             PG8_LDA(At, 1, 1); PG8_STAGE(PG8_SB(1, 0), b3, voffB); PG8_STAGE(PG8_SB(1, 1), b3 + hstepB, voffB); PG8_STAGE(PG8_SA(1, 0), a3, voffA);
;             PG8_WAIT_V(8); PG8_WAIT_L(0); PG8_BAR; PG8_MMA(1, 0, At, B0); PG8_MMA(1, 1, At, B1); PG8_BAR; PG8_SCHED;
	s_waitcnt lgkmcnt(0)
	v_mfma_f32_16x16x32_bf16 v[60:63], v[128:131], v[186:189], 0
	v_mfma_f32_16x16x32_bf16 v[56:59], v[136:139], v[186:189], 0
	v_mfma_f32_16x16x32_bf16 v[44:47], v[128:131], v[194:197], 0
	v_mfma_f32_16x16x32_bf16 v[40:43], v[136:139], v[194:197], 0
	v_mfma_f32_16x16x32_bf16 v[28:31], v[128:131], v[202:205], 0
	v_mfma_f32_16x16x32_bf16 v[24:27], v[136:139], v[202:205], 0
	v_mfma_f32_16x16x32_bf16 v[12:15], v[128:131], v[210:213], 0
	v_mfma_f32_16x16x32_bf16 v[8:11], v[136:139], v[210:213], 0
	v_mfma_f32_16x16x32_bf16 v[60:63], v[132:135], v[190:193], v[60:63]
	v_mfma_f32_16x16x32_bf16 v[56:59], v[140:143], v[190:193], v[56:59]
	v_mfma_f32_16x16x32_bf16 v[44:47], v[132:135], v[198:201], v[44:47]
	v_mfma_f32_16x16x32_bf16 v[40:43], v[140:143], v[198:201], v[40:43]
	v_mfma_f32_16x16x32_bf16 v[28:31], v[132:135], v[206:209], v[28:31]
	v_mfma_f32_16x16x32_bf16 v[24:27], v[140:143], v[206:209], v[24:27]
	v_mfma_f32_16x16x32_bf16 v[12:15], v[132:135], v[214:217], v[12:15]
	v_mfma_f32_16x16x32_bf16 v[8:11], v[140:143], v[214:217], v[8:11]
	v_mfma_f32_16x16x32_bf16 v[52:55], v[160:163], v[186:189], 0
	v_mfma_f32_16x16x32_bf16 v[48:51], v[168:171], v[186:189], 0
	v_mfma_f32_16x16x32_bf16 v[36:39], v[160:163], v[194:197], 0
	v_mfma_f32_16x16x32_bf16 v[32:35], v[168:171], v[194:197], 0
	v_mfma_f32_16x16x32_bf16 v[20:23], v[160:163], v[202:205], 0
	v_mfma_f32_16x16x32_bf16 v[16:19], v[168:171], v[202:205], 0
	v_mfma_f32_16x16x32_bf16 v[4:7], v[160:163], v[210:213], 0
	v_mfma_f32_16x16x32_bf16 v[0:3], v[168:171], v[210:213], 0
	v_mfma_f32_16x16x32_bf16 v[52:55], v[164:167], v[190:193], v[52:55]
	v_mfma_f32_16x16x32_bf16 v[48:51], v[172:175], v[190:193], v[48:51]
	v_mfma_f32_16x16x32_bf16 v[36:39], v[164:167], v[198:201], v[36:39]
	v_mfma_f32_16x16x32_bf16 v[32:35], v[172:175], v[198:201], v[32:35]
	v_mfma_f32_16x16x32_bf16 v[20:23], v[164:167], v[206:209], v[20:23]
	v_mfma_f32_16x16x32_bf16 v[16:19], v[172:175], v[206:209], v[16:19]
	v_mfma_f32_16x16x32_bf16 v[4:7], v[164:167], v[214:217], v[4:7]
	v_mfma_f32_16x16x32_bf16 v[0:3], v[172:175], v[214:217], v[0:3]
	s_barrier
	s_add_i32 s74, 0, 0x18000
	s_add_i32 s75, 0, 0x1c000
	v_add_u32_e32 v140, s74, v181
	v_add_u32_e32 v172, s75, v181
	ds_read_b128 v[128:131], v140
	ds_read_b128 v[132:135], v140 offset:1024
	ds_read_b128 v[136:139], v140 offset:2048
	ds_read_b128 v[140:143], v140 offset:3072
	ds_read_b128 v[160:163], v172
	ds_read_b128 v[164:167], v172 offset:1024
	ds_read_b128 v[168:171], v172 offset:2048
	ds_read_b128 v[172:175], v172 offset:3072
	s_add_u32 s52, s52, 0x100000
	s_addc_u32 s53, s53, 0
	s_mov_b32 m0, s56
	v_lshl_add_u64 v[224:225], s[52:53], 0, v[144:145]
	ds_read_b128 v[186:189], v184 offset:32768
	ds_read_b128 v[190:193], v184 offset:33792
	ds_read_b128 v[194:197], v184 offset:34816
	ds_read_b128 v[198:201], v184 offset:35840
	ds_read_b128 v[202:205], v184 offset:36864
	ds_read_b128 v[206:209], v184 offset:37888
	ds_read_b128 v[210:213], v184 offset:38912
	ds_read_b128 v[214:217], v184 offset:39936
	global_load_lds_dwordx4 v[224:225], off
	v_lshl_add_u64 v[224:225], s[52:53], 0, v[148:149]
	s_mov_b32 m0, s57
	s_nop 0
	global_load_lds_dwordx4 v[224:225], off
	s_waitcnt vmcnt(8)
	s_waitcnt lgkmcnt(0)
	s_barrier
	s_waitcnt lgkmcnt(0)
	v_mfma_f32_16x16x32_bf16 v[124:127], v[128:131], v[186:189], v[124:127]
	v_mfma_f32_16x16x32_bf16 v[120:123], v[136:139], v[186:189], v[120:123]
	v_mfma_f32_16x16x32_bf16 v[108:111], v[128:131], v[194:197], v[108:111]
	v_mfma_f32_16x16x32_bf16 v[104:107], v[136:139], v[194:197], v[104:107]
	v_mfma_f32_16x16x32_bf16 v[92:95], v[128:131], v[202:205], v[92:95]
	v_mfma_f32_16x16x32_bf16 v[88:91], v[136:139], v[202:205], v[88:91]
	v_mfma_f32_16x16x32_bf16 v[76:79], v[128:131], v[210:213], v[76:79]
	v_mfma_f32_16x16x32_bf16 v[72:75], v[136:139], v[210:213], v[72:75]
	v_mfma_f32_16x16x32_bf16 v[124:127], v[132:135], v[190:193], v[124:127]
	v_mfma_f32_16x16x32_bf16 v[120:123], v[140:143], v[190:193], v[120:123]
	v_mfma_f32_16x16x32_bf16 v[108:111], v[132:135], v[198:201], v[108:111]
	v_mfma_f32_16x16x32_bf16 v[104:107], v[140:143], v[198:201], v[104:107]
	v_mfma_f32_16x16x32_bf16 v[92:95], v[132:135], v[206:209], v[92:95]
	v_mfma_f32_16x16x32_bf16 v[88:91], v[140:143], v[206:209], v[88:91]
	v_mfma_f32_16x16x32_bf16 v[76:79], v[132:135], v[214:217], v[76:79]
	v_mfma_f32_16x16x32_bf16 v[72:75], v[140:143], v[214:217], v[72:75]
	v_mfma_f32_16x16x32_bf16 v[116:119], v[160:163], v[186:189], v[116:119]
	v_mfma_f32_16x16x32_bf16 v[112:115], v[168:171], v[186:189], v[112:115]
	v_mfma_f32_16x16x32_bf16 v[100:103], v[160:163], v[194:197], v[100:103]
	v_mfma_f32_16x16x32_bf16 v[96:99], v[168:171], v[194:197], v[96:99]
	v_mfma_f32_16x16x32_bf16 v[84:87], v[160:163], v[202:205], v[84:87]
	v_mfma_f32_16x16x32_bf16 v[80:83], v[168:171], v[202:205], v[80:83]
	v_mfma_f32_16x16x32_bf16 v[68:71], v[160:163], v[210:213], v[68:71]
	v_mfma_f32_16x16x32_bf16 v[64:67], v[168:171], v[210:213], v[64:67]
	v_mfma_f32_16x16x32_bf16 v[116:119], v[164:167], v[190:193], v[116:119]
	v_mfma_f32_16x16x32_bf16 v[112:115], v[172:175], v[190:193], v[112:115]
	v_mfma_f32_16x16x32_bf16 v[100:103], v[164:167], v[198:201], v[100:103]
	v_mfma_f32_16x16x32_bf16 v[96:99], v[172:175], v[198:201], v[96:99]
	v_mfma_f32_16x16x32_bf16 v[84:87], v[164:167], v[206:209], v[84:87]
	v_mfma_f32_16x16x32_bf16 v[80:83], v[172:175], v[206:209], v[80:83]
	v_mfma_f32_16x16x32_bf16 v[68:71], v[164:167], v[214:217], v[68:71]
	v_mfma_f32_16x16x32_bf16 v[64:67], v[172:175], v[214:217], v[64:67]
	s_barrier
; #define PG8_STAGE(bufoff, gbase, voff) do { _Pragma("unroll") for (int _i = 0; _i < 2; ++_i) \
;         __builtin_amdgcn_global_load_lds((const unsigned*)((const char*)(gbase) + (voff)[_i]), (LAS unsigned*)(lds + (bufoff) + ldsw + _i * 8192), 16, 0, 0); } while (0)
; #define PG8_LDA(dst, b, h) do { _Pragma("unroll") for (int m = 0; m < 4; ++m) _Pragma("unroll") for (int k = 0; k < 2; ++k) dst[m][k] = *(const LAS bf16x8*)(lds + PG8_SA(b, h) + aoff + m * 2048 + k * 1024); } while (0)
; #define PG8_LDB(dst, b, h) do { _Pragma("unroll") for (int n = 0; n < 2; ++n) _Pragma("unroll") for (int k = 0; k < 2; ++k) dst[n][k] = *(const LAS bf16x8*)(lds + PG8_SB(b, h) + boff + n * 2048 + k * 1024); } while (0)
; #define PG8_MMA(ai, bj, At, Bt) do { __builtin_amdgcn_s_setprio(1); _Pragma("unroll") for (int m = 0; m < 4; ++m) _Pragma("unroll") for (int n = 0; n < 2; ++n) _Pragma("unroll") for (int k = 0; k < 2; ++k) \
;         acc[ai][bj][m][n] = __builtin_amdgcn_mfma_f32_16x16x32_bf16(Bt[n][k], At[m][k], acc[ai][bj][m][n], 0, 0, 0); __builtin_amdgcn_s_setprio(0); } while (0)
; #define PG8_WAIT_V(n) asm volatile("s_waitcnt vmcnt(" #n ")" ::: "memory")
; #define PG8_WAIT_L(n) asm volatile("s_waitcnt lgkmcnt(" #n ")" ::: "memory")
; template <class Epi>
; __device__ __forceinline__ void gemm_phase(LAS unsigned char* lds, const Gemm g, const StaticOrder& S, const Epi& E) {
;     ...
;         for (int t = 0; t < nt; t += 2) {
;             const bool last = (t == nt - 2);
;             const char* a1 = cA + (size_t)(t + 1) * kstep;
;             const char* a2 = last ? nA : cA + (size_t)(t + 2) * kstep; const char* b2 = last ? nB : cB + (size_t)(t + 2) * kstep;
;             const char* a3 = a2 + kstep; const char* b3 = b2 + kstep;
;             PG8_LDB(B0, 0, 0); PG8_LDB(B1, 0, 1); PG8_SCHED; PG8_LDA(At, 0, 0); PG8_STAGE(PG8_SA(1, 1), a1 + hstepA, voffA);
;             PG8_WAIT_V(8); PG8_WAIT_L(0); PG8_BAR; PG8_MMA(0, 0, At, B0); PG8_MMA(0, 1, At, B1); PG8_BAR; PG8_SCHED;
;     ...
;             PG8_WAIT_V(8); PG8_WAIT_L(0); PG8_BAR; PG8_MMA(0, 0, At, B0); PG8_MMA(0, 1, At, B1); PG8_BAR; PG8_SCHED;
;             PG8_LDA(At, 1, 1); PG8_STAGE(PG8_SB(1, 0), b3, voffB); PG8_STAGE(PG8_SB(1, 1), b3 + hstepB, voffB); PG8_STAGE(PG8_SA(1, 0), a3, voffA);
;             PG8_WAIT_V(8); PG8_WAIT_L(0); PG8_BAR; PG8_MMA(1, 0, At, B0); PG8_MMA(1, 1, At, B1); PG8_BAR; PG8_SCHED;
	s_add_i32 s52, s74, s54
	v_lshl_add_u64 v[178:179], v[178:179], 0, s[12:13]
	s_mov_b32 m0, s52
	ds_read_b128 v[186:189], v184 offset:49152
	ds_read_b128 v[190:193], v184 offset:50176
	ds_read_b128 v[194:197], v184 offset:51200
	ds_read_b128 v[198:201], v184 offset:52224
	ds_read_b128 v[202:205], v184 offset:53248
	ds_read_b128 v[206:209], v184 offset:54272
	ds_read_b128 v[210:213], v184 offset:55296
	ds_read_b128 v[214:217], v184 offset:56320
	global_load_lds_dwordx4 v[178:179], off
	s_add_i32 m0, s52, 0x2000
	s_add_u32 s42, s42, 0x80080
	v_lshl_add_u64 v[178:179], v[218:219], 0, s[12:13]
	s_addc_u32 s43, s43, 0
	s_add_i32 s52, s75, s54
	global_load_lds_dwordx4 v[178:179], off
	v_lshl_add_u64 v[178:179], s[42:43], 0, v[146:147]
	s_mov_b32 m0, s52
	s_nop 0
	global_load_lds_dwordx4 v[178:179], off
	v_lshl_add_u64 v[178:179], s[42:43], 0, v[150:151]
	s_add_i32 m0, s52, 0x2000
	s_nop 0
	global_load_lds_dwordx4 v[178:179], off
	v_lshl_add_u64 v[178:179], v[220:221], 0, s[12:13]
	s_mov_b32 m0, s61
	s_nop 0
	global_load_lds_dwordx4 v[178:179], off
	v_lshl_add_u64 v[178:179], v[222:223], 0, s[12:13]
	s_mov_b32 m0, s62
	s_nop 0
	global_load_lds_dwordx4 v[178:179], off
	s_waitcnt vmcnt(8)
	s_waitcnt lgkmcnt(0)
	s_barrier
	s_waitcnt lgkmcnt(0)
	v_mfma_f32_16x16x32_bf16 v[60:63], v[128:131], v[186:189], v[60:63]
	v_mfma_f32_16x16x32_bf16 v[56:59], v[136:139], v[186:189], v[56:59]
	v_mfma_f32_16x16x32_bf16 v[44:47], v[128:131], v[194:197], v[44:47]
	v_mfma_f32_16x16x32_bf16 v[40:43], v[136:139], v[194:197], v[40:43]
	v_mfma_f32_16x16x32_bf16 v[28:31], v[128:131], v[202:205], v[28:31]
	v_mfma_f32_16x16x32_bf16 v[24:27], v[136:139], v[202:205], v[24:27]
	v_mfma_f32_16x16x32_bf16 v[12:15], v[128:131], v[210:213], v[12:15]
	v_mfma_f32_16x16x32_bf16 v[8:11], v[136:139], v[210:213], v[8:11]
	v_mfma_f32_16x16x32_bf16 v[60:63], v[132:135], v[190:193], v[60:63]
	v_mfma_f32_16x16x32_bf16 v[56:59], v[140:143], v[190:193], v[56:59]
	v_mfma_f32_16x16x32_bf16 v[44:47], v[132:135], v[198:201], v[44:47]
	v_mfma_f32_16x16x32_bf16 v[40:43], v[140:143], v[198:201], v[40:43]
	v_mfma_f32_16x16x32_bf16 v[28:31], v[132:135], v[206:209], v[28:31]
	v_mfma_f32_16x16x32_bf16 v[24:27], v[140:143], v[206:209], v[24:27]
	v_mfma_f32_16x16x32_bf16 v[12:15], v[132:135], v[214:217], v[12:15]
	v_mfma_f32_16x16x32_bf16 v[8:11], v[140:143], v[214:217], v[8:11]
	v_mfma_f32_16x16x32_bf16 v[52:55], v[160:163], v[186:189], v[52:55]
	v_mfma_f32_16x16x32_bf16 v[48:51], v[168:171], v[186:189], v[48:51]
	v_mfma_f32_16x16x32_bf16 v[36:39], v[160:163], v[194:197], v[36:39]
	v_mfma_f32_16x16x32_bf16 v[32:35], v[168:171], v[194:197], v[32:35]
	v_mfma_f32_16x16x32_bf16 v[20:23], v[160:163], v[202:205], v[20:23]
	v_mfma_f32_16x16x32_bf16 v[16:19], v[168:171], v[202:205], v[16:19]
	v_mfma_f32_16x16x32_bf16 v[4:7], v[160:163], v[210:213], v[4:7]
	v_mfma_f32_16x16x32_bf16 v[0:3], v[168:171], v[210:213], v[0:3]
	v_mfma_f32_16x16x32_bf16 v[52:55], v[164:167], v[190:193], v[52:55]
	v_mfma_f32_16x16x32_bf16 v[48:51], v[172:175], v[190:193], v[48:51]
	v_mfma_f32_16x16x32_bf16 v[36:39], v[164:167], v[198:201], v[36:39]
	v_mfma_f32_16x16x32_bf16 v[32:35], v[172:175], v[198:201], v[32:35]
	v_mfma_f32_16x16x32_bf16 v[20:23], v[164:167], v[206:209], v[20:23]
	v_mfma_f32_16x16x32_bf16 v[16:19], v[172:175], v[206:209], v[16:19]
	v_mfma_f32_16x16x32_bf16 v[4:7], v[164:167], v[214:217], v[4:7]
	v_mfma_f32_16x16x32_bf16 v[0:3], v[172:175], v[214:217], v[0:3]
	s_barrier
	s_add_i32 s73, s73, 2
	s_add_u32 s38, s38, 0x100
	s_addc_u32 s39, s39, 0
	s_add_u32 s71, s71, 0x100
	s_addc_u32 s72, s72, 0
	s_cmp_gt_u32 s73, 29
.LBB0_1314:
	ds_read_b128 v[128:131], v182
	ds_read_b128 v[132:135], v182 offset:1024
	ds_read_b128 v[136:139], v182 offset:2048
	ds_read_b128 v[140:143], v182 offset:3072
	ds_read_b128 v[160:163], v183
	ds_read_b128 v[164:167], v183 offset:1024
	ds_read_b128 v[168:171], v183 offset:2048
	ds_read_b128 v[172:175], v183 offset:3072
	s_add_u32 s42, s38, 0xfff00080
	s_addc_u32 s43, s39, -1
	s_cmp_eq_u32 s73, 28
	s_cselect_b32 s53, s1, s43
	s_cselect_b32 s52, s19, s42
	s_cselect_b32 s43, s17, s72
	s_cselect_b32 s42, s70, s71
	v_lshl_add_u64 v[178:179], s[38:39], 0, v[152:153]
	s_add_i32 m0, s35, 0xc000
	ds_read_b128 v[186:189], v184
	ds_read_b128 v[190:193], v184 offset:1024
	ds_read_b128 v[194:197], v184 offset:2048
	ds_read_b128 v[198:201], v184 offset:3072
	ds_read_b128 v[202:205], v184 offset:4096
	ds_read_b128 v[206:209], v184 offset:5120
	ds_read_b128 v[210:213], v184 offset:6144
	ds_read_b128 v[214:217], v184 offset:7168
	global_load_lds_dwordx4 v[178:179], off
	v_lshl_add_u64 v[178:179], s[38:39], 0, v[154:155]
	s_add_i32 m0, s35, 0xe000
	s_nop 0
	global_load_lds_dwordx4 v[178:179], off
	s_waitcnt vmcnt(8)
	s_waitcnt lgkmcnt(0)
	s_barrier
; #define PG8_STAGE(bufoff, gbase, voff) do { _Pragma("unroll") for (int _i = 0; _i < 2; ++_i) \
;         __builtin_amdgcn_global_load_lds((const unsigned*)((const char*)(gbase) + (voff)[_i]), (LAS unsigned*)(lds + (bufoff) + ldsw + _i * 8192), 16, 0, 0); } while (0)
; #define PG8_LDA(dst, b, h) do { _Pragma("unroll") for (int m = 0; m < 4; ++m) _Pragma("unroll") for (int k = 0; k < 2; ++k) dst[m][k] = *(const LAS bf16x8*)(lds + PG8_SA(b, h) + aoff + m * 2048 + k * 1024); } while (0)
; #define PG8_LDB(dst, b, h) do { _Pragma("unroll") for (int n = 0; n < 2; ++n) _Pragma("unroll") for (int k = 0; k < 2; ++k) dst[n][k] = *(const LAS bf16x8*)(lds + PG8_SB(b, h) + boff + n * 2048 + k * 1024); } while (0)
; #define PG8_MMA(ai, bj, At, Bt) do { __builtin_amdgcn_s_setprio(1); _Pragma("unroll") for (int m = 0; m < 4; ++m) _Pragma("unroll") for (int n = 0; n < 2; ++n) _Pragma("unroll") for (int k = 0; k < 2; ++k) \
;         acc[ai][bj][m][n] = __builtin_amdgcn_mfma_f32_16x16x32_bf16(Bt[n][k], At[m][k], acc[ai][bj][m][n], 0, 0, 0); __builtin_amdgcn_s_setprio(0); } while (0)
; #define PG8_WAIT_V(n) asm volatile("s_waitcnt vmcnt(" #n ")" ::: "memory")
; #define PG8_WAIT_L(n) asm volatile("s_waitcnt lgkmcnt(" #n ")" ::: "memory")
; #define PG8_BAR __builtin_amdgcn_s_barrier()
; #define PG8_SCHED __builtin_amdgcn_sched_barrier(0)
; template <class Epi>
; __device__ __forceinline__ void gemm_phase(LAS unsigned char* lds, const Gemm g, const StaticOrder& S, const Epi& E) {
;     ...
;             PG8_WAIT_V(8); PG8_WAIT_L(0); PG8_BAR; PG8_MMA(0, 0, At, B0); PG8_MMA(0, 1, At, B1); PG8_BAR; PG8_SCHED;
;             PG8_LDA(At, 0, 1); PG8_STAGE(PG8_SB(0, 0), b2, voffB); PG8_STAGE(PG8_SB(0, 1), b2 + hstepB, voffB); PG8_STAGE(PG8_SA(0, 0), a2, voffA);
;             PG8_WAIT_V(8); PG8_WAIT_L(0); PG8_BAR; PG8_MMA(1, 0, At, B0); PG8_MMA(1, 1, At, B1); PG8_BAR; PG8_SCHED;
;             PG8_LDB(B0, 1, 0); PG8_LDB(B1, 1, 1); PG8_SCHED; PG8_LDA(At, 1, 0); PG8_STAGE(PG8_SA(0, 1), a2 + hstepA, voffA);
;             PG8_WAIT_V(8); PG8_WAIT_L(0); PG8_BAR; PG8_MMA(0, 0, At, B0); PG8_MMA(0, 1, At, B1); PG8_BAR; PG8_SCHED;
	s_waitcnt lgkmcnt(0)
	v_mfma_f32_16x16x32_bf16 v[124:127], v[128:131], v[186:189], v[124:127]
	v_mfma_f32_16x16x32_bf16 v[120:123], v[136:139], v[186:189], v[120:123]
	v_mfma_f32_16x16x32_bf16 v[108:111], v[128:131], v[194:197], v[108:111]
	v_mfma_f32_16x16x32_bf16 v[104:107], v[136:139], v[194:197], v[104:107]
	v_mfma_f32_16x16x32_bf16 v[92:95], v[128:131], v[202:205], v[92:95]
	v_mfma_f32_16x16x32_bf16 v[88:91], v[136:139], v[202:205], v[88:91]
	v_mfma_f32_16x16x32_bf16 v[76:79], v[128:131], v[210:213], v[76:79]
	v_mfma_f32_16x16x32_bf16 v[72:75], v[136:139], v[210:213], v[72:75]
	v_mfma_f32_16x16x32_bf16 v[124:127], v[132:135], v[190:193], v[124:127]
	v_mfma_f32_16x16x32_bf16 v[120:123], v[140:143], v[190:193], v[120:123]
	v_mfma_f32_16x16x32_bf16 v[108:111], v[132:135], v[198:201], v[108:111]
	v_mfma_f32_16x16x32_bf16 v[104:107], v[140:143], v[198:201], v[104:107]
	v_mfma_f32_16x16x32_bf16 v[92:95], v[132:135], v[206:209], v[92:95]
	v_mfma_f32_16x16x32_bf16 v[88:91], v[140:143], v[206:209], v[88:91]
	v_mfma_f32_16x16x32_bf16 v[76:79], v[132:135], v[214:217], v[76:79]
	v_mfma_f32_16x16x32_bf16 v[72:75], v[140:143], v[214:217], v[72:75]
	v_mfma_f32_16x16x32_bf16 v[116:119], v[160:163], v[186:189], v[116:119]
	v_mfma_f32_16x16x32_bf16 v[112:115], v[168:171], v[186:189], v[112:115]
	v_mfma_f32_16x16x32_bf16 v[100:103], v[160:163], v[194:197], v[100:103]
	v_mfma_f32_16x16x32_bf16 v[96:99], v[168:171], v[194:197], v[96:99]
	v_mfma_f32_16x16x32_bf16 v[84:87], v[160:163], v[202:205], v[84:87]
	v_mfma_f32_16x16x32_bf16 v[80:83], v[168:171], v[202:205], v[80:83]
	v_mfma_f32_16x16x32_bf16 v[68:71], v[160:163], v[210:213], v[68:71]
	v_mfma_f32_16x16x32_bf16 v[64:67], v[168:171], v[210:213], v[64:67]
	v_mfma_f32_16x16x32_bf16 v[116:119], v[164:167], v[190:193], v[116:119]
	v_mfma_f32_16x16x32_bf16 v[112:115], v[172:175], v[190:193], v[112:115]
	v_mfma_f32_16x16x32_bf16 v[100:103], v[164:167], v[198:201], v[100:103]
	v_mfma_f32_16x16x32_bf16 v[96:99], v[172:175], v[198:201], v[96:99]
	v_mfma_f32_16x16x32_bf16 v[84:87], v[164:167], v[206:209], v[84:87]
	v_mfma_f32_16x16x32_bf16 v[80:83], v[172:175], v[206:209], v[80:83]
	v_mfma_f32_16x16x32_bf16 v[68:71], v[164:167], v[214:217], v[68:71]
	v_mfma_f32_16x16x32_bf16 v[64:67], v[172:175], v[214:217], v[64:67]
	s_barrier
	s_add_i32 s74, s68, s54
	v_lshl_add_u64 v[178:179], s[42:43], 0, v[146:147]
	s_mov_b32 m0, s74
	ds_read_b128 v[186:189], v184 offset:16384
	ds_read_b128 v[190:193], v184 offset:17408
	ds_read_b128 v[194:197], v184 offset:18432
	ds_read_b128 v[198:201], v184 offset:19456
	ds_read_b128 v[202:205], v184 offset:20480
	ds_read_b128 v[206:209], v184 offset:21504
	ds_read_b128 v[210:213], v184 offset:22528
	ds_read_b128 v[214:217], v184 offset:23552
	global_load_lds_dwordx4 v[178:179], off
	s_add_i32 m0, s74, 0x2000
	s_add_u32 s74, s42, 0x80000
	v_lshl_add_u64 v[218:219], s[42:43], 0, v[150:151]
	s_addc_u32 s75, s43, 0
	s_add_i32 s76, s69, s54
	global_load_lds_dwordx4 v[218:219], off
	v_lshl_add_u64 v[220:221], s[74:75], 0, v[146:147]
	s_mov_b32 m0, s76
	v_lshl_add_u64 v[222:223], s[52:53], 0, v[148:149]
	global_load_lds_dwordx4 v[220:221], off
	v_lshl_add_u64 v[220:221], s[74:75], 0, v[150:151]
	s_add_i32 m0, s76, 0x2000
	s_nop 0
	global_load_lds_dwordx4 v[220:221], off
	v_lshl_add_u64 v[220:221], s[52:53], 0, v[144:145]
	s_mov_b32 m0, s35
	s_nop 0
	global_load_lds_dwordx4 v[220:221], off
	s_mov_b32 m0, s55
	s_nop 0
	global_load_lds_dwordx4 v[222:223], off
	s_waitcnt vmcnt(8)
	s_waitcnt lgkmcnt(0)
	s_barrier
	s_waitcnt lgkmcnt(0)
	v_mfma_f32_16x16x32_bf16 v[60:63], v[128:131], v[186:189], v[60:63]
	v_mfma_f32_16x16x32_bf16 v[56:59], v[136:139], v[186:189], v[56:59]
	v_mfma_f32_16x16x32_bf16 v[44:47], v[128:131], v[194:197], v[44:47]
	v_mfma_f32_16x16x32_bf16 v[40:43], v[136:139], v[194:197], v[40:43]
	v_mfma_f32_16x16x32_bf16 v[28:31], v[128:131], v[202:205], v[28:31]
	v_mfma_f32_16x16x32_bf16 v[24:27], v[136:139], v[202:205], v[24:27]
	v_mfma_f32_16x16x32_bf16 v[12:15], v[128:131], v[210:213], v[12:15]
	v_mfma_f32_16x16x32_bf16 v[8:11], v[136:139], v[210:213], v[8:11]
	v_mfma_f32_16x16x32_bf16 v[60:63], v[132:135], v[190:193], v[60:63]
	v_mfma_f32_16x16x32_bf16 v[56:59], v[140:143], v[190:193], v[56:59]
	v_mfma_f32_16x16x32_bf16 v[44:47], v[132:135], v[198:201], v[44:47]
	v_mfma_f32_16x16x32_bf16 v[40:43], v[140:143], v[198:201], v[40:43]
	v_mfma_f32_16x16x32_bf16 v[28:31], v[132:135], v[206:209], v[28:31]
	v_mfma_f32_16x16x32_bf16 v[24:27], v[140:143], v[206:209], v[24:27]
	v_mfma_f32_16x16x32_bf16 v[12:15], v[132:135], v[214:217], v[12:15]
	v_mfma_f32_16x16x32_bf16 v[8:11], v[140:143], v[214:217], v[8:11]
	v_mfma_f32_16x16x32_bf16 v[52:55], v[160:163], v[186:189], v[52:55]
	v_mfma_f32_16x16x32_bf16 v[48:51], v[168:171], v[186:189], v[48:51]
	v_mfma_f32_16x16x32_bf16 v[36:39], v[160:163], v[194:197], v[36:39]
	v_mfma_f32_16x16x32_bf16 v[32:35], v[168:171], v[194:197], v[32:35]
	v_mfma_f32_16x16x32_bf16 v[20:23], v[160:163], v[202:205], v[20:23]
	v_mfma_f32_16x16x32_bf16 v[16:19], v[168:171], v[202:205], v[16:19]
	v_mfma_f32_16x16x32_bf16 v[4:7], v[160:163], v[210:213], v[4:7]
	v_mfma_f32_16x16x32_bf16 v[0:3], v[168:171], v[210:213], v[0:3]
	v_mfma_f32_16x16x32_bf16 v[52:55], v[164:167], v[190:193], v[52:55]
	v_mfma_f32_16x16x32_bf16 v[48:51], v[172:175], v[190:193], v[48:51]
	v_mfma_f32_16x16x32_bf16 v[36:39], v[164:167], v[198:201], v[36:39]
	v_mfma_f32_16x16x32_bf16 v[32:35], v[172:175], v[198:201], v[32:35]
	v_mfma_f32_16x16x32_bf16 v[20:23], v[164:167], v[206:209], v[20:23]
	v_mfma_f32_16x16x32_bf16 v[16:19], v[172:175], v[206:209], v[16:19]
	v_mfma_f32_16x16x32_bf16 v[4:7], v[164:167], v[214:217], v[4:7]
	v_mfma_f32_16x16x32_bf16 v[0:3], v[172:175], v[214:217], v[0:3]
	s_barrier
; #define PG8_STAGE(bufoff, gbase, voff) do { _Pragma("unroll") for (int _i = 0; _i < 2; ++_i) \
;         __builtin_amdgcn_global_load_lds((const unsigned*)((const char*)(gbase) + (voff)[_i]), (LAS unsigned*)(lds + (bufoff) + ldsw + _i * 8192), 16, 0, 0); } while (0)
; #define PG8_LDA(dst, b, h) do { _Pragma("unroll") for (int m = 0; m < 4; ++m) _Pragma("unroll") for (int k = 0; k < 2; ++k) dst[m][k] = *(const LAS bf16x8*)(lds + PG8_SA(b, h) + aoff + m * 2048 + k * 1024); } while (0)
; #define PG8_MMA(ai, bj, At, Bt) do { __builtin_amdgcn_s_setprio(1); _Pragma("unroll") for (int m = 0; m < 4; ++m) _Pragma("unroll") for (int n = 0; n < 2; ++n) _Pragma("unroll") for (int k = 0; k < 2; ++k) \
;         acc[ai][bj][m][n] = __builtin_amdgcn_mfma_f32_16x16x32_bf16(Bt[n][k], At[m][k], acc[ai][bj][m][n], 0, 0, 0); __builtin_amdgcn_s_setprio(0); } while (0)
; #define PG8_WAIT_V(n) asm volatile("s_waitcnt vmcnt(" #n ")" ::: "memory")
; #define PG8_WAIT_L(n) asm volatile("s_waitcnt lgkmcnt(" #n ")" ::: "memory")
; #define PG8_BAR __builtin_amdgcn_s_barrier()
; #define PG8_SCHED __builtin_amdgcn_sched_barrier(0)
; template <class Epi>
; __device__ __forceinline__ void gemm_phase(LAS unsigned char* lds, const Gemm g, const StaticOrder& S, const Epi& E) {
;     ...
;             PG8_LDA(At, 1, 1); PG8_STAGE(PG8_SB(1, 0), b3, voffB); PG8_STAGE(PG8_SB(1, 1), b3 + hstepB, voffB); PG8_STAGE(PG8_SA(1, 0), a3, voffA);
;             PG8_WAIT_V(8); PG8_WAIT_L(0); PG8_BAR; PG8_MMA(1, 0, At, B0); PG8_MMA(1, 1, At, B1); PG8_BAR; PG8_SCHED;
	s_add_i32 s74, 0, 0x18000
	s_add_i32 s75, 0, 0x1c000
	v_add_u32_e32 v140, s74, v181
	v_add_u32_e32 v172, s75, v181
	ds_read_b128 v[128:131], v140
	ds_read_b128 v[132:135], v140 offset:1024
	ds_read_b128 v[136:139], v140 offset:2048
	ds_read_b128 v[140:143], v140 offset:3072
	ds_read_b128 v[160:163], v172
	ds_read_b128 v[164:167], v172 offset:1024
	ds_read_b128 v[168:171], v172 offset:2048
	ds_read_b128 v[172:175], v172 offset:3072
	s_add_u32 s52, s52, 0x100000
	s_addc_u32 s53, s53, 0
	s_mov_b32 m0, s56
	v_lshl_add_u64 v[224:225], s[52:53], 0, v[144:145]
	ds_read_b128 v[186:189], v184 offset:32768
	ds_read_b128 v[190:193], v184 offset:33792
	ds_read_b128 v[194:197], v184 offset:34816
	ds_read_b128 v[198:201], v184 offset:35840
	ds_read_b128 v[202:205], v184 offset:36864
	ds_read_b128 v[206:209], v184 offset:37888
	ds_read_b128 v[210:213], v184 offset:38912
	ds_read_b128 v[214:217], v184 offset:39936
	global_load_lds_dwordx4 v[224:225], off
	v_lshl_add_u64 v[224:225], s[52:53], 0, v[148:149]
	s_mov_b32 m0, s57
	s_nop 0
	global_load_lds_dwordx4 v[224:225], off
	s_waitcnt vmcnt(8)
	s_waitcnt lgkmcnt(0)
	s_barrier
	s_waitcnt lgkmcnt(0)
	v_mfma_f32_16x16x32_bf16 v[124:127], v[128:131], v[186:189], v[124:127]
	v_mfma_f32_16x16x32_bf16 v[120:123], v[136:139], v[186:189], v[120:123]
	v_mfma_f32_16x16x32_bf16 v[108:111], v[128:131], v[194:197], v[108:111]
	v_mfma_f32_16x16x32_bf16 v[104:107], v[136:139], v[194:197], v[104:107]
	v_mfma_f32_16x16x32_bf16 v[92:95], v[128:131], v[202:205], v[92:95]
	v_mfma_f32_16x16x32_bf16 v[88:91], v[136:139], v[202:205], v[88:91]
	v_mfma_f32_16x16x32_bf16 v[76:79], v[128:131], v[210:213], v[76:79]
	v_mfma_f32_16x16x32_bf16 v[72:75], v[136:139], v[210:213], v[72:75]
	v_mfma_f32_16x16x32_bf16 v[124:127], v[132:135], v[190:193], v[124:127]
	v_mfma_f32_16x16x32_bf16 v[120:123], v[140:143], v[190:193], v[120:123]
	v_mfma_f32_16x16x32_bf16 v[108:111], v[132:135], v[198:201], v[108:111]
	v_mfma_f32_16x16x32_bf16 v[104:107], v[140:143], v[198:201], v[104:107]
	v_mfma_f32_16x16x32_bf16 v[92:95], v[132:135], v[206:209], v[92:95]
	v_mfma_f32_16x16x32_bf16 v[88:91], v[140:143], v[206:209], v[88:91]
	v_mfma_f32_16x16x32_bf16 v[76:79], v[132:135], v[214:217], v[76:79]
	v_mfma_f32_16x16x32_bf16 v[72:75], v[140:143], v[214:217], v[72:75]
	v_mfma_f32_16x16x32_bf16 v[116:119], v[160:163], v[186:189], v[116:119]
	v_mfma_f32_16x16x32_bf16 v[112:115], v[168:171], v[186:189], v[112:115]
	v_mfma_f32_16x16x32_bf16 v[100:103], v[160:163], v[194:197], v[100:103]
	v_mfma_f32_16x16x32_bf16 v[96:99], v[168:171], v[194:197], v[96:99]
	v_mfma_f32_16x16x32_bf16 v[84:87], v[160:163], v[202:205], v[84:87]
	v_mfma_f32_16x16x32_bf16 v[80:83], v[168:171], v[202:205], v[80:83]
	v_mfma_f32_16x16x32_bf16 v[68:71], v[160:163], v[210:213], v[68:71]
	v_mfma_f32_16x16x32_bf16 v[64:67], v[168:171], v[210:213], v[64:67]
	v_mfma_f32_16x16x32_bf16 v[116:119], v[164:167], v[190:193], v[116:119]
	v_mfma_f32_16x16x32_bf16 v[112:115], v[172:175], v[190:193], v[112:115]
	v_mfma_f32_16x16x32_bf16 v[100:103], v[164:167], v[198:201], v[100:103]
	v_mfma_f32_16x16x32_bf16 v[96:99], v[172:175], v[198:201], v[96:99]
	v_mfma_f32_16x16x32_bf16 v[84:87], v[164:167], v[206:209], v[84:87]
	v_mfma_f32_16x16x32_bf16 v[80:83], v[172:175], v[206:209], v[80:83]
	v_mfma_f32_16x16x32_bf16 v[68:71], v[164:167], v[214:217], v[68:71]
	v_mfma_f32_16x16x32_bf16 v[64:67], v[172:175], v[214:217], v[64:67]
	s_barrier
; #define PG8_MMA(ai, bj, At, Bt) do { __builtin_amdgcn_s_setprio(1); _Pragma("unroll") for (int m = 0; m < 4; ++m) _Pragma("unroll") for (int n = 0; n < 2; ++n) _Pragma("unroll") for (int k = 0; k < 2; ++k) \
;         acc[ai][bj][m][n] = __builtin_amdgcn_mfma_f32_16x16x32_bf16(Bt[n][k], At[m][k], acc[ai][bj][m][n], 0, 0, 0); __builtin_amdgcn_s_setprio(0); } while (0)
; #define PG8_WAIT_V(n) asm volatile("s_waitcnt vmcnt(" #n ")" ::: "memory")
; #define PG8_WAIT_L(n) asm volatile("s_waitcnt lgkmcnt(" #n ")" ::: "memory")
; #define PG8_BAR __builtin_amdgcn_s_barrier()
; #define PG8_SCHED __builtin_amdgcn_sched_barrier(0)
; template <class Epi>
; __device__ __forceinline__ void gemm_phase(LAS unsigned char* lds, const Gemm g, const StaticOrder& S, const Epi& E) {
;     ...
;             PG8_WAIT_V(8); PG8_WAIT_L(0); PG8_BAR; PG8_MMA(1, 0, At, B0); PG8_MMA(1, 1, At, B1); PG8_BAR; PG8_SCHED;
;         }
;         if (wr == 0) PG8_BAR;
	s_add_i32 s52, s74, s54
	v_lshl_add_u64 v[178:179], v[178:179], 0, s[12:13]
	s_mov_b32 m0, s52
	ds_read_b128 v[186:189], v184 offset:49152
	ds_read_b128 v[190:193], v184 offset:50176
	ds_read_b128 v[194:197], v184 offset:51200
	ds_read_b128 v[198:201], v184 offset:52224
	ds_read_b128 v[202:205], v184 offset:53248
	ds_read_b128 v[206:209], v184 offset:54272
	ds_read_b128 v[210:213], v184 offset:55296
	ds_read_b128 v[214:217], v184 offset:56320
	global_load_lds_dwordx4 v[178:179], off
	s_add_i32 m0, s52, 0x2000
	s_add_u32 s42, s42, 0x80080
	v_lshl_add_u64 v[178:179], v[218:219], 0, s[12:13]
	s_addc_u32 s43, s43, 0
	s_add_i32 s52, s75, s54
	global_load_lds_dwordx4 v[178:179], off
	v_lshl_add_u64 v[178:179], s[42:43], 0, v[146:147]
	s_mov_b32 m0, s52
	s_nop 0
	global_load_lds_dwordx4 v[178:179], off
	v_lshl_add_u64 v[178:179], s[42:43], 0, v[150:151]
	s_add_i32 m0, s52, 0x2000
	s_nop 0
	global_load_lds_dwordx4 v[178:179], off
	v_lshl_add_u64 v[178:179], v[220:221], 0, s[12:13]
	s_mov_b32 m0, s61
	s_nop 0
	global_load_lds_dwordx4 v[178:179], off
	v_lshl_add_u64 v[178:179], v[222:223], 0, s[12:13]
	s_mov_b32 m0, s62
	s_nop 0
	global_load_lds_dwordx4 v[178:179], off
	s_waitcnt vmcnt(8)
	s_waitcnt lgkmcnt(0)
	s_barrier
	s_waitcnt lgkmcnt(0)
	v_mfma_f32_16x16x32_bf16 v[60:63], v[128:131], v[186:189], v[60:63]
	v_mfma_f32_16x16x32_bf16 v[56:59], v[136:139], v[186:189], v[56:59]
	v_mfma_f32_16x16x32_bf16 v[44:47], v[128:131], v[194:197], v[44:47]
	v_mfma_f32_16x16x32_bf16 v[40:43], v[136:139], v[194:197], v[40:43]
	v_mfma_f32_16x16x32_bf16 v[28:31], v[128:131], v[202:205], v[28:31]
	v_mfma_f32_16x16x32_bf16 v[24:27], v[136:139], v[202:205], v[24:27]
	v_mfma_f32_16x16x32_bf16 v[12:15], v[128:131], v[210:213], v[12:15]
	v_mfma_f32_16x16x32_bf16 v[8:11], v[136:139], v[210:213], v[8:11]
	v_mfma_f32_16x16x32_bf16 v[60:63], v[132:135], v[190:193], v[60:63]
	v_mfma_f32_16x16x32_bf16 v[56:59], v[140:143], v[190:193], v[56:59]
	v_mfma_f32_16x16x32_bf16 v[44:47], v[132:135], v[198:201], v[44:47]
	v_mfma_f32_16x16x32_bf16 v[40:43], v[140:143], v[198:201], v[40:43]
	v_mfma_f32_16x16x32_bf16 v[28:31], v[132:135], v[206:209], v[28:31]
	v_mfma_f32_16x16x32_bf16 v[24:27], v[140:143], v[206:209], v[24:27]
	v_mfma_f32_16x16x32_bf16 v[12:15], v[132:135], v[214:217], v[12:15]
	v_mfma_f32_16x16x32_bf16 v[8:11], v[140:143], v[214:217], v[8:11]
	v_mfma_f32_16x16x32_bf16 v[52:55], v[160:163], v[186:189], v[52:55]
	v_mfma_f32_16x16x32_bf16 v[48:51], v[168:171], v[186:189], v[48:51]
	v_mfma_f32_16x16x32_bf16 v[36:39], v[160:163], v[194:197], v[36:39]
	v_mfma_f32_16x16x32_bf16 v[32:35], v[168:171], v[194:197], v[32:35]
	v_mfma_f32_16x16x32_bf16 v[20:23], v[160:163], v[202:205], v[20:23]
	v_mfma_f32_16x16x32_bf16 v[16:19], v[168:171], v[202:205], v[16:19]
	v_mfma_f32_16x16x32_bf16 v[4:7], v[160:163], v[210:213], v[4:7]
	v_mfma_f32_16x16x32_bf16 v[0:3], v[168:171], v[210:213], v[0:3]
	v_mfma_f32_16x16x32_bf16 v[52:55], v[164:167], v[190:193], v[52:55]
	v_mfma_f32_16x16x32_bf16 v[48:51], v[172:175], v[190:193], v[48:51]
	v_mfma_f32_16x16x32_bf16 v[36:39], v[164:167], v[198:201], v[36:39]
	v_mfma_f32_16x16x32_bf16 v[32:35], v[172:175], v[198:201], v[32:35]
	v_mfma_f32_16x16x32_bf16 v[20:23], v[164:167], v[206:209], v[20:23]
	v_mfma_f32_16x16x32_bf16 v[16:19], v[172:175], v[206:209], v[16:19]
	v_mfma_f32_16x16x32_bf16 v[4:7], v[164:167], v[214:217], v[4:7]
	v_mfma_f32_16x16x32_bf16 v[0:3], v[172:175], v[214:217], v[0:3]
	s_barrier
	s_add_i32 s73, s73, 2
	s_add_u32 s38, s38, 0x100
	s_addc_u32 s39, s39, 0
	s_add_u32 s71, s71, 0x100
	s_addc_u32 s72, s72, 0
	s_cmp_gt_u32 s73, 29
	s_cbranch_scc0 .LBB0_1314
	s_and_b64 vcc, exec, s[14:15]
	s_cbranch_vccz .LBB0_1317
	s_barrier

; #define PG8_STAGE(bufoff, gbase, voff) do { _Pragma("unroll") for (int _i = 0; _i < 2; ++_i) \
;         __builtin_amdgcn_global_load_lds((const unsigned*)((const char*)(gbase) + (voff)[_i]), (LAS unsigned*)(lds + (bufoff) + ldsw + _i * 8192), 16, 0, 0); } while (0)
; #define PG8_LDA(dst, b, h) do { _Pragma("unroll") for (int m = 0; m < 4; ++m) _Pragma("unroll") for (int k = 0; k < 2; ++k) dst[m][k] = *(const LAS bf16x8*)(lds + PG8_SA(b, h) + aoff + m * 2048 + k * 1024); } while (0)
; #define PG8_LDB(dst, b, h) do { _Pragma("unroll") for (int n = 0; n < 2; ++n) _Pragma("unroll") for (int k = 0; k < 2; ++k) dst[n][k] = *(const LAS bf16x8*)(lds + PG8_SB(b, h) + boff + n * 2048 + k * 1024); } while (0)
; #define PG8_MMA(ai, bj, At, Bt) do { __builtin_amdgcn_s_setprio(1); _Pragma("unroll") for (int m = 0; m < 4; ++m) _Pragma("unroll") for (int n = 0; n < 2; ++n) _Pragma("unroll") for (int k = 0; k < 2; ++k) \
;         acc[ai][bj][m][n] = __builtin_amdgcn_mfma_f32_16x16x32_bf16(Bt[n][k], At[m][k], acc[ai][bj][m][n], 0, 0, 0); __builtin_amdgcn_s_setprio(0); } while (0)
; #define PG8_BAR __builtin_amdgcn_s_barrier()
; template <class Epi>
; __device__ __forceinline__ void gemm_phase(LAS unsigned char* lds, const Gemm g, const StaticOrder& S, const Epi& E) {
;     ...
;         const bool has_next = S.next(ui + 1, nxt);
;         const char* nA = has_next ? (const char*)g.A + (size_t)nxt.pm * tstepA : cA; const char* nB = has_next ? (const char*)g.Bt + (size_t)nxt.pn * tstepB : cB;
; #pragma nounroll
;         for (int t = 0; t < nt; t += 2) {
;             const bool last = (t == nt - 2);
;             const char* a1 = cA + (size_t)(t + 1) * kstep;
;             const char* a2 = last ? nA : cA + (size_t)(t + 2) * kstep; const char* b2 = last ? nB : cB + (size_t)(t + 2) * kstep;
;             const char* a3 = a2 + kstep; const char* b3 = b2 + kstep;
;             PG8_LDB(B0, 0, 0); PG8_LDB(B1, 0, 1); PG8_SCHED; PG8_LDA(At, 0, 0); PG8_STAGE(PG8_SA(1, 1), a1 + hstepA, voffA);
;             PG8_WAIT_V(8); PG8_WAIT_L(0); PG8_BAR; PG8_MMA(0, 0, At, B0); PG8_MMA(0, 1, At, B1); PG8_BAR; PG8_SCHED;
;             PG8_LDA(At, 0, 1); PG8_STAGE(PG8_SB(0, 0), b2, voffB); PG8_STAGE(PG8_SB(0, 1), b2 + hstepB, voffB); PG8_STAGE(PG8_SA(0, 0), a2, voffA);
;             PG8_WAIT_V(8); PG8_WAIT_L(0); PG8_BAR; PG8_MMA(1, 0, At, B0); PG8_MMA(1, 1, At, B1); PG8_BAR; PG8_SCHED;
.LBB0_1402:
	s_ashr_i32 s69, s68, 31
	s_lshl_b64 s[12:13], s[68:69], 19
	s_add_u32 s70, s24, s12
	s_addc_u32 s71, s25, s13
	s_and_b64 s[12:13], s[4:5], exec
	s_cselect_b32 s1, s71, s9
	s_cselect_b32 s7, s70, s8
	s_ashr_i32 s65, s64, 31
	s_lshl_b64 s[12:13], s[64:65], 19
	s_add_u32 s72, s3, s12
	s_addc_u32 s73, s33, s13
	s_and_b64 s[12:13], s[4:5], exec
	s_cselect_b32 s65, s73, s11
	s_cselect_b32 s69, s72, s10
	s_add_u32 s8, s8, 0x40080
	s_addc_u32 s9, s9, 0
	s_add_u32 s74, s10, 0x100
	s_addc_u32 s75, s11, 0
	s_mov_b32 s87, -2
	v_lshl_add_u32 v248, s6, 8, v151
	v_add_u32_e32 v248, s63, v248
	v_ashrrev_i32_e32 v249, 31, v248
	v_lshl_add_u64 v[248:249], v[248:249], 2, s[18:19]
	global_load_dword v240, v[248:249], off
	global_load_dword v241, v[248:249], off offset:64
	global_load_dword v242, v[248:249], off offset:128
	global_load_dword v243, v[248:249], off offset:192
	global_load_dword v244, v[248:249], off offset:512
	global_load_dword v245, v[248:249], off offset:576
	global_load_dword v246, v[248:249], off offset:640
	global_load_dword v247, v[248:249], off offset:704
	ds_read_b128 v[146:149], v162
	ds_read_b128 v[166:169], v162 offset:1024
	ds_read_b128 v[170:173], v162 offset:2048
	ds_read_b128 v[178:181], v162 offset:3072
	ds_read_b128 v[182:185], v163
	ds_read_b128 v[186:189], v163 offset:1024
	ds_read_b128 v[190:193], v163 offset:2048
	ds_read_b128 v[194:197], v163 offset:3072
	s_add_u32 s10, s8, 0xfffc0080
	s_addc_u32 s11, s9, -1
	s_cmp_eq_u32 s87, 12
	s_cselect_b32 s13, s1, s11
	s_cselect_b32 s12, s7, s10
	s_cselect_b32 s11, s65, s75
	s_cselect_b32 s10, s69, s74
	v_lshl_add_u64 v[174:175], s[8:9], 0, v[138:139]
	s_add_i32 m0, s53, 0xc000
	ds_read_b128 v[198:201], v164
	ds_read_b128 v[202:205], v164 offset:1024
	ds_read_b128 v[206:209], v164 offset:2048
	ds_read_b128 v[210:213], v164 offset:3072
	ds_read_b128 v[214:217], v164 offset:4096
	ds_read_b128 v[218:221], v164 offset:5120
	ds_read_b128 v[222:225], v164 offset:6144
	ds_read_b128 v[226:229], v164 offset:7168
	global_load_lds_dwordx4 v[174:175], off
	v_lshl_add_u64 v[174:175], s[8:9], 0, v[140:141]
	s_add_i32 m0, s53, 0xe000
	s_nop 0
	global_load_lds_dwordx4 v[174:175], off
	s_waitcnt vmcnt(8)
	s_waitcnt lgkmcnt(0)
	s_barrier
	s_waitcnt lgkmcnt(0)
	v_mfma_f32_16x16x32_bf16 v[124:127], v[146:149], v[198:201], 0
	v_mfma_f32_16x16x32_bf16 v[120:123], v[170:173], v[198:201], 0
	v_mfma_f32_16x16x32_bf16 v[112:115], v[146:149], v[206:209], 0
	v_mfma_f32_16x16x32_bf16 v[104:107], v[170:173], v[206:209], 0
	v_mfma_f32_16x16x32_bf16 v[100:103], v[146:149], v[214:217], 0
	v_mfma_f32_16x16x32_bf16 v[92:95], v[170:173], v[214:217], 0
	v_mfma_f32_16x16x32_bf16 v[84:87], v[146:149], v[222:225], 0
	v_mfma_f32_16x16x32_bf16 v[76:79], v[170:173], v[222:225], 0
	v_mfma_f32_16x16x32_bf16 v[124:127], v[166:169], v[202:205], v[124:127]
	v_mfma_f32_16x16x32_bf16 v[120:123], v[178:181], v[202:205], v[120:123]
	v_mfma_f32_16x16x32_bf16 v[112:115], v[166:169], v[210:213], v[112:115]
	v_mfma_f32_16x16x32_bf16 v[104:107], v[178:181], v[210:213], v[104:107]
	v_mfma_f32_16x16x32_bf16 v[100:103], v[166:169], v[218:221], v[100:103]
	v_mfma_f32_16x16x32_bf16 v[92:95], v[178:181], v[218:221], v[92:95]
	v_mfma_f32_16x16x32_bf16 v[84:87], v[166:169], v[226:229], v[84:87]
	v_mfma_f32_16x16x32_bf16 v[76:79], v[178:181], v[226:229], v[76:79]
	v_mfma_f32_16x16x32_bf16 v[116:119], v[182:185], v[198:201], 0
	v_mfma_f32_16x16x32_bf16 v[108:111], v[190:193], v[198:201], 0
	v_mfma_f32_16x16x32_bf16 v[96:99], v[182:185], v[206:209], 0
	v_mfma_f32_16x16x32_bf16 v[88:91], v[190:193], v[206:209], 0
	v_mfma_f32_16x16x32_bf16 v[80:83], v[182:185], v[214:217], 0
	v_mfma_f32_16x16x32_bf16 v[72:75], v[190:193], v[214:217], 0
	v_mfma_f32_16x16x32_bf16 v[68:71], v[182:185], v[222:225], 0
	v_mfma_f32_16x16x32_bf16 v[64:67], v[190:193], v[222:225], 0
	v_mfma_f32_16x16x32_bf16 v[116:119], v[186:189], v[202:205], v[116:119]
	v_mfma_f32_16x16x32_bf16 v[108:111], v[194:197], v[202:205], v[108:111]
	v_mfma_f32_16x16x32_bf16 v[96:99], v[186:189], v[210:213], v[96:99]
	v_mfma_f32_16x16x32_bf16 v[88:91], v[194:197], v[210:213], v[88:91]
	v_mfma_f32_16x16x32_bf16 v[80:83], v[186:189], v[218:221], v[80:83]
	v_mfma_f32_16x16x32_bf16 v[72:75], v[194:197], v[218:221], v[72:75]
	v_mfma_f32_16x16x32_bf16 v[68:71], v[186:189], v[226:229], v[68:71]
	v_mfma_f32_16x16x32_bf16 v[64:67], v[194:197], v[226:229], v[64:67]
	s_barrier
	s_add_i32 s88, s83, s43
	v_lshl_add_u64 v[174:175], s[10:11], 0, v[130:131]
	s_mov_b32 m0, s88
	ds_read_b128 v[198:201], v164 offset:16384
	ds_read_b128 v[202:205], v164 offset:17408
	ds_read_b128 v[206:209], v164 offset:18432
	ds_read_b128 v[210:213], v164 offset:19456
	ds_read_b128 v[214:217], v164 offset:20480
	ds_read_b128 v[218:221], v164 offset:21504
	ds_read_b128 v[222:225], v164 offset:22528
	ds_read_b128 v[226:229], v164 offset:23552
	global_load_lds_dwordx4 v[174:175], off
	s_add_i32 m0, s88, 0x2000
	s_add_u32 s88, s10, 0x40000
	v_lshl_add_u64 v[230:231], s[10:11], 0, v[134:135]
	s_addc_u32 s89, s11, 0
	s_add_i32 s90, s84, s43
	global_load_lds_dwordx4 v[230:231], off
	v_lshl_add_u64 v[232:233], s[88:89], 0, v[130:131]
	s_mov_b32 m0, s90
	v_lshl_add_u64 v[234:235], s[12:13], 0, v[132:133]
	global_load_lds_dwordx4 v[232:233], off
	v_lshl_add_u64 v[232:233], s[88:89], 0, v[134:135]
	s_add_i32 m0, s90, 0x2000
	s_nop 0
	global_load_lds_dwordx4 v[232:233], off
	v_lshl_add_u64 v[232:233], s[12:13], 0, v[128:129]
	s_mov_b32 m0, s53
	s_nop 0
	global_load_lds_dwordx4 v[232:233], off
	s_mov_b32 m0, s55
	s_nop 0
	global_load_lds_dwordx4 v[234:235], off
	s_waitcnt vmcnt(8)
	s_waitcnt lgkmcnt(0)
	s_barrier
; #define PG8_STAGE(bufoff, gbase, voff) do { _Pragma("unroll") for (int _i = 0; _i < 2; ++_i) \
;         __builtin_amdgcn_global_load_lds((const unsigned*)((const char*)(gbase) + (voff)[_i]), (LAS unsigned*)(lds + (bufoff) + ldsw + _i * 8192), 16, 0, 0); } while (0)
; #define PG8_LDA(dst, b, h) do { _Pragma("unroll") for (int m = 0; m < 4; ++m) _Pragma("unroll") for (int k = 0; k < 2; ++k) dst[m][k] = *(const LAS bf16x8*)(lds + PG8_SA(b, h) + aoff + m * 2048 + k * 1024); } while (0)
; #define PG8_LDB(dst, b, h) do { _Pragma("unroll") for (int n = 0; n < 2; ++n) _Pragma("unroll") for (int k = 0; k < 2; ++k) dst[n][k] = *(const LAS bf16x8*)(lds + PG8_SB(b, h) + boff + n * 2048 + k * 1024); } while (0)
; #define PG8_MMA(ai, bj, At, Bt) do { __builtin_amdgcn_s_setprio(1); _Pragma("unroll") for (int m = 0; m < 4; ++m) _Pragma("unroll") for (int n = 0; n < 2; ++n) _Pragma("unroll") for (int k = 0; k < 2; ++k) \
;         acc[ai][bj][m][n] = __builtin_amdgcn_mfma_f32_16x16x32_bf16(Bt[n][k], At[m][k], acc[ai][bj][m][n], 0, 0, 0); __builtin_amdgcn_s_setprio(0); } while (0)
; #define PG8_WAIT_V(n) asm volatile("s_waitcnt vmcnt(" #n ")" ::: "memory")
; #define PG8_BAR __builtin_amdgcn_s_barrier()
; template <class Epi>
; __device__ __forceinline__ void gemm_phase(LAS unsigned char* lds, const Gemm g, const StaticOrder& S, const Epi& E) {
;     ...
;             PG8_LDB(B0, 0, 0); PG8_LDB(B1, 0, 1); PG8_SCHED; PG8_LDA(At, 0, 0); PG8_STAGE(PG8_SA(1, 1), a1 + hstepA, voffA);
;             PG8_WAIT_V(8); PG8_WAIT_L(0); PG8_BAR; PG8_MMA(0, 0, At, B0); PG8_MMA(0, 1, At, B1); PG8_BAR; PG8_SCHED;
;             PG8_LDA(At, 0, 1); PG8_STAGE(PG8_SB(0, 0), b2, voffB); PG8_STAGE(PG8_SB(0, 1), b2 + hstepB, voffB); PG8_STAGE(PG8_SA(0, 0), a2, voffA);
;             PG8_WAIT_V(8); PG8_WAIT_L(0); PG8_BAR; PG8_MMA(1, 0, At, B0); PG8_MMA(1, 1, At, B1); PG8_BAR; PG8_SCHED;
;             PG8_LDB(B0, 1, 0); PG8_LDB(B1, 1, 1); PG8_SCHED; PG8_LDA(At, 1, 0); PG8_STAGE(PG8_SA(0, 1), a2 + hstepA, voffA);
;             PG8_WAIT_V(8); PG8_WAIT_L(0); PG8_BAR; PG8_MMA(0, 0, At, B0); PG8_MMA(0, 1, At, B1); PG8_BAR; PG8_SCHED;
;             PG8_LDA(At, 1, 1); PG8_STAGE(PG8_SB(1, 0), b3, voffB); PG8_STAGE(PG8_SB(1, 1), b3 + hstepB, voffB); PG8_STAGE(PG8_SA(1, 0), a3, voffA);
;             PG8_WAIT_V(8); PG8_WAIT_L(0); PG8_BAR; PG8_MMA(1, 0, At, B0); PG8_MMA(1, 1, At, B1); PG8_BAR; PG8_SCHED;
	s_waitcnt lgkmcnt(0)
	v_mfma_f32_16x16x32_bf16 v[60:63], v[146:149], v[198:201], 0
	v_mfma_f32_16x16x32_bf16 v[56:59], v[170:173], v[198:201], 0
	v_mfma_f32_16x16x32_bf16 v[52:55], v[146:149], v[206:209], 0
	v_mfma_f32_16x16x32_bf16 v[44:47], v[170:173], v[206:209], 0
	v_mfma_f32_16x16x32_bf16 v[36:39], v[146:149], v[214:217], 0
	v_mfma_f32_16x16x32_bf16 v[28:31], v[170:173], v[214:217], 0
	v_mfma_f32_16x16x32_bf16 v[20:23], v[146:149], v[222:225], 0
	v_mfma_f32_16x16x32_bf16 v[12:15], v[170:173], v[222:225], 0
	v_mfma_f32_16x16x32_bf16 v[60:63], v[166:169], v[202:205], v[60:63]
	v_mfma_f32_16x16x32_bf16 v[56:59], v[178:181], v[202:205], v[56:59]
	v_mfma_f32_16x16x32_bf16 v[52:55], v[166:169], v[210:213], v[52:55]
	v_mfma_f32_16x16x32_bf16 v[44:47], v[178:181], v[210:213], v[44:47]
	v_mfma_f32_16x16x32_bf16 v[36:39], v[166:169], v[218:221], v[36:39]
	v_mfma_f32_16x16x32_bf16 v[28:31], v[178:181], v[218:221], v[28:31]
	v_mfma_f32_16x16x32_bf16 v[20:23], v[166:169], v[226:229], v[20:23]
	v_mfma_f32_16x16x32_bf16 v[12:15], v[178:181], v[226:229], v[12:15]
	v_mfma_f32_16x16x32_bf16 v[48:51], v[182:185], v[198:201], 0
	v_mfma_f32_16x16x32_bf16 v[40:43], v[190:193], v[198:201], 0
	v_mfma_f32_16x16x32_bf16 v[32:35], v[182:185], v[206:209], 0
	v_mfma_f32_16x16x32_bf16 v[24:27], v[190:193], v[206:209], 0
	v_mfma_f32_16x16x32_bf16 v[16:19], v[182:185], v[214:217], 0
	v_mfma_f32_16x16x32_bf16 v[8:11], v[190:193], v[214:217], 0
	v_mfma_f32_16x16x32_bf16 v[4:7], v[182:185], v[222:225], 0
	v_mfma_f32_16x16x32_bf16 v[0:3], v[190:193], v[222:225], 0
	v_mfma_f32_16x16x32_bf16 v[48:51], v[186:189], v[202:205], v[48:51]
	v_mfma_f32_16x16x32_bf16 v[40:43], v[194:197], v[202:205], v[40:43]
	v_mfma_f32_16x16x32_bf16 v[32:35], v[186:189], v[210:213], v[32:35]
	v_mfma_f32_16x16x32_bf16 v[24:27], v[194:197], v[210:213], v[24:27]
	v_mfma_f32_16x16x32_bf16 v[16:19], v[186:189], v[218:221], v[16:19]
	v_mfma_f32_16x16x32_bf16 v[8:11], v[194:197], v[218:221], v[8:11]
	v_mfma_f32_16x16x32_bf16 v[4:7], v[186:189], v[226:229], v[4:7]
	v_mfma_f32_16x16x32_bf16 v[0:3], v[194:197], v[226:229], v[0:3]
	s_barrier
	s_add_i32 s88, 0, 0x18000
	v_add_u32_e32 v136, s88, v161
	s_add_i32 s89, 0, 0x1c000
	ds_read_b128 v[146:149], v136
	ds_read_b128 v[166:169], v136 offset:1024
	ds_read_b128 v[170:173], v136 offset:2048
	ds_read_b128 v[178:181], v136 offset:3072
	v_add_u32_e32 v136, s89, v161
	ds_read_b128 v[182:185], v136
	ds_read_b128 v[186:189], v136 offset:1024
	ds_read_b128 v[190:193], v136 offset:2048
	ds_read_b128 v[194:197], v136 offset:3072
	s_add_u32 s12, s12, 0x40000
	s_addc_u32 s13, s13, 0
	s_mov_b32 m0, s57
	v_lshl_add_u64 v[236:237], s[12:13], 0, v[128:129]
	ds_read_b128 v[198:201], v164 offset:32768
	ds_read_b128 v[202:205], v164 offset:33792
	ds_read_b128 v[206:209], v164 offset:34816
	ds_read_b128 v[210:213], v164 offset:35840
	ds_read_b128 v[214:217], v164 offset:36864
	ds_read_b128 v[218:221], v164 offset:37888
	ds_read_b128 v[222:225], v164 offset:38912
	ds_read_b128 v[226:229], v164 offset:39936
	global_load_lds_dwordx4 v[236:237], off
	v_lshl_add_u64 v[236:237], s[12:13], 0, v[132:133]
	s_mov_b32 m0, s59
	s_nop 0
	global_load_lds_dwordx4 v[236:237], off
	s_waitcnt vmcnt(8)
	s_waitcnt lgkmcnt(0)
	s_barrier
	s_waitcnt lgkmcnt(0)
	v_mfma_f32_16x16x32_bf16 v[124:127], v[146:149], v[198:201], v[124:127]
	v_mfma_f32_16x16x32_bf16 v[120:123], v[170:173], v[198:201], v[120:123]
	v_mfma_f32_16x16x32_bf16 v[112:115], v[146:149], v[206:209], v[112:115]
	v_mfma_f32_16x16x32_bf16 v[104:107], v[170:173], v[206:209], v[104:107]
	v_mfma_f32_16x16x32_bf16 v[100:103], v[146:149], v[214:217], v[100:103]
	v_mfma_f32_16x16x32_bf16 v[92:95], v[170:173], v[214:217], v[92:95]
	v_mfma_f32_16x16x32_bf16 v[84:87], v[146:149], v[222:225], v[84:87]
	v_mfma_f32_16x16x32_bf16 v[76:79], v[170:173], v[222:225], v[76:79]
	v_mfma_f32_16x16x32_bf16 v[124:127], v[166:169], v[202:205], v[124:127]
	v_mfma_f32_16x16x32_bf16 v[120:123], v[178:181], v[202:205], v[120:123]
	v_mfma_f32_16x16x32_bf16 v[112:115], v[166:169], v[210:213], v[112:115]
	v_mfma_f32_16x16x32_bf16 v[104:107], v[178:181], v[210:213], v[104:107]
	v_mfma_f32_16x16x32_bf16 v[100:103], v[166:169], v[218:221], v[100:103]
	v_mfma_f32_16x16x32_bf16 v[92:95], v[178:181], v[218:221], v[92:95]
	v_mfma_f32_16x16x32_bf16 v[84:87], v[166:169], v[226:229], v[84:87]
	v_mfma_f32_16x16x32_bf16 v[76:79], v[178:181], v[226:229], v[76:79]
	v_mfma_f32_16x16x32_bf16 v[116:119], v[182:185], v[198:201], v[116:119]
	v_mfma_f32_16x16x32_bf16 v[108:111], v[190:193], v[198:201], v[108:111]
	v_mfma_f32_16x16x32_bf16 v[96:99], v[182:185], v[206:209], v[96:99]
	v_mfma_f32_16x16x32_bf16 v[88:91], v[190:193], v[206:209], v[88:91]
	v_mfma_f32_16x16x32_bf16 v[80:83], v[182:185], v[214:217], v[80:83]
	v_mfma_f32_16x16x32_bf16 v[72:75], v[190:193], v[214:217], v[72:75]
	v_mfma_f32_16x16x32_bf16 v[68:71], v[182:185], v[222:225], v[68:71]
	v_mfma_f32_16x16x32_bf16 v[64:67], v[190:193], v[222:225], v[64:67]
	v_mfma_f32_16x16x32_bf16 v[116:119], v[186:189], v[202:205], v[116:119]
	v_mfma_f32_16x16x32_bf16 v[108:111], v[194:197], v[202:205], v[108:111]
	v_mfma_f32_16x16x32_bf16 v[96:99], v[186:189], v[210:213], v[96:99]
	v_mfma_f32_16x16x32_bf16 v[88:91], v[194:197], v[210:213], v[88:91]
	v_mfma_f32_16x16x32_bf16 v[80:83], v[186:189], v[218:221], v[80:83]
	v_mfma_f32_16x16x32_bf16 v[72:75], v[194:197], v[218:221], v[72:75]
	v_mfma_f32_16x16x32_bf16 v[68:71], v[186:189], v[226:229], v[68:71]
	v_mfma_f32_16x16x32_bf16 v[64:67], v[194:197], v[226:229], v[64:67]
	s_barrier
; #define PG8_STAGE(bufoff, gbase, voff) do { _Pragma("unroll") for (int _i = 0; _i < 2; ++_i) \
;         __builtin_amdgcn_global_load_lds((const unsigned*)((const char*)(gbase) + (voff)[_i]), (LAS unsigned*)(lds + (bufoff) + ldsw + _i * 8192), 16, 0, 0); } while (0)
; #define PG8_LDA(dst, b, h) do { _Pragma("unroll") for (int m = 0; m < 4; ++m) _Pragma("unroll") for (int k = 0; k < 2; ++k) dst[m][k] = *(const LAS bf16x8*)(lds + PG8_SA(b, h) + aoff + m * 2048 + k * 1024); } while (0)
; #define PG8_LDB(dst, b, h) do { _Pragma("unroll") for (int n = 0; n < 2; ++n) _Pragma("unroll") for (int k = 0; k < 2; ++k) dst[n][k] = *(const LAS bf16x8*)(lds + PG8_SB(b, h) + boff + n * 2048 + k * 1024); } while (0)
; #define PG8_WAIT_V(n) asm volatile("s_waitcnt vmcnt(" #n ")" ::: "memory")
; #define PG8_WAIT_L(n) asm volatile("s_waitcnt lgkmcnt(" #n ")" ::: "memory")
; #define PG8_BAR __builtin_amdgcn_s_barrier()
; template <class Epi>
; __device__ __forceinline__ void gemm_phase(LAS unsigned char* lds, const Gemm g, const StaticOrder& S, const Epi& E) {
;     ...
;             const bool last = (t == nt - 2);
;             const char* a1 = cA + (size_t)(t + 1) * kstep;
;             const char* a2 = last ? nA : cA + (size_t)(t + 2) * kstep; const char* b2 = last ? nB : cB + (size_t)(t + 2) * kstep;
;             const char* a3 = a2 + kstep; const char* b3 = b2 + kstep;
;             PG8_LDB(B0, 0, 0); PG8_LDB(B1, 0, 1); PG8_SCHED; PG8_LDA(At, 0, 0); PG8_STAGE(PG8_SA(1, 1), a1 + hstepA, voffA);
;             PG8_WAIT_V(8); PG8_WAIT_L(0); PG8_BAR; PG8_MMA(0, 0, At, B0); PG8_MMA(0, 1, At, B1); PG8_BAR; PG8_SCHED;
;             PG8_LDA(At, 0, 1); PG8_STAGE(PG8_SB(0, 0), b2, voffB); PG8_STAGE(PG8_SB(0, 1), b2 + hstepB, voffB); PG8_STAGE(PG8_SA(0, 0), a2, voffA);
;             PG8_WAIT_V(8); PG8_WAIT_L(0); PG8_BAR; PG8_MMA(1, 0, At, B0); PG8_MMA(1, 1, At, B1); PG8_BAR; PG8_SCHED;
;             PG8_LDB(B0, 1, 0); PG8_LDB(B1, 1, 1); PG8_SCHED; PG8_LDA(At, 1, 0); PG8_STAGE(PG8_SA(0, 1), a2 + hstepA, voffA);
;             PG8_WAIT_V(8); PG8_WAIT_L(0); PG8_BAR; PG8_MMA(0, 0, At, B0); PG8_MMA(0, 1, At, B1); PG8_BAR; PG8_SCHED;
;             PG8_LDA(At, 1, 1); PG8_STAGE(PG8_SB(1, 0), b3, voffB); PG8_STAGE(PG8_SB(1, 1), b3 + hstepB, voffB); PG8_STAGE(PG8_SA(1, 0), a3, voffA);
;             PG8_WAIT_V(8); PG8_WAIT_L(0); PG8_BAR; PG8_MMA(1, 0, At, B0); PG8_MMA(1, 1, At, B1); PG8_BAR; PG8_SCHED;
	s_add_i32 s12, s88, s43
	v_lshl_add_u64 v[174:175], v[174:175], 0, s[34:35]
	s_mov_b32 m0, s12
	ds_read_b128 v[198:201], v164 offset:49152
	ds_read_b128 v[202:205], v164 offset:50176
	ds_read_b128 v[206:209], v164 offset:51200
	ds_read_b128 v[210:213], v164 offset:52224
	ds_read_b128 v[214:217], v164 offset:53248
	ds_read_b128 v[218:221], v164 offset:54272
	ds_read_b128 v[222:225], v164 offset:55296
	ds_read_b128 v[226:229], v164 offset:56320
	global_load_lds_dwordx4 v[174:175], off
	s_add_i32 m0, s12, 0x2000
	s_add_u32 s10, s10, 0x40080
	v_lshl_add_u64 v[174:175], v[230:231], 0, s[34:35]
	s_addc_u32 s11, s11, 0
	s_add_i32 s12, s89, s43
	global_load_lds_dwordx4 v[174:175], off
	v_lshl_add_u64 v[174:175], s[10:11], 0, v[130:131]
	s_mov_b32 m0, s12
	s_nop 0
	global_load_lds_dwordx4 v[174:175], off
	v_lshl_add_u64 v[174:175], s[10:11], 0, v[134:135]
	s_add_i32 m0, s12, 0x2000
	s_nop 0
	global_load_lds_dwordx4 v[174:175], off
	v_lshl_add_u64 v[174:175], v[232:233], 0, s[34:35]
	s_mov_b32 m0, s77
	s_nop 0
	global_load_lds_dwordx4 v[174:175], off
	v_lshl_add_u64 v[174:175], v[234:235], 0, s[34:35]
	s_mov_b32 m0, s78
	s_nop 0
	global_load_lds_dwordx4 v[174:175], off
	s_waitcnt vmcnt(8)
	s_waitcnt lgkmcnt(0)
	s_barrier
	s_waitcnt lgkmcnt(0)
	v_mfma_f32_16x16x32_bf16 v[60:63], v[146:149], v[198:201], v[60:63]
	v_mfma_f32_16x16x32_bf16 v[56:59], v[170:173], v[198:201], v[56:59]
	v_mfma_f32_16x16x32_bf16 v[52:55], v[146:149], v[206:209], v[52:55]
	v_mfma_f32_16x16x32_bf16 v[44:47], v[170:173], v[206:209], v[44:47]
	v_mfma_f32_16x16x32_bf16 v[36:39], v[146:149], v[214:217], v[36:39]
	v_mfma_f32_16x16x32_bf16 v[28:31], v[170:173], v[214:217], v[28:31]
	v_mfma_f32_16x16x32_bf16 v[20:23], v[146:149], v[222:225], v[20:23]
	v_mfma_f32_16x16x32_bf16 v[12:15], v[170:173], v[222:225], v[12:15]
	v_mfma_f32_16x16x32_bf16 v[60:63], v[166:169], v[202:205], v[60:63]
	v_mfma_f32_16x16x32_bf16 v[56:59], v[178:181], v[202:205], v[56:59]
	v_mfma_f32_16x16x32_bf16 v[52:55], v[166:169], v[210:213], v[52:55]
	v_mfma_f32_16x16x32_bf16 v[44:47], v[178:181], v[210:213], v[44:47]
	v_mfma_f32_16x16x32_bf16 v[36:39], v[166:169], v[218:221], v[36:39]
	v_mfma_f32_16x16x32_bf16 v[28:31], v[178:181], v[218:221], v[28:31]
	v_mfma_f32_16x16x32_bf16 v[20:23], v[166:169], v[226:229], v[20:23]
	v_mfma_f32_16x16x32_bf16 v[12:15], v[178:181], v[226:229], v[12:15]
	v_mfma_f32_16x16x32_bf16 v[48:51], v[182:185], v[198:201], v[48:51]
	v_mfma_f32_16x16x32_bf16 v[40:43], v[190:193], v[198:201], v[40:43]
	v_mfma_f32_16x16x32_bf16 v[32:35], v[182:185], v[206:209], v[32:35]
	v_mfma_f32_16x16x32_bf16 v[24:27], v[190:193], v[206:209], v[24:27]
	v_mfma_f32_16x16x32_bf16 v[16:19], v[182:185], v[214:217], v[16:19]
	v_mfma_f32_16x16x32_bf16 v[8:11], v[190:193], v[214:217], v[8:11]
	v_mfma_f32_16x16x32_bf16 v[4:7], v[182:185], v[222:225], v[4:7]
	v_mfma_f32_16x16x32_bf16 v[0:3], v[190:193], v[222:225], v[0:3]
	v_mfma_f32_16x16x32_bf16 v[48:51], v[186:189], v[202:205], v[48:51]
	v_mfma_f32_16x16x32_bf16 v[40:43], v[194:197], v[202:205], v[40:43]
	v_mfma_f32_16x16x32_bf16 v[32:35], v[186:189], v[210:213], v[32:35]
	v_mfma_f32_16x16x32_bf16 v[24:27], v[194:197], v[210:213], v[24:27]
	v_mfma_f32_16x16x32_bf16 v[16:19], v[186:189], v[218:221], v[16:19]
	v_mfma_f32_16x16x32_bf16 v[8:11], v[194:197], v[218:221], v[8:11]
	v_mfma_f32_16x16x32_bf16 v[4:7], v[186:189], v[226:229], v[4:7]
	v_mfma_f32_16x16x32_bf16 v[0:3], v[194:197], v[226:229], v[0:3]
	s_barrier
	s_add_i32 s87, s87, 2
	s_add_u32 s8, s8, 0x100
	s_addc_u32 s9, s9, 0
	s_add_u32 s74, s74, 0x100
	s_addc_u32 s75, s75, 0
	s_cmp_gt_u32 s87, 13
.LBB0_1403:
	ds_read_b128 v[146:149], v162
	ds_read_b128 v[166:169], v162 offset:1024
	ds_read_b128 v[170:173], v162 offset:2048
	ds_read_b128 v[178:181], v162 offset:3072
	ds_read_b128 v[182:185], v163
	ds_read_b128 v[186:189], v163 offset:1024
	ds_read_b128 v[190:193], v163 offset:2048
	ds_read_b128 v[194:197], v163 offset:3072
	s_add_u32 s10, s8, 0xfffc0080
	s_addc_u32 s11, s9, -1
	s_cmp_eq_u32 s87, 12
	s_cselect_b32 s13, s1, s11
	s_cselect_b32 s12, s7, s10
	s_cselect_b32 s11, s65, s75
	s_cselect_b32 s10, s69, s74
	v_lshl_add_u64 v[174:175], s[8:9], 0, v[138:139]
	s_add_i32 m0, s53, 0xc000
	ds_read_b128 v[198:201], v164
	ds_read_b128 v[202:205], v164 offset:1024
	ds_read_b128 v[206:209], v164 offset:2048
	ds_read_b128 v[210:213], v164 offset:3072
	ds_read_b128 v[214:217], v164 offset:4096
	ds_read_b128 v[218:221], v164 offset:5120
	ds_read_b128 v[222:225], v164 offset:6144
	ds_read_b128 v[226:229], v164 offset:7168
	global_load_lds_dwordx4 v[174:175], off
	v_lshl_add_u64 v[174:175], s[8:9], 0, v[140:141]
	s_add_i32 m0, s53, 0xe000
	s_nop 0
	global_load_lds_dwordx4 v[174:175], off
	s_waitcnt vmcnt(8)
	s_waitcnt lgkmcnt(0)
	s_barrier
; #define PG8_STAGE(bufoff, gbase, voff) do { _Pragma("unroll") for (int _i = 0; _i < 2; ++_i) \
;         __builtin_amdgcn_global_load_lds((const unsigned*)((const char*)(gbase) + (voff)[_i]), (LAS unsigned*)(lds + (bufoff) + ldsw + _i * 8192), 16, 0, 0); } while (0)
; #define PG8_LDA(dst, b, h) do { _Pragma("unroll") for (int m = 0; m < 4; ++m) _Pragma("unroll") for (int k = 0; k < 2; ++k) dst[m][k] = *(const LAS bf16x8*)(lds + PG8_SA(b, h) + aoff + m * 2048 + k * 1024); } while (0)
; #define PG8_LDB(dst, b, h) do { _Pragma("unroll") for (int n = 0; n < 2; ++n) _Pragma("unroll") for (int k = 0; k < 2; ++k) dst[n][k] = *(const LAS bf16x8*)(lds + PG8_SB(b, h) + boff + n * 2048 + k * 1024); } while (0)
; #define PG8_MMA(ai, bj, At, Bt) do { __builtin_amdgcn_s_setprio(1); _Pragma("unroll") for (int m = 0; m < 4; ++m) _Pragma("unroll") for (int n = 0; n < 2; ++n) _Pragma("unroll") for (int k = 0; k < 2; ++k) \
;         acc[ai][bj][m][n] = __builtin_amdgcn_mfma_f32_16x16x32_bf16(Bt[n][k], At[m][k], acc[ai][bj][m][n], 0, 0, 0); __builtin_amdgcn_s_setprio(0); } while (0)
; #define PG8_WAIT_V(n) asm volatile("s_waitcnt vmcnt(" #n ")" ::: "memory")
; #define PG8_BAR __builtin_amdgcn_s_barrier()
; template <class Epi>
; __device__ __forceinline__ void gemm_phase(LAS unsigned char* lds, const Gemm g, const StaticOrder& S, const Epi& E) {
;     ...
;             PG8_LDB(B0, 0, 0); PG8_LDB(B1, 0, 1); PG8_SCHED; PG8_LDA(At, 0, 0); PG8_STAGE(PG8_SA(1, 1), a1 + hstepA, voffA);
;             PG8_WAIT_V(8); PG8_WAIT_L(0); PG8_BAR; PG8_MMA(0, 0, At, B0); PG8_MMA(0, 1, At, B1); PG8_BAR; PG8_SCHED;
;             PG8_LDA(At, 0, 1); PG8_STAGE(PG8_SB(0, 0), b2, voffB); PG8_STAGE(PG8_SB(0, 1), b2 + hstepB, voffB); PG8_STAGE(PG8_SA(0, 0), a2, voffA);
;             PG8_WAIT_V(8); PG8_WAIT_L(0); PG8_BAR; PG8_MMA(1, 0, At, B0); PG8_MMA(1, 1, At, B1); PG8_BAR; PG8_SCHED;
;             PG8_LDB(B0, 1, 0); PG8_LDB(B1, 1, 1); PG8_SCHED; PG8_LDA(At, 1, 0); PG8_STAGE(PG8_SA(0, 1), a2 + hstepA, voffA);
;             PG8_WAIT_V(8); PG8_WAIT_L(0); PG8_BAR; PG8_MMA(0, 0, At, B0); PG8_MMA(0, 1, At, B1); PG8_BAR; PG8_SCHED;
;             PG8_LDA(At, 1, 1); PG8_STAGE(PG8_SB(1, 0), b3, voffB); PG8_STAGE(PG8_SB(1, 1), b3 + hstepB, voffB); PG8_STAGE(PG8_SA(1, 0), a3, voffA);
;             PG8_WAIT_V(8); PG8_WAIT_L(0); PG8_BAR; PG8_MMA(1, 0, At, B0); PG8_MMA(1, 1, At, B1); PG8_BAR; PG8_SCHED;
	s_waitcnt lgkmcnt(0)
	v_mfma_f32_16x16x32_bf16 v[124:127], v[146:149], v[198:201], v[124:127]
	v_mfma_f32_16x16x32_bf16 v[120:123], v[170:173], v[198:201], v[120:123]
	v_mfma_f32_16x16x32_bf16 v[112:115], v[146:149], v[206:209], v[112:115]
	v_mfma_f32_16x16x32_bf16 v[104:107], v[170:173], v[206:209], v[104:107]
	v_mfma_f32_16x16x32_bf16 v[100:103], v[146:149], v[214:217], v[100:103]
	v_mfma_f32_16x16x32_bf16 v[92:95], v[170:173], v[214:217], v[92:95]
	v_mfma_f32_16x16x32_bf16 v[84:87], v[146:149], v[222:225], v[84:87]
	v_mfma_f32_16x16x32_bf16 v[76:79], v[170:173], v[222:225], v[76:79]
	v_mfma_f32_16x16x32_bf16 v[124:127], v[166:169], v[202:205], v[124:127]
	v_mfma_f32_16x16x32_bf16 v[120:123], v[178:181], v[202:205], v[120:123]
	v_mfma_f32_16x16x32_bf16 v[112:115], v[166:169], v[210:213], v[112:115]
	v_mfma_f32_16x16x32_bf16 v[104:107], v[178:181], v[210:213], v[104:107]
	v_mfma_f32_16x16x32_bf16 v[100:103], v[166:169], v[218:221], v[100:103]
	v_mfma_f32_16x16x32_bf16 v[92:95], v[178:181], v[218:221], v[92:95]
	v_mfma_f32_16x16x32_bf16 v[84:87], v[166:169], v[226:229], v[84:87]
	v_mfma_f32_16x16x32_bf16 v[76:79], v[178:181], v[226:229], v[76:79]
	v_mfma_f32_16x16x32_bf16 v[116:119], v[182:185], v[198:201], v[116:119]
	v_mfma_f32_16x16x32_bf16 v[108:111], v[190:193], v[198:201], v[108:111]
	v_mfma_f32_16x16x32_bf16 v[96:99], v[182:185], v[206:209], v[96:99]
	v_mfma_f32_16x16x32_bf16 v[88:91], v[190:193], v[206:209], v[88:91]
	v_mfma_f32_16x16x32_bf16 v[80:83], v[182:185], v[214:217], v[80:83]
	v_mfma_f32_16x16x32_bf16 v[72:75], v[190:193], v[214:217], v[72:75]
	v_mfma_f32_16x16x32_bf16 v[68:71], v[182:185], v[222:225], v[68:71]
	v_mfma_f32_16x16x32_bf16 v[64:67], v[190:193], v[222:225], v[64:67]
	v_mfma_f32_16x16x32_bf16 v[116:119], v[186:189], v[202:205], v[116:119]
	v_mfma_f32_16x16x32_bf16 v[108:111], v[194:197], v[202:205], v[108:111]
	v_mfma_f32_16x16x32_bf16 v[96:99], v[186:189], v[210:213], v[96:99]
	v_mfma_f32_16x16x32_bf16 v[88:91], v[194:197], v[210:213], v[88:91]
	v_mfma_f32_16x16x32_bf16 v[80:83], v[186:189], v[218:221], v[80:83]
	v_mfma_f32_16x16x32_bf16 v[72:75], v[194:197], v[218:221], v[72:75]
	v_mfma_f32_16x16x32_bf16 v[68:71], v[186:189], v[226:229], v[68:71]
	v_mfma_f32_16x16x32_bf16 v[64:67], v[194:197], v[226:229], v[64:67]
	s_barrier
	s_add_i32 s88, s83, s43
	v_lshl_add_u64 v[174:175], s[10:11], 0, v[130:131]
	s_mov_b32 m0, s88
	ds_read_b128 v[198:201], v164 offset:16384
	ds_read_b128 v[202:205], v164 offset:17408
	ds_read_b128 v[206:209], v164 offset:18432
	ds_read_b128 v[210:213], v164 offset:19456
	ds_read_b128 v[214:217], v164 offset:20480
	ds_read_b128 v[218:221], v164 offset:21504
	ds_read_b128 v[222:225], v164 offset:22528
	ds_read_b128 v[226:229], v164 offset:23552
	global_load_lds_dwordx4 v[174:175], off
	s_add_i32 m0, s88, 0x2000
	s_add_u32 s88, s10, 0x40000
	v_lshl_add_u64 v[230:231], s[10:11], 0, v[134:135]
	s_addc_u32 s89, s11, 0
	s_add_i32 s90, s84, s43
	global_load_lds_dwordx4 v[230:231], off
	v_lshl_add_u64 v[232:233], s[88:89], 0, v[130:131]
	s_mov_b32 m0, s90
	v_lshl_add_u64 v[234:235], s[12:13], 0, v[132:133]
	global_load_lds_dwordx4 v[232:233], off
	v_lshl_add_u64 v[232:233], s[88:89], 0, v[134:135]
	s_add_i32 m0, s90, 0x2000
	s_nop 0
	global_load_lds_dwordx4 v[232:233], off
	v_lshl_add_u64 v[232:233], s[12:13], 0, v[128:129]
	s_mov_b32 m0, s53
	s_nop 0
	global_load_lds_dwordx4 v[232:233], off
	s_mov_b32 m0, s55
	s_nop 0
	global_load_lds_dwordx4 v[234:235], off
	s_waitcnt vmcnt(8)
	s_waitcnt lgkmcnt(0)
	s_barrier
	s_waitcnt lgkmcnt(0)
	v_mfma_f32_16x16x32_bf16 v[60:63], v[146:149], v[198:201], v[60:63]
	v_mfma_f32_16x16x32_bf16 v[56:59], v[170:173], v[198:201], v[56:59]
	v_mfma_f32_16x16x32_bf16 v[52:55], v[146:149], v[206:209], v[52:55]
	v_mfma_f32_16x16x32_bf16 v[44:47], v[170:173], v[206:209], v[44:47]
	v_mfma_f32_16x16x32_bf16 v[36:39], v[146:149], v[214:217], v[36:39]
	v_mfma_f32_16x16x32_bf16 v[28:31], v[170:173], v[214:217], v[28:31]
	v_mfma_f32_16x16x32_bf16 v[20:23], v[146:149], v[222:225], v[20:23]
	v_mfma_f32_16x16x32_bf16 v[12:15], v[170:173], v[222:225], v[12:15]
	v_mfma_f32_16x16x32_bf16 v[60:63], v[166:169], v[202:205], v[60:63]
	v_mfma_f32_16x16x32_bf16 v[56:59], v[178:181], v[202:205], v[56:59]
	v_mfma_f32_16x16x32_bf16 v[52:55], v[166:169], v[210:213], v[52:55]
	v_mfma_f32_16x16x32_bf16 v[44:47], v[178:181], v[210:213], v[44:47]
	v_mfma_f32_16x16x32_bf16 v[36:39], v[166:169], v[218:221], v[36:39]
	v_mfma_f32_16x16x32_bf16 v[28:31], v[178:181], v[218:221], v[28:31]
	v_mfma_f32_16x16x32_bf16 v[20:23], v[166:169], v[226:229], v[20:23]
	v_mfma_f32_16x16x32_bf16 v[12:15], v[178:181], v[226:229], v[12:15]
	v_mfma_f32_16x16x32_bf16 v[48:51], v[182:185], v[198:201], v[48:51]
	v_mfma_f32_16x16x32_bf16 v[40:43], v[190:193], v[198:201], v[40:43]
	v_mfma_f32_16x16x32_bf16 v[32:35], v[182:185], v[206:209], v[32:35]
	v_mfma_f32_16x16x32_bf16 v[24:27], v[190:193], v[206:209], v[24:27]
	v_mfma_f32_16x16x32_bf16 v[16:19], v[182:185], v[214:217], v[16:19]
	v_mfma_f32_16x16x32_bf16 v[8:11], v[190:193], v[214:217], v[8:11]
	v_mfma_f32_16x16x32_bf16 v[4:7], v[182:185], v[222:225], v[4:7]
	v_mfma_f32_16x16x32_bf16 v[0:3], v[190:193], v[222:225], v[0:3]
	v_mfma_f32_16x16x32_bf16 v[48:51], v[186:189], v[202:205], v[48:51]
	v_mfma_f32_16x16x32_bf16 v[40:43], v[194:197], v[202:205], v[40:43]
	v_mfma_f32_16x16x32_bf16 v[32:35], v[186:189], v[210:213], v[32:35]
	v_mfma_f32_16x16x32_bf16 v[24:27], v[194:197], v[210:213], v[24:27]
	v_mfma_f32_16x16x32_bf16 v[16:19], v[186:189], v[218:221], v[16:19]
	v_mfma_f32_16x16x32_bf16 v[8:11], v[194:197], v[218:221], v[8:11]
	v_mfma_f32_16x16x32_bf16 v[4:7], v[186:189], v[226:229], v[4:7]
	v_mfma_f32_16x16x32_bf16 v[0:3], v[194:197], v[226:229], v[0:3]
	s_barrier
; #define PG8_STAGE(bufoff, gbase, voff) do { _Pragma("unroll") for (int _i = 0; _i < 2; ++_i) \
;         __builtin_amdgcn_global_load_lds((const unsigned*)((const char*)(gbase) + (voff)[_i]), (LAS unsigned*)(lds + (bufoff) + ldsw + _i * 8192), 16, 0, 0); } while (0)
; #define PG8_LDA(dst, b, h) do { _Pragma("unroll") for (int m = 0; m < 4; ++m) _Pragma("unroll") for (int k = 0; k < 2; ++k) dst[m][k] = *(const LAS bf16x8*)(lds + PG8_SA(b, h) + aoff + m * 2048 + k * 1024); } while (0)
; #define PG8_LDB(dst, b, h) do { _Pragma("unroll") for (int n = 0; n < 2; ++n) _Pragma("unroll") for (int k = 0; k < 2; ++k) dst[n][k] = *(const LAS bf16x8*)(lds + PG8_SB(b, h) + boff + n * 2048 + k * 1024); } while (0)
; #define PG8_MMA(ai, bj, At, Bt) do { __builtin_amdgcn_s_setprio(1); _Pragma("unroll") for (int m = 0; m < 4; ++m) _Pragma("unroll") for (int n = 0; n < 2; ++n) _Pragma("unroll") for (int k = 0; k < 2; ++k) \
;         acc[ai][bj][m][n] = __builtin_amdgcn_mfma_f32_16x16x32_bf16(Bt[n][k], At[m][k], acc[ai][bj][m][n], 0, 0, 0); __builtin_amdgcn_s_setprio(0); } while (0)
; #define PG8_WAIT_V(n) asm volatile("s_waitcnt vmcnt(" #n ")" ::: "memory")
; #define PG8_WAIT_L(n) asm volatile("s_waitcnt lgkmcnt(" #n ")" ::: "memory")
; #define PG8_BAR __builtin_amdgcn_s_barrier()
; #define PG8_SCHED __builtin_amdgcn_sched_barrier(0)
; template <class Epi>
; __device__ __forceinline__ void gemm_phase(LAS unsigned char* lds, const Gemm g, const StaticOrder& S, const Epi& E) {
;     ...
;             PG8_LDB(B0, 1, 0); PG8_LDB(B1, 1, 1); PG8_SCHED; PG8_LDA(At, 1, 0); PG8_STAGE(PG8_SA(0, 1), a2 + hstepA, voffA);
;             PG8_WAIT_V(8); PG8_WAIT_L(0); PG8_BAR; PG8_MMA(0, 0, At, B0); PG8_MMA(0, 1, At, B1); PG8_BAR; PG8_SCHED;
	s_add_i32 s88, 0, 0x18000
	v_add_u32_e32 v136, s88, v161
	s_add_i32 s89, 0, 0x1c000
	ds_read_b128 v[146:149], v136
	ds_read_b128 v[166:169], v136 offset:1024
	ds_read_b128 v[170:173], v136 offset:2048
	ds_read_b128 v[178:181], v136 offset:3072
	v_add_u32_e32 v136, s89, v161
	ds_read_b128 v[182:185], v136
	ds_read_b128 v[186:189], v136 offset:1024
	ds_read_b128 v[190:193], v136 offset:2048
	ds_read_b128 v[194:197], v136 offset:3072
	s_add_u32 s12, s12, 0x40000
	s_addc_u32 s13, s13, 0
	s_mov_b32 m0, s57
	v_lshl_add_u64 v[236:237], s[12:13], 0, v[128:129]
	ds_read_b128 v[198:201], v164 offset:32768
	ds_read_b128 v[202:205], v164 offset:33792
	ds_read_b128 v[206:209], v164 offset:34816
	ds_read_b128 v[210:213], v164 offset:35840
	ds_read_b128 v[214:217], v164 offset:36864
	ds_read_b128 v[218:221], v164 offset:37888
	ds_read_b128 v[222:225], v164 offset:38912
	ds_read_b128 v[226:229], v164 offset:39936
	global_load_lds_dwordx4 v[236:237], off
	v_lshl_add_u64 v[236:237], s[12:13], 0, v[132:133]
	s_mov_b32 m0, s59
	s_nop 0
	global_load_lds_dwordx4 v[236:237], off
	s_waitcnt vmcnt(8)
	s_waitcnt lgkmcnt(0)
	s_barrier
	s_waitcnt lgkmcnt(0)
	v_mfma_f32_16x16x32_bf16 v[124:127], v[146:149], v[198:201], v[124:127]
	v_mfma_f32_16x16x32_bf16 v[120:123], v[170:173], v[198:201], v[120:123]
	v_mfma_f32_16x16x32_bf16 v[112:115], v[146:149], v[206:209], v[112:115]
	v_mfma_f32_16x16x32_bf16 v[104:107], v[170:173], v[206:209], v[104:107]
	v_mfma_f32_16x16x32_bf16 v[100:103], v[146:149], v[214:217], v[100:103]
	v_mfma_f32_16x16x32_bf16 v[92:95], v[170:173], v[214:217], v[92:95]
	v_mfma_f32_16x16x32_bf16 v[84:87], v[146:149], v[222:225], v[84:87]
	v_mfma_f32_16x16x32_bf16 v[76:79], v[170:173], v[222:225], v[76:79]
	v_mfma_f32_16x16x32_bf16 v[124:127], v[166:169], v[202:205], v[124:127]
	v_mfma_f32_16x16x32_bf16 v[120:123], v[178:181], v[202:205], v[120:123]
	v_mfma_f32_16x16x32_bf16 v[112:115], v[166:169], v[210:213], v[112:115]
	v_mfma_f32_16x16x32_bf16 v[104:107], v[178:181], v[210:213], v[104:107]
	v_mfma_f32_16x16x32_bf16 v[100:103], v[166:169], v[218:221], v[100:103]
	v_mfma_f32_16x16x32_bf16 v[92:95], v[178:181], v[218:221], v[92:95]
	v_mfma_f32_16x16x32_bf16 v[84:87], v[166:169], v[226:229], v[84:87]
	v_mfma_f32_16x16x32_bf16 v[76:79], v[178:181], v[226:229], v[76:79]
	v_mfma_f32_16x16x32_bf16 v[116:119], v[182:185], v[198:201], v[116:119]
	v_mfma_f32_16x16x32_bf16 v[108:111], v[190:193], v[198:201], v[108:111]
	v_mfma_f32_16x16x32_bf16 v[96:99], v[182:185], v[206:209], v[96:99]
	v_mfma_f32_16x16x32_bf16 v[88:91], v[190:193], v[206:209], v[88:91]
	v_mfma_f32_16x16x32_bf16 v[80:83], v[182:185], v[214:217], v[80:83]
	v_mfma_f32_16x16x32_bf16 v[72:75], v[190:193], v[214:217], v[72:75]
	v_mfma_f32_16x16x32_bf16 v[68:71], v[182:185], v[222:225], v[68:71]
	v_mfma_f32_16x16x32_bf16 v[64:67], v[190:193], v[222:225], v[64:67]
	v_mfma_f32_16x16x32_bf16 v[116:119], v[186:189], v[202:205], v[116:119]
	v_mfma_f32_16x16x32_bf16 v[108:111], v[194:197], v[202:205], v[108:111]
	v_mfma_f32_16x16x32_bf16 v[96:99], v[186:189], v[210:213], v[96:99]
	v_mfma_f32_16x16x32_bf16 v[88:91], v[194:197], v[210:213], v[88:91]
	v_mfma_f32_16x16x32_bf16 v[80:83], v[186:189], v[218:221], v[80:83]
	v_mfma_f32_16x16x32_bf16 v[72:75], v[194:197], v[218:221], v[72:75]
	v_mfma_f32_16x16x32_bf16 v[68:71], v[186:189], v[226:229], v[68:71]
	v_mfma_f32_16x16x32_bf16 v[64:67], v[194:197], v[226:229], v[64:67]
	s_barrier
; #define PG8_STAGE(bufoff, gbase, voff) do { _Pragma("unroll") for (int _i = 0; _i < 2; ++_i) \
;         __builtin_amdgcn_global_load_lds((const unsigned*)((const char*)(gbase) + (voff)[_i]), (LAS unsigned*)(lds + (bufoff) + ldsw + _i * 8192), 16, 0, 0); } while (0)
; #define PG8_LDA(dst, b, h) do { _Pragma("unroll") for (int m = 0; m < 4; ++m) _Pragma("unroll") for (int k = 0; k < 2; ++k) dst[m][k] = *(const LAS bf16x8*)(lds + PG8_SA(b, h) + aoff + m * 2048 + k * 1024); } while (0)
; #define PG8_MMA(ai, bj, At, Bt) do { __builtin_amdgcn_s_setprio(1); _Pragma("unroll") for (int m = 0; m < 4; ++m) _Pragma("unroll") for (int n = 0; n < 2; ++n) _Pragma("unroll") for (int k = 0; k < 2; ++k) \
;         acc[ai][bj][m][n] = __builtin_amdgcn_mfma_f32_16x16x32_bf16(Bt[n][k], At[m][k], acc[ai][bj][m][n], 0, 0, 0); __builtin_amdgcn_s_setprio(0); } while (0)
; #define PG8_WAIT_V(n) asm volatile("s_waitcnt vmcnt(" #n ")" ::: "memory")
; #define PG8_WAIT_L(n) asm volatile("s_waitcnt lgkmcnt(" #n ")" ::: "memory")
; #define PG8_BAR __builtin_amdgcn_s_barrier()
; #define PG8_SCHED __builtin_amdgcn_sched_barrier(0)
; template <class Epi>
; __device__ __forceinline__ void gemm_phase(LAS unsigned char* lds, const Gemm g, const StaticOrder& S, const Epi& E) {
;     ...
;             PG8_LDA(At, 1, 1); PG8_STAGE(PG8_SB(1, 0), b3, voffB); PG8_STAGE(PG8_SB(1, 1), b3 + hstepB, voffB); PG8_STAGE(PG8_SA(1, 0), a3, voffA);
;             PG8_WAIT_V(8); PG8_WAIT_L(0); PG8_BAR; PG8_MMA(1, 0, At, B0); PG8_MMA(1, 1, At, B1); PG8_BAR; PG8_SCHED;
;         }
;         if (wr == 0) PG8_BAR;
	s_add_i32 s12, s88, s43
	v_lshl_add_u64 v[174:175], v[174:175], 0, s[34:35]
	s_mov_b32 m0, s12
	ds_read_b128 v[198:201], v164 offset:49152
	ds_read_b128 v[202:205], v164 offset:50176
	ds_read_b128 v[206:209], v164 offset:51200
	ds_read_b128 v[210:213], v164 offset:52224
	ds_read_b128 v[214:217], v164 offset:53248
	ds_read_b128 v[218:221], v164 offset:54272
	ds_read_b128 v[222:225], v164 offset:55296
	ds_read_b128 v[226:229], v164 offset:56320
	global_load_lds_dwordx4 v[174:175], off
	s_add_i32 m0, s12, 0x2000
	s_add_u32 s10, s10, 0x40080
	v_lshl_add_u64 v[174:175], v[230:231], 0, s[34:35]
	s_addc_u32 s11, s11, 0
	s_add_i32 s12, s89, s43
	global_load_lds_dwordx4 v[174:175], off
	v_lshl_add_u64 v[174:175], s[10:11], 0, v[130:131]
	s_mov_b32 m0, s12
	s_nop 0
	global_load_lds_dwordx4 v[174:175], off
	v_lshl_add_u64 v[174:175], s[10:11], 0, v[134:135]
	s_add_i32 m0, s12, 0x2000
	s_nop 0
	global_load_lds_dwordx4 v[174:175], off
	v_lshl_add_u64 v[174:175], v[232:233], 0, s[34:35]
	s_mov_b32 m0, s77
	s_nop 0
	global_load_lds_dwordx4 v[174:175], off
	v_lshl_add_u64 v[174:175], v[234:235], 0, s[34:35]
	s_mov_b32 m0, s78
	s_nop 0
	global_load_lds_dwordx4 v[174:175], off
	s_waitcnt vmcnt(8)
	s_waitcnt lgkmcnt(0)
	s_barrier
	s_waitcnt lgkmcnt(0)
	v_mfma_f32_16x16x32_bf16 v[60:63], v[146:149], v[198:201], v[60:63]
	v_mfma_f32_16x16x32_bf16 v[56:59], v[170:173], v[198:201], v[56:59]
	v_mfma_f32_16x16x32_bf16 v[52:55], v[146:149], v[206:209], v[52:55]
	v_mfma_f32_16x16x32_bf16 v[44:47], v[170:173], v[206:209], v[44:47]
	v_mfma_f32_16x16x32_bf16 v[36:39], v[146:149], v[214:217], v[36:39]
	v_mfma_f32_16x16x32_bf16 v[28:31], v[170:173], v[214:217], v[28:31]
	v_mfma_f32_16x16x32_bf16 v[20:23], v[146:149], v[222:225], v[20:23]
	v_mfma_f32_16x16x32_bf16 v[12:15], v[170:173], v[222:225], v[12:15]
	v_mfma_f32_16x16x32_bf16 v[60:63], v[166:169], v[202:205], v[60:63]
	v_mfma_f32_16x16x32_bf16 v[56:59], v[178:181], v[202:205], v[56:59]
	v_mfma_f32_16x16x32_bf16 v[52:55], v[166:169], v[210:213], v[52:55]
	v_mfma_f32_16x16x32_bf16 v[44:47], v[178:181], v[210:213], v[44:47]
	v_mfma_f32_16x16x32_bf16 v[36:39], v[166:169], v[218:221], v[36:39]
	v_mfma_f32_16x16x32_bf16 v[28:31], v[178:181], v[218:221], v[28:31]
	v_mfma_f32_16x16x32_bf16 v[20:23], v[166:169], v[226:229], v[20:23]
	v_mfma_f32_16x16x32_bf16 v[12:15], v[178:181], v[226:229], v[12:15]
	v_mfma_f32_16x16x32_bf16 v[48:51], v[182:185], v[198:201], v[48:51]
	v_mfma_f32_16x16x32_bf16 v[40:43], v[190:193], v[198:201], v[40:43]
	v_mfma_f32_16x16x32_bf16 v[32:35], v[182:185], v[206:209], v[32:35]
	v_mfma_f32_16x16x32_bf16 v[24:27], v[190:193], v[206:209], v[24:27]
	v_mfma_f32_16x16x32_bf16 v[16:19], v[182:185], v[214:217], v[16:19]
	v_mfma_f32_16x16x32_bf16 v[8:11], v[190:193], v[214:217], v[8:11]
	v_mfma_f32_16x16x32_bf16 v[4:7], v[182:185], v[222:225], v[4:7]
	v_mfma_f32_16x16x32_bf16 v[0:3], v[190:193], v[222:225], v[0:3]
	v_mfma_f32_16x16x32_bf16 v[48:51], v[186:189], v[202:205], v[48:51]
	v_mfma_f32_16x16x32_bf16 v[40:43], v[194:197], v[202:205], v[40:43]
	v_mfma_f32_16x16x32_bf16 v[32:35], v[186:189], v[210:213], v[32:35]
	v_mfma_f32_16x16x32_bf16 v[24:27], v[194:197], v[210:213], v[24:27]
	v_mfma_f32_16x16x32_bf16 v[16:19], v[186:189], v[218:221], v[16:19]
	v_mfma_f32_16x16x32_bf16 v[8:11], v[194:197], v[218:221], v[8:11]
	v_mfma_f32_16x16x32_bf16 v[4:7], v[186:189], v[226:229], v[4:7]
	v_mfma_f32_16x16x32_bf16 v[0:3], v[194:197], v[226:229], v[0:3]
	s_barrier
	s_add_i32 s87, s87, 2
	s_add_u32 s8, s8, 0x100
	s_addc_u32 s9, s9, 0
	s_add_u32 s74, s74, 0x100
	s_addc_u32 s75, s75, 0
	s_cmp_gt_u32 s87, 13
	s_cbranch_scc0 .LBB0_1403
	s_and_b64 vcc, exec, s[38:39]
	s_cbranch_vccz .LBB0_1406
	s_barrier

; #define PG8_STAGE(bufoff, gbase, voff) do { _Pragma("unroll") for (int _i = 0; _i < 2; ++_i) \
;         __builtin_amdgcn_global_load_lds((const unsigned*)((const char*)(gbase) + (voff)[_i]), (LAS unsigned*)(lds + (bufoff) + ldsw + _i * 8192), 16, 0, 0); } while (0)
; #define PG8_LDA(dst, b, h) do { _Pragma("unroll") for (int m = 0; m < 4; ++m) _Pragma("unroll") for (int k = 0; k < 2; ++k) dst[m][k] = *(const LAS bf16x8*)(lds + PG8_SA(b, h) + aoff + m * 2048 + k * 1024); } while (0)
; #define PG8_WAIT_V(n) asm volatile("s_waitcnt vmcnt(" #n ")" ::: "memory")
; #define PG8_WAIT_L(n) asm volatile("s_waitcnt lgkmcnt(" #n ")" ::: "memory")
; template <class Epi>
; __device__ __forceinline__ void gemm_phase(LAS unsigned char* lds, const Gemm g, const StaticOrder& S, const Epi& E) {
;     ...
;         const char* nA = has_next ? (const char*)g.A + (size_t)nxt.pm * tstepA : cA; const char* nB = has_next ? (const char*)g.Bt + (size_t)nxt.pn * tstepB : cB;
; #pragma nounroll
;         for (int t = 0; t < nt; t += 2) {
;             const bool last = (t == nt - 2);
;             const char* a1 = cA + (size_t)(t + 1) * kstep;
;             const char* a2 = last ? nA : cA + (size_t)(t + 2) * kstep; const char* b2 = last ? nB : cB + (size_t)(t + 2) * kstep;
;             const char* a3 = a2 + kstep; const char* b3 = b2 + kstep;
;             PG8_LDB(B0, 0, 0); PG8_LDB(B1, 0, 1); PG8_SCHED; PG8_LDA(At, 0, 0); PG8_STAGE(PG8_SA(1, 1), a1 + hstepA, voffA);
;             PG8_WAIT_V(8); PG8_WAIT_L(0); PG8_BAR; PG8_MMA(0, 0, At, B0); PG8_MMA(0, 1, At, B1); PG8_BAR; PG8_SCHED;
;             PG8_LDA(At, 0, 1); PG8_STAGE(PG8_SB(0, 0), b2, voffB); PG8_STAGE(PG8_SB(0, 1), b2 + hstepB, voffB); PG8_STAGE(PG8_SA(0, 0), a2, voffA);
;             PG8_WAIT_V(8); PG8_WAIT_L(0); PG8_BAR; PG8_MMA(1, 0, At, B0); PG8_MMA(1, 1, At, B1); PG8_BAR; PG8_SCHED;
;             PG8_LDB(B0, 1, 0); PG8_LDB(B1, 1, 1); PG8_SCHED; PG8_LDA(At, 1, 0); PG8_STAGE(PG8_SA(0, 1), a2 + hstepA, voffA);
;             PG8_WAIT_V(8); PG8_WAIT_L(0); PG8_BAR; PG8_MMA(0, 0, At, B0); PG8_MMA(0, 1, At, B1); PG8_BAR; PG8_SCHED;
;             PG8_LDA(At, 1, 1); PG8_STAGE(PG8_SB(1, 0), b3, voffB); PG8_STAGE(PG8_SB(1, 1), b3 + hstepB, voffB); PG8_STAGE(PG8_SA(1, 0), a3, voffA);
;             PG8_WAIT_V(8); PG8_WAIT_L(0); PG8_BAR; PG8_MMA(1, 0, At, B0); PG8_MMA(1, 1, At, B1); PG8_BAR; PG8_SCHED;
.LBB0_1469:
	s_add_u32 s62, s42, s56
	s_addc_u32 s63, s43, s57
	s_add_u32 s60, s62, 0x100
	s_addc_u32 s61, s63, 0
	s_and_b64 s[58:59], s[54:55], exec
	s_cselect_b32 s59, s1, s61
	s_cselect_b32 s58, s19, s60
	s_add_u32 s56, s38, s56
	s_addc_u32 s57, s39, s57
	s_add_u32 s56, s56, 0x100
	s_addc_u32 s57, s57, 0
	s_and_b64 s[54:55], s[54:55], exec
	s_cselect_b32 s61, s17, s57
	s_cselect_b32 s60, s84, s56
	s_add_u32 s64, s62, 0x10080
	ds_read_b128 v[140:143], v145
	ds_read_b128 v[154:157], v145 offset:1024
	ds_read_b128 v[158:161], v145 offset:2048
	ds_read_b128 v[162:165], v145 offset:3072
	ds_read_b128 v[166:169], v146
	ds_read_b128 v[170:173], v146 offset:1024
	ds_read_b128 v[178:181], v146 offset:2048
	ds_read_b128 v[182:185], v146 offset:3072
	s_addc_u32 s65, s63, 0
	s_add_i32 s94, s82, s70
	s_add_i32 m0, s35, 0xc000
	s_add_i32 s95, s35, 0xe000
	s_add_i32 s91, s94, 0x2000
	s_add_u32 s62, s60, 0x10000
	s_addc_u32 s63, s61, 0
	s_add_i32 s93, s83, s70
	s_add_i32 s92, s93, 0x2000
	s_add_i32 s90, 0, 0x18000
	s_add_i32 s89, 0, 0x1c000
	s_add_u32 s56, s58, 0x10000
	s_addc_u32 s57, s59, 0
	s_add_i32 s88, s90, s70
	s_add_i32 s86, s88, 0x2000
	s_add_u32 s54, s60, 0x10080
	s_addc_u32 s55, s61, 0
	s_add_i32 s87, s89, s70
	s_add_i32 s85, s87, 0x2000
	v_lshl_add_u64 v[174:175], s[64:65], 0, v[128:129]
	ds_read_b128 v[186:189], v147
	ds_read_b128 v[190:193], v147 offset:1024
	ds_read_b128 v[194:197], v147 offset:2048
	ds_read_b128 v[198:201], v147 offset:3072
	ds_read_b128 v[202:205], v147 offset:4096
	ds_read_b128 v[206:209], v147 offset:5120
	ds_read_b128 v[210:213], v147 offset:6144
	ds_read_b128 v[214:217], v147 offset:7168
	global_load_lds_dwordx4 v[174:175], off
	v_lshl_add_u64 v[174:175], s[64:65], 0, v[132:133]
	s_mov_b32 m0, s95
	s_nop 0
	global_load_lds_dwordx4 v[174:175], off
	s_waitcnt vmcnt(8)
	s_waitcnt lgkmcnt(0)
	s_barrier
	s_waitcnt lgkmcnt(0)
	v_mfma_f32_16x16x32_bf16 v[124:127], v[140:143], v[186:189], v[124:127]
	v_mfma_f32_16x16x32_bf16 v[120:123], v[158:161], v[186:189], v[120:123]
	v_mfma_f32_16x16x32_bf16 v[108:111], v[140:143], v[194:197], v[108:111]
	v_mfma_f32_16x16x32_bf16 v[104:107], v[158:161], v[194:197], v[104:107]
	v_mfma_f32_16x16x32_bf16 v[92:95], v[140:143], v[202:205], v[92:95]
	v_mfma_f32_16x16x32_bf16 v[88:91], v[158:161], v[202:205], v[88:91]
	v_mfma_f32_16x16x32_bf16 v[76:79], v[140:143], v[210:213], v[76:79]
	v_mfma_f32_16x16x32_bf16 v[72:75], v[158:161], v[210:213], v[72:75]
	v_mfma_f32_16x16x32_bf16 v[124:127], v[154:157], v[190:193], v[124:127]
	v_mfma_f32_16x16x32_bf16 v[120:123], v[162:165], v[190:193], v[120:123]
	v_mfma_f32_16x16x32_bf16 v[108:111], v[154:157], v[198:201], v[108:111]
	v_mfma_f32_16x16x32_bf16 v[104:107], v[162:165], v[198:201], v[104:107]
	v_mfma_f32_16x16x32_bf16 v[92:95], v[154:157], v[206:209], v[92:95]
	v_mfma_f32_16x16x32_bf16 v[88:91], v[162:165], v[206:209], v[88:91]
	v_mfma_f32_16x16x32_bf16 v[76:79], v[154:157], v[214:217], v[76:79]
	v_mfma_f32_16x16x32_bf16 v[72:75], v[162:165], v[214:217], v[72:75]
	v_mfma_f32_16x16x32_bf16 v[116:119], v[166:169], v[186:189], v[116:119]
	v_mfma_f32_16x16x32_bf16 v[112:115], v[178:181], v[186:189], v[112:115]
	v_mfma_f32_16x16x32_bf16 v[100:103], v[166:169], v[194:197], v[100:103]
	v_mfma_f32_16x16x32_bf16 v[96:99], v[178:181], v[194:197], v[96:99]
	v_mfma_f32_16x16x32_bf16 v[84:87], v[166:169], v[202:205], v[84:87]
	v_mfma_f32_16x16x32_bf16 v[80:83], v[178:181], v[202:205], v[80:83]
	v_mfma_f32_16x16x32_bf16 v[68:71], v[166:169], v[210:213], v[68:71]
	v_mfma_f32_16x16x32_bf16 v[64:67], v[178:181], v[210:213], v[64:67]
	v_mfma_f32_16x16x32_bf16 v[116:119], v[170:173], v[190:193], v[116:119]
	v_mfma_f32_16x16x32_bf16 v[112:115], v[182:185], v[190:193], v[112:115]
	v_mfma_f32_16x16x32_bf16 v[100:103], v[170:173], v[198:201], v[100:103]
	v_mfma_f32_16x16x32_bf16 v[96:99], v[182:185], v[198:201], v[96:99]
	v_mfma_f32_16x16x32_bf16 v[84:87], v[170:173], v[206:209], v[84:87]
	v_mfma_f32_16x16x32_bf16 v[80:83], v[182:185], v[206:209], v[80:83]
	v_mfma_f32_16x16x32_bf16 v[68:71], v[170:173], v[214:217], v[68:71]
	v_mfma_f32_16x16x32_bf16 v[64:67], v[182:185], v[214:217], v[64:67]
	s_barrier
	s_mov_b32 m0, s94
	v_lshl_add_u64 v[174:175], s[60:61], 0, v[130:131]
	ds_read_b128 v[186:189], v147 offset:16384
	ds_read_b128 v[190:193], v147 offset:17408
	ds_read_b128 v[194:197], v147 offset:18432
	ds_read_b128 v[198:201], v147 offset:19456
	ds_read_b128 v[202:205], v147 offset:20480
	ds_read_b128 v[206:209], v147 offset:21504
	ds_read_b128 v[210:213], v147 offset:22528
	ds_read_b128 v[214:217], v147 offset:23552
	global_load_lds_dwordx4 v[174:175], off
	v_lshl_add_u64 v[218:219], s[60:61], 0, v[134:135]
	s_mov_b32 m0, s91
	v_lshl_add_u64 v[220:221], s[62:63], 0, v[130:131]
	global_load_lds_dwordx4 v[218:219], off
	s_mov_b32 m0, s93
	v_lshl_add_u64 v[222:223], s[58:59], 0, v[132:133]
	global_load_lds_dwordx4 v[220:221], off
	v_lshl_add_u64 v[220:221], s[62:63], 0, v[134:135]
	s_mov_b32 m0, s92
	s_nop 0
	global_load_lds_dwordx4 v[220:221], off
	v_lshl_add_u64 v[220:221], s[58:59], 0, v[128:129]
	s_mov_b32 m0, s35
	s_nop 0
	global_load_lds_dwordx4 v[220:221], off
	s_mov_b32 m0, s71
	s_nop 0
	global_load_lds_dwordx4 v[222:223], off
	s_waitcnt vmcnt(8)
	s_waitcnt lgkmcnt(0)
	s_barrier
; #define PG8_STAGE(bufoff, gbase, voff) do { _Pragma("unroll") for (int _i = 0; _i < 2; ++_i) \
;         __builtin_amdgcn_global_load_lds((const unsigned*)((const char*)(gbase) + (voff)[_i]), (LAS unsigned*)(lds + (bufoff) + ldsw + _i * 8192), 16, 0, 0); } while (0)
; #define PG8_LDA(dst, b, h) do { _Pragma("unroll") for (int m = 0; m < 4; ++m) _Pragma("unroll") for (int k = 0; k < 2; ++k) dst[m][k] = *(const LAS bf16x8*)(lds + PG8_SA(b, h) + aoff + m * 2048 + k * 1024); } while (0)
; #define PG8_LDB(dst, b, h) do { _Pragma("unroll") for (int n = 0; n < 2; ++n) _Pragma("unroll") for (int k = 0; k < 2; ++k) dst[n][k] = *(const LAS bf16x8*)(lds + PG8_SB(b, h) + boff + n * 2048 + k * 1024); } while (0)
; #define PG8_MMA(ai, bj, At, Bt) do { __builtin_amdgcn_s_setprio(1); _Pragma("unroll") for (int m = 0; m < 4; ++m) _Pragma("unroll") for (int n = 0; n < 2; ++n) _Pragma("unroll") for (int k = 0; k < 2; ++k) \
;         acc[ai][bj][m][n] = __builtin_amdgcn_mfma_f32_16x16x32_bf16(Bt[n][k], At[m][k], acc[ai][bj][m][n], 0, 0, 0); __builtin_amdgcn_s_setprio(0); } while (0)
; #define PG8_WAIT_V(n) asm volatile("s_waitcnt vmcnt(" #n ")" ::: "memory")
; #define PG8_WAIT_L(n) asm volatile("s_waitcnt lgkmcnt(" #n ")" ::: "memory")
; #define PG8_BAR __builtin_amdgcn_s_barrier()
; #define PG8_SCHED __builtin_amdgcn_sched_barrier(0)
; template <class Epi>
; __device__ __forceinline__ void gemm_phase(LAS unsigned char* lds, const Gemm g, const StaticOrder& S, const Epi& E) {
;     ...
;             PG8_WAIT_V(8); PG8_WAIT_L(0); PG8_BAR; PG8_MMA(1, 0, At, B0); PG8_MMA(1, 1, At, B1); PG8_BAR; PG8_SCHED;
;             PG8_LDB(B0, 1, 0); PG8_LDB(B1, 1, 1); PG8_SCHED; PG8_LDA(At, 1, 0); PG8_STAGE(PG8_SA(0, 1), a2 + hstepA, voffA);
;             PG8_WAIT_V(8); PG8_WAIT_L(0); PG8_BAR; PG8_MMA(0, 0, At, B0); PG8_MMA(0, 1, At, B1); PG8_BAR; PG8_SCHED;
	s_waitcnt lgkmcnt(0)
	v_mfma_f32_16x16x32_bf16 v[60:63], v[140:143], v[186:189], v[60:63]
	v_mfma_f32_16x16x32_bf16 v[56:59], v[158:161], v[186:189], v[56:59]
	v_mfma_f32_16x16x32_bf16 v[44:47], v[140:143], v[194:197], v[44:47]
	v_mfma_f32_16x16x32_bf16 v[40:43], v[158:161], v[194:197], v[40:43]
	v_mfma_f32_16x16x32_bf16 v[28:31], v[140:143], v[202:205], v[28:31]
	v_mfma_f32_16x16x32_bf16 v[24:27], v[158:161], v[202:205], v[24:27]
	v_mfma_f32_16x16x32_bf16 v[12:15], v[140:143], v[210:213], v[12:15]
	v_mfma_f32_16x16x32_bf16 v[8:11], v[158:161], v[210:213], v[8:11]
	v_mfma_f32_16x16x32_bf16 v[60:63], v[154:157], v[190:193], v[60:63]
	v_mfma_f32_16x16x32_bf16 v[56:59], v[162:165], v[190:193], v[56:59]
	v_mfma_f32_16x16x32_bf16 v[44:47], v[154:157], v[198:201], v[44:47]
	v_mfma_f32_16x16x32_bf16 v[40:43], v[162:165], v[198:201], v[40:43]
	v_mfma_f32_16x16x32_bf16 v[28:31], v[154:157], v[206:209], v[28:31]
	v_mfma_f32_16x16x32_bf16 v[24:27], v[162:165], v[206:209], v[24:27]
	v_mfma_f32_16x16x32_bf16 v[12:15], v[154:157], v[214:217], v[12:15]
	v_mfma_f32_16x16x32_bf16 v[8:11], v[162:165], v[214:217], v[8:11]
	v_mfma_f32_16x16x32_bf16 v[52:55], v[166:169], v[186:189], v[52:55]
	v_mfma_f32_16x16x32_bf16 v[48:51], v[178:181], v[186:189], v[48:51]
	v_mfma_f32_16x16x32_bf16 v[36:39], v[166:169], v[194:197], v[36:39]
	v_mfma_f32_16x16x32_bf16 v[32:35], v[178:181], v[194:197], v[32:35]
	v_mfma_f32_16x16x32_bf16 v[20:23], v[166:169], v[202:205], v[20:23]
	v_mfma_f32_16x16x32_bf16 v[16:19], v[178:181], v[202:205], v[16:19]
	v_mfma_f32_16x16x32_bf16 v[4:7], v[166:169], v[210:213], v[4:7]
	v_mfma_f32_16x16x32_bf16 v[0:3], v[178:181], v[210:213], v[0:3]
	v_mfma_f32_16x16x32_bf16 v[52:55], v[170:173], v[190:193], v[52:55]
	v_mfma_f32_16x16x32_bf16 v[48:51], v[182:185], v[190:193], v[48:51]
	v_mfma_f32_16x16x32_bf16 v[36:39], v[170:173], v[198:201], v[36:39]
	v_mfma_f32_16x16x32_bf16 v[32:35], v[182:185], v[198:201], v[32:35]
	v_mfma_f32_16x16x32_bf16 v[20:23], v[170:173], v[206:209], v[20:23]
	v_mfma_f32_16x16x32_bf16 v[16:19], v[182:185], v[206:209], v[16:19]
	v_mfma_f32_16x16x32_bf16 v[4:7], v[170:173], v[214:217], v[4:7]
	v_mfma_f32_16x16x32_bf16 v[0:3], v[182:185], v[214:217], v[0:3]
	s_barrier
	v_add_u32_e32 v149, s90, v144
	ds_read_b128 v[140:143], v149
	ds_read_b128 v[154:157], v149 offset:1024
	ds_read_b128 v[158:161], v149 offset:2048
	ds_read_b128 v[162:165], v149 offset:3072
	v_add_u32_e32 v149, s89, v144
	ds_read_b128 v[166:169], v149
	ds_read_b128 v[170:173], v149 offset:1024
	ds_read_b128 v[178:181], v149 offset:2048
	ds_read_b128 v[182:185], v149 offset:3072
	s_mov_b32 m0, s72
	v_lshl_add_u64 v[224:225], s[56:57], 0, v[128:129]
	ds_read_b128 v[186:189], v147 offset:32768
	ds_read_b128 v[190:193], v147 offset:33792
	ds_read_b128 v[194:197], v147 offset:34816
	ds_read_b128 v[198:201], v147 offset:35840
	ds_read_b128 v[202:205], v147 offset:36864
	ds_read_b128 v[206:209], v147 offset:37888
	ds_read_b128 v[210:213], v147 offset:38912
	ds_read_b128 v[214:217], v147 offset:39936
	global_load_lds_dwordx4 v[224:225], off
	v_lshl_add_u64 v[224:225], s[56:57], 0, v[132:133]
	s_mov_b32 m0, s73
	s_nop 0
	global_load_lds_dwordx4 v[224:225], off
	s_waitcnt vmcnt(8)
	s_waitcnt lgkmcnt(0)
	s_barrier
	s_waitcnt lgkmcnt(0)
	v_mfma_f32_16x16x32_bf16 v[124:127], v[140:143], v[186:189], v[124:127]
	v_mfma_f32_16x16x32_bf16 v[120:123], v[158:161], v[186:189], v[120:123]
	v_mfma_f32_16x16x32_bf16 v[108:111], v[140:143], v[194:197], v[108:111]
	v_mfma_f32_16x16x32_bf16 v[104:107], v[158:161], v[194:197], v[104:107]
	v_mfma_f32_16x16x32_bf16 v[92:95], v[140:143], v[202:205], v[92:95]
	v_mfma_f32_16x16x32_bf16 v[88:91], v[158:161], v[202:205], v[88:91]
	v_mfma_f32_16x16x32_bf16 v[76:79], v[140:143], v[210:213], v[76:79]
	v_mfma_f32_16x16x32_bf16 v[72:75], v[158:161], v[210:213], v[72:75]
	v_mfma_f32_16x16x32_bf16 v[124:127], v[154:157], v[190:193], v[124:127]
	v_mfma_f32_16x16x32_bf16 v[120:123], v[162:165], v[190:193], v[120:123]
	v_mfma_f32_16x16x32_bf16 v[108:111], v[154:157], v[198:201], v[108:111]
	v_mfma_f32_16x16x32_bf16 v[104:107], v[162:165], v[198:201], v[104:107]
	v_mfma_f32_16x16x32_bf16 v[92:95], v[154:157], v[206:209], v[92:95]
	v_mfma_f32_16x16x32_bf16 v[88:91], v[162:165], v[206:209], v[88:91]
	v_mfma_f32_16x16x32_bf16 v[76:79], v[154:157], v[214:217], v[76:79]
	v_mfma_f32_16x16x32_bf16 v[72:75], v[162:165], v[214:217], v[72:75]
	v_mfma_f32_16x16x32_bf16 v[116:119], v[166:169], v[186:189], v[116:119]
	v_mfma_f32_16x16x32_bf16 v[112:115], v[178:181], v[186:189], v[112:115]
	v_mfma_f32_16x16x32_bf16 v[100:103], v[166:169], v[194:197], v[100:103]
	v_mfma_f32_16x16x32_bf16 v[96:99], v[178:181], v[194:197], v[96:99]
	v_mfma_f32_16x16x32_bf16 v[84:87], v[166:169], v[202:205], v[84:87]
	v_mfma_f32_16x16x32_bf16 v[80:83], v[178:181], v[202:205], v[80:83]
	v_mfma_f32_16x16x32_bf16 v[68:71], v[166:169], v[210:213], v[68:71]
	v_mfma_f32_16x16x32_bf16 v[64:67], v[178:181], v[210:213], v[64:67]
	v_mfma_f32_16x16x32_bf16 v[116:119], v[170:173], v[190:193], v[116:119]
	v_mfma_f32_16x16x32_bf16 v[112:115], v[182:185], v[190:193], v[112:115]
	v_mfma_f32_16x16x32_bf16 v[100:103], v[170:173], v[198:201], v[100:103]
	v_mfma_f32_16x16x32_bf16 v[96:99], v[182:185], v[198:201], v[96:99]
	v_mfma_f32_16x16x32_bf16 v[84:87], v[170:173], v[206:209], v[84:87]
	v_mfma_f32_16x16x32_bf16 v[80:83], v[182:185], v[206:209], v[80:83]
	v_mfma_f32_16x16x32_bf16 v[68:71], v[170:173], v[214:217], v[68:71]
	v_mfma_f32_16x16x32_bf16 v[64:67], v[182:185], v[214:217], v[64:67]
	s_barrier
; #define PG8_STAGE(bufoff, gbase, voff) do { _Pragma("unroll") for (int _i = 0; _i < 2; ++_i) \
;         __builtin_amdgcn_global_load_lds((const unsigned*)((const char*)(gbase) + (voff)[_i]), (LAS unsigned*)(lds + (bufoff) + ldsw + _i * 8192), 16, 0, 0); } while (0)
; #define PG8_LDA(dst, b, h) do { _Pragma("unroll") for (int m = 0; m < 4; ++m) _Pragma("unroll") for (int k = 0; k < 2; ++k) dst[m][k] = *(const LAS bf16x8*)(lds + PG8_SA(b, h) + aoff + m * 2048 + k * 1024); } while (0)
; #define PG8_MMA(ai, bj, At, Bt) do { __builtin_amdgcn_s_setprio(1); _Pragma("unroll") for (int m = 0; m < 4; ++m) _Pragma("unroll") for (int n = 0; n < 2; ++n) _Pragma("unroll") for (int k = 0; k < 2; ++k) \
;         acc[ai][bj][m][n] = __builtin_amdgcn_mfma_f32_16x16x32_bf16(Bt[n][k], At[m][k], acc[ai][bj][m][n], 0, 0, 0); __builtin_amdgcn_s_setprio(0); } while (0)
; #define PG8_WAIT_V(n) asm volatile("s_waitcnt vmcnt(" #n ")" ::: "memory")
; #define PG8_WAIT_L(n) asm volatile("s_waitcnt lgkmcnt(" #n ")" ::: "memory")
; #define PG8_BAR __builtin_amdgcn_s_barrier()
; #define PG8_SCHED __builtin_amdgcn_sched_barrier(0)
; template <class Epi>
; __device__ __forceinline__ void gemm_phase(LAS unsigned char* lds, const Gemm g, const StaticOrder& S, const Epi& E) {
;     ...
;             PG8_LDA(At, 1, 1); PG8_STAGE(PG8_SB(1, 0), b3, voffB); PG8_STAGE(PG8_SB(1, 1), b3 + hstepB, voffB); PG8_STAGE(PG8_SA(1, 0), a3, voffA);
;             PG8_WAIT_V(8); PG8_WAIT_L(0); PG8_BAR; PG8_MMA(1, 0, At, B0); PG8_MMA(1, 1, At, B1); PG8_BAR; PG8_SCHED;
	s_mov_b32 m0, s88
	v_lshl_add_u64 v[174:175], v[174:175], 0, s[10:11]
	ds_read_b128 v[186:189], v147 offset:49152
	ds_read_b128 v[190:193], v147 offset:50176
	ds_read_b128 v[194:197], v147 offset:51200
	ds_read_b128 v[198:201], v147 offset:52224
	ds_read_b128 v[202:205], v147 offset:53248
	ds_read_b128 v[206:209], v147 offset:54272
	ds_read_b128 v[210:213], v147 offset:55296
	ds_read_b128 v[214:217], v147 offset:56320
	global_load_lds_dwordx4 v[174:175], off
	v_lshl_add_u64 v[174:175], v[218:219], 0, s[10:11]
	s_mov_b32 m0, s86
	s_nop 0
	global_load_lds_dwordx4 v[174:175], off
	v_lshl_add_u64 v[174:175], s[54:55], 0, v[130:131]
	s_mov_b32 m0, s87
	s_nop 0
	global_load_lds_dwordx4 v[174:175], off
	v_lshl_add_u64 v[174:175], s[54:55], 0, v[134:135]
	s_mov_b32 m0, s85
	s_nop 0
	global_load_lds_dwordx4 v[174:175], off
	v_lshl_add_u64 v[174:175], v[220:221], 0, s[10:11]
	s_mov_b32 m0, s77
	s_nop 0
	global_load_lds_dwordx4 v[174:175], off
	v_lshl_add_u64 v[174:175], v[222:223], 0, s[10:11]
	s_mov_b32 m0, s78
	s_nop 0
	global_load_lds_dwordx4 v[174:175], off
	s_waitcnt vmcnt(8)
	s_waitcnt lgkmcnt(0)
	s_barrier
	s_waitcnt lgkmcnt(0)
	v_mfma_f32_16x16x32_bf16 v[60:63], v[140:143], v[186:189], v[60:63]
	v_mfma_f32_16x16x32_bf16 v[56:59], v[158:161], v[186:189], v[56:59]
	v_mfma_f32_16x16x32_bf16 v[44:47], v[140:143], v[194:197], v[44:47]
	v_mfma_f32_16x16x32_bf16 v[40:43], v[158:161], v[194:197], v[40:43]
	v_mfma_f32_16x16x32_bf16 v[28:31], v[140:143], v[202:205], v[28:31]
	v_mfma_f32_16x16x32_bf16 v[24:27], v[158:161], v[202:205], v[24:27]
	v_mfma_f32_16x16x32_bf16 v[12:15], v[140:143], v[210:213], v[12:15]
	v_mfma_f32_16x16x32_bf16 v[8:11], v[158:161], v[210:213], v[8:11]
	v_mfma_f32_16x16x32_bf16 v[60:63], v[154:157], v[190:193], v[60:63]
	v_mfma_f32_16x16x32_bf16 v[56:59], v[162:165], v[190:193], v[56:59]
	v_mfma_f32_16x16x32_bf16 v[44:47], v[154:157], v[198:201], v[44:47]
	v_mfma_f32_16x16x32_bf16 v[40:43], v[162:165], v[198:201], v[40:43]
	v_mfma_f32_16x16x32_bf16 v[28:31], v[154:157], v[206:209], v[28:31]
	v_mfma_f32_16x16x32_bf16 v[24:27], v[162:165], v[206:209], v[24:27]
	v_mfma_f32_16x16x32_bf16 v[12:15], v[154:157], v[214:217], v[12:15]
	v_mfma_f32_16x16x32_bf16 v[8:11], v[162:165], v[214:217], v[8:11]
	v_mfma_f32_16x16x32_bf16 v[52:55], v[166:169], v[186:189], v[52:55]
	v_mfma_f32_16x16x32_bf16 v[48:51], v[178:181], v[186:189], v[48:51]
	v_mfma_f32_16x16x32_bf16 v[36:39], v[166:169], v[194:197], v[36:39]
	v_mfma_f32_16x16x32_bf16 v[32:35], v[178:181], v[194:197], v[32:35]
	v_mfma_f32_16x16x32_bf16 v[20:23], v[166:169], v[202:205], v[20:23]
	v_mfma_f32_16x16x32_bf16 v[16:19], v[178:181], v[202:205], v[16:19]
	v_mfma_f32_16x16x32_bf16 v[4:7], v[166:169], v[210:213], v[4:7]
	v_mfma_f32_16x16x32_bf16 v[0:3], v[178:181], v[210:213], v[0:3]
	v_mfma_f32_16x16x32_bf16 v[52:55], v[170:173], v[190:193], v[52:55]
	v_mfma_f32_16x16x32_bf16 v[48:51], v[182:185], v[190:193], v[48:51]
	v_mfma_f32_16x16x32_bf16 v[36:39], v[170:173], v[198:201], v[36:39]
	v_mfma_f32_16x16x32_bf16 v[32:35], v[182:185], v[198:201], v[32:35]
	v_mfma_f32_16x16x32_bf16 v[20:23], v[170:173], v[206:209], v[20:23]
	v_mfma_f32_16x16x32_bf16 v[16:19], v[182:185], v[206:209], v[16:19]
	v_mfma_f32_16x16x32_bf16 v[4:7], v[170:173], v[214:217], v[4:7]
	v_mfma_f32_16x16x32_bf16 v[0:3], v[182:185], v[214:217], v[0:3]
	s_barrier
	s_andn2_b64 vcc, exec, s[52:53]
	s_mov_b64 s[54:55], -1
	s_mov_b64 s[52:53], 0
	s_mov_b64 s[56:57], 0x100
	s_cbranch_vccz .LBB0_1469
	s_and_b64 vcc, exec, s[12:13]
	s_cbranch_vccz .LBB0_1472
	s_barrier

; #define PG8_STAGE(bufoff, gbase, voff) do { _Pragma("unroll") for (int _i = 0; _i < 2; ++_i) \
;         __builtin_amdgcn_global_load_lds((const unsigned*)((const char*)(gbase) + (voff)[_i]), (LAS unsigned*)(lds + (bufoff) + ldsw + _i * 8192), 16, 0, 0); } while (0)
; #define PG8_LDA(dst, b, h) do { _Pragma("unroll") for (int m = 0; m < 4; ++m) _Pragma("unroll") for (int k = 0; k < 2; ++k) dst[m][k] = *(const LAS bf16x8*)(lds + PG8_SA(b, h) + aoff + m * 2048 + k * 1024); } while (0)
; #define PG8_LDB(dst, b, h) do { _Pragma("unroll") for (int n = 0; n < 2; ++n) _Pragma("unroll") for (int k = 0; k < 2; ++k) dst[n][k] = *(const LAS bf16x8*)(lds + PG8_SB(b, h) + boff + n * 2048 + k * 1024); } while (0)
; #define PG8_MMA(ai, bj, At, Bt) do { __builtin_amdgcn_s_setprio(1); _Pragma("unroll") for (int m = 0; m < 4; ++m) _Pragma("unroll") for (int n = 0; n < 2; ++n) _Pragma("unroll") for (int k = 0; k < 2; ++k) \
;         acc[ai][bj][m][n] = __builtin_amdgcn_mfma_f32_16x16x32_bf16(Bt[n][k], At[m][k], acc[ai][bj][m][n], 0, 0, 0); __builtin_amdgcn_s_setprio(0); } while (0)
; #define PG8_WAIT_V(n) asm volatile("s_waitcnt vmcnt(" #n ")" ::: "memory")
; #define PG8_WAIT_L(n) asm volatile("s_waitcnt lgkmcnt(" #n ")" ::: "memory")
; #define PG8_BAR __builtin_amdgcn_s_barrier()
; #define PG8_SCHED __builtin_amdgcn_sched_barrier(0)
; template <class Epi>
; __device__ __forceinline__ void gemm_phase(LAS unsigned char* lds, const Gemm g, const StaticOrder& S, const Epi& E) {
;     ...
;             const bool last = (t == nt - 2);
;             const char* a1 = cA + (size_t)(t + 1) * kstep;
;             const char* a2 = last ? nA : cA + (size_t)(t + 2) * kstep; const char* b2 = last ? nB : cB + (size_t)(t + 2) * kstep;
;             const char* a3 = a2 + kstep; const char* b3 = b2 + kstep;
;             PG8_LDB(B0, 0, 0); PG8_LDB(B1, 0, 1); PG8_SCHED; PG8_LDA(At, 0, 0); PG8_STAGE(PG8_SA(1, 1), a1 + hstepA, voffA);
;             PG8_WAIT_V(8); PG8_WAIT_L(0); PG8_BAR; PG8_MMA(0, 0, At, B0); PG8_MMA(0, 1, At, B1); PG8_BAR; PG8_SCHED;
;             PG8_LDA(At, 0, 1); PG8_STAGE(PG8_SB(0, 0), b2, voffB); PG8_STAGE(PG8_SB(0, 1), b2 + hstepB, voffB); PG8_STAGE(PG8_SA(0, 0), a2, voffA);
;             PG8_WAIT_V(8); PG8_WAIT_L(0); PG8_BAR; PG8_MMA(1, 0, At, B0); PG8_MMA(1, 1, At, B1); PG8_BAR; PG8_SCHED;
.LBB0_1648:
	s_add_u32 s0, s0, 0xb0080
	s_addc_u32 s1, s1, 0
	s_add_u32 s61, s20, 0x100
	s_addc_u32 s62, s21, 0
	s_mov_b32 s63, -2
	s_waitcnt lgkmcnt(0)
	ds_read_b128 v[128:131], v182
	ds_read_b128 v[132:135], v182 offset:1024
	ds_read_b128 v[136:139], v182 offset:2048
	ds_read_b128 v[140:143], v182 offset:3072
	ds_read_b128 v[160:163], v183
	ds_read_b128 v[164:167], v183 offset:1024
	ds_read_b128 v[168:171], v183 offset:2048
	ds_read_b128 v[172:175], v183 offset:3072
	s_add_u32 s20, s0, 0xfff50080
	s_addc_u32 s21, s1, -1
	s_cmp_eq_u32 s63, 40
	s_cselect_b32 s23, s7, s21
	s_cselect_b32 s22, s6, s20
	s_cselect_b32 s21, s19, s62
	s_cselect_b32 s20, s18, s61
	v_lshl_add_u64 v[178:179], s[0:1], 0, v[152:153]
	s_add_i32 m0, s33, 0xc000
	ds_read_b128 v[186:189], v184
	ds_read_b128 v[190:193], v184 offset:1024
	ds_read_b128 v[194:197], v184 offset:2048
	ds_read_b128 v[198:201], v184 offset:3072
	ds_read_b128 v[202:205], v184 offset:4096
	ds_read_b128 v[206:209], v184 offset:5120
	ds_read_b128 v[210:213], v184 offset:6144
	ds_read_b128 v[214:217], v184 offset:7168
	global_load_lds_dwordx4 v[178:179], off
	v_lshl_add_u64 v[178:179], s[0:1], 0, v[154:155]
	s_add_i32 m0, s33, 0xe000
	s_nop 0
	global_load_lds_dwordx4 v[178:179], off
	s_waitcnt vmcnt(8)
	s_waitcnt lgkmcnt(0)
	s_barrier
	s_waitcnt lgkmcnt(0)
	v_mfma_f32_16x16x32_bf16 v[124:127], v[128:131], v[186:189], 0
	v_mfma_f32_16x16x32_bf16 v[120:123], v[136:139], v[186:189], 0
	v_mfma_f32_16x16x32_bf16 v[108:111], v[128:131], v[194:197], 0
	v_mfma_f32_16x16x32_bf16 v[104:107], v[136:139], v[194:197], 0
	v_mfma_f32_16x16x32_bf16 v[92:95], v[128:131], v[202:205], 0
	v_mfma_f32_16x16x32_bf16 v[88:91], v[136:139], v[202:205], 0
	v_mfma_f32_16x16x32_bf16 v[76:79], v[128:131], v[210:213], 0
	v_mfma_f32_16x16x32_bf16 v[72:75], v[136:139], v[210:213], 0
	v_mfma_f32_16x16x32_bf16 v[124:127], v[132:135], v[190:193], v[124:127]
	v_mfma_f32_16x16x32_bf16 v[120:123], v[140:143], v[190:193], v[120:123]
	v_mfma_f32_16x16x32_bf16 v[108:111], v[132:135], v[198:201], v[108:111]
	v_mfma_f32_16x16x32_bf16 v[104:107], v[140:143], v[198:201], v[104:107]
	v_mfma_f32_16x16x32_bf16 v[92:95], v[132:135], v[206:209], v[92:95]
	v_mfma_f32_16x16x32_bf16 v[88:91], v[140:143], v[206:209], v[88:91]
	v_mfma_f32_16x16x32_bf16 v[76:79], v[132:135], v[214:217], v[76:79]
	v_mfma_f32_16x16x32_bf16 v[72:75], v[140:143], v[214:217], v[72:75]
	v_mfma_f32_16x16x32_bf16 v[116:119], v[160:163], v[186:189], 0
	v_mfma_f32_16x16x32_bf16 v[112:115], v[168:171], v[186:189], 0
	v_mfma_f32_16x16x32_bf16 v[100:103], v[160:163], v[194:197], 0
	v_mfma_f32_16x16x32_bf16 v[96:99], v[168:171], v[194:197], 0
	v_mfma_f32_16x16x32_bf16 v[84:87], v[160:163], v[202:205], 0
	v_mfma_f32_16x16x32_bf16 v[80:83], v[168:171], v[202:205], 0
	v_mfma_f32_16x16x32_bf16 v[68:71], v[160:163], v[210:213], 0
	v_mfma_f32_16x16x32_bf16 v[64:67], v[168:171], v[210:213], 0
	v_mfma_f32_16x16x32_bf16 v[116:119], v[164:167], v[190:193], v[116:119]
	v_mfma_f32_16x16x32_bf16 v[112:115], v[172:175], v[190:193], v[112:115]
	v_mfma_f32_16x16x32_bf16 v[100:103], v[164:167], v[198:201], v[100:103]
	v_mfma_f32_16x16x32_bf16 v[96:99], v[172:175], v[198:201], v[96:99]
	v_mfma_f32_16x16x32_bf16 v[84:87], v[164:167], v[206:209], v[84:87]
	v_mfma_f32_16x16x32_bf16 v[80:83], v[172:175], v[206:209], v[80:83]
	v_mfma_f32_16x16x32_bf16 v[68:71], v[164:167], v[214:217], v[68:71]
	v_mfma_f32_16x16x32_bf16 v[64:67], v[172:175], v[214:217], v[64:67]
	s_barrier
	s_add_i32 s64, s55, s29
	v_lshl_add_u64 v[178:179], s[20:21], 0, v[146:147]
	s_mov_b32 m0, s64
	ds_read_b128 v[186:189], v184 offset:16384
	ds_read_b128 v[190:193], v184 offset:17408
	ds_read_b128 v[194:197], v184 offset:18432
	ds_read_b128 v[198:201], v184 offset:19456
	ds_read_b128 v[202:205], v184 offset:20480
	ds_read_b128 v[206:209], v184 offset:21504
	ds_read_b128 v[210:213], v184 offset:22528
	ds_read_b128 v[214:217], v184 offset:23552
	global_load_lds_dwordx4 v[178:179], off
	s_add_i32 m0, s64, 0x2000
	s_add_u32 s64, s20, 0xb0000
	v_lshl_add_u64 v[218:219], s[20:21], 0, v[150:151]
	s_addc_u32 s65, s21, 0
	s_add_i32 s66, s56, s29
	global_load_lds_dwordx4 v[218:219], off
	v_lshl_add_u64 v[220:221], s[64:65], 0, v[146:147]
	s_mov_b32 m0, s66
	v_lshl_add_u64 v[222:223], s[22:23], 0, v[148:149]
	global_load_lds_dwordx4 v[220:221], off
	v_lshl_add_u64 v[220:221], s[64:65], 0, v[150:151]
	s_add_i32 m0, s66, 0x2000
	s_nop 0
	global_load_lds_dwordx4 v[220:221], off
	v_lshl_add_u64 v[220:221], s[22:23], 0, v[144:145]
	s_mov_b32 m0, s33
	s_nop 0
	global_load_lds_dwordx4 v[220:221], off
	s_mov_b32 m0, s34
	s_nop 0
	global_load_lds_dwordx4 v[222:223], off
	s_waitcnt vmcnt(8)
	s_waitcnt lgkmcnt(0)
	s_barrier
; #define PG8_STAGE(bufoff, gbase, voff) do { _Pragma("unroll") for (int _i = 0; _i < 2; ++_i) \
;         __builtin_amdgcn_global_load_lds((const unsigned*)((const char*)(gbase) + (voff)[_i]), (LAS unsigned*)(lds + (bufoff) + ldsw + _i * 8192), 16, 0, 0); } while (0)
; #define PG8_LDA(dst, b, h) do { _Pragma("unroll") for (int m = 0; m < 4; ++m) _Pragma("unroll") for (int k = 0; k < 2; ++k) dst[m][k] = *(const LAS bf16x8*)(lds + PG8_SA(b, h) + aoff + m * 2048 + k * 1024); } while (0)
; #define PG8_LDB(dst, b, h) do { _Pragma("unroll") for (int n = 0; n < 2; ++n) _Pragma("unroll") for (int k = 0; k < 2; ++k) dst[n][k] = *(const LAS bf16x8*)(lds + PG8_SB(b, h) + boff + n * 2048 + k * 1024); } while (0)
; #define PG8_MMA(ai, bj, At, Bt) do { __builtin_amdgcn_s_setprio(1); _Pragma("unroll") for (int m = 0; m < 4; ++m) _Pragma("unroll") for (int n = 0; n < 2; ++n) _Pragma("unroll") for (int k = 0; k < 2; ++k) \
;         acc[ai][bj][m][n] = __builtin_amdgcn_mfma_f32_16x16x32_bf16(Bt[n][k], At[m][k], acc[ai][bj][m][n], 0, 0, 0); __builtin_amdgcn_s_setprio(0); } while (0)
; #define PG8_WAIT_V(n) asm volatile("s_waitcnt vmcnt(" #n ")" ::: "memory")
; #define PG8_WAIT_L(n) asm volatile("s_waitcnt lgkmcnt(" #n ")" ::: "memory")
; #define PG8_BAR __builtin_amdgcn_s_barrier()
; #define PG8_SCHED __builtin_amdgcn_sched_barrier(0)
; template <class Epi>
; __device__ __forceinline__ void gemm_phase(LAS unsigned char* lds, const Gemm g, const StaticOrder& S, const Epi& E) {
;     ...
;             PG8_WAIT_V(8); PG8_WAIT_L(0); PG8_BAR; PG8_MMA(1, 0, At, B0); PG8_MMA(1, 1, At, B1); PG8_BAR; PG8_SCHED;
;             PG8_LDB(B0, 1, 0); PG8_LDB(B1, 1, 1); PG8_SCHED; PG8_LDA(At, 1, 0); PG8_STAGE(PG8_SA(0, 1), a2 + hstepA, voffA);
;             PG8_WAIT_V(8); PG8_WAIT_L(0); PG8_BAR; PG8_MMA(0, 0, At, B0); PG8_MMA(0, 1, At, B1); PG8_BAR; PG8_SCHED;
	s_waitcnt lgkmcnt(0)
	v_mfma_f32_16x16x32_bf16 v[60:63], v[128:131], v[186:189], 0
	v_mfma_f32_16x16x32_bf16 v[56:59], v[136:139], v[186:189], 0
	v_mfma_f32_16x16x32_bf16 v[44:47], v[128:131], v[194:197], 0
	v_mfma_f32_16x16x32_bf16 v[40:43], v[136:139], v[194:197], 0
	v_mfma_f32_16x16x32_bf16 v[28:31], v[128:131], v[202:205], 0
	v_mfma_f32_16x16x32_bf16 v[24:27], v[136:139], v[202:205], 0
	v_mfma_f32_16x16x32_bf16 v[12:15], v[128:131], v[210:213], 0
	v_mfma_f32_16x16x32_bf16 v[8:11], v[136:139], v[210:213], 0
	v_mfma_f32_16x16x32_bf16 v[60:63], v[132:135], v[190:193], v[60:63]
	v_mfma_f32_16x16x32_bf16 v[56:59], v[140:143], v[190:193], v[56:59]
	v_mfma_f32_16x16x32_bf16 v[44:47], v[132:135], v[198:201], v[44:47]
	v_mfma_f32_16x16x32_bf16 v[40:43], v[140:143], v[198:201], v[40:43]
	v_mfma_f32_16x16x32_bf16 v[28:31], v[132:135], v[206:209], v[28:31]
	v_mfma_f32_16x16x32_bf16 v[24:27], v[140:143], v[206:209], v[24:27]
	v_mfma_f32_16x16x32_bf16 v[12:15], v[132:135], v[214:217], v[12:15]
	v_mfma_f32_16x16x32_bf16 v[8:11], v[140:143], v[214:217], v[8:11]
	v_mfma_f32_16x16x32_bf16 v[52:55], v[160:163], v[186:189], 0
	v_mfma_f32_16x16x32_bf16 v[48:51], v[168:171], v[186:189], 0
	v_mfma_f32_16x16x32_bf16 v[36:39], v[160:163], v[194:197], 0
	v_mfma_f32_16x16x32_bf16 v[32:35], v[168:171], v[194:197], 0
	v_mfma_f32_16x16x32_bf16 v[20:23], v[160:163], v[202:205], 0
	v_mfma_f32_16x16x32_bf16 v[16:19], v[168:171], v[202:205], 0
	v_mfma_f32_16x16x32_bf16 v[4:7], v[160:163], v[210:213], 0
	v_mfma_f32_16x16x32_bf16 v[0:3], v[168:171], v[210:213], 0
	v_mfma_f32_16x16x32_bf16 v[52:55], v[164:167], v[190:193], v[52:55]
	v_mfma_f32_16x16x32_bf16 v[48:51], v[172:175], v[190:193], v[48:51]
	v_mfma_f32_16x16x32_bf16 v[36:39], v[164:167], v[198:201], v[36:39]
	v_mfma_f32_16x16x32_bf16 v[32:35], v[172:175], v[198:201], v[32:35]
	v_mfma_f32_16x16x32_bf16 v[20:23], v[164:167], v[206:209], v[20:23]
	v_mfma_f32_16x16x32_bf16 v[16:19], v[172:175], v[206:209], v[16:19]
	v_mfma_f32_16x16x32_bf16 v[4:7], v[164:167], v[214:217], v[4:7]
	v_mfma_f32_16x16x32_bf16 v[0:3], v[172:175], v[214:217], v[0:3]
	s_barrier
	s_add_i32 s64, 0, 0x18000
	s_add_i32 s65, 0, 0x1c000
	v_add_u32_e32 v140, s64, v181
	v_add_u32_e32 v172, s65, v181
	ds_read_b128 v[128:131], v140
	ds_read_b128 v[132:135], v140 offset:1024
	ds_read_b128 v[136:139], v140 offset:2048
	ds_read_b128 v[140:143], v140 offset:3072
	ds_read_b128 v[160:163], v172
	ds_read_b128 v[164:167], v172 offset:1024
	ds_read_b128 v[168:171], v172 offset:2048
	ds_read_b128 v[172:175], v172 offset:3072
	s_add_u32 s22, s22, 0xb0000
	s_addc_u32 s23, s23, 0
	s_mov_b32 m0, s35
	v_lshl_add_u64 v[224:225], s[22:23], 0, v[144:145]
	ds_read_b128 v[186:189], v184 offset:32768
	ds_read_b128 v[190:193], v184 offset:33792
	ds_read_b128 v[194:197], v184 offset:34816
	ds_read_b128 v[198:201], v184 offset:35840
	ds_read_b128 v[202:205], v184 offset:36864
	ds_read_b128 v[206:209], v184 offset:37888
	ds_read_b128 v[210:213], v184 offset:38912
	ds_read_b128 v[214:217], v184 offset:39936
	global_load_lds_dwordx4 v[224:225], off
	v_lshl_add_u64 v[224:225], s[22:23], 0, v[148:149]
	s_mov_b32 m0, s36
	s_nop 0
	global_load_lds_dwordx4 v[224:225], off
	s_waitcnt vmcnt(8)
	s_waitcnt lgkmcnt(0)
	s_barrier
	s_waitcnt lgkmcnt(0)
	v_mfma_f32_16x16x32_bf16 v[124:127], v[128:131], v[186:189], v[124:127]
	v_mfma_f32_16x16x32_bf16 v[120:123], v[136:139], v[186:189], v[120:123]
	v_mfma_f32_16x16x32_bf16 v[108:111], v[128:131], v[194:197], v[108:111]
	v_mfma_f32_16x16x32_bf16 v[104:107], v[136:139], v[194:197], v[104:107]
	v_mfma_f32_16x16x32_bf16 v[92:95], v[128:131], v[202:205], v[92:95]
	v_mfma_f32_16x16x32_bf16 v[88:91], v[136:139], v[202:205], v[88:91]
	v_mfma_f32_16x16x32_bf16 v[76:79], v[128:131], v[210:213], v[76:79]
	v_mfma_f32_16x16x32_bf16 v[72:75], v[136:139], v[210:213], v[72:75]
	v_mfma_f32_16x16x32_bf16 v[124:127], v[132:135], v[190:193], v[124:127]
	v_mfma_f32_16x16x32_bf16 v[120:123], v[140:143], v[190:193], v[120:123]
	v_mfma_f32_16x16x32_bf16 v[108:111], v[132:135], v[198:201], v[108:111]
	v_mfma_f32_16x16x32_bf16 v[104:107], v[140:143], v[198:201], v[104:107]
	v_mfma_f32_16x16x32_bf16 v[92:95], v[132:135], v[206:209], v[92:95]
	v_mfma_f32_16x16x32_bf16 v[88:91], v[140:143], v[206:209], v[88:91]
	v_mfma_f32_16x16x32_bf16 v[76:79], v[132:135], v[214:217], v[76:79]
	v_mfma_f32_16x16x32_bf16 v[72:75], v[140:143], v[214:217], v[72:75]
	v_mfma_f32_16x16x32_bf16 v[116:119], v[160:163], v[186:189], v[116:119]
	v_mfma_f32_16x16x32_bf16 v[112:115], v[168:171], v[186:189], v[112:115]
	v_mfma_f32_16x16x32_bf16 v[100:103], v[160:163], v[194:197], v[100:103]
	v_mfma_f32_16x16x32_bf16 v[96:99], v[168:171], v[194:197], v[96:99]
	v_mfma_f32_16x16x32_bf16 v[84:87], v[160:163], v[202:205], v[84:87]
	v_mfma_f32_16x16x32_bf16 v[80:83], v[168:171], v[202:205], v[80:83]
	v_mfma_f32_16x16x32_bf16 v[68:71], v[160:163], v[210:213], v[68:71]
	v_mfma_f32_16x16x32_bf16 v[64:67], v[168:171], v[210:213], v[64:67]
	v_mfma_f32_16x16x32_bf16 v[116:119], v[164:167], v[190:193], v[116:119]
	v_mfma_f32_16x16x32_bf16 v[112:115], v[172:175], v[190:193], v[112:115]
	v_mfma_f32_16x16x32_bf16 v[100:103], v[164:167], v[198:201], v[100:103]
	v_mfma_f32_16x16x32_bf16 v[96:99], v[172:175], v[198:201], v[96:99]
	v_mfma_f32_16x16x32_bf16 v[84:87], v[164:167], v[206:209], v[84:87]
	v_mfma_f32_16x16x32_bf16 v[80:83], v[172:175], v[206:209], v[80:83]
	v_mfma_f32_16x16x32_bf16 v[68:71], v[164:167], v[214:217], v[68:71]
	v_mfma_f32_16x16x32_bf16 v[64:67], v[172:175], v[214:217], v[64:67]
	s_barrier
; #define PG8_STAGE(bufoff, gbase, voff) do { _Pragma("unroll") for (int _i = 0; _i < 2; ++_i) \
;         __builtin_amdgcn_global_load_lds((const unsigned*)((const char*)(gbase) + (voff)[_i]), (LAS unsigned*)(lds + (bufoff) + ldsw + _i * 8192), 16, 0, 0); } while (0)
; #define PG8_LDA(dst, b, h) do { _Pragma("unroll") for (int m = 0; m < 4; ++m) _Pragma("unroll") for (int k = 0; k < 2; ++k) dst[m][k] = *(const LAS bf16x8*)(lds + PG8_SA(b, h) + aoff + m * 2048 + k * 1024); } while (0)
; #define PG8_LDB(dst, b, h) do { _Pragma("unroll") for (int n = 0; n < 2; ++n) _Pragma("unroll") for (int k = 0; k < 2; ++k) dst[n][k] = *(const LAS bf16x8*)(lds + PG8_SB(b, h) + boff + n * 2048 + k * 1024); } while (0)
; #define PG8_MMA(ai, bj, At, Bt) do { __builtin_amdgcn_s_setprio(1); _Pragma("unroll") for (int m = 0; m < 4; ++m) _Pragma("unroll") for (int n = 0; n < 2; ++n) _Pragma("unroll") for (int k = 0; k < 2; ++k) \
;         acc[ai][bj][m][n] = __builtin_amdgcn_mfma_f32_16x16x32_bf16(Bt[n][k], At[m][k], acc[ai][bj][m][n], 0, 0, 0); __builtin_amdgcn_s_setprio(0); } while (0)
; #define PG8_WAIT_V(n) asm volatile("s_waitcnt vmcnt(" #n ")" ::: "memory")
; #define PG8_WAIT_L(n) asm volatile("s_waitcnt lgkmcnt(" #n ")" ::: "memory")
; #define PG8_BAR __builtin_amdgcn_s_barrier()
; #define PG8_SCHED __builtin_amdgcn_sched_barrier(0)
; template <class Epi>
; __device__ __forceinline__ void gemm_phase(LAS unsigned char* lds, const Gemm g, const StaticOrder& S, const Epi& E) {
;     ...
;             PG8_LDB(B0, 0, 0); PG8_LDB(B1, 0, 1); PG8_SCHED; PG8_LDA(At, 0, 0); PG8_STAGE(PG8_SA(1, 1), a1 + hstepA, voffA);
;     ...
;             PG8_LDA(At, 1, 1); PG8_STAGE(PG8_SB(1, 0), b3, voffB); PG8_STAGE(PG8_SB(1, 1), b3 + hstepB, voffB); PG8_STAGE(PG8_SA(1, 0), a3, voffA);
;             PG8_WAIT_V(8); PG8_WAIT_L(0); PG8_BAR; PG8_MMA(1, 0, At, B0); PG8_MMA(1, 1, At, B1); PG8_BAR; PG8_SCHED;
	s_add_i32 s22, s64, s29
	v_lshl_add_u64 v[178:179], v[178:179], 0, s[14:15]
	s_mov_b32 m0, s22
	ds_read_b128 v[186:189], v184 offset:49152
	ds_read_b128 v[190:193], v184 offset:50176
	ds_read_b128 v[194:197], v184 offset:51200
	ds_read_b128 v[198:201], v184 offset:52224
	ds_read_b128 v[202:205], v184 offset:53248
	ds_read_b128 v[206:209], v184 offset:54272
	ds_read_b128 v[210:213], v184 offset:55296
	ds_read_b128 v[214:217], v184 offset:56320
	global_load_lds_dwordx4 v[178:179], off
	s_add_i32 m0, s22, 0x2000
	s_add_u32 s20, s20, 0xb0080
	v_lshl_add_u64 v[178:179], v[218:219], 0, s[14:15]
	s_addc_u32 s21, s21, 0
	s_add_i32 s22, s65, s29
	global_load_lds_dwordx4 v[178:179], off
	v_lshl_add_u64 v[178:179], s[20:21], 0, v[146:147]
	s_mov_b32 m0, s22
	s_nop 0
	global_load_lds_dwordx4 v[178:179], off
	v_lshl_add_u64 v[178:179], s[20:21], 0, v[150:151]
	s_add_i32 m0, s22, 0x2000
	s_nop 0
	global_load_lds_dwordx4 v[178:179], off
	v_lshl_add_u64 v[178:179], v[220:221], 0, s[14:15]
	s_mov_b32 m0, s42
	s_nop 0
	global_load_lds_dwordx4 v[178:179], off
	v_lshl_add_u64 v[178:179], v[222:223], 0, s[14:15]
	s_mov_b32 m0, s43
	s_nop 0
	global_load_lds_dwordx4 v[178:179], off
	s_waitcnt vmcnt(8)
	s_waitcnt lgkmcnt(0)
	s_barrier
	s_waitcnt lgkmcnt(0)
	v_mfma_f32_16x16x32_bf16 v[60:63], v[128:131], v[186:189], v[60:63]
	v_mfma_f32_16x16x32_bf16 v[56:59], v[136:139], v[186:189], v[56:59]
	v_mfma_f32_16x16x32_bf16 v[44:47], v[128:131], v[194:197], v[44:47]
	v_mfma_f32_16x16x32_bf16 v[40:43], v[136:139], v[194:197], v[40:43]
	v_mfma_f32_16x16x32_bf16 v[28:31], v[128:131], v[202:205], v[28:31]
	v_mfma_f32_16x16x32_bf16 v[24:27], v[136:139], v[202:205], v[24:27]
	v_mfma_f32_16x16x32_bf16 v[12:15], v[128:131], v[210:213], v[12:15]
	v_mfma_f32_16x16x32_bf16 v[8:11], v[136:139], v[210:213], v[8:11]
	v_mfma_f32_16x16x32_bf16 v[60:63], v[132:135], v[190:193], v[60:63]
	v_mfma_f32_16x16x32_bf16 v[56:59], v[140:143], v[190:193], v[56:59]
	v_mfma_f32_16x16x32_bf16 v[44:47], v[132:135], v[198:201], v[44:47]
	v_mfma_f32_16x16x32_bf16 v[40:43], v[140:143], v[198:201], v[40:43]
	v_mfma_f32_16x16x32_bf16 v[28:31], v[132:135], v[206:209], v[28:31]
	v_mfma_f32_16x16x32_bf16 v[24:27], v[140:143], v[206:209], v[24:27]
	v_mfma_f32_16x16x32_bf16 v[12:15], v[132:135], v[214:217], v[12:15]
	v_mfma_f32_16x16x32_bf16 v[8:11], v[140:143], v[214:217], v[8:11]
	v_mfma_f32_16x16x32_bf16 v[52:55], v[160:163], v[186:189], v[52:55]
	v_mfma_f32_16x16x32_bf16 v[48:51], v[168:171], v[186:189], v[48:51]
	v_mfma_f32_16x16x32_bf16 v[36:39], v[160:163], v[194:197], v[36:39]
	v_mfma_f32_16x16x32_bf16 v[32:35], v[168:171], v[194:197], v[32:35]
	v_mfma_f32_16x16x32_bf16 v[20:23], v[160:163], v[202:205], v[20:23]
	v_mfma_f32_16x16x32_bf16 v[16:19], v[168:171], v[202:205], v[16:19]
	v_mfma_f32_16x16x32_bf16 v[4:7], v[160:163], v[210:213], v[4:7]
	v_mfma_f32_16x16x32_bf16 v[0:3], v[168:171], v[210:213], v[0:3]
	v_mfma_f32_16x16x32_bf16 v[52:55], v[164:167], v[190:193], v[52:55]
	v_mfma_f32_16x16x32_bf16 v[48:51], v[172:175], v[190:193], v[48:51]
	v_mfma_f32_16x16x32_bf16 v[36:39], v[164:167], v[198:201], v[36:39]
	v_mfma_f32_16x16x32_bf16 v[32:35], v[172:175], v[198:201], v[32:35]
	v_mfma_f32_16x16x32_bf16 v[20:23], v[164:167], v[206:209], v[20:23]
	v_mfma_f32_16x16x32_bf16 v[16:19], v[172:175], v[206:209], v[16:19]
	v_mfma_f32_16x16x32_bf16 v[4:7], v[164:167], v[214:217], v[4:7]
	v_mfma_f32_16x16x32_bf16 v[0:3], v[172:175], v[214:217], v[0:3]
	s_barrier
	s_add_i32 s63, s63, 2
	s_add_u32 s0, s0, 0x100
	s_addc_u32 s1, s1, 0
	s_add_u32 s61, s61, 0x100
	s_addc_u32 s62, s62, 0
	s_cmp_gt_u32 s63, 41
.LBB0_1649:
	ds_read_b128 v[128:131], v182
	ds_read_b128 v[132:135], v182 offset:1024
	ds_read_b128 v[136:139], v182 offset:2048
	ds_read_b128 v[140:143], v182 offset:3072
	ds_read_b128 v[160:163], v183
	ds_read_b128 v[164:167], v183 offset:1024
	ds_read_b128 v[168:171], v183 offset:2048
	ds_read_b128 v[172:175], v183 offset:3072
	s_add_u32 s20, s0, 0xfff50080
	s_addc_u32 s21, s1, -1
	s_cmp_eq_u32 s63, 40
	s_cselect_b32 s23, s7, s21
	s_cselect_b32 s22, s6, s20
	s_cselect_b32 s21, s19, s62
	s_cselect_b32 s20, s18, s61
	v_lshl_add_u64 v[178:179], s[0:1], 0, v[152:153]
	s_add_i32 m0, s33, 0xc000
	ds_read_b128 v[186:189], v184
	ds_read_b128 v[190:193], v184 offset:1024
	ds_read_b128 v[194:197], v184 offset:2048
	ds_read_b128 v[198:201], v184 offset:3072
	ds_read_b128 v[202:205], v184 offset:4096
	ds_read_b128 v[206:209], v184 offset:5120
	ds_read_b128 v[210:213], v184 offset:6144
	ds_read_b128 v[214:217], v184 offset:7168
	global_load_lds_dwordx4 v[178:179], off
	v_lshl_add_u64 v[178:179], s[0:1], 0, v[154:155]
	s_add_i32 m0, s33, 0xe000
	s_nop 0
	global_load_lds_dwordx4 v[178:179], off
	s_waitcnt vmcnt(8)
	s_waitcnt lgkmcnt(0)
	s_barrier
; #define PG8_STAGE(bufoff, gbase, voff) do { _Pragma("unroll") for (int _i = 0; _i < 2; ++_i) \
;         __builtin_amdgcn_global_load_lds((const unsigned*)((const char*)(gbase) + (voff)[_i]), (LAS unsigned*)(lds + (bufoff) + ldsw + _i * 8192), 16, 0, 0); } while (0)
; #define PG8_LDA(dst, b, h) do { _Pragma("unroll") for (int m = 0; m < 4; ++m) _Pragma("unroll") for (int k = 0; k < 2; ++k) dst[m][k] = *(const LAS bf16x8*)(lds + PG8_SA(b, h) + aoff + m * 2048 + k * 1024); } while (0)
; #define PG8_LDB(dst, b, h) do { _Pragma("unroll") for (int n = 0; n < 2; ++n) _Pragma("unroll") for (int k = 0; k < 2; ++k) dst[n][k] = *(const LAS bf16x8*)(lds + PG8_SB(b, h) + boff + n * 2048 + k * 1024); } while (0)
; #define PG8_MMA(ai, bj, At, Bt) do { __builtin_amdgcn_s_setprio(1); _Pragma("unroll") for (int m = 0; m < 4; ++m) _Pragma("unroll") for (int n = 0; n < 2; ++n) _Pragma("unroll") for (int k = 0; k < 2; ++k) \
;         acc[ai][bj][m][n] = __builtin_amdgcn_mfma_f32_16x16x32_bf16(Bt[n][k], At[m][k], acc[ai][bj][m][n], 0, 0, 0); __builtin_amdgcn_s_setprio(0); } while (0)
; #define PG8_WAIT_V(n) asm volatile("s_waitcnt vmcnt(" #n ")" ::: "memory")
; #define PG8_WAIT_L(n) asm volatile("s_waitcnt lgkmcnt(" #n ")" ::: "memory")
; #define PG8_BAR __builtin_amdgcn_s_barrier()
; #define PG8_SCHED __builtin_amdgcn_sched_barrier(0)
; template <class Epi>
; __device__ __forceinline__ void gemm_phase(LAS unsigned char* lds, const Gemm g, const StaticOrder& S, const Epi& E) {
;     ...
;             PG8_LDB(B0, 0, 0); PG8_LDB(B1, 0, 1); PG8_SCHED; PG8_LDA(At, 0, 0); PG8_STAGE(PG8_SA(1, 1), a1 + hstepA, voffA);
;             PG8_WAIT_V(8); PG8_WAIT_L(0); PG8_BAR; PG8_MMA(0, 0, At, B0); PG8_MMA(0, 1, At, B1); PG8_BAR; PG8_SCHED;
;             PG8_LDA(At, 0, 1); PG8_STAGE(PG8_SB(0, 0), b2, voffB); PG8_STAGE(PG8_SB(0, 1), b2 + hstepB, voffB); PG8_STAGE(PG8_SA(0, 0), a2, voffA);
;             PG8_WAIT_V(8); PG8_WAIT_L(0); PG8_BAR; PG8_MMA(1, 0, At, B0); PG8_MMA(1, 1, At, B1); PG8_BAR; PG8_SCHED;
	s_waitcnt lgkmcnt(0)
	v_mfma_f32_16x16x32_bf16 v[124:127], v[128:131], v[186:189], v[124:127]
	v_mfma_f32_16x16x32_bf16 v[120:123], v[136:139], v[186:189], v[120:123]
	v_mfma_f32_16x16x32_bf16 v[108:111], v[128:131], v[194:197], v[108:111]
	v_mfma_f32_16x16x32_bf16 v[104:107], v[136:139], v[194:197], v[104:107]
	v_mfma_f32_16x16x32_bf16 v[92:95], v[128:131], v[202:205], v[92:95]
	v_mfma_f32_16x16x32_bf16 v[88:91], v[136:139], v[202:205], v[88:91]
	v_mfma_f32_16x16x32_bf16 v[76:79], v[128:131], v[210:213], v[76:79]
	v_mfma_f32_16x16x32_bf16 v[72:75], v[136:139], v[210:213], v[72:75]
	v_mfma_f32_16x16x32_bf16 v[124:127], v[132:135], v[190:193], v[124:127]
	v_mfma_f32_16x16x32_bf16 v[120:123], v[140:143], v[190:193], v[120:123]
	v_mfma_f32_16x16x32_bf16 v[108:111], v[132:135], v[198:201], v[108:111]
	v_mfma_f32_16x16x32_bf16 v[104:107], v[140:143], v[198:201], v[104:107]
	v_mfma_f32_16x16x32_bf16 v[92:95], v[132:135], v[206:209], v[92:95]
	v_mfma_f32_16x16x32_bf16 v[88:91], v[140:143], v[206:209], v[88:91]
	v_mfma_f32_16x16x32_bf16 v[76:79], v[132:135], v[214:217], v[76:79]
	v_mfma_f32_16x16x32_bf16 v[72:75], v[140:143], v[214:217], v[72:75]
	v_mfma_f32_16x16x32_bf16 v[116:119], v[160:163], v[186:189], v[116:119]
	v_mfma_f32_16x16x32_bf16 v[112:115], v[168:171], v[186:189], v[112:115]
	v_mfma_f32_16x16x32_bf16 v[100:103], v[160:163], v[194:197], v[100:103]
	v_mfma_f32_16x16x32_bf16 v[96:99], v[168:171], v[194:197], v[96:99]
	v_mfma_f32_16x16x32_bf16 v[84:87], v[160:163], v[202:205], v[84:87]
	v_mfma_f32_16x16x32_bf16 v[80:83], v[168:171], v[202:205], v[80:83]
	v_mfma_f32_16x16x32_bf16 v[68:71], v[160:163], v[210:213], v[68:71]
	v_mfma_f32_16x16x32_bf16 v[64:67], v[168:171], v[210:213], v[64:67]
	v_mfma_f32_16x16x32_bf16 v[116:119], v[164:167], v[190:193], v[116:119]
	v_mfma_f32_16x16x32_bf16 v[112:115], v[172:175], v[190:193], v[112:115]
	v_mfma_f32_16x16x32_bf16 v[100:103], v[164:167], v[198:201], v[100:103]
	v_mfma_f32_16x16x32_bf16 v[96:99], v[172:175], v[198:201], v[96:99]
	v_mfma_f32_16x16x32_bf16 v[84:87], v[164:167], v[206:209], v[84:87]
	v_mfma_f32_16x16x32_bf16 v[80:83], v[172:175], v[206:209], v[80:83]
	v_mfma_f32_16x16x32_bf16 v[68:71], v[164:167], v[214:217], v[68:71]
	v_mfma_f32_16x16x32_bf16 v[64:67], v[172:175], v[214:217], v[64:67]
	s_barrier
	s_add_i32 s64, s55, s29
	v_lshl_add_u64 v[178:179], s[20:21], 0, v[146:147]
	s_mov_b32 m0, s64
	ds_read_b128 v[186:189], v184 offset:16384
	ds_read_b128 v[190:193], v184 offset:17408
	ds_read_b128 v[194:197], v184 offset:18432
	ds_read_b128 v[198:201], v184 offset:19456
	ds_read_b128 v[202:205], v184 offset:20480
	ds_read_b128 v[206:209], v184 offset:21504
	ds_read_b128 v[210:213], v184 offset:22528
	ds_read_b128 v[214:217], v184 offset:23552
	global_load_lds_dwordx4 v[178:179], off
	s_add_i32 m0, s64, 0x2000
	s_add_u32 s64, s20, 0xb0000
	v_lshl_add_u64 v[218:219], s[20:21], 0, v[150:151]
	s_addc_u32 s65, s21, 0
	s_add_i32 s66, s56, s29
	global_load_lds_dwordx4 v[218:219], off
	v_lshl_add_u64 v[220:221], s[64:65], 0, v[146:147]
	s_mov_b32 m0, s66
	v_lshl_add_u64 v[222:223], s[22:23], 0, v[148:149]
	global_load_lds_dwordx4 v[220:221], off
	v_lshl_add_u64 v[220:221], s[64:65], 0, v[150:151]
	s_add_i32 m0, s66, 0x2000
	s_nop 0
	global_load_lds_dwordx4 v[220:221], off
	v_lshl_add_u64 v[220:221], s[22:23], 0, v[144:145]
	s_mov_b32 m0, s33
	s_nop 0
	global_load_lds_dwordx4 v[220:221], off
	s_mov_b32 m0, s34
	s_nop 0
	global_load_lds_dwordx4 v[222:223], off
	s_waitcnt vmcnt(8)
	s_waitcnt lgkmcnt(0)
	s_barrier
	s_waitcnt lgkmcnt(0)
	v_mfma_f32_16x16x32_bf16 v[60:63], v[128:131], v[186:189], v[60:63]
	v_mfma_f32_16x16x32_bf16 v[56:59], v[136:139], v[186:189], v[56:59]
	v_mfma_f32_16x16x32_bf16 v[44:47], v[128:131], v[194:197], v[44:47]
	v_mfma_f32_16x16x32_bf16 v[40:43], v[136:139], v[194:197], v[40:43]
	v_mfma_f32_16x16x32_bf16 v[28:31], v[128:131], v[202:205], v[28:31]
	v_mfma_f32_16x16x32_bf16 v[24:27], v[136:139], v[202:205], v[24:27]
	v_mfma_f32_16x16x32_bf16 v[12:15], v[128:131], v[210:213], v[12:15]
	v_mfma_f32_16x16x32_bf16 v[8:11], v[136:139], v[210:213], v[8:11]
	v_mfma_f32_16x16x32_bf16 v[60:63], v[132:135], v[190:193], v[60:63]
	v_mfma_f32_16x16x32_bf16 v[56:59], v[140:143], v[190:193], v[56:59]
	v_mfma_f32_16x16x32_bf16 v[44:47], v[132:135], v[198:201], v[44:47]
	v_mfma_f32_16x16x32_bf16 v[40:43], v[140:143], v[198:201], v[40:43]
	v_mfma_f32_16x16x32_bf16 v[28:31], v[132:135], v[206:209], v[28:31]
	v_mfma_f32_16x16x32_bf16 v[24:27], v[140:143], v[206:209], v[24:27]
	v_mfma_f32_16x16x32_bf16 v[12:15], v[132:135], v[214:217], v[12:15]
	v_mfma_f32_16x16x32_bf16 v[8:11], v[140:143], v[214:217], v[8:11]
	v_mfma_f32_16x16x32_bf16 v[52:55], v[160:163], v[186:189], v[52:55]
	v_mfma_f32_16x16x32_bf16 v[48:51], v[168:171], v[186:189], v[48:51]
	v_mfma_f32_16x16x32_bf16 v[36:39], v[160:163], v[194:197], v[36:39]
	v_mfma_f32_16x16x32_bf16 v[32:35], v[168:171], v[194:197], v[32:35]
	v_mfma_f32_16x16x32_bf16 v[20:23], v[160:163], v[202:205], v[20:23]
	v_mfma_f32_16x16x32_bf16 v[16:19], v[168:171], v[202:205], v[16:19]
	v_mfma_f32_16x16x32_bf16 v[4:7], v[160:163], v[210:213], v[4:7]
	v_mfma_f32_16x16x32_bf16 v[0:3], v[168:171], v[210:213], v[0:3]
	v_mfma_f32_16x16x32_bf16 v[52:55], v[164:167], v[190:193], v[52:55]
	v_mfma_f32_16x16x32_bf16 v[48:51], v[172:175], v[190:193], v[48:51]
	v_mfma_f32_16x16x32_bf16 v[36:39], v[164:167], v[198:201], v[36:39]
	v_mfma_f32_16x16x32_bf16 v[32:35], v[172:175], v[198:201], v[32:35]
	v_mfma_f32_16x16x32_bf16 v[20:23], v[164:167], v[206:209], v[20:23]
	v_mfma_f32_16x16x32_bf16 v[16:19], v[172:175], v[206:209], v[16:19]
	v_mfma_f32_16x16x32_bf16 v[4:7], v[164:167], v[214:217], v[4:7]
	v_mfma_f32_16x16x32_bf16 v[0:3], v[172:175], v[214:217], v[0:3]
	s_barrier
; #define PG8_STAGE(bufoff, gbase, voff) do { _Pragma("unroll") for (int _i = 0; _i < 2; ++_i) \
;         __builtin_amdgcn_global_load_lds((const unsigned*)((const char*)(gbase) + (voff)[_i]), (LAS unsigned*)(lds + (bufoff) + ldsw + _i * 8192), 16, 0, 0); } while (0)
; #define PG8_LDA(dst, b, h) do { _Pragma("unroll") for (int m = 0; m < 4; ++m) _Pragma("unroll") for (int k = 0; k < 2; ++k) dst[m][k] = *(const LAS bf16x8*)(lds + PG8_SA(b, h) + aoff + m * 2048 + k * 1024); } while (0)
; #define PG8_LDB(dst, b, h) do { _Pragma("unroll") for (int n = 0; n < 2; ++n) _Pragma("unroll") for (int k = 0; k < 2; ++k) dst[n][k] = *(const LAS bf16x8*)(lds + PG8_SB(b, h) + boff + n * 2048 + k * 1024); } while (0)
; #define PG8_MMA(ai, bj, At, Bt) do { __builtin_amdgcn_s_setprio(1); _Pragma("unroll") for (int m = 0; m < 4; ++m) _Pragma("unroll") for (int n = 0; n < 2; ++n) _Pragma("unroll") for (int k = 0; k < 2; ++k) \
;         acc[ai][bj][m][n] = __builtin_amdgcn_mfma_f32_16x16x32_bf16(Bt[n][k], At[m][k], acc[ai][bj][m][n], 0, 0, 0); __builtin_amdgcn_s_setprio(0); } while (0)
; #define PG8_WAIT_V(n) asm volatile("s_waitcnt vmcnt(" #n ")" ::: "memory")
; #define PG8_WAIT_L(n) asm volatile("s_waitcnt lgkmcnt(" #n ")" ::: "memory")
; #define PG8_BAR __builtin_amdgcn_s_barrier()
; #define PG8_SCHED __builtin_amdgcn_sched_barrier(0)
; template <class Epi>
; __device__ __forceinline__ void gemm_phase(LAS unsigned char* lds, const Gemm g, const StaticOrder& S, const Epi& E) {
;     ...
;             PG8_LDB(B0, 1, 0); PG8_LDB(B1, 1, 1); PG8_SCHED; PG8_LDA(At, 1, 0); PG8_STAGE(PG8_SA(0, 1), a2 + hstepA, voffA);
;             PG8_WAIT_V(8); PG8_WAIT_L(0); PG8_BAR; PG8_MMA(0, 0, At, B0); PG8_MMA(0, 1, At, B1); PG8_BAR; PG8_SCHED;
	s_add_i32 s64, 0, 0x18000
	s_add_i32 s65, 0, 0x1c000
	v_add_u32_e32 v140, s64, v181
	v_add_u32_e32 v172, s65, v181
	ds_read_b128 v[128:131], v140
	ds_read_b128 v[132:135], v140 offset:1024
	ds_read_b128 v[136:139], v140 offset:2048
	ds_read_b128 v[140:143], v140 offset:3072
	ds_read_b128 v[160:163], v172
	ds_read_b128 v[164:167], v172 offset:1024
	ds_read_b128 v[168:171], v172 offset:2048
	ds_read_b128 v[172:175], v172 offset:3072
	s_add_u32 s22, s22, 0xb0000
	s_addc_u32 s23, s23, 0
	s_mov_b32 m0, s35
	v_lshl_add_u64 v[224:225], s[22:23], 0, v[144:145]
	ds_read_b128 v[186:189], v184 offset:32768
	ds_read_b128 v[190:193], v184 offset:33792
	ds_read_b128 v[194:197], v184 offset:34816
	ds_read_b128 v[198:201], v184 offset:35840
	ds_read_b128 v[202:205], v184 offset:36864
	ds_read_b128 v[206:209], v184 offset:37888
	ds_read_b128 v[210:213], v184 offset:38912
	ds_read_b128 v[214:217], v184 offset:39936
	global_load_lds_dwordx4 v[224:225], off
	v_lshl_add_u64 v[224:225], s[22:23], 0, v[148:149]
	s_mov_b32 m0, s36
	s_nop 0
	global_load_lds_dwordx4 v[224:225], off
	s_waitcnt vmcnt(8)
	s_waitcnt lgkmcnt(0)
	s_barrier
	s_waitcnt lgkmcnt(0)
	v_mfma_f32_16x16x32_bf16 v[124:127], v[128:131], v[186:189], v[124:127]
	v_mfma_f32_16x16x32_bf16 v[120:123], v[136:139], v[186:189], v[120:123]
	v_mfma_f32_16x16x32_bf16 v[108:111], v[128:131], v[194:197], v[108:111]
	v_mfma_f32_16x16x32_bf16 v[104:107], v[136:139], v[194:197], v[104:107]
	v_mfma_f32_16x16x32_bf16 v[92:95], v[128:131], v[202:205], v[92:95]
	v_mfma_f32_16x16x32_bf16 v[88:91], v[136:139], v[202:205], v[88:91]
	v_mfma_f32_16x16x32_bf16 v[76:79], v[128:131], v[210:213], v[76:79]
	v_mfma_f32_16x16x32_bf16 v[72:75], v[136:139], v[210:213], v[72:75]
	v_mfma_f32_16x16x32_bf16 v[124:127], v[132:135], v[190:193], v[124:127]
	v_mfma_f32_16x16x32_bf16 v[120:123], v[140:143], v[190:193], v[120:123]
	v_mfma_f32_16x16x32_bf16 v[108:111], v[132:135], v[198:201], v[108:111]
	v_mfma_f32_16x16x32_bf16 v[104:107], v[140:143], v[198:201], v[104:107]
	v_mfma_f32_16x16x32_bf16 v[92:95], v[132:135], v[206:209], v[92:95]
	v_mfma_f32_16x16x32_bf16 v[88:91], v[140:143], v[206:209], v[88:91]
	v_mfma_f32_16x16x32_bf16 v[76:79], v[132:135], v[214:217], v[76:79]
	v_mfma_f32_16x16x32_bf16 v[72:75], v[140:143], v[214:217], v[72:75]
	v_mfma_f32_16x16x32_bf16 v[116:119], v[160:163], v[186:189], v[116:119]
	v_mfma_f32_16x16x32_bf16 v[112:115], v[168:171], v[186:189], v[112:115]
	v_mfma_f32_16x16x32_bf16 v[100:103], v[160:163], v[194:197], v[100:103]
	v_mfma_f32_16x16x32_bf16 v[96:99], v[168:171], v[194:197], v[96:99]
	v_mfma_f32_16x16x32_bf16 v[84:87], v[160:163], v[202:205], v[84:87]
	v_mfma_f32_16x16x32_bf16 v[80:83], v[168:171], v[202:205], v[80:83]
	v_mfma_f32_16x16x32_bf16 v[68:71], v[160:163], v[210:213], v[68:71]
	v_mfma_f32_16x16x32_bf16 v[64:67], v[168:171], v[210:213], v[64:67]
	v_mfma_f32_16x16x32_bf16 v[116:119], v[164:167], v[190:193], v[116:119]
	v_mfma_f32_16x16x32_bf16 v[112:115], v[172:175], v[190:193], v[112:115]
	v_mfma_f32_16x16x32_bf16 v[100:103], v[164:167], v[198:201], v[100:103]
	v_mfma_f32_16x16x32_bf16 v[96:99], v[172:175], v[198:201], v[96:99]
	v_mfma_f32_16x16x32_bf16 v[84:87], v[164:167], v[206:209], v[84:87]
	v_mfma_f32_16x16x32_bf16 v[80:83], v[172:175], v[206:209], v[80:83]
	v_mfma_f32_16x16x32_bf16 v[68:71], v[164:167], v[214:217], v[68:71]
	v_mfma_f32_16x16x32_bf16 v[64:67], v[172:175], v[214:217], v[64:67]
	s_barrier
; #define PG8_STAGE(bufoff, gbase, voff) do { _Pragma("unroll") for (int _i = 0; _i < 2; ++_i) \
;         __builtin_amdgcn_global_load_lds((const unsigned*)((const char*)(gbase) + (voff)[_i]), (LAS unsigned*)(lds + (bufoff) + ldsw + _i * 8192), 16, 0, 0); } while (0)
; #define PG8_LDA(dst, b, h) do { _Pragma("unroll") for (int m = 0; m < 4; ++m) _Pragma("unroll") for (int k = 0; k < 2; ++k) dst[m][k] = *(const LAS bf16x8*)(lds + PG8_SA(b, h) + aoff + m * 2048 + k * 1024); } while (0)
; #define PG8_MMA(ai, bj, At, Bt) do { __builtin_amdgcn_s_setprio(1); _Pragma("unroll") for (int m = 0; m < 4; ++m) _Pragma("unroll") for (int n = 0; n < 2; ++n) _Pragma("unroll") for (int k = 0; k < 2; ++k) \
;         acc[ai][bj][m][n] = __builtin_amdgcn_mfma_f32_16x16x32_bf16(Bt[n][k], At[m][k], acc[ai][bj][m][n], 0, 0, 0); __builtin_amdgcn_s_setprio(0); } while (0)
; #define PG8_WAIT_V(n) asm volatile("s_waitcnt vmcnt(" #n ")" ::: "memory")
; #define PG8_WAIT_L(n) asm volatile("s_waitcnt lgkmcnt(" #n ")" ::: "memory")
; #define PG8_BAR __builtin_amdgcn_s_barrier()
; #define PG8_SCHED __builtin_amdgcn_sched_barrier(0)
; template <class Epi>
; __device__ __forceinline__ void gemm_phase(LAS unsigned char* lds, const Gemm g, const StaticOrder& S, const Epi& E) {
;     ...
;             PG8_LDA(At, 1, 1); PG8_STAGE(PG8_SB(1, 0), b3, voffB); PG8_STAGE(PG8_SB(1, 1), b3 + hstepB, voffB); PG8_STAGE(PG8_SA(1, 0), a3, voffA);
;             PG8_WAIT_V(8); PG8_WAIT_L(0); PG8_BAR; PG8_MMA(1, 0, At, B0); PG8_MMA(1, 1, At, B1); PG8_BAR; PG8_SCHED;
;         }
;         if (wr == 0) PG8_BAR;
	s_add_i32 s22, s64, s29
	v_lshl_add_u64 v[178:179], v[178:179], 0, s[14:15]
	s_mov_b32 m0, s22
	ds_read_b128 v[186:189], v184 offset:49152
	ds_read_b128 v[190:193], v184 offset:50176
	ds_read_b128 v[194:197], v184 offset:51200
	ds_read_b128 v[198:201], v184 offset:52224
	ds_read_b128 v[202:205], v184 offset:53248
	ds_read_b128 v[206:209], v184 offset:54272
	ds_read_b128 v[210:213], v184 offset:55296
	ds_read_b128 v[214:217], v184 offset:56320
	global_load_lds_dwordx4 v[178:179], off
	s_add_i32 m0, s22, 0x2000
	s_add_u32 s20, s20, 0xb0080
	v_lshl_add_u64 v[178:179], v[218:219], 0, s[14:15]
	s_addc_u32 s21, s21, 0
	s_add_i32 s22, s65, s29
	global_load_lds_dwordx4 v[178:179], off
	v_lshl_add_u64 v[178:179], s[20:21], 0, v[146:147]
	s_mov_b32 m0, s22
	s_nop 0
	global_load_lds_dwordx4 v[178:179], off
	v_lshl_add_u64 v[178:179], s[20:21], 0, v[150:151]
	s_add_i32 m0, s22, 0x2000
	s_nop 0
	global_load_lds_dwordx4 v[178:179], off
	v_lshl_add_u64 v[178:179], v[220:221], 0, s[14:15]
	s_mov_b32 m0, s42
	s_nop 0
	global_load_lds_dwordx4 v[178:179], off
	v_lshl_add_u64 v[178:179], v[222:223], 0, s[14:15]
	s_mov_b32 m0, s43
	s_nop 0
	global_load_lds_dwordx4 v[178:179], off
	s_waitcnt vmcnt(8)
	s_waitcnt lgkmcnt(0)
	s_barrier
	s_waitcnt lgkmcnt(0)
	v_mfma_f32_16x16x32_bf16 v[60:63], v[128:131], v[186:189], v[60:63]
	v_mfma_f32_16x16x32_bf16 v[56:59], v[136:139], v[186:189], v[56:59]
	v_mfma_f32_16x16x32_bf16 v[44:47], v[128:131], v[194:197], v[44:47]
	v_mfma_f32_16x16x32_bf16 v[40:43], v[136:139], v[194:197], v[40:43]
	v_mfma_f32_16x16x32_bf16 v[28:31], v[128:131], v[202:205], v[28:31]
	v_mfma_f32_16x16x32_bf16 v[24:27], v[136:139], v[202:205], v[24:27]
	v_mfma_f32_16x16x32_bf16 v[12:15], v[128:131], v[210:213], v[12:15]
	v_mfma_f32_16x16x32_bf16 v[8:11], v[136:139], v[210:213], v[8:11]
	v_mfma_f32_16x16x32_bf16 v[60:63], v[132:135], v[190:193], v[60:63]
	v_mfma_f32_16x16x32_bf16 v[56:59], v[140:143], v[190:193], v[56:59]
	v_mfma_f32_16x16x32_bf16 v[44:47], v[132:135], v[198:201], v[44:47]
	v_mfma_f32_16x16x32_bf16 v[40:43], v[140:143], v[198:201], v[40:43]
	v_mfma_f32_16x16x32_bf16 v[28:31], v[132:135], v[206:209], v[28:31]
	v_mfma_f32_16x16x32_bf16 v[24:27], v[140:143], v[206:209], v[24:27]
	v_mfma_f32_16x16x32_bf16 v[12:15], v[132:135], v[214:217], v[12:15]
	v_mfma_f32_16x16x32_bf16 v[8:11], v[140:143], v[214:217], v[8:11]
	v_mfma_f32_16x16x32_bf16 v[52:55], v[160:163], v[186:189], v[52:55]
	v_mfma_f32_16x16x32_bf16 v[48:51], v[168:171], v[186:189], v[48:51]
	v_mfma_f32_16x16x32_bf16 v[36:39], v[160:163], v[194:197], v[36:39]
	v_mfma_f32_16x16x32_bf16 v[32:35], v[168:171], v[194:197], v[32:35]
	v_mfma_f32_16x16x32_bf16 v[20:23], v[160:163], v[202:205], v[20:23]
	v_mfma_f32_16x16x32_bf16 v[16:19], v[168:171], v[202:205], v[16:19]
	v_mfma_f32_16x16x32_bf16 v[4:7], v[160:163], v[210:213], v[4:7]
	v_mfma_f32_16x16x32_bf16 v[0:3], v[168:171], v[210:213], v[0:3]
	v_mfma_f32_16x16x32_bf16 v[52:55], v[164:167], v[190:193], v[52:55]
	v_mfma_f32_16x16x32_bf16 v[48:51], v[172:175], v[190:193], v[48:51]
	v_mfma_f32_16x16x32_bf16 v[36:39], v[164:167], v[198:201], v[36:39]
	v_mfma_f32_16x16x32_bf16 v[32:35], v[172:175], v[198:201], v[32:35]
	v_mfma_f32_16x16x32_bf16 v[20:23], v[164:167], v[206:209], v[20:23]
	v_mfma_f32_16x16x32_bf16 v[16:19], v[172:175], v[206:209], v[16:19]
	v_mfma_f32_16x16x32_bf16 v[4:7], v[164:167], v[214:217], v[4:7]
	v_mfma_f32_16x16x32_bf16 v[0:3], v[172:175], v[214:217], v[0:3]
	s_barrier
	s_add_i32 s63, s63, 2
	s_add_u32 s0, s0, 0x100
	s_addc_u32 s1, s1, 0
	s_add_u32 s61, s61, 0x100
	s_addc_u32 s62, s62, 0
	s_cmp_gt_u32 s63, 41
	s_cbranch_scc0 .LBB0_1649
	s_and_b64 vcc, exec, s[16:17]
	s_cbranch_vccz .LBB0_1652
	s_barrier

; #define PG8_STAGE(bufoff, gbase, voff) do { _Pragma("unroll") for (int _i = 0; _i < 2; ++_i) \
;         __builtin_amdgcn_global_load_lds((const unsigned*)((const char*)(gbase) + (voff)[_i]), (LAS unsigned*)(lds + (bufoff) + ldsw + _i * 8192), 16, 0, 0); } while (0)
; #define PG8_LDA(dst, b, h) do { _Pragma("unroll") for (int m = 0; m < 4; ++m) _Pragma("unroll") for (int k = 0; k < 2; ++k) dst[m][k] = *(const LAS bf16x8*)(lds + PG8_SA(b, h) + aoff + m * 2048 + k * 1024); } while (0)
; #define PG8_LDB(dst, b, h) do { _Pragma("unroll") for (int n = 0; n < 2; ++n) _Pragma("unroll") for (int k = 0; k < 2; ++k) dst[n][k] = *(const LAS bf16x8*)(lds + PG8_SB(b, h) + boff + n * 2048 + k * 1024); } while (0)
; #define PG8_MMA(ai, bj, At, Bt) do { __builtin_amdgcn_s_setprio(1); _Pragma("unroll") for (int m = 0; m < 4; ++m) _Pragma("unroll") for (int n = 0; n < 2; ++n) _Pragma("unroll") for (int k = 0; k < 2; ++k) \
;         acc[ai][bj][m][n] = __builtin_amdgcn_mfma_f32_16x16x32_bf16(Bt[n][k], At[m][k], acc[ai][bj][m][n], 0, 0, 0); __builtin_amdgcn_s_setprio(0); } while (0)
; #define PG8_BAR __builtin_amdgcn_s_barrier()
; template <class Epi>
; __device__ __forceinline__ void gemm_phase(LAS unsigned char* lds, const Gemm g, const StaticOrder& S, const Epi& E) {
;     ...
;         const bool has_next = S.next(ui + 1, nxt);
;         const char* nA = has_next ? (const char*)g.A + (size_t)nxt.pm * tstepA : cA; const char* nB = has_next ? (const char*)g.Bt + (size_t)nxt.pn * tstepB : cB;
; #pragma nounroll
;         for (int t = 0; t < nt; t += 2) {
;             const bool last = (t == nt - 2);
;             const char* a1 = cA + (size_t)(t + 1) * kstep;
;             const char* a2 = last ? nA : cA + (size_t)(t + 2) * kstep; const char* b2 = last ? nB : cB + (size_t)(t + 2) * kstep;
;             const char* a3 = a2 + kstep; const char* b3 = b2 + kstep;
;             PG8_LDB(B0, 0, 0); PG8_LDB(B1, 0, 1); PG8_SCHED; PG8_LDA(At, 0, 0); PG8_STAGE(PG8_SA(1, 1), a1 + hstepA, voffA);
;             PG8_WAIT_V(8); PG8_WAIT_L(0); PG8_BAR; PG8_MMA(0, 0, At, B0); PG8_MMA(0, 1, At, B1); PG8_BAR; PG8_SCHED;
;             PG8_LDA(At, 0, 1); PG8_STAGE(PG8_SB(0, 0), b2, voffB); PG8_STAGE(PG8_SB(0, 1), b2 + hstepB, voffB); PG8_STAGE(PG8_SA(0, 0), a2, voffA);
;             PG8_WAIT_V(8); PG8_WAIT_L(0); PG8_BAR; PG8_MMA(1, 0, At, B0); PG8_MMA(1, 1, At, B1); PG8_BAR; PG8_SCHED;
.LBB0_1745:
	s_ashr_i32 s35, s34, 31
	s_lshl_b64 s[36:37], s[34:35], 19
	s_add_u32 s36, s30, s36
	s_addc_u32 s37, s31, s37
	s_and_b64 s[38:39], s[4:5], exec
	s_cselect_b32 s7, s37, s43
	s_cselect_b32 s9, s36, s42
	s_ashr_i32 s29, s28, 31
	s_lshl_b64 s[38:39], s[28:29], 19
	s_add_u32 s38, s3, s38
	s_addc_u32 s39, s33, s39
	s_and_b64 s[44:45], s[4:5], exec
	s_cselect_b32 s29, s39, s53
	s_cselect_b32 s35, s38, s52
	s_add_u32 s42, s42, 0x40080
	s_addc_u32 s43, s43, 0
	s_add_u32 s69, s52, 0x100
	s_addc_u32 s70, s53, 0
	s_mov_b32 s71, -2
	s_waitcnt lgkmcnt(0)
	ds_read_b128 v[40:43], v208
	ds_read_b128 v[44:47], v208 offset:1024
	ds_read_b128 v[56:59], v208 offset:2048
	ds_read_b128 v[60:63], v208 offset:3072
	ds_read_b128 v[144:147], v209
	ds_read_b128 v[148:151], v209 offset:1024
	ds_read_b128 v[152:155], v209 offset:2048
	ds_read_b128 v[156:159], v209 offset:3072
	s_add_u32 s44, s42, 0xfffc0080
	s_addc_u32 s45, s43, -1
	s_cmp_eq_u32 s71, 12
	s_cselect_b32 s53, s7, s45
	s_cselect_b32 s52, s9, s44
	s_cselect_b32 s45, s29, s70
	s_cselect_b32 s44, s35, s69
	v_lshl_add_u64 v[218:219], s[42:43], 0, v[178:179]
	s_add_i32 m0, s55, 0xc000
	ds_read_b128 v[160:163], v210
	ds_read_b128 v[164:167], v210 offset:1024
	ds_read_b128 v[186:189], v210 offset:2048
	ds_read_b128 v[190:193], v210 offset:3072
	ds_read_b128 v[194:197], v210 offset:4096
	ds_read_b128 v[198:201], v210 offset:5120
	ds_read_b128 v[202:205], v210 offset:6144
	ds_read_b128 v[214:217], v210 offset:7168
	global_load_lds_dwordx4 v[218:219], off
	v_lshl_add_u64 v[218:219], s[42:43], 0, v[180:181]
	s_add_i32 m0, s55, 0xe000
	s_nop 0
	global_load_lds_dwordx4 v[218:219], off
	s_waitcnt vmcnt(8)
	s_waitcnt lgkmcnt(0)
	s_barrier
	s_waitcnt lgkmcnt(0)
	v_mfma_f32_16x16x32_bf16 v[140:143], v[40:43], v[160:163], 0
	v_mfma_f32_16x16x32_bf16 v[136:139], v[56:59], v[160:163], 0
	v_mfma_f32_16x16x32_bf16 v[124:127], v[40:43], v[186:189], 0
	v_mfma_f32_16x16x32_bf16 v[120:123], v[56:59], v[186:189], 0
	v_mfma_f32_16x16x32_bf16 v[108:111], v[40:43], v[194:197], 0
	v_mfma_f32_16x16x32_bf16 v[104:107], v[56:59], v[194:197], 0
	v_mfma_f32_16x16x32_bf16 v[92:95], v[40:43], v[202:205], 0
	v_mfma_f32_16x16x32_bf16 v[88:91], v[56:59], v[202:205], 0
	v_mfma_f32_16x16x32_bf16 v[140:143], v[44:47], v[164:167], v[140:143]
	v_mfma_f32_16x16x32_bf16 v[136:139], v[60:63], v[164:167], v[136:139]
	v_mfma_f32_16x16x32_bf16 v[124:127], v[44:47], v[190:193], v[124:127]
	v_mfma_f32_16x16x32_bf16 v[120:123], v[60:63], v[190:193], v[120:123]
	v_mfma_f32_16x16x32_bf16 v[108:111], v[44:47], v[198:201], v[108:111]
	v_mfma_f32_16x16x32_bf16 v[104:107], v[60:63], v[198:201], v[104:107]
	v_mfma_f32_16x16x32_bf16 v[92:95], v[44:47], v[214:217], v[92:95]
	v_mfma_f32_16x16x32_bf16 v[88:91], v[60:63], v[214:217], v[88:91]
	v_mfma_f32_16x16x32_bf16 v[132:135], v[144:147], v[160:163], 0
	v_mfma_f32_16x16x32_bf16 v[128:131], v[152:155], v[160:163], 0
	v_mfma_f32_16x16x32_bf16 v[116:119], v[144:147], v[186:189], 0
	v_mfma_f32_16x16x32_bf16 v[112:115], v[152:155], v[186:189], 0
	v_mfma_f32_16x16x32_bf16 v[100:103], v[144:147], v[194:197], 0
	v_mfma_f32_16x16x32_bf16 v[96:99], v[152:155], v[194:197], 0
	v_mfma_f32_16x16x32_bf16 v[84:87], v[144:147], v[202:205], 0
	v_mfma_f32_16x16x32_bf16 v[80:83], v[152:155], v[202:205], 0
	v_mfma_f32_16x16x32_bf16 v[132:135], v[148:151], v[164:167], v[132:135]
	v_mfma_f32_16x16x32_bf16 v[128:131], v[156:159], v[164:167], v[128:131]
	v_mfma_f32_16x16x32_bf16 v[116:119], v[148:151], v[190:193], v[116:119]
	v_mfma_f32_16x16x32_bf16 v[112:115], v[156:159], v[190:193], v[112:115]
	v_mfma_f32_16x16x32_bf16 v[100:103], v[148:151], v[198:201], v[100:103]
	v_mfma_f32_16x16x32_bf16 v[96:99], v[156:159], v[198:201], v[96:99]
	v_mfma_f32_16x16x32_bf16 v[84:87], v[148:151], v[214:217], v[84:87]
	v_mfma_f32_16x16x32_bf16 v[80:83], v[156:159], v[214:217], v[80:83]
	s_barrier
	s_add_i32 s72, s67, s54
	v_lshl_add_u64 v[218:219], s[44:45], 0, v[170:171]
	s_mov_b32 m0, s72
	ds_read_b128 v[160:163], v210 offset:16384
	ds_read_b128 v[164:167], v210 offset:17408
	ds_read_b128 v[186:189], v210 offset:18432
	ds_read_b128 v[190:193], v210 offset:19456
	ds_read_b128 v[194:197], v210 offset:20480
	ds_read_b128 v[198:201], v210 offset:21504
	ds_read_b128 v[202:205], v210 offset:22528
	ds_read_b128 v[214:217], v210 offset:23552
	global_load_lds_dwordx4 v[218:219], off
	s_add_i32 m0, s72, 0x2000
	s_add_u32 s72, s44, 0x40000
	v_lshl_add_u64 v[220:221], s[44:45], 0, v[174:175]
	s_addc_u32 s73, s45, 0
	s_add_i32 s74, s68, s54
	global_load_lds_dwordx4 v[220:221], off
	v_lshl_add_u64 v[222:223], s[72:73], 0, v[170:171]
	s_mov_b32 m0, s74
	v_lshl_add_u64 v[224:225], s[52:53], 0, v[172:173]
	global_load_lds_dwordx4 v[222:223], off
	v_lshl_add_u64 v[222:223], s[72:73], 0, v[174:175]
	s_add_i32 m0, s74, 0x2000
	s_nop 0
	global_load_lds_dwordx4 v[222:223], off
	v_lshl_add_u64 v[222:223], s[52:53], 0, v[168:169]
	s_mov_b32 m0, s55
	s_nop 0
	global_load_lds_dwordx4 v[222:223], off
	s_mov_b32 m0, s56
	s_nop 0
	global_load_lds_dwordx4 v[224:225], off
	s_waitcnt vmcnt(8)
	s_waitcnt lgkmcnt(0)
	s_barrier
; #define PG8_STAGE(bufoff, gbase, voff) do { _Pragma("unroll") for (int _i = 0; _i < 2; ++_i) \
;         __builtin_amdgcn_global_load_lds((const unsigned*)((const char*)(gbase) + (voff)[_i]), (LAS unsigned*)(lds + (bufoff) + ldsw + _i * 8192), 16, 0, 0); } while (0)
; #define PG8_LDA(dst, b, h) do { _Pragma("unroll") for (int m = 0; m < 4; ++m) _Pragma("unroll") for (int k = 0; k < 2; ++k) dst[m][k] = *(const LAS bf16x8*)(lds + PG8_SA(b, h) + aoff + m * 2048 + k * 1024); } while (0)
; #define PG8_LDB(dst, b, h) do { _Pragma("unroll") for (int n = 0; n < 2; ++n) _Pragma("unroll") for (int k = 0; k < 2; ++k) dst[n][k] = *(const LAS bf16x8*)(lds + PG8_SB(b, h) + boff + n * 2048 + k * 1024); } while (0)
; #define PG8_MMA(ai, bj, At, Bt) do { __builtin_amdgcn_s_setprio(1); _Pragma("unroll") for (int m = 0; m < 4; ++m) _Pragma("unroll") for (int n = 0; n < 2; ++n) _Pragma("unroll") for (int k = 0; k < 2; ++k) \
;         acc[ai][bj][m][n] = __builtin_amdgcn_mfma_f32_16x16x32_bf16(Bt[n][k], At[m][k], acc[ai][bj][m][n], 0, 0, 0); __builtin_amdgcn_s_setprio(0); } while (0)
; #define PG8_WAIT_V(n) asm volatile("s_waitcnt vmcnt(" #n ")" ::: "memory")
; #define PG8_WAIT_L(n) asm volatile("s_waitcnt lgkmcnt(" #n ")" ::: "memory")
; #define PG8_BAR __builtin_amdgcn_s_barrier()
; #define PG8_SCHED __builtin_amdgcn_sched_barrier(0)
; template <class Epi>
; __device__ __forceinline__ void gemm_phase(LAS unsigned char* lds, const Gemm g, const StaticOrder& S, const Epi& E) {
;     ...
;             PG8_WAIT_V(8); PG8_WAIT_L(0); PG8_BAR; PG8_MMA(1, 0, At, B0); PG8_MMA(1, 1, At, B1); PG8_BAR; PG8_SCHED;
;             PG8_LDB(B0, 1, 0); PG8_LDB(B1, 1, 1); PG8_SCHED; PG8_LDA(At, 1, 0); PG8_STAGE(PG8_SA(0, 1), a2 + hstepA, voffA);
;             PG8_WAIT_V(8); PG8_WAIT_L(0); PG8_BAR; PG8_MMA(0, 0, At, B0); PG8_MMA(0, 1, At, B1); PG8_BAR; PG8_SCHED;
	s_waitcnt lgkmcnt(0)
	v_mfma_f32_16x16x32_bf16 v[76:79], v[40:43], v[160:163], 0
	v_mfma_f32_16x16x32_bf16 v[72:75], v[56:59], v[160:163], 0
	v_mfma_f32_16x16x32_bf16 v[52:55], v[40:43], v[186:189], 0
	v_mfma_f32_16x16x32_bf16 v[48:51], v[56:59], v[186:189], 0
	v_mfma_f32_16x16x32_bf16 v[28:31], v[40:43], v[194:197], 0
	v_mfma_f32_16x16x32_bf16 v[24:27], v[56:59], v[194:197], 0
	v_mfma_f32_16x16x32_bf16 v[12:15], v[40:43], v[202:205], 0
	v_mfma_f32_16x16x32_bf16 v[8:11], v[56:59], v[202:205], 0
	v_mfma_f32_16x16x32_bf16 v[76:79], v[44:47], v[164:167], v[76:79]
	v_mfma_f32_16x16x32_bf16 v[72:75], v[60:63], v[164:167], v[72:75]
	v_mfma_f32_16x16x32_bf16 v[52:55], v[44:47], v[190:193], v[52:55]
	v_mfma_f32_16x16x32_bf16 v[48:51], v[60:63], v[190:193], v[48:51]
	v_mfma_f32_16x16x32_bf16 v[28:31], v[44:47], v[198:201], v[28:31]
	v_mfma_f32_16x16x32_bf16 v[24:27], v[60:63], v[198:201], v[24:27]
	v_mfma_f32_16x16x32_bf16 v[12:15], v[44:47], v[214:217], v[12:15]
	v_mfma_f32_16x16x32_bf16 v[8:11], v[60:63], v[214:217], v[8:11]
	v_mfma_f32_16x16x32_bf16 v[36:39], v[144:147], v[186:189], 0
	v_mfma_f32_16x16x32_bf16 v[32:35], v[152:155], v[186:189], 0
	v_mfma_f32_16x16x32_bf16 v[20:23], v[144:147], v[194:197], 0
	v_mfma_f32_16x16x32_bf16 v[16:19], v[152:155], v[194:197], 0
	v_mfma_f32_16x16x32_bf16 v[4:7], v[144:147], v[202:205], 0
	v_mfma_f32_16x16x32_bf16 v[0:3], v[152:155], v[202:205], 0
	v_mfma_f32_16x16x32_bf16 v[40:43], v[144:147], v[160:163], 0
	v_mfma_f32_16x16x32_bf16 v[44:47], v[152:155], v[160:163], 0
	v_mfma_f32_16x16x32_bf16 v[36:39], v[148:151], v[190:193], v[36:39]
	v_mfma_f32_16x16x32_bf16 v[32:35], v[156:159], v[190:193], v[32:35]
	v_mfma_f32_16x16x32_bf16 v[20:23], v[148:151], v[198:201], v[20:23]
	v_mfma_f32_16x16x32_bf16 v[16:19], v[156:159], v[198:201], v[16:19]
	v_mfma_f32_16x16x32_bf16 v[4:7], v[148:151], v[214:217], v[4:7]
	v_mfma_f32_16x16x32_bf16 v[0:3], v[156:159], v[214:217], v[0:3]
	v_mfma_f32_16x16x32_bf16 v[40:43], v[148:151], v[164:167], v[40:43]
	v_mfma_f32_16x16x32_bf16 v[44:47], v[156:159], v[164:167], v[44:47]
	s_barrier
	s_add_i32 s72, 0, 0x18000
	s_add_i32 s73, 0, 0x1c000
	v_add_u32_e32 v68, s72, v207
	v_add_u32_e32 v156, s73, v207
	ds_read_b128 v[56:59], v68
	ds_read_b128 v[60:63], v68 offset:1024
	ds_read_b128 v[64:67], v68 offset:2048
	ds_read_b128 v[68:71], v68 offset:3072
	ds_read_b128 v[144:147], v156
	ds_read_b128 v[148:151], v156 offset:1024
	ds_read_b128 v[152:155], v156 offset:2048
	ds_read_b128 v[156:159], v156 offset:3072
	s_add_u32 s52, s52, 0x40000
	s_addc_u32 s53, s53, 0
	s_mov_b32 m0, s57
	v_lshl_add_u64 v[226:227], s[52:53], 0, v[168:169]
	ds_read_b128 v[160:163], v210 offset:32768
	ds_read_b128 v[164:167], v210 offset:33792
	ds_read_b128 v[186:189], v210 offset:34816
	ds_read_b128 v[190:193], v210 offset:35840
	ds_read_b128 v[194:197], v210 offset:36864
	ds_read_b128 v[198:201], v210 offset:37888
	ds_read_b128 v[202:205], v210 offset:38912
	ds_read_b128 v[214:217], v210 offset:39936
	global_load_lds_dwordx4 v[226:227], off
	v_lshl_add_u64 v[226:227], s[52:53], 0, v[172:173]
	s_mov_b32 m0, s58
	s_nop 0
	global_load_lds_dwordx4 v[226:227], off
	s_waitcnt vmcnt(8)
	s_waitcnt lgkmcnt(0)
	s_barrier
	s_waitcnt lgkmcnt(0)
	v_mfma_f32_16x16x32_bf16 v[140:143], v[56:59], v[160:163], v[140:143]
	v_mfma_f32_16x16x32_bf16 v[136:139], v[64:67], v[160:163], v[136:139]
	v_mfma_f32_16x16x32_bf16 v[124:127], v[56:59], v[186:189], v[124:127]
	v_mfma_f32_16x16x32_bf16 v[120:123], v[64:67], v[186:189], v[120:123]
	v_mfma_f32_16x16x32_bf16 v[108:111], v[56:59], v[194:197], v[108:111]
	v_mfma_f32_16x16x32_bf16 v[104:107], v[64:67], v[194:197], v[104:107]
	v_mfma_f32_16x16x32_bf16 v[92:95], v[56:59], v[202:205], v[92:95]
	v_mfma_f32_16x16x32_bf16 v[88:91], v[64:67], v[202:205], v[88:91]
	v_mfma_f32_16x16x32_bf16 v[140:143], v[60:63], v[164:167], v[140:143]
	v_mfma_f32_16x16x32_bf16 v[136:139], v[68:71], v[164:167], v[136:139]
	v_mfma_f32_16x16x32_bf16 v[124:127], v[60:63], v[190:193], v[124:127]
	v_mfma_f32_16x16x32_bf16 v[120:123], v[68:71], v[190:193], v[120:123]
	v_mfma_f32_16x16x32_bf16 v[108:111], v[60:63], v[198:201], v[108:111]
	v_mfma_f32_16x16x32_bf16 v[104:107], v[68:71], v[198:201], v[104:107]
	v_mfma_f32_16x16x32_bf16 v[92:95], v[60:63], v[214:217], v[92:95]
	v_mfma_f32_16x16x32_bf16 v[88:91], v[68:71], v[214:217], v[88:91]
	v_mfma_f32_16x16x32_bf16 v[132:135], v[144:147], v[160:163], v[132:135]
	v_mfma_f32_16x16x32_bf16 v[128:131], v[152:155], v[160:163], v[128:131]
	v_mfma_f32_16x16x32_bf16 v[116:119], v[144:147], v[186:189], v[116:119]
	v_mfma_f32_16x16x32_bf16 v[112:115], v[152:155], v[186:189], v[112:115]
	v_mfma_f32_16x16x32_bf16 v[100:103], v[144:147], v[194:197], v[100:103]
	v_mfma_f32_16x16x32_bf16 v[96:99], v[152:155], v[194:197], v[96:99]
	v_mfma_f32_16x16x32_bf16 v[84:87], v[144:147], v[202:205], v[84:87]
	v_mfma_f32_16x16x32_bf16 v[80:83], v[152:155], v[202:205], v[80:83]
	v_mfma_f32_16x16x32_bf16 v[132:135], v[148:151], v[164:167], v[132:135]
	v_mfma_f32_16x16x32_bf16 v[128:131], v[156:159], v[164:167], v[128:131]
	v_mfma_f32_16x16x32_bf16 v[116:119], v[148:151], v[190:193], v[116:119]
	v_mfma_f32_16x16x32_bf16 v[112:115], v[156:159], v[190:193], v[112:115]
	v_mfma_f32_16x16x32_bf16 v[100:103], v[148:151], v[198:201], v[100:103]
	v_mfma_f32_16x16x32_bf16 v[96:99], v[156:159], v[198:201], v[96:99]
	v_mfma_f32_16x16x32_bf16 v[84:87], v[148:151], v[214:217], v[84:87]
	v_mfma_f32_16x16x32_bf16 v[80:83], v[156:159], v[214:217], v[80:83]
	s_barrier
; #define PG8_STAGE(bufoff, gbase, voff) do { _Pragma("unroll") for (int _i = 0; _i < 2; ++_i) \
;         __builtin_amdgcn_global_load_lds((const unsigned*)((const char*)(gbase) + (voff)[_i]), (LAS unsigned*)(lds + (bufoff) + ldsw + _i * 8192), 16, 0, 0); } while (0)
; #define PG8_LDA(dst, b, h) do { _Pragma("unroll") for (int m = 0; m < 4; ++m) _Pragma("unroll") for (int k = 0; k < 2; ++k) dst[m][k] = *(const LAS bf16x8*)(lds + PG8_SA(b, h) + aoff + m * 2048 + k * 1024); } while (0)
; #define PG8_LDB(dst, b, h) do { _Pragma("unroll") for (int n = 0; n < 2; ++n) _Pragma("unroll") for (int k = 0; k < 2; ++k) dst[n][k] = *(const LAS bf16x8*)(lds + PG8_SB(b, h) + boff + n * 2048 + k * 1024); } while (0)
; #define PG8_MMA(ai, bj, At, Bt) do { __builtin_amdgcn_s_setprio(1); _Pragma("unroll") for (int m = 0; m < 4; ++m) _Pragma("unroll") for (int n = 0; n < 2; ++n) _Pragma("unroll") for (int k = 0; k < 2; ++k) \
;         acc[ai][bj][m][n] = __builtin_amdgcn_mfma_f32_16x16x32_bf16(Bt[n][k], At[m][k], acc[ai][bj][m][n], 0, 0, 0); __builtin_amdgcn_s_setprio(0); } while (0)
; #define PG8_WAIT_V(n) asm volatile("s_waitcnt vmcnt(" #n ")" ::: "memory")
; #define PG8_WAIT_L(n) asm volatile("s_waitcnt lgkmcnt(" #n ")" ::: "memory")
; #define PG8_BAR __builtin_amdgcn_s_barrier()
; #define PG8_SCHED __builtin_amdgcn_sched_barrier(0)
; template <class Epi>
; __device__ __forceinline__ void gemm_phase(LAS unsigned char* lds, const Gemm g, const StaticOrder& S, const Epi& E) {
;     ...
;             PG8_LDB(B0, 0, 0); PG8_LDB(B1, 0, 1); PG8_SCHED; PG8_LDA(At, 0, 0); PG8_STAGE(PG8_SA(1, 1), a1 + hstepA, voffA);
;     ...
;             PG8_LDA(At, 1, 1); PG8_STAGE(PG8_SB(1, 0), b3, voffB); PG8_STAGE(PG8_SB(1, 1), b3 + hstepB, voffB); PG8_STAGE(PG8_SA(1, 0), a3, voffA);
;             PG8_WAIT_V(8); PG8_WAIT_L(0); PG8_BAR; PG8_MMA(1, 0, At, B0); PG8_MMA(1, 1, At, B1); PG8_BAR; PG8_SCHED;
	s_add_i32 s52, s72, s54
	v_lshl_add_u64 v[218:219], v[218:219], 0, s[20:21]
	s_mov_b32 m0, s52
	ds_read_b128 v[160:163], v210 offset:49152
	ds_read_b128 v[164:167], v210 offset:50176
	ds_read_b128 v[186:189], v210 offset:51200
	ds_read_b128 v[190:193], v210 offset:52224
	ds_read_b128 v[194:197], v210 offset:53248
	ds_read_b128 v[198:201], v210 offset:54272
	ds_read_b128 v[202:205], v210 offset:55296
	ds_read_b128 v[214:217], v210 offset:56320
	global_load_lds_dwordx4 v[218:219], off
	s_add_i32 m0, s52, 0x2000
	s_add_u32 s44, s44, 0x40080
	v_lshl_add_u64 v[218:219], v[220:221], 0, s[20:21]
	s_addc_u32 s45, s45, 0
	s_add_i32 s52, s73, s54
	global_load_lds_dwordx4 v[218:219], off
	v_lshl_add_u64 v[218:219], s[44:45], 0, v[170:171]
	s_mov_b32 m0, s52
	s_nop 0
	global_load_lds_dwordx4 v[218:219], off
	v_lshl_add_u64 v[218:219], s[44:45], 0, v[174:175]
	s_add_i32 m0, s52, 0x2000
	s_nop 0
	global_load_lds_dwordx4 v[218:219], off
	v_lshl_add_u64 v[218:219], v[222:223], 0, s[20:21]
	s_mov_b32 m0, s62
	s_nop 0
	global_load_lds_dwordx4 v[218:219], off
	v_lshl_add_u64 v[218:219], v[224:225], 0, s[20:21]
	s_mov_b32 m0, s63
	s_nop 0
	global_load_lds_dwordx4 v[218:219], off
	s_waitcnt vmcnt(8)
	s_waitcnt lgkmcnt(0)
	s_barrier
	s_waitcnt lgkmcnt(0)
	v_mfma_f32_16x16x32_bf16 v[76:79], v[56:59], v[160:163], v[76:79]
	v_mfma_f32_16x16x32_bf16 v[72:75], v[64:67], v[160:163], v[72:75]
	v_mfma_f32_16x16x32_bf16 v[52:55], v[56:59], v[186:189], v[52:55]
	v_mfma_f32_16x16x32_bf16 v[48:51], v[64:67], v[186:189], v[48:51]
	v_mfma_f32_16x16x32_bf16 v[28:31], v[56:59], v[194:197], v[28:31]
	v_mfma_f32_16x16x32_bf16 v[24:27], v[64:67], v[194:197], v[24:27]
	v_mfma_f32_16x16x32_bf16 v[12:15], v[56:59], v[202:205], v[12:15]
	v_mfma_f32_16x16x32_bf16 v[8:11], v[64:67], v[202:205], v[8:11]
	v_mfma_f32_16x16x32_bf16 v[76:79], v[60:63], v[164:167], v[76:79]
	v_mfma_f32_16x16x32_bf16 v[72:75], v[68:71], v[164:167], v[72:75]
	v_mfma_f32_16x16x32_bf16 v[52:55], v[60:63], v[190:193], v[52:55]
	v_mfma_f32_16x16x32_bf16 v[48:51], v[68:71], v[190:193], v[48:51]
	v_mfma_f32_16x16x32_bf16 v[28:31], v[60:63], v[198:201], v[28:31]
	v_mfma_f32_16x16x32_bf16 v[24:27], v[68:71], v[198:201], v[24:27]
	v_mfma_f32_16x16x32_bf16 v[12:15], v[60:63], v[214:217], v[12:15]
	v_mfma_f32_16x16x32_bf16 v[8:11], v[68:71], v[214:217], v[8:11]
	v_mfma_f32_16x16x32_bf16 v[40:43], v[144:147], v[160:163], v[40:43]
	v_mfma_f32_16x16x32_bf16 v[68:71], v[148:151], v[164:167], v[40:43]
	v_mfma_f32_16x16x32_bf16 v[40:43], v[152:155], v[160:163], v[44:47]
	v_mfma_f32_16x16x32_bf16 v[36:39], v[144:147], v[186:189], v[36:39]
	v_mfma_f32_16x16x32_bf16 v[32:35], v[152:155], v[186:189], v[32:35]
	v_mfma_f32_16x16x32_bf16 v[20:23], v[144:147], v[194:197], v[20:23]
	v_mfma_f32_16x16x32_bf16 v[16:19], v[152:155], v[194:197], v[16:19]
	v_mfma_f32_16x16x32_bf16 v[4:7], v[144:147], v[202:205], v[4:7]
	v_mfma_f32_16x16x32_bf16 v[0:3], v[152:155], v[202:205], v[0:3]
	v_mfma_f32_16x16x32_bf16 v[64:67], v[156:159], v[164:167], v[40:43]
	v_mfma_f32_16x16x32_bf16 v[36:39], v[148:151], v[190:193], v[36:39]
	v_mfma_f32_16x16x32_bf16 v[32:35], v[156:159], v[190:193], v[32:35]
	v_mfma_f32_16x16x32_bf16 v[20:23], v[148:151], v[198:201], v[20:23]
	v_mfma_f32_16x16x32_bf16 v[16:19], v[156:159], v[198:201], v[16:19]
	v_mfma_f32_16x16x32_bf16 v[4:7], v[148:151], v[214:217], v[4:7]
	v_mfma_f32_16x16x32_bf16 v[0:3], v[156:159], v[214:217], v[0:3]
	s_barrier
	s_add_i32 s71, s71, 2
	s_add_u32 s42, s42, 0x100
	s_addc_u32 s43, s43, 0
	s_add_u32 s69, s69, 0x100
	s_addc_u32 s70, s70, 0
	s_cmp_gt_u32 s71, 13
.LBB0_1746:
	ds_read_b128 v[40:43], v208
	ds_read_b128 v[44:47], v208 offset:1024
	ds_read_b128 v[56:59], v208 offset:2048
	ds_read_b128 v[60:63], v208 offset:3072
	ds_read_b128 v[144:147], v209
	ds_read_b128 v[148:151], v209 offset:1024
	ds_read_b128 v[152:155], v209 offset:2048
	ds_read_b128 v[156:159], v209 offset:3072
	s_add_u32 s44, s42, 0xfffc0080
	s_addc_u32 s45, s43, -1
	s_cmp_eq_u32 s71, 12
	s_cselect_b32 s53, s7, s45
	s_cselect_b32 s52, s9, s44
	s_cselect_b32 s45, s29, s70
	s_cselect_b32 s44, s35, s69
	v_lshl_add_u64 v[218:219], s[42:43], 0, v[178:179]
	s_add_i32 m0, s55, 0xc000
	ds_read_b128 v[160:163], v210
	ds_read_b128 v[164:167], v210 offset:1024
	ds_read_b128 v[186:189], v210 offset:2048
	ds_read_b128 v[190:193], v210 offset:3072
	ds_read_b128 v[194:197], v210 offset:4096
	ds_read_b128 v[198:201], v210 offset:5120
	ds_read_b128 v[202:205], v210 offset:6144
	ds_read_b128 v[214:217], v210 offset:7168
	global_load_lds_dwordx4 v[218:219], off
	v_lshl_add_u64 v[218:219], s[42:43], 0, v[180:181]
	s_add_i32 m0, s55, 0xe000
	s_nop 0
	global_load_lds_dwordx4 v[218:219], off
	s_waitcnt vmcnt(8)
	s_waitcnt lgkmcnt(0)
	s_barrier
; #define PG8_STAGE(bufoff, gbase, voff) do { _Pragma("unroll") for (int _i = 0; _i < 2; ++_i) \
;         __builtin_amdgcn_global_load_lds((const unsigned*)((const char*)(gbase) + (voff)[_i]), (LAS unsigned*)(lds + (bufoff) + ldsw + _i * 8192), 16, 0, 0); } while (0)
; #define PG8_LDA(dst, b, h) do { _Pragma("unroll") for (int m = 0; m < 4; ++m) _Pragma("unroll") for (int k = 0; k < 2; ++k) dst[m][k] = *(const LAS bf16x8*)(lds + PG8_SA(b, h) + aoff + m * 2048 + k * 1024); } while (0)
; #define PG8_LDB(dst, b, h) do { _Pragma("unroll") for (int n = 0; n < 2; ++n) _Pragma("unroll") for (int k = 0; k < 2; ++k) dst[n][k] = *(const LAS bf16x8*)(lds + PG8_SB(b, h) + boff + n * 2048 + k * 1024); } while (0)
; #define PG8_MMA(ai, bj, At, Bt) do { __builtin_amdgcn_s_setprio(1); _Pragma("unroll") for (int m = 0; m < 4; ++m) _Pragma("unroll") for (int n = 0; n < 2; ++n) _Pragma("unroll") for (int k = 0; k < 2; ++k) \
;         acc[ai][bj][m][n] = __builtin_amdgcn_mfma_f32_16x16x32_bf16(Bt[n][k], At[m][k], acc[ai][bj][m][n], 0, 0, 0); __builtin_amdgcn_s_setprio(0); } while (0)
; #define PG8_WAIT_V(n) asm volatile("s_waitcnt vmcnt(" #n ")" ::: "memory")
; #define PG8_WAIT_L(n) asm volatile("s_waitcnt lgkmcnt(" #n ")" ::: "memory")
; #define PG8_BAR __builtin_amdgcn_s_barrier()
; #define PG8_SCHED __builtin_amdgcn_sched_barrier(0)
; template <class Epi>
; __device__ __forceinline__ void gemm_phase(LAS unsigned char* lds, const Gemm g, const StaticOrder& S, const Epi& E) {
;     ...
;             PG8_LDB(B0, 0, 0); PG8_LDB(B1, 0, 1); PG8_SCHED; PG8_LDA(At, 0, 0); PG8_STAGE(PG8_SA(1, 1), a1 + hstepA, voffA);
;             PG8_WAIT_V(8); PG8_WAIT_L(0); PG8_BAR; PG8_MMA(0, 0, At, B0); PG8_MMA(0, 1, At, B1); PG8_BAR; PG8_SCHED;
;             PG8_LDA(At, 0, 1); PG8_STAGE(PG8_SB(0, 0), b2, voffB); PG8_STAGE(PG8_SB(0, 1), b2 + hstepB, voffB); PG8_STAGE(PG8_SA(0, 0), a2, voffA);
;             PG8_WAIT_V(8); PG8_WAIT_L(0); PG8_BAR; PG8_MMA(1, 0, At, B0); PG8_MMA(1, 1, At, B1); PG8_BAR; PG8_SCHED;
	s_waitcnt lgkmcnt(0)
	v_mfma_f32_16x16x32_bf16 v[140:143], v[40:43], v[160:163], v[140:143]
	v_mfma_f32_16x16x32_bf16 v[136:139], v[56:59], v[160:163], v[136:139]
	v_mfma_f32_16x16x32_bf16 v[124:127], v[40:43], v[186:189], v[124:127]
	v_mfma_f32_16x16x32_bf16 v[120:123], v[56:59], v[186:189], v[120:123]
	v_mfma_f32_16x16x32_bf16 v[108:111], v[40:43], v[194:197], v[108:111]
	v_mfma_f32_16x16x32_bf16 v[104:107], v[56:59], v[194:197], v[104:107]
	v_mfma_f32_16x16x32_bf16 v[92:95], v[40:43], v[202:205], v[92:95]
	v_mfma_f32_16x16x32_bf16 v[88:91], v[56:59], v[202:205], v[88:91]
	v_mfma_f32_16x16x32_bf16 v[140:143], v[44:47], v[164:167], v[140:143]
	v_mfma_f32_16x16x32_bf16 v[136:139], v[60:63], v[164:167], v[136:139]
	v_mfma_f32_16x16x32_bf16 v[124:127], v[44:47], v[190:193], v[124:127]
	v_mfma_f32_16x16x32_bf16 v[120:123], v[60:63], v[190:193], v[120:123]
	v_mfma_f32_16x16x32_bf16 v[108:111], v[44:47], v[198:201], v[108:111]
	v_mfma_f32_16x16x32_bf16 v[104:107], v[60:63], v[198:201], v[104:107]
	v_mfma_f32_16x16x32_bf16 v[92:95], v[44:47], v[214:217], v[92:95]
	v_mfma_f32_16x16x32_bf16 v[88:91], v[60:63], v[214:217], v[88:91]
	v_mfma_f32_16x16x32_bf16 v[132:135], v[144:147], v[160:163], v[132:135]
	v_mfma_f32_16x16x32_bf16 v[128:131], v[152:155], v[160:163], v[128:131]
	v_mfma_f32_16x16x32_bf16 v[116:119], v[144:147], v[186:189], v[116:119]
	v_mfma_f32_16x16x32_bf16 v[112:115], v[152:155], v[186:189], v[112:115]
	v_mfma_f32_16x16x32_bf16 v[100:103], v[144:147], v[194:197], v[100:103]
	v_mfma_f32_16x16x32_bf16 v[96:99], v[152:155], v[194:197], v[96:99]
	v_mfma_f32_16x16x32_bf16 v[84:87], v[144:147], v[202:205], v[84:87]
	v_mfma_f32_16x16x32_bf16 v[80:83], v[152:155], v[202:205], v[80:83]
	v_mfma_f32_16x16x32_bf16 v[132:135], v[148:151], v[164:167], v[132:135]
	v_mfma_f32_16x16x32_bf16 v[128:131], v[156:159], v[164:167], v[128:131]
	v_mfma_f32_16x16x32_bf16 v[116:119], v[148:151], v[190:193], v[116:119]
	v_mfma_f32_16x16x32_bf16 v[112:115], v[156:159], v[190:193], v[112:115]
	v_mfma_f32_16x16x32_bf16 v[100:103], v[148:151], v[198:201], v[100:103]
	v_mfma_f32_16x16x32_bf16 v[96:99], v[156:159], v[198:201], v[96:99]
	v_mfma_f32_16x16x32_bf16 v[84:87], v[148:151], v[214:217], v[84:87]
	v_mfma_f32_16x16x32_bf16 v[80:83], v[156:159], v[214:217], v[80:83]
	s_barrier
	s_add_i32 s72, s67, s54
	v_lshl_add_u64 v[218:219], s[44:45], 0, v[170:171]
	s_mov_b32 m0, s72
	ds_read_b128 v[160:163], v210 offset:16384
	ds_read_b128 v[164:167], v210 offset:17408
	ds_read_b128 v[186:189], v210 offset:18432
	ds_read_b128 v[190:193], v210 offset:19456
	ds_read_b128 v[194:197], v210 offset:20480
	ds_read_b128 v[198:201], v210 offset:21504
	ds_read_b128 v[202:205], v210 offset:22528
	ds_read_b128 v[214:217], v210 offset:23552
	global_load_lds_dwordx4 v[218:219], off
	s_add_i32 m0, s72, 0x2000
	s_add_u32 s72, s44, 0x40000
	v_lshl_add_u64 v[220:221], s[44:45], 0, v[174:175]
	s_addc_u32 s73, s45, 0
	s_add_i32 s74, s68, s54
	global_load_lds_dwordx4 v[220:221], off
	v_lshl_add_u64 v[222:223], s[72:73], 0, v[170:171]
	s_mov_b32 m0, s74
	v_lshl_add_u64 v[224:225], s[52:53], 0, v[172:173]
	global_load_lds_dwordx4 v[222:223], off
	v_lshl_add_u64 v[222:223], s[72:73], 0, v[174:175]
	s_add_i32 m0, s74, 0x2000
	s_nop 0
	global_load_lds_dwordx4 v[222:223], off
	v_lshl_add_u64 v[222:223], s[52:53], 0, v[168:169]
	s_mov_b32 m0, s55
	s_nop 0
	global_load_lds_dwordx4 v[222:223], off
	s_mov_b32 m0, s56
	s_nop 0
	global_load_lds_dwordx4 v[224:225], off
	s_waitcnt vmcnt(8)
	s_waitcnt lgkmcnt(0)
	s_barrier
	s_waitcnt lgkmcnt(0)
	v_mfma_f32_16x16x32_bf16 v[76:79], v[40:43], v[160:163], v[76:79]
	v_mfma_f32_16x16x32_bf16 v[72:75], v[56:59], v[160:163], v[72:75]
	v_mfma_f32_16x16x32_bf16 v[52:55], v[40:43], v[186:189], v[52:55]
	v_mfma_f32_16x16x32_bf16 v[48:51], v[56:59], v[186:189], v[48:51]
	v_mfma_f32_16x16x32_bf16 v[28:31], v[40:43], v[194:197], v[28:31]
	v_mfma_f32_16x16x32_bf16 v[24:27], v[56:59], v[194:197], v[24:27]
	v_mfma_f32_16x16x32_bf16 v[12:15], v[40:43], v[202:205], v[12:15]
	v_mfma_f32_16x16x32_bf16 v[8:11], v[56:59], v[202:205], v[8:11]
	v_mfma_f32_16x16x32_bf16 v[76:79], v[44:47], v[164:167], v[76:79]
	v_mfma_f32_16x16x32_bf16 v[72:75], v[60:63], v[164:167], v[72:75]
	v_mfma_f32_16x16x32_bf16 v[52:55], v[44:47], v[190:193], v[52:55]
	v_mfma_f32_16x16x32_bf16 v[48:51], v[60:63], v[190:193], v[48:51]
	v_mfma_f32_16x16x32_bf16 v[28:31], v[44:47], v[198:201], v[28:31]
	v_mfma_f32_16x16x32_bf16 v[24:27], v[60:63], v[198:201], v[24:27]
	v_mfma_f32_16x16x32_bf16 v[12:15], v[44:47], v[214:217], v[12:15]
	v_mfma_f32_16x16x32_bf16 v[8:11], v[60:63], v[214:217], v[8:11]
	v_mfma_f32_16x16x32_bf16 v[36:39], v[144:147], v[186:189], v[36:39]
	v_mfma_f32_16x16x32_bf16 v[32:35], v[152:155], v[186:189], v[32:35]
	v_mfma_f32_16x16x32_bf16 v[20:23], v[144:147], v[194:197], v[20:23]
	v_mfma_f32_16x16x32_bf16 v[16:19], v[152:155], v[194:197], v[16:19]
	v_mfma_f32_16x16x32_bf16 v[4:7], v[144:147], v[202:205], v[4:7]
	v_mfma_f32_16x16x32_bf16 v[0:3], v[152:155], v[202:205], v[0:3]
	v_mfma_f32_16x16x32_bf16 v[40:43], v[144:147], v[160:163], v[68:71]
	v_mfma_f32_16x16x32_bf16 v[44:47], v[152:155], v[160:163], v[64:67]
	v_mfma_f32_16x16x32_bf16 v[36:39], v[148:151], v[190:193], v[36:39]
	v_mfma_f32_16x16x32_bf16 v[32:35], v[156:159], v[190:193], v[32:35]
	v_mfma_f32_16x16x32_bf16 v[20:23], v[148:151], v[198:201], v[20:23]
	v_mfma_f32_16x16x32_bf16 v[16:19], v[156:159], v[198:201], v[16:19]
	v_mfma_f32_16x16x32_bf16 v[4:7], v[148:151], v[214:217], v[4:7]
	v_mfma_f32_16x16x32_bf16 v[0:3], v[156:159], v[214:217], v[0:3]
	v_mfma_f32_16x16x32_bf16 v[40:43], v[148:151], v[164:167], v[40:43]
	v_mfma_f32_16x16x32_bf16 v[44:47], v[156:159], v[164:167], v[44:47]
	s_barrier
; #define PG8_STAGE(bufoff, gbase, voff) do { _Pragma("unroll") for (int _i = 0; _i < 2; ++_i) \
;         __builtin_amdgcn_global_load_lds((const unsigned*)((const char*)(gbase) + (voff)[_i]), (LAS unsigned*)(lds + (bufoff) + ldsw + _i * 8192), 16, 0, 0); } while (0)
; #define PG8_LDA(dst, b, h) do { _Pragma("unroll") for (int m = 0; m < 4; ++m) _Pragma("unroll") for (int k = 0; k < 2; ++k) dst[m][k] = *(const LAS bf16x8*)(lds + PG8_SA(b, h) + aoff + m * 2048 + k * 1024); } while (0)
; #define PG8_LDB(dst, b, h) do { _Pragma("unroll") for (int n = 0; n < 2; ++n) _Pragma("unroll") for (int k = 0; k < 2; ++k) dst[n][k] = *(const LAS bf16x8*)(lds + PG8_SB(b, h) + boff + n * 2048 + k * 1024); } while (0)
; #define PG8_MMA(ai, bj, At, Bt) do { __builtin_amdgcn_s_setprio(1); _Pragma("unroll") for (int m = 0; m < 4; ++m) _Pragma("unroll") for (int n = 0; n < 2; ++n) _Pragma("unroll") for (int k = 0; k < 2; ++k) \
;         acc[ai][bj][m][n] = __builtin_amdgcn_mfma_f32_16x16x32_bf16(Bt[n][k], At[m][k], acc[ai][bj][m][n], 0, 0, 0); __builtin_amdgcn_s_setprio(0); } while (0)
; #define PG8_WAIT_V(n) asm volatile("s_waitcnt vmcnt(" #n ")" ::: "memory")
; #define PG8_WAIT_L(n) asm volatile("s_waitcnt lgkmcnt(" #n ")" ::: "memory")
; #define PG8_BAR __builtin_amdgcn_s_barrier()
; #define PG8_SCHED __builtin_amdgcn_sched_barrier(0)
; template <class Epi>
; __device__ __forceinline__ void gemm_phase(LAS unsigned char* lds, const Gemm g, const StaticOrder& S, const Epi& E) {
;     ...
;             PG8_LDB(B0, 1, 0); PG8_LDB(B1, 1, 1); PG8_SCHED; PG8_LDA(At, 1, 0); PG8_STAGE(PG8_SA(0, 1), a2 + hstepA, voffA);
;             PG8_WAIT_V(8); PG8_WAIT_L(0); PG8_BAR; PG8_MMA(0, 0, At, B0); PG8_MMA(0, 1, At, B1); PG8_BAR; PG8_SCHED;
	s_add_i32 s72, 0, 0x18000
	s_add_i32 s73, 0, 0x1c000
	v_add_u32_e32 v68, s72, v207
	v_add_u32_e32 v156, s73, v207
	ds_read_b128 v[56:59], v68
	ds_read_b128 v[60:63], v68 offset:1024
	ds_read_b128 v[64:67], v68 offset:2048
	ds_read_b128 v[68:71], v68 offset:3072
	ds_read_b128 v[144:147], v156
	ds_read_b128 v[148:151], v156 offset:1024
	ds_read_b128 v[152:155], v156 offset:2048
	ds_read_b128 v[156:159], v156 offset:3072
	s_add_u32 s52, s52, 0x40000
	s_addc_u32 s53, s53, 0
	s_mov_b32 m0, s57
	v_lshl_add_u64 v[226:227], s[52:53], 0, v[168:169]
	ds_read_b128 v[160:163], v210 offset:32768
	ds_read_b128 v[164:167], v210 offset:33792
	ds_read_b128 v[186:189], v210 offset:34816
	ds_read_b128 v[190:193], v210 offset:35840
	ds_read_b128 v[194:197], v210 offset:36864
	ds_read_b128 v[198:201], v210 offset:37888
	ds_read_b128 v[202:205], v210 offset:38912
	ds_read_b128 v[214:217], v210 offset:39936
	global_load_lds_dwordx4 v[226:227], off
	v_lshl_add_u64 v[226:227], s[52:53], 0, v[172:173]
	s_mov_b32 m0, s58
	s_nop 0
	global_load_lds_dwordx4 v[226:227], off
	s_waitcnt vmcnt(8)
	s_waitcnt lgkmcnt(0)
	s_barrier
	s_waitcnt lgkmcnt(0)
	v_mfma_f32_16x16x32_bf16 v[140:143], v[56:59], v[160:163], v[140:143]
	v_mfma_f32_16x16x32_bf16 v[136:139], v[64:67], v[160:163], v[136:139]
	v_mfma_f32_16x16x32_bf16 v[124:127], v[56:59], v[186:189], v[124:127]
	v_mfma_f32_16x16x32_bf16 v[120:123], v[64:67], v[186:189], v[120:123]
	v_mfma_f32_16x16x32_bf16 v[108:111], v[56:59], v[194:197], v[108:111]
	v_mfma_f32_16x16x32_bf16 v[104:107], v[64:67], v[194:197], v[104:107]
	v_mfma_f32_16x16x32_bf16 v[92:95], v[56:59], v[202:205], v[92:95]
	v_mfma_f32_16x16x32_bf16 v[88:91], v[64:67], v[202:205], v[88:91]
	v_mfma_f32_16x16x32_bf16 v[140:143], v[60:63], v[164:167], v[140:143]
	v_mfma_f32_16x16x32_bf16 v[136:139], v[68:71], v[164:167], v[136:139]
	v_mfma_f32_16x16x32_bf16 v[124:127], v[60:63], v[190:193], v[124:127]
	v_mfma_f32_16x16x32_bf16 v[120:123], v[68:71], v[190:193], v[120:123]
	v_mfma_f32_16x16x32_bf16 v[108:111], v[60:63], v[198:201], v[108:111]
	v_mfma_f32_16x16x32_bf16 v[104:107], v[68:71], v[198:201], v[104:107]
	v_mfma_f32_16x16x32_bf16 v[92:95], v[60:63], v[214:217], v[92:95]
	v_mfma_f32_16x16x32_bf16 v[88:91], v[68:71], v[214:217], v[88:91]
	v_mfma_f32_16x16x32_bf16 v[132:135], v[144:147], v[160:163], v[132:135]
	v_mfma_f32_16x16x32_bf16 v[128:131], v[152:155], v[160:163], v[128:131]
	v_mfma_f32_16x16x32_bf16 v[116:119], v[144:147], v[186:189], v[116:119]
	v_mfma_f32_16x16x32_bf16 v[112:115], v[152:155], v[186:189], v[112:115]
	v_mfma_f32_16x16x32_bf16 v[100:103], v[144:147], v[194:197], v[100:103]
	v_mfma_f32_16x16x32_bf16 v[96:99], v[152:155], v[194:197], v[96:99]
	v_mfma_f32_16x16x32_bf16 v[84:87], v[144:147], v[202:205], v[84:87]
	v_mfma_f32_16x16x32_bf16 v[80:83], v[152:155], v[202:205], v[80:83]
	v_mfma_f32_16x16x32_bf16 v[132:135], v[148:151], v[164:167], v[132:135]
	v_mfma_f32_16x16x32_bf16 v[128:131], v[156:159], v[164:167], v[128:131]
	v_mfma_f32_16x16x32_bf16 v[116:119], v[148:151], v[190:193], v[116:119]
	v_mfma_f32_16x16x32_bf16 v[112:115], v[156:159], v[190:193], v[112:115]
	v_mfma_f32_16x16x32_bf16 v[100:103], v[148:151], v[198:201], v[100:103]
	v_mfma_f32_16x16x32_bf16 v[96:99], v[156:159], v[198:201], v[96:99]
	v_mfma_f32_16x16x32_bf16 v[84:87], v[148:151], v[214:217], v[84:87]
	v_mfma_f32_16x16x32_bf16 v[80:83], v[156:159], v[214:217], v[80:83]
	s_barrier
; #define PG8_STAGE(bufoff, gbase, voff) do { _Pragma("unroll") for (int _i = 0; _i < 2; ++_i) \
;         __builtin_amdgcn_global_load_lds((const unsigned*)((const char*)(gbase) + (voff)[_i]), (LAS unsigned*)(lds + (bufoff) + ldsw + _i * 8192), 16, 0, 0); } while (0)
; #define PG8_LDA(dst, b, h) do { _Pragma("unroll") for (int m = 0; m < 4; ++m) _Pragma("unroll") for (int k = 0; k < 2; ++k) dst[m][k] = *(const LAS bf16x8*)(lds + PG8_SA(b, h) + aoff + m * 2048 + k * 1024); } while (0)
; #define PG8_MMA(ai, bj, At, Bt) do { __builtin_amdgcn_s_setprio(1); _Pragma("unroll") for (int m = 0; m < 4; ++m) _Pragma("unroll") for (int n = 0; n < 2; ++n) _Pragma("unroll") for (int k = 0; k < 2; ++k) \
;         acc[ai][bj][m][n] = __builtin_amdgcn_mfma_f32_16x16x32_bf16(Bt[n][k], At[m][k], acc[ai][bj][m][n], 0, 0, 0); __builtin_amdgcn_s_setprio(0); } while (0)
; #define PG8_WAIT_V(n) asm volatile("s_waitcnt vmcnt(" #n ")" ::: "memory")
; #define PG8_WAIT_L(n) asm volatile("s_waitcnt lgkmcnt(" #n ")" ::: "memory")
; #define PG8_BAR __builtin_amdgcn_s_barrier()
; #define PG8_SCHED __builtin_amdgcn_sched_barrier(0)
; template <class Epi>
; __device__ __forceinline__ void gemm_phase(LAS unsigned char* lds, const Gemm g, const StaticOrder& S, const Epi& E) {
;     ...
;             PG8_LDA(At, 1, 1); PG8_STAGE(PG8_SB(1, 0), b3, voffB); PG8_STAGE(PG8_SB(1, 1), b3 + hstepB, voffB); PG8_STAGE(PG8_SA(1, 0), a3, voffA);
;             PG8_WAIT_V(8); PG8_WAIT_L(0); PG8_BAR; PG8_MMA(1, 0, At, B0); PG8_MMA(1, 1, At, B1); PG8_BAR; PG8_SCHED;
;         }
;         if (wr == 0) PG8_BAR;
	s_add_i32 s52, s72, s54
	v_lshl_add_u64 v[218:219], v[218:219], 0, s[20:21]
	s_mov_b32 m0, s52
	ds_read_b128 v[160:163], v210 offset:49152
	ds_read_b128 v[164:167], v210 offset:50176
	ds_read_b128 v[186:189], v210 offset:51200
	ds_read_b128 v[190:193], v210 offset:52224
	ds_read_b128 v[194:197], v210 offset:53248
	ds_read_b128 v[198:201], v210 offset:54272
	ds_read_b128 v[202:205], v210 offset:55296
	ds_read_b128 v[214:217], v210 offset:56320
	global_load_lds_dwordx4 v[218:219], off
	s_add_i32 m0, s52, 0x2000
	s_add_u32 s44, s44, 0x40080
	v_lshl_add_u64 v[218:219], v[220:221], 0, s[20:21]
	s_addc_u32 s45, s45, 0
	s_add_i32 s52, s73, s54
	global_load_lds_dwordx4 v[218:219], off
	v_lshl_add_u64 v[218:219], s[44:45], 0, v[170:171]
	s_mov_b32 m0, s52
	s_nop 0
	global_load_lds_dwordx4 v[218:219], off
	v_lshl_add_u64 v[218:219], s[44:45], 0, v[174:175]
	s_add_i32 m0, s52, 0x2000
	s_nop 0
	global_load_lds_dwordx4 v[218:219], off
	v_lshl_add_u64 v[218:219], v[222:223], 0, s[20:21]
	s_mov_b32 m0, s62
	s_nop 0
	global_load_lds_dwordx4 v[218:219], off
	v_lshl_add_u64 v[218:219], v[224:225], 0, s[20:21]
	s_mov_b32 m0, s63
	s_nop 0
	global_load_lds_dwordx4 v[218:219], off
	s_waitcnt vmcnt(8)
	s_waitcnt lgkmcnt(0)
	s_barrier
	s_waitcnt lgkmcnt(0)
	v_mfma_f32_16x16x32_bf16 v[76:79], v[56:59], v[160:163], v[76:79]
	v_mfma_f32_16x16x32_bf16 v[72:75], v[64:67], v[160:163], v[72:75]
	v_mfma_f32_16x16x32_bf16 v[52:55], v[56:59], v[186:189], v[52:55]
	v_mfma_f32_16x16x32_bf16 v[48:51], v[64:67], v[186:189], v[48:51]
	v_mfma_f32_16x16x32_bf16 v[28:31], v[56:59], v[194:197], v[28:31]
	v_mfma_f32_16x16x32_bf16 v[24:27], v[64:67], v[194:197], v[24:27]
	v_mfma_f32_16x16x32_bf16 v[12:15], v[56:59], v[202:205], v[12:15]
	v_mfma_f32_16x16x32_bf16 v[8:11], v[64:67], v[202:205], v[8:11]
	v_mfma_f32_16x16x32_bf16 v[76:79], v[60:63], v[164:167], v[76:79]
	v_mfma_f32_16x16x32_bf16 v[72:75], v[68:71], v[164:167], v[72:75]
	v_mfma_f32_16x16x32_bf16 v[52:55], v[60:63], v[190:193], v[52:55]
	v_mfma_f32_16x16x32_bf16 v[48:51], v[68:71], v[190:193], v[48:51]
	v_mfma_f32_16x16x32_bf16 v[28:31], v[60:63], v[198:201], v[28:31]
	v_mfma_f32_16x16x32_bf16 v[24:27], v[68:71], v[198:201], v[24:27]
	v_mfma_f32_16x16x32_bf16 v[12:15], v[60:63], v[214:217], v[12:15]
	v_mfma_f32_16x16x32_bf16 v[8:11], v[68:71], v[214:217], v[8:11]
	v_mfma_f32_16x16x32_bf16 v[40:43], v[144:147], v[160:163], v[40:43]
	v_mfma_f32_16x16x32_bf16 v[68:71], v[148:151], v[164:167], v[40:43]
	v_mfma_f32_16x16x32_bf16 v[40:43], v[152:155], v[160:163], v[44:47]
	v_mfma_f32_16x16x32_bf16 v[36:39], v[144:147], v[186:189], v[36:39]
	v_mfma_f32_16x16x32_bf16 v[32:35], v[152:155], v[186:189], v[32:35]
	v_mfma_f32_16x16x32_bf16 v[20:23], v[144:147], v[194:197], v[20:23]
	v_mfma_f32_16x16x32_bf16 v[16:19], v[152:155], v[194:197], v[16:19]
	v_mfma_f32_16x16x32_bf16 v[4:7], v[144:147], v[202:205], v[4:7]
	v_mfma_f32_16x16x32_bf16 v[0:3], v[152:155], v[202:205], v[0:3]
	v_mfma_f32_16x16x32_bf16 v[64:67], v[156:159], v[164:167], v[40:43]
	v_mfma_f32_16x16x32_bf16 v[36:39], v[148:151], v[190:193], v[36:39]
	v_mfma_f32_16x16x32_bf16 v[32:35], v[156:159], v[190:193], v[32:35]
	v_mfma_f32_16x16x32_bf16 v[20:23], v[148:151], v[198:201], v[20:23]
	v_mfma_f32_16x16x32_bf16 v[16:19], v[156:159], v[198:201], v[16:19]
	v_mfma_f32_16x16x32_bf16 v[4:7], v[148:151], v[214:217], v[4:7]
	v_mfma_f32_16x16x32_bf16 v[0:3], v[156:159], v[214:217], v[0:3]
	s_barrier
	s_add_i32 s71, s71, 2
	s_add_u32 s42, s42, 0x100
	s_addc_u32 s43, s43, 0
	s_add_u32 s69, s69, 0x100
	s_addc_u32 s70, s70, 0
	s_cmp_gt_u32 s71, 13
	s_cbranch_scc0 .LBB0_1746
	s_and_b64 vcc, exec, s[22:23]
	s_cbranch_vccz .LBB0_1749
	s_barrier
